# weight-conversion loops (20 copies): both 16-load batches of an item issued before the first LDS write (32 loads in flight instead of 16)
# baseline (speedup 1.0000x reference)
.LBB0_668:
	s_lshl_b32 s13, s4, 1
	s_lshl_b32 s14, s5, 1
	v_or_b32_e32 v7, s13, v1
	v_or_b32_e32 v9, s14, v0
	s_add_i32 s15, s13, 4
	s_add_i32 s22, s14, 4
	s_add_i32 s23, s13, 8
	s_add_i32 s24, s14, 8
	s_add_i32 s25, s13, 12
	s_add_i32 s26, s14, 12
	s_add_i32 s27, s13, 16
	s_add_i32 s30, s14, 16
	s_add_i32 s36, s13, 20
	s_add_i32 s37, s14, 20
	s_add_i32 s40, s13, 24
	s_add_i32 s41, s14, 24
	s_add_i32 s13, s13, 28
	s_add_i32 s14, s14, 28
	v_add_u32_e32 v11, s1, v7
	v_add_u32_e32 v13, s8, v9
	v_or_b32_e32 v15, s15, v1
	v_or_b32_e32 v19, s22, v0
	v_or_b32_e32 v41, s23, v1
	v_or_b32_e32 v43, s24, v0
	v_or_b32_e32 v45, s25, v1
	v_or_b32_e32 v47, s26, v0
	v_or_b32_e32 v49, s27, v1
	v_or_b32_e32 v82, s30, v0
	v_or_b32_e32 v86, s36, v1
	v_or_b32_e32 v87, s37, v0
	v_or_b32_e32 v88, s40, v1
	v_or_b32_e32 v89, s41, v0
	v_or_b32_e32 v90, s13, v1
	v_or_b32_e32 v91, s14, v0
	v_mad_i64_i32 v[52:53], s[14:15], v13, s80, v[50:51]
	v_mad_i64_i32 v[54:55], s[14:15], v11, s80, v[50:51]
	v_add_u32_e32 v11, s1, v15
	v_add_u32_e32 v13, s8, v19
	v_add_u32_e32 v62, s1, v41
	v_add_u32_e32 v60, s8, v43
	v_add_u32_e32 v66, s1, v45
	v_add_u32_e32 v64, s8, v47
	v_add_u32_e32 v70, s1, v49
	v_add_u32_e32 v68, s8, v82
	v_add_u32_e32 v74, s1, v86
	v_add_u32_e32 v72, s8, v87
	v_add_u32_e32 v78, s1, v88
	v_add_u32_e32 v76, s8, v89
	v_add_u32_e32 v84, s1, v90
	v_add_u32_e32 v80, s8, v91
	v_mad_i64_i32 v[56:57], s[14:15], v13, s80, v[50:51]
	v_mad_i64_i32 v[58:59], s[14:15], v11, s80, v[50:51]
	v_mad_i64_i32 v[60:61], s[14:15], v60, s80, v[50:51]
	v_mad_i64_i32 v[62:63], s[14:15], v62, s80, v[50:51]
	v_mad_i64_i32 v[64:65], s[14:15], v64, s80, v[50:51]
	v_mad_i64_i32 v[66:67], s[14:15], v66, s80, v[50:51]
	v_mad_i64_i32 v[68:69], s[14:15], v68, s80, v[50:51]
	v_mad_i64_i32 v[70:71], s[14:15], v70, s80, v[50:51]
	v_mad_i64_i32 v[72:73], s[14:15], v72, s80, v[50:51]
	v_mad_i64_i32 v[74:75], s[14:15], v74, s80, v[50:51]
	v_mad_i64_i32 v[76:77], s[14:15], v76, s80, v[50:51]
	v_mad_i64_i32 v[78:79], s[14:15], v78, s80, v[50:51]
	v_mad_i64_i32 v[80:81], s[14:15], v80, s80, v[50:51]
	v_mad_i64_i32 v[84:85], s[14:15], v84, s80, v[50:51]
	global_load_dword v11, v[52:53], off
	global_load_dword v13, v[54:55], off
	global_load_dword v92, v[56:57], off
	global_load_dword v93, v[58:59], off
	global_load_dword v94, v[60:61], off
	global_load_dword v95, v[62:63], off
	global_load_dword v96, v[64:65], off
	global_load_dword v97, v[66:67], off
	global_load_dword v98, v[68:69], off
	global_load_dword v99, v[70:71], off
	global_load_dword v100, v[72:73], off
	global_load_dword v101, v[74:75], off
	global_load_dword v102, v[76:77], off
	global_load_dword v103, v[78:79], off
	global_load_dword v104, v[80:81], off
	global_load_dword v105, v[84:85], off
	s_add_i32 s5, s5, 16
	s_add_i32 s4, s4, 16
	s_lshl_b32 s13, s4, 1
	s_lshl_b32 s14, s5, 1
	v_or_b32_e32 v106, s13, v1
	v_or_b32_e32 v107, s14, v0
	s_add_i32 s15, s13, 4
	s_add_i32 s22, s14, 4
	s_add_i32 s23, s13, 8
	s_add_i32 s24, s14, 8
	s_add_i32 s25, s13, 12
	s_add_i32 s26, s14, 12
	s_add_i32 s27, s13, 16
	s_add_i32 s30, s14, 16
	s_add_i32 s36, s13, 20
	s_add_i32 s37, s14, 20
	s_add_i32 s40, s13, 24
	s_add_i32 s41, s14, 24
	s_add_i32 s13, s13, 28
	s_add_i32 s14, s14, 28
	v_add_u32_e32 v108, s1, v106
	v_add_u32_e32 v109, s8, v107
	v_or_b32_e32 v110, s15, v1
	v_or_b32_e32 v111, s22, v0
	v_or_b32_e32 v112, s23, v1
	v_or_b32_e32 v113, s24, v0
	v_or_b32_e32 v114, s25, v1
	v_or_b32_e32 v115, s26, v0
	v_or_b32_e32 v116, s27, v1
	v_or_b32_e32 v117, s30, v0
	v_or_b32_e32 v118, s36, v1
	v_or_b32_e32 v119, s37, v0
	v_or_b32_e32 v120, s40, v1
	v_or_b32_e32 v121, s41, v0
	v_or_b32_e32 v122, s13, v1
	v_or_b32_e32 v123, s14, v0
	v_mad_i64_i32 v[130:131], s[14:15], v109, s80, v[50:51]
	v_mad_i64_i32 v[132:133], s[14:15], v108, s80, v[50:51]
	v_add_u32_e32 v108, s1, v110
	v_add_u32_e32 v109, s8, v111
	v_add_u32_e32 v140, s1, v112
	v_add_u32_e32 v138, s8, v113
	v_add_u32_e32 v144, s1, v114
	v_add_u32_e32 v142, s8, v115
	v_add_u32_e32 v148, s1, v116
	v_add_u32_e32 v146, s8, v117
	v_add_u32_e32 v152, s1, v118
	v_add_u32_e32 v150, s8, v119
	v_add_u32_e32 v156, s1, v120
	v_add_u32_e32 v154, s8, v121
	v_add_u32_e32 v160, s1, v122
	v_add_u32_e32 v158, s8, v123
	v_mad_i64_i32 v[134:135], s[14:15], v109, s80, v[50:51]
	v_mad_i64_i32 v[136:137], s[14:15], v108, s80, v[50:51]
	v_mad_i64_i32 v[138:139], s[14:15], v138, s80, v[50:51]
	v_mad_i64_i32 v[140:141], s[14:15], v140, s80, v[50:51]
	v_mad_i64_i32 v[142:143], s[14:15], v142, s80, v[50:51]
	v_mad_i64_i32 v[144:145], s[14:15], v144, s80, v[50:51]
	v_mad_i64_i32 v[146:147], s[14:15], v146, s80, v[50:51]
	v_mad_i64_i32 v[148:149], s[14:15], v148, s80, v[50:51]
	v_mad_i64_i32 v[150:151], s[14:15], v150, s80, v[50:51]
	v_mad_i64_i32 v[152:153], s[14:15], v152, s80, v[50:51]
	v_mad_i64_i32 v[154:155], s[14:15], v154, s80, v[50:51]
	v_mad_i64_i32 v[156:157], s[14:15], v156, s80, v[50:51]
	v_mad_i64_i32 v[158:159], s[14:15], v158, s80, v[50:51]
	v_mad_i64_i32 v[160:161], s[14:15], v160, s80, v[50:51]
	global_load_dword v108, v[130:131], off
	global_load_dword v109, v[132:133], off
	global_load_dword v124, v[134:135], off
	global_load_dword v125, v[136:137], off
	global_load_dword v126, v[138:139], off
	global_load_dword v127, v[140:141], off
	global_load_dword v162, v[142:143], off
	global_load_dword v163, v[144:145], off
	global_load_dword v164, v[146:147], off
	global_load_dword v165, v[148:149], off
	global_load_dword v166, v[150:151], off
	global_load_dword v167, v[152:153], off
	global_load_dword v168, v[154:155], off
	global_load_dword v169, v[156:157], off
	global_load_dword v170, v[158:159], off
	global_load_dword v171, v[160:161], off
	v_mad_u64_u32 v[52:53], s[14:15], v9, s78, v[4:5]
	v_mad_u64_u32 v[54:55], s[14:15], v7, s78, v[4:5]
	v_mad_u64_u32 v[56:57], s[14:15], v19, s78, v[4:5]
	v_mad_u64_u32 v[58:59], s[14:15], v15, s78, v[4:5]
	v_mad_u64_u32 v[60:61], s[14:15], v43, s78, v[4:5]
	v_mad_u64_u32 v[62:63], s[14:15], v41, s78, v[4:5]
	v_mad_u64_u32 v[64:65], s[14:15], v47, s78, v[4:5]
	v_mad_u64_u32 v[66:67], s[14:15], v45, s78, v[4:5]
	v_mad_u64_u32 v[68:69], s[14:15], v82, s78, v[4:5]
	v_mad_u64_u32 v[70:71], s[14:15], v49, s78, v[4:5]
	v_mad_u64_u32 v[72:73], s[14:15], v87, s78, v[4:5]
	v_mad_u64_u32 v[74:75], s[14:15], v86, s78, v[4:5]
	v_mad_u64_u32 v[76:77], s[14:15], v89, s78, v[4:5]
	v_mad_u64_u32 v[78:79], s[14:15], v88, s78, v[4:5]
	v_mad_u64_u32 v[80:81], s[14:15], v91, s78, v[4:5]
	v_mad_u64_u32 v[84:85], s[14:15], v90, s78, v[4:5]
	s_waitcnt vmcnt(31)
	ds_write_b32 v52, v11
	s_waitcnt vmcnt(30)
	ds_write_b32 v54, v13
	s_waitcnt vmcnt(29)
	ds_write_b32 v56, v92
	s_waitcnt vmcnt(28)
	ds_write_b32 v58, v93
	s_waitcnt vmcnt(27)
	ds_write_b32 v60, v94
	s_waitcnt vmcnt(26)
	ds_write_b32 v62, v95
	s_waitcnt vmcnt(25)
	ds_write_b32 v64, v96
	s_waitcnt vmcnt(24)
	ds_write_b32 v66, v97
	s_waitcnt vmcnt(23)
	ds_write_b32 v68, v98
	s_waitcnt vmcnt(22)
	ds_write_b32 v70, v99
	s_waitcnt vmcnt(21)
	ds_write_b32 v72, v100
	s_waitcnt vmcnt(20)
	ds_write_b32 v74, v101
	s_waitcnt vmcnt(19)
	ds_write_b32 v76, v102
	s_waitcnt vmcnt(18)
	ds_write_b32 v78, v103
	s_waitcnt vmcnt(17)
	ds_write_b32 v80, v104
	s_waitcnt vmcnt(16)
	ds_write_b32 v84, v105
	v_mad_u64_u32 v[130:131], s[14:15], v107, s78, v[4:5]
	v_mad_u64_u32 v[132:133], s[14:15], v106, s78, v[4:5]
	v_mad_u64_u32 v[134:135], s[14:15], v111, s78, v[4:5]
	v_mad_u64_u32 v[136:137], s[14:15], v110, s78, v[4:5]
	v_mad_u64_u32 v[138:139], s[14:15], v113, s78, v[4:5]
	v_mad_u64_u32 v[140:141], s[14:15], v112, s78, v[4:5]
	v_mad_u64_u32 v[142:143], s[14:15], v115, s78, v[4:5]
	v_mad_u64_u32 v[144:145], s[14:15], v114, s78, v[4:5]
	v_mad_u64_u32 v[146:147], s[14:15], v117, s78, v[4:5]
	v_mad_u64_u32 v[148:149], s[14:15], v116, s78, v[4:5]
	v_mad_u64_u32 v[150:151], s[14:15], v119, s78, v[4:5]
	v_mad_u64_u32 v[152:153], s[14:15], v118, s78, v[4:5]
	v_mad_u64_u32 v[154:155], s[14:15], v121, s78, v[4:5]
	v_mad_u64_u32 v[156:157], s[14:15], v120, s78, v[4:5]
	v_mad_u64_u32 v[158:159], s[14:15], v123, s78, v[4:5]
	v_mad_u64_u32 v[160:161], s[14:15], v122, s78, v[4:5]
	s_waitcnt vmcnt(15)
	ds_write_b32 v130, v108
	s_waitcnt vmcnt(14)
	ds_write_b32 v132, v109
	s_waitcnt vmcnt(13)
	ds_write_b32 v134, v124
	s_waitcnt vmcnt(12)
	ds_write_b32 v136, v125
	s_waitcnt vmcnt(11)
	ds_write_b32 v138, v126
	s_waitcnt vmcnt(10)
	ds_write_b32 v140, v127
	s_waitcnt vmcnt(9)
	ds_write_b32 v142, v162
	s_waitcnt vmcnt(8)
	ds_write_b32 v144, v163
	s_waitcnt vmcnt(7)
	ds_write_b32 v146, v164
	s_waitcnt vmcnt(6)
	ds_write_b32 v148, v165
	s_waitcnt vmcnt(5)
	ds_write_b32 v150, v166
	s_waitcnt vmcnt(4)
	ds_write_b32 v152, v167
	s_waitcnt vmcnt(3)
	ds_write_b32 v154, v168
	s_waitcnt vmcnt(2)
	ds_write_b32 v156, v169
	s_waitcnt vmcnt(1)
	ds_write_b32 v158, v170
	s_waitcnt vmcnt(0)
	ds_write_b32 v160, v171
	s_add_i32 s5, s5, 16
	s_add_i32 s4, s4, 16
	s_add_i32 s9, s9, -16
	s_add_i32 s9, s9, -16
	s_cmp_lg_u32 s9, 0
	s_waitcnt lgkmcnt(0)
	s_add_i32 s1, s12, 0xf500
	ds_read2_b32 v[54:55], v5 offset1:8
	s_cmpk_lt_i32 s0, 0x58
	ds_read2_b32 v[58:59], v5 offset0:33 offset1:41
	s_cselect_b32 s0, s12, s1
	s_sext_i32_i16 s1, s0
	ds_read2_b32 v[60:61], v5 offset0:66 offset1:74
	s_cselect_b32 s4, 0, 0x80
	s_bfe_u32 s1, s1, 0x70018
	ds_read2_b32 v[62:63], v5 offset0:99 offset1:107
	s_add_i32 s1, s0, s1
	s_waitcnt lgkmcnt(3)
	v_bfe_u32 v7, v54, 16, 1
	s_sext_i32_i16 s5, s1
	s_and_b32 s1, s1, 0xff80
	v_add3_u32 v7, v54, v7, s33
	s_waitcnt lgkmcnt(2)
	v_bfe_u32 v9, v58, 16, 1
	ds_read2_b32 v[64:65], v5 offset0:132 offset1:140
	s_sub_i32 s0, s0, s1
	v_lshrrev_b32_e32 v7, 16, v7
	v_add3_u32 v9, v58, v9, s33
	ds_read2_b32 v[66:67], v5 offset0:165 offset1:173
	s_lshl_b32 s5, s5, 1
	s_sext_i32_i16 s0, s0
	v_and_or_b32 v50, v9, s69, v7
	s_waitcnt lgkmcnt(3)
	v_bfe_u32 v7, v60, 16, 1
	s_and_b32 s5, s5, 0xffffff00
	s_add_i32 s0, s4, s0
	v_add3_u32 v7, v60, v7, s33
	s_waitcnt lgkmcnt(2)
	v_bfe_u32 v9, v62, 16, 1
	ds_read2_b32 v[68:69], v5 offset0:198 offset1:206
	s_add_i32 s0, s0, s5
	v_lshrrev_b32_e32 v7, 16, v7
	v_add3_u32 v9, v62, v9, s33
	ds_read2_b32 v[70:71], v5 offset0:231 offset1:239
	s_ashr_i32 s1, s0, 31
	v_and_or_b32 v51, v9, s69, v7
	s_waitcnt lgkmcnt(3)
	v_bfe_u32 v7, v64, 16, 1
	s_lshl_b64 s[0:1], s[0:1], 11
	v_add3_u32 v7, v64, v7, s33
	s_waitcnt lgkmcnt(2)
	v_bfe_u32 v9, v66, 16, 1
	s_add_u32 s4, s17, s0
	v_lshrrev_b32_e32 v7, 16, v7
	v_add3_u32 v9, v66, v9, s33
	s_addc_u32 s5, s29, s1
	s_ashr_i32 s9, s8, 31
	v_and_or_b32 v52, v9, s69, v7
	s_waitcnt lgkmcnt(1)
	v_bfe_u32 v7, v68, 16, 1
	s_lshl_b64 s[0:1], s[8:9], 1
	v_add3_u32 v7, v68, v7, s33
	s_waitcnt lgkmcnt(0)
	v_bfe_u32 v9, v70, 16, 1
	s_add_u32 s0, s4, s0
	v_lshrrev_b32_e32 v7, 16, v7
	v_add3_u32 v9, v70, v9, s33
	s_addc_u32 s1, s5, s1
	v_lshlrev_b32_e32 v128, 1, v6
	v_and_or_b32 v53, v9, s69, v7
	v_bfe_u32 v7, v55, 16, 1
	v_lshl_add_u64 v[56:57], s[0:1], 0, v[128:129]
	v_lshlrev_b32_e32 v128, 1, v8
	v_add3_u32 v7, v55, v7, s33
	v_bfe_u32 v9, v59, 16, 1
	v_lshl_add_u64 v[72:73], v[56:57], 0, v[128:129]
	v_lshrrev_b32_e32 v7, 16, v7
	v_add3_u32 v9, v59, v9, s33
	global_store_dwordx4 v[72:73], v[50:53], off
	v_lshlrev_b32_e32 v128, 1, v10
	ds_read2_b32 v[54:55], v5 offset0:16 offset1:24
	v_and_or_b32 v50, v9, s69, v7
	v_bfe_u32 v7, v61, 16, 1
	v_add3_u32 v7, v61, v7, s33
	v_bfe_u32 v9, v63, 16, 1
	v_lshrrev_b32_e32 v7, 16, v7
	v_add3_u32 v9, v63, v9, s33
	v_and_or_b32 v51, v9, s69, v7
	v_bfe_u32 v7, v65, 16, 1
	v_add3_u32 v7, v65, v7, s33
	v_bfe_u32 v9, v67, 16, 1
	v_lshrrev_b32_e32 v7, 16, v7
	v_add3_u32 v9, v67, v9, s33
	v_and_or_b32 v52, v9, s69, v7
	v_bfe_u32 v7, v69, 16, 1
	v_add3_u32 v7, v69, v7, s33
	v_bfe_u32 v9, v71, 16, 1
	v_lshrrev_b32_e32 v7, 16, v7
	v_add3_u32 v9, v71, v9, s33
	v_and_or_b32 v53, v9, s69, v7
	v_lshl_add_u64 v[58:59], v[56:57], 0, v[128:129]
	global_store_dwordx4 v[58:59], v[50:53], off
	ds_read2_b32 v[58:59], v5 offset0:49 offset1:57
	ds_read2_b32 v[60:61], v5 offset0:82 offset1:90
	ds_read2_b32 v[62:63], v5 offset0:115 offset1:123
	s_waitcnt lgkmcnt(3)
	v_bfe_u32 v7, v54, 16, 1
	v_add3_u32 v7, v54, v7, s33
	s_waitcnt lgkmcnt(2)
	v_bfe_u32 v9, v58, 16, 1
	ds_read2_b32 v[64:65], v5 offset0:148 offset1:156
	v_lshrrev_b32_e32 v7, 16, v7
	v_add3_u32 v9, v58, v9, s33
	ds_read2_b32 v[66:67], v5 offset0:181 offset1:189
	v_and_or_b32 v50, v9, s69, v7
	s_waitcnt lgkmcnt(3)
	v_bfe_u32 v7, v60, 16, 1
	v_add3_u32 v7, v60, v7, s33
	s_waitcnt lgkmcnt(2)
	v_bfe_u32 v9, v62, 16, 1
	ds_read2_b32 v[68:69], v5 offset0:214 offset1:222
	v_lshrrev_b32_e32 v7, 16, v7
	v_add3_u32 v9, v62, v9, s33
	ds_read2_b32 v[70:71], v5 offset0:247 offset1:255
	v_and_or_b32 v51, v9, s69, v7
	s_waitcnt lgkmcnt(3)
	v_bfe_u32 v7, v64, 16, 1
	v_add3_u32 v7, v64, v7, s33
	s_waitcnt lgkmcnt(2)
	v_bfe_u32 v9, v66, 16, 1
	v_lshrrev_b32_e32 v7, 16, v7
	v_add3_u32 v9, v66, v9, s33
	v_and_or_b32 v52, v9, s69, v7
	s_waitcnt lgkmcnt(1)
	v_bfe_u32 v7, v68, 16, 1
	v_add3_u32 v7, v68, v7, s33
	s_waitcnt lgkmcnt(0)
	v_bfe_u32 v9, v70, 16, 1
	v_lshrrev_b32_e32 v7, 16, v7
	v_add3_u32 v9, v70, v9, s33
	v_and_or_b32 v53, v9, s69, v7
	v_bfe_u32 v7, v55, 16, 1
	v_lshlrev_b32_e32 v128, 1, v12
	v_add3_u32 v7, v55, v7, s33
	v_bfe_u32 v9, v59, 16, 1
	v_lshl_add_u64 v[72:73], v[56:57], 0, v[128:129]
	v_lshrrev_b32_e32 v7, 16, v7
	v_add3_u32 v9, v59, v9, s33
	global_store_dwordx4 v[72:73], v[50:53], off
	v_lshlrev_b32_e32 v128, 1, v14
	v_lshl_add_u64 v[54:55], v[56:57], 0, v[128:129]
	v_and_or_b32 v50, v9, s69, v7
	v_bfe_u32 v7, v61, 16, 1
	v_add3_u32 v7, v61, v7, s33
	v_bfe_u32 v9, v63, 16, 1
	v_lshrrev_b32_e32 v7, 16, v7
	v_add3_u32 v9, v63, v9, s33
	v_and_or_b32 v51, v9, s69, v7
	v_bfe_u32 v7, v65, 16, 1
	v_add3_u32 v7, v65, v7, s33
	v_bfe_u32 v9, v67, 16, 1
	v_lshrrev_b32_e32 v7, 16, v7
	v_add3_u32 v9, v67, v9, s33
	v_and_or_b32 v52, v9, s69, v7
	v_bfe_u32 v7, v69, 16, 1
	v_add3_u32 v7, v69, v7, s33
	v_bfe_u32 v9, v71, 16, 1
	v_lshrrev_b32_e32 v7, 16, v7
	v_add3_u32 v9, v71, v9, s33
	v_and_or_b32 v53, v9, s69, v7
	global_store_dwordx4 v[54:55], v[50:53], off
	s_waitcnt lgkmcnt(0)
	s_mov_b32 s0, s28
	s_mov_b64 s[8:9], -1
	s_andn2_b64 vcc, exec, s[10:11]
	s_mov_b64 s[10:11], -1
	s_cbranch_vccnz .LBB0_744

.LBB0_675:
	s_lshl_b32 s15, s1, 1
	s_lshl_b32 s22, s5, 1
	v_or_b32_e32 v7, s15, v1
	v_or_b32_e32 v9, s22, v0
	s_add_i32 s23, s15, 4
	s_add_i32 s24, s22, 4
	s_add_i32 s25, s15, 8
	s_add_i32 s26, s22, 8
	s_add_i32 s27, s15, 12
	s_add_i32 s30, s22, 12
	s_add_i32 s36, s15, 16
	s_add_i32 s37, s22, 16
	s_add_i32 s40, s15, 20
	s_add_i32 s41, s22, 20
	s_add_i32 s42, s15, 24
	s_add_i32 s43, s22, 24
	s_add_i32 s15, s15, 28
	s_add_i32 s22, s22, 28
	v_add_u32_e32 v54, s12, v9
	v_or_b32_e32 v11, s23, v1
	v_or_b32_e32 v13, s24, v0
	v_or_b32_e32 v15, s25, v1
	v_or_b32_e32 v19, s26, v0
	v_or_b32_e32 v41, s27, v1
	v_or_b32_e32 v43, s30, v0
	v_or_b32_e32 v45, s36, v1
	v_or_b32_e32 v47, s37, v0
	v_or_b32_e32 v49, s40, v1
	v_or_b32_e32 v82, s41, v0
	v_or_b32_e32 v86, s42, v1
	v_or_b32_e32 v87, s43, v0
	v_or_b32_e32 v88, s15, v1
	v_or_b32_e32 v89, s22, v0
	v_add_u32_e32 v52, s4, v7
	v_ashrrev_i32_e32 v55, 31, v54
	v_add_u32_e32 v56, s4, v11
	v_add_u32_e32 v58, s12, v13
	v_add_u32_e32 v60, s4, v15
	v_add_u32_e32 v62, s12, v19
	v_add_u32_e32 v64, s4, v41
	v_add_u32_e32 v66, s12, v43
	v_add_u32_e32 v68, s4, v45
	v_add_u32_e32 v70, s12, v47
	v_add_u32_e32 v72, s4, v49
	v_add_u32_e32 v74, s12, v82
	v_add_u32_e32 v76, s4, v86
	v_add_u32_e32 v78, s12, v87
	v_add_u32_e32 v80, s4, v88
	v_add_u32_e32 v84, s12, v89
	v_ashrrev_i32_e32 v53, 31, v52
	v_lshlrev_b64 v[54:55], 12, v[54:55]
	v_ashrrev_i32_e32 v59, 31, v58
	v_ashrrev_i32_e32 v57, 31, v56
	v_ashrrev_i32_e32 v63, 31, v62
	v_ashrrev_i32_e32 v61, 31, v60
	v_ashrrev_i32_e32 v67, 31, v66
	v_ashrrev_i32_e32 v65, 31, v64
	v_ashrrev_i32_e32 v71, 31, v70
	v_ashrrev_i32_e32 v69, 31, v68
	v_ashrrev_i32_e32 v75, 31, v74
	v_ashrrev_i32_e32 v73, 31, v72
	v_ashrrev_i32_e32 v79, 31, v78
	v_ashrrev_i32_e32 v77, 31, v76
	v_ashrrev_i32_e32 v85, 31, v84
	v_ashrrev_i32_e32 v81, 31, v80
	v_lshlrev_b64 v[52:53], 12, v[52:53]
	v_lshl_add_u64 v[54:55], v[50:51], 0, v[54:55]
	v_lshlrev_b64 v[56:57], 12, v[56:57]
	v_lshlrev_b64 v[58:59], 12, v[58:59]
	v_lshlrev_b64 v[60:61], 12, v[60:61]
	v_lshlrev_b64 v[62:63], 12, v[62:63]
	v_lshlrev_b64 v[64:65], 12, v[64:65]
	v_lshlrev_b64 v[66:67], 12, v[66:67]
	v_lshlrev_b64 v[68:69], 12, v[68:69]
	v_lshlrev_b64 v[70:71], 12, v[70:71]
	v_lshlrev_b64 v[72:73], 12, v[72:73]
	v_lshlrev_b64 v[74:75], 12, v[74:75]
	v_lshlrev_b64 v[76:77], 12, v[76:77]
	v_lshlrev_b64 v[78:79], 12, v[78:79]
	v_lshlrev_b64 v[80:81], 12, v[80:81]
	v_lshlrev_b64 v[84:85], 12, v[84:85]
	v_lshl_add_u64 v[52:53], v[50:51], 0, v[52:53]
	v_lshl_add_u64 v[58:59], v[50:51], 0, v[58:59]
	v_lshl_add_u64 v[56:57], v[50:51], 0, v[56:57]
	v_lshl_add_u64 v[62:63], v[50:51], 0, v[62:63]
	v_lshl_add_u64 v[60:61], v[50:51], 0, v[60:61]
	v_lshl_add_u64 v[66:67], v[50:51], 0, v[66:67]
	v_lshl_add_u64 v[64:65], v[50:51], 0, v[64:65]
	v_lshl_add_u64 v[70:71], v[50:51], 0, v[70:71]
	v_lshl_add_u64 v[68:69], v[50:51], 0, v[68:69]
	v_lshl_add_u64 v[74:75], v[50:51], 0, v[74:75]
	v_lshl_add_u64 v[72:73], v[50:51], 0, v[72:73]
	v_lshl_add_u64 v[78:79], v[50:51], 0, v[78:79]
	v_lshl_add_u64 v[76:77], v[50:51], 0, v[76:77]
	v_lshl_add_u64 v[84:85], v[50:51], 0, v[84:85]
	v_lshl_add_u64 v[80:81], v[50:51], 0, v[80:81]
	global_load_dword v90, v[54:55], off
	global_load_dword v91, v[52:53], off
	global_load_dword v92, v[58:59], off
	global_load_dword v93, v[56:57], off
	global_load_dword v94, v[62:63], off
	global_load_dword v95, v[60:61], off
	global_load_dword v96, v[66:67], off
	global_load_dword v97, v[64:65], off
	global_load_dword v98, v[70:71], off
	global_load_dword v99, v[68:69], off
	global_load_dword v100, v[74:75], off
	global_load_dword v101, v[72:73], off
	global_load_dword v102, v[78:79], off
	global_load_dword v103, v[76:77], off
	global_load_dword v104, v[84:85], off
	global_load_dword v105, v[80:81], off
	s_add_i32 s5, s5, 16
	s_add_i32 s1, s1, 16
	s_lshl_b32 s15, s1, 1
	s_lshl_b32 s22, s5, 1
	v_or_b32_e32 v106, s15, v1
	v_or_b32_e32 v107, s22, v0
	s_add_i32 s23, s15, 4
	s_add_i32 s24, s22, 4
	s_add_i32 s25, s15, 8
	s_add_i32 s26, s22, 8
	s_add_i32 s27, s15, 12
	s_add_i32 s30, s22, 12
	s_add_i32 s36, s15, 16
	s_add_i32 s37, s22, 16
	s_add_i32 s40, s15, 20
	s_add_i32 s41, s22, 20
	s_add_i32 s42, s15, 24
	s_add_i32 s43, s22, 24
	s_add_i32 s15, s15, 28
	s_add_i32 s22, s22, 28
	v_add_u32_e32 v132, s12, v107
	v_or_b32_e32 v108, s23, v1
	v_or_b32_e32 v109, s24, v0
	v_or_b32_e32 v110, s25, v1
	v_or_b32_e32 v111, s26, v0
	v_or_b32_e32 v112, s27, v1
	v_or_b32_e32 v113, s30, v0
	v_or_b32_e32 v114, s36, v1
	v_or_b32_e32 v115, s37, v0
	v_or_b32_e32 v116, s40, v1
	v_or_b32_e32 v117, s41, v0
	v_or_b32_e32 v118, s42, v1
	v_or_b32_e32 v119, s43, v0
	v_or_b32_e32 v120, s15, v1
	v_or_b32_e32 v121, s22, v0
	v_add_u32_e32 v130, s4, v106
	v_ashrrev_i32_e32 v133, 31, v132
	v_add_u32_e32 v134, s4, v108
	v_add_u32_e32 v136, s12, v109
	v_add_u32_e32 v138, s4, v110
	v_add_u32_e32 v140, s12, v111
	v_add_u32_e32 v142, s4, v112
	v_add_u32_e32 v144, s12, v113
	v_add_u32_e32 v146, s4, v114
	v_add_u32_e32 v148, s12, v115
	v_add_u32_e32 v150, s4, v116
	v_add_u32_e32 v152, s12, v117
	v_add_u32_e32 v154, s4, v118
	v_add_u32_e32 v156, s12, v119
	v_add_u32_e32 v158, s4, v120
	v_add_u32_e32 v160, s12, v121
	v_ashrrev_i32_e32 v131, 31, v130
	v_lshlrev_b64 v[132:133], 12, v[132:133]
	v_ashrrev_i32_e32 v137, 31, v136
	v_ashrrev_i32_e32 v135, 31, v134
	v_ashrrev_i32_e32 v141, 31, v140
	v_ashrrev_i32_e32 v139, 31, v138
	v_ashrrev_i32_e32 v145, 31, v144
	v_ashrrev_i32_e32 v143, 31, v142
	v_ashrrev_i32_e32 v149, 31, v148
	v_ashrrev_i32_e32 v147, 31, v146
	v_ashrrev_i32_e32 v153, 31, v152
	v_ashrrev_i32_e32 v151, 31, v150
	v_ashrrev_i32_e32 v157, 31, v156
	v_ashrrev_i32_e32 v155, 31, v154
	v_ashrrev_i32_e32 v161, 31, v160
	v_ashrrev_i32_e32 v159, 31, v158
	v_lshlrev_b64 v[130:131], 12, v[130:131]
	v_lshl_add_u64 v[132:133], v[50:51], 0, v[132:133]
	v_lshlrev_b64 v[134:135], 12, v[134:135]
	v_lshlrev_b64 v[136:137], 12, v[136:137]
	v_lshlrev_b64 v[138:139], 12, v[138:139]
	v_lshlrev_b64 v[140:141], 12, v[140:141]
	v_lshlrev_b64 v[142:143], 12, v[142:143]
	v_lshlrev_b64 v[144:145], 12, v[144:145]
	v_lshlrev_b64 v[146:147], 12, v[146:147]
	v_lshlrev_b64 v[148:149], 12, v[148:149]
	v_lshlrev_b64 v[150:151], 12, v[150:151]
	v_lshlrev_b64 v[152:153], 12, v[152:153]
	v_lshlrev_b64 v[154:155], 12, v[154:155]
	v_lshlrev_b64 v[156:157], 12, v[156:157]
	v_lshlrev_b64 v[158:159], 12, v[158:159]
	v_lshlrev_b64 v[160:161], 12, v[160:161]
	v_lshl_add_u64 v[130:131], v[50:51], 0, v[130:131]
	v_lshl_add_u64 v[136:137], v[50:51], 0, v[136:137]
	v_lshl_add_u64 v[134:135], v[50:51], 0, v[134:135]
	v_lshl_add_u64 v[140:141], v[50:51], 0, v[140:141]
	v_lshl_add_u64 v[138:139], v[50:51], 0, v[138:139]
	v_lshl_add_u64 v[144:145], v[50:51], 0, v[144:145]
	v_lshl_add_u64 v[142:143], v[50:51], 0, v[142:143]
	v_lshl_add_u64 v[148:149], v[50:51], 0, v[148:149]
	v_lshl_add_u64 v[146:147], v[50:51], 0, v[146:147]
	v_lshl_add_u64 v[152:153], v[50:51], 0, v[152:153]
	v_lshl_add_u64 v[150:151], v[50:51], 0, v[150:151]
	v_lshl_add_u64 v[156:157], v[50:51], 0, v[156:157]
	v_lshl_add_u64 v[154:155], v[50:51], 0, v[154:155]
	v_lshl_add_u64 v[160:161], v[50:51], 0, v[160:161]
	v_lshl_add_u64 v[158:159], v[50:51], 0, v[158:159]
	global_load_dword v122, v[132:133], off
	global_load_dword v123, v[130:131], off
	global_load_dword v124, v[136:137], off
	global_load_dword v125, v[134:135], off
	global_load_dword v126, v[140:141], off
	global_load_dword v127, v[138:139], off
	global_load_dword v162, v[144:145], off
	global_load_dword v163, v[142:143], off
	global_load_dword v164, v[148:149], off
	global_load_dword v165, v[146:147], off
	global_load_dword v166, v[152:153], off
	global_load_dword v167, v[150:151], off
	global_load_dword v168, v[156:157], off
	global_load_dword v169, v[154:155], off
	global_load_dword v170, v[160:161], off
	global_load_dword v171, v[158:159], off
	v_mad_u64_u32 v[52:53], s[22:23], v9, s78, v[4:5]
	v_mad_u64_u32 v[54:55], s[22:23], v7, s78, v[4:5]
	v_mad_u64_u32 v[56:57], s[22:23], v13, s78, v[4:5]
	v_mad_u64_u32 v[58:59], s[22:23], v11, s78, v[4:5]
	v_mad_u64_u32 v[60:61], s[22:23], v19, s78, v[4:5]
	v_mad_u64_u32 v[62:63], s[22:23], v15, s78, v[4:5]
	v_mad_u64_u32 v[64:65], s[22:23], v43, s78, v[4:5]
	v_mad_u64_u32 v[66:67], s[22:23], v41, s78, v[4:5]
	v_mad_u64_u32 v[68:69], s[22:23], v47, s78, v[4:5]
	v_mad_u64_u32 v[70:71], s[22:23], v45, s78, v[4:5]
	v_mad_u64_u32 v[72:73], s[22:23], v82, s78, v[4:5]
	v_mad_u64_u32 v[74:75], s[22:23], v49, s78, v[4:5]
	v_mad_u64_u32 v[76:77], s[22:23], v87, s78, v[4:5]
	v_mad_u64_u32 v[78:79], s[22:23], v86, s78, v[4:5]
	v_mad_u64_u32 v[80:81], s[22:23], v89, s78, v[4:5]
	v_mad_u64_u32 v[84:85], s[22:23], v88, s78, v[4:5]
	s_waitcnt vmcnt(31)
	ds_write_b32 v52, v90
	s_waitcnt vmcnt(30)
	ds_write_b32 v54, v91
	s_waitcnt vmcnt(29)
	ds_write_b32 v56, v92
	s_waitcnt vmcnt(28)
	ds_write_b32 v58, v93
	s_waitcnt vmcnt(27)
	ds_write_b32 v60, v94
	s_waitcnt vmcnt(26)
	ds_write_b32 v62, v95
	s_waitcnt vmcnt(25)
	ds_write_b32 v64, v96
	s_waitcnt vmcnt(24)
	ds_write_b32 v66, v97
	s_waitcnt vmcnt(23)
	ds_write_b32 v68, v98
	s_waitcnt vmcnt(22)
	ds_write_b32 v70, v99
	s_waitcnt vmcnt(21)
	ds_write_b32 v72, v100
	s_waitcnt vmcnt(20)
	ds_write_b32 v74, v101
	s_waitcnt vmcnt(19)
	ds_write_b32 v76, v102
	s_waitcnt vmcnt(18)
	ds_write_b32 v78, v103
	s_waitcnt vmcnt(17)
	ds_write_b32 v80, v104
	s_waitcnt vmcnt(16)
	ds_write_b32 v84, v105
	v_mad_u64_u32 v[130:131], s[22:23], v107, s78, v[4:5]
	v_mad_u64_u32 v[132:133], s[22:23], v106, s78, v[4:5]
	v_mad_u64_u32 v[134:135], s[22:23], v109, s78, v[4:5]
	v_mad_u64_u32 v[136:137], s[22:23], v108, s78, v[4:5]
	v_mad_u64_u32 v[138:139], s[22:23], v111, s78, v[4:5]
	v_mad_u64_u32 v[140:141], s[22:23], v110, s78, v[4:5]
	v_mad_u64_u32 v[142:143], s[22:23], v113, s78, v[4:5]
	v_mad_u64_u32 v[144:145], s[22:23], v112, s78, v[4:5]
	v_mad_u64_u32 v[146:147], s[22:23], v115, s78, v[4:5]
	v_mad_u64_u32 v[148:149], s[22:23], v114, s78, v[4:5]
	v_mad_u64_u32 v[150:151], s[22:23], v117, s78, v[4:5]
	v_mad_u64_u32 v[152:153], s[22:23], v116, s78, v[4:5]
	v_mad_u64_u32 v[154:155], s[22:23], v119, s78, v[4:5]
	v_mad_u64_u32 v[156:157], s[22:23], v118, s78, v[4:5]
	v_mad_u64_u32 v[158:159], s[22:23], v121, s78, v[4:5]
	v_mad_u64_u32 v[160:161], s[22:23], v120, s78, v[4:5]
	s_waitcnt vmcnt(15)
	ds_write_b32 v130, v122
	s_waitcnt vmcnt(14)
	ds_write_b32 v132, v123
	s_waitcnt vmcnt(13)
	ds_write_b32 v134, v124
	s_waitcnt vmcnt(12)
	ds_write_b32 v136, v125
	s_waitcnt vmcnt(11)
	ds_write_b32 v138, v126
	s_waitcnt vmcnt(10)
	ds_write_b32 v140, v127
	s_waitcnt vmcnt(9)
	ds_write_b32 v142, v162
	s_waitcnt vmcnt(8)
	ds_write_b32 v144, v163
	s_waitcnt vmcnt(7)
	ds_write_b32 v146, v164
	s_waitcnt vmcnt(6)
	ds_write_b32 v148, v165
	s_waitcnt vmcnt(5)
	ds_write_b32 v150, v166
	s_waitcnt vmcnt(4)
	ds_write_b32 v152, v167
	s_waitcnt vmcnt(3)
	ds_write_b32 v154, v168
	s_waitcnt vmcnt(2)
	ds_write_b32 v156, v169
	s_waitcnt vmcnt(1)
	ds_write_b32 v158, v170
	s_waitcnt vmcnt(0)
	ds_write_b32 v160, v171
	s_add_i32 s5, s5, 16
	s_add_i32 s1, s1, 16
	s_add_i32 s13, s13, -16
	s_add_i32 s13, s13, -16
	s_cmp_lg_u32 s13, 0
	s_waitcnt lgkmcnt(0)
	ds_read2_b32 v[54:55], v5 offset1:8
	ds_read2_b32 v[58:59], v5 offset0:33 offset1:41
	ds_read2_b32 v[60:61], v5 offset0:66 offset1:74
	ds_read2_b32 v[62:63], v5 offset0:99 offset1:107
	ds_read2_b32 v[64:65], v5 offset0:132 offset1:140
	s_waitcnt lgkmcnt(4)
	v_bfe_u32 v7, v54, 16, 1
	v_add3_u32 v7, v54, v7, s33
	s_waitcnt lgkmcnt(3)
	v_bfe_u32 v9, v58, 16, 1
	v_lshrrev_b32_e32 v7, 16, v7
	v_add3_u32 v9, v58, v9, s33
	ds_read2_b32 v[66:67], v5 offset0:165 offset1:173
	v_and_or_b32 v50, v9, s69, v7
	s_waitcnt lgkmcnt(3)
	v_bfe_u32 v7, v60, 16, 1
	v_add3_u32 v7, v60, v7, s33
	s_waitcnt lgkmcnt(2)
	v_bfe_u32 v9, v62, 16, 1
	ds_read2_b32 v[68:69], v5 offset0:198 offset1:206
	v_lshrrev_b32_e32 v7, 16, v7
	v_add3_u32 v9, v62, v9, s33
	ds_read2_b32 v[70:71], v5 offset0:231 offset1:239
	v_and_or_b32 v51, v9, s69, v7
	s_waitcnt lgkmcnt(3)
	v_bfe_u32 v7, v64, 16, 1
	s_mul_i32 s4, s14, 0x1600
	v_add3_u32 v7, v64, v7, s33
	s_waitcnt lgkmcnt(2)
	v_bfe_u32 v9, v66, 16, 1
	s_mul_hi_i32 s1, s14, 0x1600
	s_add_u32 s14, s18, s4
	v_lshrrev_b32_e32 v7, 16, v7
	v_add3_u32 v9, v66, v9, s33
	s_addc_u32 s1, s19, s1
	s_ashr_i32 s13, s12, 31
	v_and_or_b32 v52, v9, s69, v7
	s_waitcnt lgkmcnt(1)
	v_bfe_u32 v7, v68, 16, 1
	s_lshl_b64 s[4:5], s[12:13], 1
	v_add3_u32 v7, v68, v7, s33
	s_waitcnt lgkmcnt(0)
	v_bfe_u32 v9, v70, 16, 1
	s_add_u32 s4, s14, s4
	v_lshrrev_b32_e32 v7, 16, v7
	v_add3_u32 v9, v70, v9, s33
	s_addc_u32 s5, s1, s5
	v_lshlrev_b32_e32 v128, 1, v6
	v_and_or_b32 v53, v9, s69, v7
	v_bfe_u32 v7, v55, 16, 1
	v_lshl_add_u64 v[56:57], s[4:5], 0, v[128:129]
	v_lshlrev_b32_e32 v128, 1, v18
	v_add3_u32 v7, v55, v7, s33
	v_bfe_u32 v9, v59, 16, 1
	v_lshl_add_u64 v[56:57], v[56:57], 0, v[128:129]
	v_lshrrev_b32_e32 v7, 16, v7
	v_add3_u32 v9, v59, v9, s33
	global_store_dwordx4 v[56:57], v[50:53], off
	s_mov_b32 s1, 0xb000
	v_add_co_u32_e32 v58, vcc, s1, v56
	v_and_or_b32 v50, v9, s69, v7
	v_bfe_u32 v7, v61, 16, 1
	v_add3_u32 v7, v61, v7, s33
	v_bfe_u32 v9, v63, 16, 1
	v_lshrrev_b32_e32 v7, 16, v7
	v_add3_u32 v9, v63, v9, s33
	v_and_or_b32 v51, v9, s69, v7
	v_bfe_u32 v7, v65, 16, 1
	v_add3_u32 v7, v65, v7, s33
	v_bfe_u32 v9, v67, 16, 1
	v_lshrrev_b32_e32 v7, 16, v7
	v_add3_u32 v9, v67, v9, s33
	v_and_or_b32 v52, v9, s69, v7
	v_bfe_u32 v7, v69, 16, 1
	v_add3_u32 v7, v69, v7, s33
	v_bfe_u32 v9, v71, 16, 1
	v_lshrrev_b32_e32 v7, 16, v7
	v_add3_u32 v9, v71, v9, s33
	v_and_or_b32 v53, v9, s69, v7
	ds_read2_b32 v[54:55], v5 offset0:16 offset1:24
	v_addc_co_u32_e32 v59, vcc, 0, v57, vcc
	global_store_dwordx4 v[58:59], v[50:53], off
	ds_read2_b32 v[58:59], v5 offset0:49 offset1:57
	ds_read2_b32 v[60:61], v5 offset0:82 offset1:90
	ds_read2_b32 v[62:63], v5 offset0:115 offset1:123
	s_waitcnt lgkmcnt(3)
	v_bfe_u32 v7, v54, 16, 1
	v_add3_u32 v7, v54, v7, s33
	s_waitcnt lgkmcnt(2)
	v_bfe_u32 v9, v58, 16, 1
	ds_read2_b32 v[64:65], v5 offset0:148 offset1:156
	v_lshrrev_b32_e32 v7, 16, v7
	v_add3_u32 v9, v58, v9, s33
	ds_read2_b32 v[66:67], v5 offset0:181 offset1:189
	v_and_or_b32 v50, v9, s69, v7
	s_waitcnt lgkmcnt(3)
	v_bfe_u32 v7, v60, 16, 1
	v_add3_u32 v7, v60, v7, s33
	s_waitcnt lgkmcnt(2)
	v_bfe_u32 v9, v62, 16, 1
	ds_read2_b32 v[68:69], v5 offset0:214 offset1:222
	v_lshrrev_b32_e32 v7, 16, v7
	v_add3_u32 v9, v62, v9, s33
	ds_read2_b32 v[70:71], v5 offset0:247 offset1:255
	v_and_or_b32 v51, v9, s69, v7
	s_waitcnt lgkmcnt(3)
	v_bfe_u32 v7, v64, 16, 1
	v_add3_u32 v7, v64, v7, s33
	s_waitcnt lgkmcnt(2)
	v_bfe_u32 v9, v66, 16, 1
	v_lshrrev_b32_e32 v7, 16, v7
	v_add3_u32 v9, v66, v9, s33
	v_and_or_b32 v52, v9, s69, v7
	s_waitcnt lgkmcnt(1)
	v_bfe_u32 v7, v68, 16, 1
	v_add3_u32 v7, v68, v7, s33
	s_waitcnt lgkmcnt(0)
	v_bfe_u32 v9, v70, 16, 1
	v_lshrrev_b32_e32 v7, 16, v7
	v_add3_u32 v9, v70, v9, s33
	v_and_or_b32 v53, v9, s69, v7
	s_mov_b32 s1, 0x16000
	v_bfe_u32 v7, v55, 16, 1
	v_add_co_u32_e32 v72, vcc, s1, v56
	v_add3_u32 v7, v55, v7, s33
	v_bfe_u32 v9, v59, 16, 1
	v_addc_co_u32_e32 v73, vcc, 0, v57, vcc
	v_lshrrev_b32_e32 v7, 16, v7
	v_add3_u32 v9, v59, v9, s33
	global_store_dwordx4 v[72:73], v[50:53], off
	v_add_co_u32_e32 v54, vcc, 0x21000, v56
	s_nop 0
	v_and_or_b32 v50, v9, s69, v7
	v_bfe_u32 v7, v61, 16, 1
	v_add3_u32 v7, v61, v7, s33
	v_bfe_u32 v9, v63, 16, 1
	v_lshrrev_b32_e32 v7, 16, v7
	v_add3_u32 v9, v63, v9, s33
	v_and_or_b32 v51, v9, s69, v7
	v_bfe_u32 v7, v65, 16, 1
	v_add3_u32 v7, v65, v7, s33
	v_bfe_u32 v9, v67, 16, 1
	v_lshrrev_b32_e32 v7, 16, v7
	v_add3_u32 v9, v67, v9, s33
	v_and_or_b32 v52, v9, s69, v7
	v_bfe_u32 v7, v69, 16, 1
	v_add3_u32 v7, v69, v7, s33
	v_bfe_u32 v9, v71, 16, 1
	v_lshrrev_b32_e32 v7, 16, v7
	v_add3_u32 v9, v71, v9, s33
	v_and_or_b32 v53, v9, s69, v7
	v_addc_co_u32_e32 v55, vcc, 0, v57, vcc
	global_store_dwordx4 v[54:55], v[50:53], off
	s_waitcnt lgkmcnt(0)
	s_mov_b32 s4, s0
	s_andn2_b64 vcc, exec, s[10:11]
	s_mov_b64 s[10:11], -1
	s_cbranch_vccnz .LBB0_744

.LBB0_682:
	s_lshl_b32 s22, s5, 1
	s_lshl_b32 s23, s13, 1
	v_or_b32_e32 v7, s22, v1
	v_or_b32_e32 v9, s23, v0
	s_add_i32 s24, s22, 4
	s_add_i32 s25, s23, 4
	s_add_i32 s26, s22, 8
	s_add_i32 s27, s23, 8
	s_add_i32 s30, s22, 12
	s_add_i32 s36, s23, 12
	s_add_i32 s37, s22, 16
	s_add_i32 s40, s23, 16
	s_add_i32 s41, s22, 20
	s_add_i32 s42, s23, 20
	s_add_i32 s43, s22, 24
	s_add_i32 s52, s23, 24
	s_add_i32 s22, s22, 28
	s_add_i32 s23, s23, 28
	v_add_u32_e32 v11, s1, v7
	v_add_u32_e32 v13, s12, v9
	v_or_b32_e32 v15, s24, v1
	v_or_b32_e32 v19, s25, v0
	v_or_b32_e32 v41, s26, v1
	v_or_b32_e32 v43, s27, v0
	v_or_b32_e32 v45, s30, v1
	v_or_b32_e32 v47, s36, v0
	v_or_b32_e32 v49, s37, v1
	v_or_b32_e32 v82, s40, v0
	v_or_b32_e32 v86, s41, v1
	v_or_b32_e32 v87, s42, v0
	v_or_b32_e32 v88, s43, v1
	v_or_b32_e32 v89, s52, v0
	v_or_b32_e32 v90, s22, v1
	v_or_b32_e32 v91, s23, v0
	v_mad_i64_i32 v[52:53], s[22:23], v13, s80, v[50:51]
	v_mad_i64_i32 v[54:55], s[22:23], v11, s80, v[50:51]
	v_add_u32_e32 v11, s1, v15
	v_add_u32_e32 v13, s12, v19
	v_add_u32_e32 v62, s1, v41
	v_add_u32_e32 v60, s12, v43
	v_add_u32_e32 v66, s1, v45
	v_add_u32_e32 v64, s12, v47
	v_add_u32_e32 v70, s1, v49
	v_add_u32_e32 v68, s12, v82
	v_add_u32_e32 v74, s1, v86
	v_add_u32_e32 v72, s12, v87
	v_add_u32_e32 v78, s1, v88
	v_add_u32_e32 v76, s12, v89
	v_add_u32_e32 v84, s1, v90
	v_add_u32_e32 v80, s12, v91
	v_mad_i64_i32 v[56:57], s[22:23], v13, s80, v[50:51]
	v_mad_i64_i32 v[58:59], s[22:23], v11, s80, v[50:51]
	v_mad_i64_i32 v[60:61], s[22:23], v60, s80, v[50:51]
	v_mad_i64_i32 v[62:63], s[22:23], v62, s80, v[50:51]
	v_mad_i64_i32 v[64:65], s[22:23], v64, s80, v[50:51]
	v_mad_i64_i32 v[66:67], s[22:23], v66, s80, v[50:51]
	v_mad_i64_i32 v[68:69], s[22:23], v68, s80, v[50:51]
	v_mad_i64_i32 v[70:71], s[22:23], v70, s80, v[50:51]
	v_mad_i64_i32 v[72:73], s[22:23], v72, s80, v[50:51]
	v_mad_i64_i32 v[74:75], s[22:23], v74, s80, v[50:51]
	v_mad_i64_i32 v[76:77], s[22:23], v76, s80, v[50:51]
	v_mad_i64_i32 v[78:79], s[22:23], v78, s80, v[50:51]
	v_mad_i64_i32 v[80:81], s[22:23], v80, s80, v[50:51]
	v_mad_i64_i32 v[84:85], s[22:23], v84, s80, v[50:51]
	global_load_dword v11, v[52:53], off
	global_load_dword v13, v[54:55], off
	global_load_dword v92, v[56:57], off
	global_load_dword v93, v[58:59], off
	global_load_dword v94, v[60:61], off
	global_load_dword v95, v[62:63], off
	global_load_dword v96, v[64:65], off
	global_load_dword v97, v[66:67], off
	global_load_dword v98, v[68:69], off
	global_load_dword v99, v[70:71], off
	global_load_dword v100, v[72:73], off
	global_load_dword v101, v[74:75], off
	global_load_dword v102, v[76:77], off
	global_load_dword v103, v[78:79], off
	global_load_dword v104, v[80:81], off
	global_load_dword v105, v[84:85], off
	s_add_i32 s13, s13, 16
	s_add_i32 s5, s5, 16
	s_lshl_b32 s22, s5, 1
	s_lshl_b32 s23, s13, 1
	v_or_b32_e32 v106, s22, v1
	v_or_b32_e32 v107, s23, v0
	s_add_i32 s24, s22, 4
	s_add_i32 s25, s23, 4
	s_add_i32 s26, s22, 8
	s_add_i32 s27, s23, 8
	s_add_i32 s30, s22, 12
	s_add_i32 s36, s23, 12
	s_add_i32 s37, s22, 16
	s_add_i32 s40, s23, 16
	s_add_i32 s41, s22, 20
	s_add_i32 s42, s23, 20
	s_add_i32 s43, s22, 24
	s_add_i32 s52, s23, 24
	s_add_i32 s22, s22, 28
	s_add_i32 s23, s23, 28
	v_add_u32_e32 v108, s1, v106
	v_add_u32_e32 v109, s12, v107
	v_or_b32_e32 v110, s24, v1
	v_or_b32_e32 v111, s25, v0
	v_or_b32_e32 v112, s26, v1
	v_or_b32_e32 v113, s27, v0
	v_or_b32_e32 v114, s30, v1
	v_or_b32_e32 v115, s36, v0
	v_or_b32_e32 v116, s37, v1
	v_or_b32_e32 v117, s40, v0
	v_or_b32_e32 v118, s41, v1
	v_or_b32_e32 v119, s42, v0
	v_or_b32_e32 v120, s43, v1
	v_or_b32_e32 v121, s52, v0
	v_or_b32_e32 v122, s22, v1
	v_or_b32_e32 v123, s23, v0
	v_mad_i64_i32 v[130:131], s[22:23], v109, s80, v[50:51]
	v_mad_i64_i32 v[132:133], s[22:23], v108, s80, v[50:51]
	v_add_u32_e32 v108, s1, v110
	v_add_u32_e32 v109, s12, v111
	v_add_u32_e32 v140, s1, v112
	v_add_u32_e32 v138, s12, v113
	v_add_u32_e32 v144, s1, v114
	v_add_u32_e32 v142, s12, v115
	v_add_u32_e32 v148, s1, v116
	v_add_u32_e32 v146, s12, v117
	v_add_u32_e32 v152, s1, v118
	v_add_u32_e32 v150, s12, v119
	v_add_u32_e32 v156, s1, v120
	v_add_u32_e32 v154, s12, v121
	v_add_u32_e32 v160, s1, v122
	v_add_u32_e32 v158, s12, v123
	v_mad_i64_i32 v[134:135], s[22:23], v109, s80, v[50:51]
	v_mad_i64_i32 v[136:137], s[22:23], v108, s80, v[50:51]
	v_mad_i64_i32 v[138:139], s[22:23], v138, s80, v[50:51]
	v_mad_i64_i32 v[140:141], s[22:23], v140, s80, v[50:51]
	v_mad_i64_i32 v[142:143], s[22:23], v142, s80, v[50:51]
	v_mad_i64_i32 v[144:145], s[22:23], v144, s80, v[50:51]
	v_mad_i64_i32 v[146:147], s[22:23], v146, s80, v[50:51]
	v_mad_i64_i32 v[148:149], s[22:23], v148, s80, v[50:51]
	v_mad_i64_i32 v[150:151], s[22:23], v150, s80, v[50:51]
	v_mad_i64_i32 v[152:153], s[22:23], v152, s80, v[50:51]
	v_mad_i64_i32 v[154:155], s[22:23], v154, s80, v[50:51]
	v_mad_i64_i32 v[156:157], s[22:23], v156, s80, v[50:51]
	v_mad_i64_i32 v[158:159], s[22:23], v158, s80, v[50:51]
	v_mad_i64_i32 v[160:161], s[22:23], v160, s80, v[50:51]
	global_load_dword v108, v[130:131], off
	global_load_dword v109, v[132:133], off
	global_load_dword v124, v[134:135], off
	global_load_dword v125, v[136:137], off
	global_load_dword v126, v[138:139], off
	global_load_dword v127, v[140:141], off
	global_load_dword v162, v[142:143], off
	global_load_dword v163, v[144:145], off
	global_load_dword v164, v[146:147], off
	global_load_dword v165, v[148:149], off
	global_load_dword v166, v[150:151], off
	global_load_dword v167, v[152:153], off
	global_load_dword v168, v[154:155], off
	global_load_dword v169, v[156:157], off
	global_load_dword v170, v[158:159], off
	global_load_dword v171, v[160:161], off
	v_mad_u64_u32 v[52:53], s[22:23], v9, s78, v[4:5]
	v_mad_u64_u32 v[54:55], s[22:23], v7, s78, v[4:5]
	v_mad_u64_u32 v[56:57], s[22:23], v19, s78, v[4:5]
	v_mad_u64_u32 v[58:59], s[22:23], v15, s78, v[4:5]
	v_mad_u64_u32 v[60:61], s[22:23], v43, s78, v[4:5]
	v_mad_u64_u32 v[62:63], s[22:23], v41, s78, v[4:5]
	v_mad_u64_u32 v[64:65], s[22:23], v47, s78, v[4:5]
	v_mad_u64_u32 v[66:67], s[22:23], v45, s78, v[4:5]
	v_mad_u64_u32 v[68:69], s[22:23], v82, s78, v[4:5]
	v_mad_u64_u32 v[70:71], s[22:23], v49, s78, v[4:5]
	v_mad_u64_u32 v[72:73], s[22:23], v87, s78, v[4:5]
	v_mad_u64_u32 v[74:75], s[22:23], v86, s78, v[4:5]
	v_mad_u64_u32 v[76:77], s[22:23], v89, s78, v[4:5]
	v_mad_u64_u32 v[78:79], s[22:23], v88, s78, v[4:5]
	v_mad_u64_u32 v[80:81], s[22:23], v91, s78, v[4:5]
	v_mad_u64_u32 v[84:85], s[22:23], v90, s78, v[4:5]
	s_waitcnt vmcnt(31)
	ds_write_b32 v52, v11
	s_waitcnt vmcnt(30)
	ds_write_b32 v54, v13
	s_waitcnt vmcnt(29)
	ds_write_b32 v56, v92
	s_waitcnt vmcnt(28)
	ds_write_b32 v58, v93
	s_waitcnt vmcnt(27)
	ds_write_b32 v60, v94
	s_waitcnt vmcnt(26)
	ds_write_b32 v62, v95
	s_waitcnt vmcnt(25)
	ds_write_b32 v64, v96
	s_waitcnt vmcnt(24)
	ds_write_b32 v66, v97
	s_waitcnt vmcnt(23)
	ds_write_b32 v68, v98
	s_waitcnt vmcnt(22)
	ds_write_b32 v70, v99
	s_waitcnt vmcnt(21)
	ds_write_b32 v72, v100
	s_waitcnt vmcnt(20)
	ds_write_b32 v74, v101
	s_waitcnt vmcnt(19)
	ds_write_b32 v76, v102
	s_waitcnt vmcnt(18)
	ds_write_b32 v78, v103
	s_waitcnt vmcnt(17)
	ds_write_b32 v80, v104
	s_waitcnt vmcnt(16)
	ds_write_b32 v84, v105
	v_mad_u64_u32 v[130:131], s[22:23], v107, s78, v[4:5]
	v_mad_u64_u32 v[132:133], s[22:23], v106, s78, v[4:5]
	v_mad_u64_u32 v[134:135], s[22:23], v111, s78, v[4:5]
	v_mad_u64_u32 v[136:137], s[22:23], v110, s78, v[4:5]
	v_mad_u64_u32 v[138:139], s[22:23], v113, s78, v[4:5]
	v_mad_u64_u32 v[140:141], s[22:23], v112, s78, v[4:5]
	v_mad_u64_u32 v[142:143], s[22:23], v115, s78, v[4:5]
	v_mad_u64_u32 v[144:145], s[22:23], v114, s78, v[4:5]
	v_mad_u64_u32 v[146:147], s[22:23], v117, s78, v[4:5]
	v_mad_u64_u32 v[148:149], s[22:23], v116, s78, v[4:5]
	v_mad_u64_u32 v[150:151], s[22:23], v119, s78, v[4:5]
	v_mad_u64_u32 v[152:153], s[22:23], v118, s78, v[4:5]
	v_mad_u64_u32 v[154:155], s[22:23], v121, s78, v[4:5]
	v_mad_u64_u32 v[156:157], s[22:23], v120, s78, v[4:5]
	v_mad_u64_u32 v[158:159], s[22:23], v123, s78, v[4:5]
	v_mad_u64_u32 v[160:161], s[22:23], v122, s78, v[4:5]
	s_waitcnt vmcnt(15)
	ds_write_b32 v130, v108
	s_waitcnt vmcnt(14)
	ds_write_b32 v132, v109
	s_waitcnt vmcnt(13)
	ds_write_b32 v134, v124
	s_waitcnt vmcnt(12)
	ds_write_b32 v136, v125
	s_waitcnt vmcnt(11)
	ds_write_b32 v138, v126
	s_waitcnt vmcnt(10)
	ds_write_b32 v140, v127
	s_waitcnt vmcnt(9)
	ds_write_b32 v142, v162
	s_waitcnt vmcnt(8)
	ds_write_b32 v144, v163
	s_waitcnt vmcnt(7)
	ds_write_b32 v146, v164
	s_waitcnt vmcnt(6)
	ds_write_b32 v148, v165
	s_waitcnt vmcnt(5)
	ds_write_b32 v150, v166
	s_waitcnt vmcnt(4)
	ds_write_b32 v152, v167
	s_waitcnt vmcnt(3)
	ds_write_b32 v154, v168
	s_waitcnt vmcnt(2)
	ds_write_b32 v156, v169
	s_waitcnt vmcnt(1)
	ds_write_b32 v158, v170
	s_waitcnt vmcnt(0)
	ds_write_b32 v160, v171
	s_add_i32 s13, s13, 16
	s_add_i32 s5, s5, 16
	s_add_i32 s15, s15, -16
	s_add_i32 s15, s15, -16
	s_cmp_lg_u32 s15, 0
	s_waitcnt lgkmcnt(0)
	s_add_i32 s1, s14, 0xf500
	ds_read2_b32 v[54:55], v5 offset1:8
	s_cmpk_lt_i32 s0, 0x58
	ds_read2_b32 v[58:59], v5 offset0:33 offset1:41
	s_cselect_b32 s0, s14, s1
	s_sext_i32_i16 s1, s0
	ds_read2_b32 v[60:61], v5 offset0:66 offset1:74
	s_cselect_b32 s5, 0, 0x80
	s_bfe_u32 s1, s1, 0x70018
	ds_read2_b32 v[62:63], v5 offset0:99 offset1:107
	s_add_i32 s1, s0, s1
	s_waitcnt lgkmcnt(3)
	v_bfe_u32 v7, v54, 16, 1
	s_sext_i32_i16 s13, s1
	s_and_b32 s1, s1, 0xff80
	v_add3_u32 v7, v54, v7, s33
	s_waitcnt lgkmcnt(2)
	v_bfe_u32 v9, v58, 16, 1
	ds_read2_b32 v[64:65], v5 offset0:132 offset1:140
	s_sub_i32 s0, s0, s1
	v_lshrrev_b32_e32 v7, 16, v7
	v_add3_u32 v9, v58, v9, s33
	ds_read2_b32 v[66:67], v5 offset0:165 offset1:173
	s_lshl_b32 s13, s13, 1
	s_sext_i32_i16 s0, s0
	v_and_or_b32 v50, v9, s69, v7
	s_waitcnt lgkmcnt(3)
	v_bfe_u32 v7, v60, 16, 1
	s_and_b32 s13, s13, 0xffffff00
	s_add_i32 s0, s5, s0
	v_add3_u32 v7, v60, v7, s33
	s_waitcnt lgkmcnt(2)
	v_bfe_u32 v9, v62, 16, 1
	ds_read2_b32 v[68:69], v5 offset0:198 offset1:206
	s_add_i32 s0, s0, s13
	v_lshrrev_b32_e32 v7, 16, v7
	v_add3_u32 v9, v62, v9, s33
	ds_read2_b32 v[70:71], v5 offset0:231 offset1:239
	s_ashr_i32 s1, s0, 31
	v_and_or_b32 v51, v9, s69, v7
	s_waitcnt lgkmcnt(3)
	v_bfe_u32 v7, v64, 16, 1
	s_lshl_b64 s[0:1], s[0:1], 11
	v_add3_u32 v7, v64, v7, s33
	s_waitcnt lgkmcnt(2)
	v_bfe_u32 v9, v66, 16, 1
	s_add_u32 s5, s20, s0
	v_lshrrev_b32_e32 v7, 16, v7
	v_add3_u32 v9, v66, v9, s33
	s_addc_u32 s14, s21, s1
	s_ashr_i32 s13, s12, 31
	v_and_or_b32 v52, v9, s69, v7
	s_waitcnt lgkmcnt(1)
	v_bfe_u32 v7, v68, 16, 1
	s_lshl_b64 s[0:1], s[12:13], 1
	v_add3_u32 v7, v68, v7, s33
	s_waitcnt lgkmcnt(0)
	v_bfe_u32 v9, v70, 16, 1
	s_add_u32 s0, s5, s0
	v_lshrrev_b32_e32 v7, 16, v7
	v_add3_u32 v9, v70, v9, s33
	s_addc_u32 s1, s14, s1
	v_lshlrev_b32_e32 v128, 1, v6
	v_and_or_b32 v53, v9, s69, v7
	v_bfe_u32 v7, v55, 16, 1
	v_lshl_add_u64 v[56:57], s[0:1], 0, v[128:129]
	v_lshlrev_b32_e32 v128, 1, v8
	v_add3_u32 v7, v55, v7, s33
	v_bfe_u32 v9, v59, 16, 1
	v_lshl_add_u64 v[72:73], v[56:57], 0, v[128:129]
	v_lshrrev_b32_e32 v7, 16, v7
	v_add3_u32 v9, v59, v9, s33
	global_store_dwordx4 v[72:73], v[50:53], off
	v_lshlrev_b32_e32 v128, 1, v10
	ds_read2_b32 v[54:55], v5 offset0:16 offset1:24
	v_and_or_b32 v50, v9, s69, v7
	v_bfe_u32 v7, v61, 16, 1
	v_add3_u32 v7, v61, v7, s33
	v_bfe_u32 v9, v63, 16, 1
	v_lshrrev_b32_e32 v7, 16, v7
	v_add3_u32 v9, v63, v9, s33
	v_and_or_b32 v51, v9, s69, v7
	v_bfe_u32 v7, v65, 16, 1
	v_add3_u32 v7, v65, v7, s33
	v_bfe_u32 v9, v67, 16, 1
	v_lshrrev_b32_e32 v7, 16, v7
	v_add3_u32 v9, v67, v9, s33
	v_and_or_b32 v52, v9, s69, v7
	v_bfe_u32 v7, v69, 16, 1
	v_add3_u32 v7, v69, v7, s33
	v_bfe_u32 v9, v71, 16, 1
	v_lshrrev_b32_e32 v7, 16, v7
	v_add3_u32 v9, v71, v9, s33
	v_and_or_b32 v53, v9, s69, v7
	v_lshl_add_u64 v[58:59], v[56:57], 0, v[128:129]
	global_store_dwordx4 v[58:59], v[50:53], off
	ds_read2_b32 v[58:59], v5 offset0:49 offset1:57
	ds_read2_b32 v[60:61], v5 offset0:82 offset1:90
	ds_read2_b32 v[62:63], v5 offset0:115 offset1:123
	s_waitcnt lgkmcnt(3)
	v_bfe_u32 v7, v54, 16, 1
	v_add3_u32 v7, v54, v7, s33
	s_waitcnt lgkmcnt(2)
	v_bfe_u32 v9, v58, 16, 1
	ds_read2_b32 v[64:65], v5 offset0:148 offset1:156
	v_lshrrev_b32_e32 v7, 16, v7
	v_add3_u32 v9, v58, v9, s33
	ds_read2_b32 v[66:67], v5 offset0:181 offset1:189
	v_and_or_b32 v50, v9, s69, v7
	s_waitcnt lgkmcnt(3)
	v_bfe_u32 v7, v60, 16, 1
	v_add3_u32 v7, v60, v7, s33
	s_waitcnt lgkmcnt(2)
	v_bfe_u32 v9, v62, 16, 1
	ds_read2_b32 v[68:69], v5 offset0:214 offset1:222
	v_lshrrev_b32_e32 v7, 16, v7
	v_add3_u32 v9, v62, v9, s33
	ds_read2_b32 v[70:71], v5 offset0:247 offset1:255
	v_and_or_b32 v51, v9, s69, v7
	s_waitcnt lgkmcnt(3)
	v_bfe_u32 v7, v64, 16, 1
	v_add3_u32 v7, v64, v7, s33
	s_waitcnt lgkmcnt(2)
	v_bfe_u32 v9, v66, 16, 1
	v_lshrrev_b32_e32 v7, 16, v7
	v_add3_u32 v9, v66, v9, s33
	v_and_or_b32 v52, v9, s69, v7
	s_waitcnt lgkmcnt(1)
	v_bfe_u32 v7, v68, 16, 1
	v_add3_u32 v7, v68, v7, s33
	s_waitcnt lgkmcnt(0)
	v_bfe_u32 v9, v70, 16, 1
	v_lshrrev_b32_e32 v7, 16, v7
	v_add3_u32 v9, v70, v9, s33
	v_and_or_b32 v53, v9, s69, v7
	v_bfe_u32 v7, v55, 16, 1
	v_lshlrev_b32_e32 v128, 1, v12
	v_add3_u32 v7, v55, v7, s33
	v_bfe_u32 v9, v59, 16, 1
	v_lshl_add_u64 v[72:73], v[56:57], 0, v[128:129]
	v_lshrrev_b32_e32 v7, 16, v7
	v_add3_u32 v9, v59, v9, s33
	global_store_dwordx4 v[72:73], v[50:53], off
	v_lshlrev_b32_e32 v128, 1, v14
	v_lshl_add_u64 v[54:55], v[56:57], 0, v[128:129]
	v_and_or_b32 v50, v9, s69, v7
	v_bfe_u32 v7, v61, 16, 1
	v_add3_u32 v7, v61, v7, s33
	v_bfe_u32 v9, v63, 16, 1
	v_lshrrev_b32_e32 v7, 16, v7
	v_add3_u32 v9, v63, v9, s33
	v_and_or_b32 v51, v9, s69, v7
	v_bfe_u32 v7, v65, 16, 1
	v_add3_u32 v7, v65, v7, s33
	v_bfe_u32 v9, v67, 16, 1
	v_lshrrev_b32_e32 v7, 16, v7
	v_add3_u32 v9, v67, v9, s33
	v_and_or_b32 v52, v9, s69, v7
	v_bfe_u32 v7, v69, 16, 1
	v_add3_u32 v7, v69, v7, s33
	v_bfe_u32 v9, v71, 16, 1
	v_lshrrev_b32_e32 v7, 16, v7
	v_add3_u32 v9, v71, v9, s33
	v_and_or_b32 v53, v9, s69, v7
	global_store_dwordx4 v[54:55], v[50:53], off
	s_waitcnt lgkmcnt(0)
	s_mov_b32 s1, s4
	s_andn2_b64 vcc, exec, s[10:11]
	s_mov_b64 s[10:11], -1
	s_cbranch_vccnz .LBB0_744

.LBB0_689:
	s_lshl_b32 s15, s0, 1
	s_lshl_b32 s22, s5, 1
	v_or_b32_e32 v7, s15, v1
	v_or_b32_e32 v9, s22, v0
	s_add_i32 s23, s15, 4
	s_add_i32 s24, s22, 4
	s_add_i32 s25, s15, 8
	s_add_i32 s26, s22, 8
	s_add_i32 s27, s15, 12
	s_add_i32 s30, s22, 12
	s_add_i32 s36, s15, 16
	s_add_i32 s37, s22, 16
	s_add_i32 s40, s15, 20
	s_add_i32 s41, s22, 20
	s_add_i32 s42, s15, 24
	s_add_i32 s43, s22, 24
	s_add_i32 s15, s15, 28
	s_add_i32 s22, s22, 28
	v_add_u32_e32 v54, s12, v9
	v_or_b32_e32 v11, s23, v1
	v_or_b32_e32 v13, s24, v0
	v_or_b32_e32 v15, s25, v1
	v_or_b32_e32 v19, s26, v0
	v_or_b32_e32 v41, s27, v1
	v_or_b32_e32 v43, s30, v0
	v_or_b32_e32 v45, s36, v1
	v_or_b32_e32 v47, s37, v0
	v_or_b32_e32 v49, s40, v1
	v_or_b32_e32 v82, s41, v0
	v_or_b32_e32 v86, s42, v1
	v_or_b32_e32 v87, s43, v0
	v_or_b32_e32 v88, s15, v1
	v_or_b32_e32 v89, s22, v0
	v_add_u32_e32 v52, s4, v7
	v_ashrrev_i32_e32 v55, 31, v54
	v_add_u32_e32 v56, s4, v11
	v_add_u32_e32 v58, s12, v13
	v_add_u32_e32 v60, s4, v15
	v_add_u32_e32 v62, s12, v19
	v_add_u32_e32 v64, s4, v41
	v_add_u32_e32 v66, s12, v43
	v_add_u32_e32 v68, s4, v45
	v_add_u32_e32 v70, s12, v47
	v_add_u32_e32 v72, s4, v49
	v_add_u32_e32 v74, s12, v82
	v_add_u32_e32 v76, s4, v86
	v_add_u32_e32 v78, s12, v87
	v_add_u32_e32 v80, s4, v88
	v_add_u32_e32 v84, s12, v89
	v_ashrrev_i32_e32 v53, 31, v52
	v_lshlrev_b64 v[54:55], 12, v[54:55]
	v_ashrrev_i32_e32 v59, 31, v58
	v_ashrrev_i32_e32 v57, 31, v56
	v_ashrrev_i32_e32 v63, 31, v62
	v_ashrrev_i32_e32 v61, 31, v60
	v_ashrrev_i32_e32 v67, 31, v66
	v_ashrrev_i32_e32 v65, 31, v64
	v_ashrrev_i32_e32 v71, 31, v70
	v_ashrrev_i32_e32 v69, 31, v68
	v_ashrrev_i32_e32 v75, 31, v74
	v_ashrrev_i32_e32 v73, 31, v72
	v_ashrrev_i32_e32 v79, 31, v78
	v_ashrrev_i32_e32 v77, 31, v76
	v_ashrrev_i32_e32 v85, 31, v84
	v_ashrrev_i32_e32 v81, 31, v80
	v_lshlrev_b64 v[52:53], 12, v[52:53]
	v_lshl_add_u64 v[54:55], v[50:51], 0, v[54:55]
	v_lshlrev_b64 v[56:57], 12, v[56:57]
	v_lshlrev_b64 v[58:59], 12, v[58:59]
	v_lshlrev_b64 v[60:61], 12, v[60:61]
	v_lshlrev_b64 v[62:63], 12, v[62:63]
	v_lshlrev_b64 v[64:65], 12, v[64:65]
	v_lshlrev_b64 v[66:67], 12, v[66:67]
	v_lshlrev_b64 v[68:69], 12, v[68:69]
	v_lshlrev_b64 v[70:71], 12, v[70:71]
	v_lshlrev_b64 v[72:73], 12, v[72:73]
	v_lshlrev_b64 v[74:75], 12, v[74:75]
	v_lshlrev_b64 v[76:77], 12, v[76:77]
	v_lshlrev_b64 v[78:79], 12, v[78:79]
	v_lshlrev_b64 v[80:81], 12, v[80:81]
	v_lshlrev_b64 v[84:85], 12, v[84:85]
	v_lshl_add_u64 v[52:53], v[50:51], 0, v[52:53]
	v_lshl_add_u64 v[58:59], v[50:51], 0, v[58:59]
	v_lshl_add_u64 v[56:57], v[50:51], 0, v[56:57]
	v_lshl_add_u64 v[62:63], v[50:51], 0, v[62:63]
	v_lshl_add_u64 v[60:61], v[50:51], 0, v[60:61]
	v_lshl_add_u64 v[66:67], v[50:51], 0, v[66:67]
	v_lshl_add_u64 v[64:65], v[50:51], 0, v[64:65]
	v_lshl_add_u64 v[70:71], v[50:51], 0, v[70:71]
	v_lshl_add_u64 v[68:69], v[50:51], 0, v[68:69]
	v_lshl_add_u64 v[74:75], v[50:51], 0, v[74:75]
	v_lshl_add_u64 v[72:73], v[50:51], 0, v[72:73]
	v_lshl_add_u64 v[78:79], v[50:51], 0, v[78:79]
	v_lshl_add_u64 v[76:77], v[50:51], 0, v[76:77]
	v_lshl_add_u64 v[84:85], v[50:51], 0, v[84:85]
	v_lshl_add_u64 v[80:81], v[50:51], 0, v[80:81]
	global_load_dword v90, v[54:55], off
	global_load_dword v91, v[52:53], off
	global_load_dword v92, v[58:59], off
	global_load_dword v93, v[56:57], off
	global_load_dword v94, v[62:63], off
	global_load_dword v95, v[60:61], off
	global_load_dword v96, v[66:67], off
	global_load_dword v97, v[64:65], off
	global_load_dword v98, v[70:71], off
	global_load_dword v99, v[68:69], off
	global_load_dword v100, v[74:75], off
	global_load_dword v101, v[72:73], off
	global_load_dword v102, v[78:79], off
	global_load_dword v103, v[76:77], off
	global_load_dword v104, v[84:85], off
	global_load_dword v105, v[80:81], off
	s_add_i32 s5, s5, 16
	s_add_i32 s0, s0, 16
	s_lshl_b32 s15, s0, 1
	s_lshl_b32 s22, s5, 1
	v_or_b32_e32 v106, s15, v1
	v_or_b32_e32 v107, s22, v0
	s_add_i32 s23, s15, 4
	s_add_i32 s24, s22, 4
	s_add_i32 s25, s15, 8
	s_add_i32 s26, s22, 8
	s_add_i32 s27, s15, 12
	s_add_i32 s30, s22, 12
	s_add_i32 s36, s15, 16
	s_add_i32 s37, s22, 16
	s_add_i32 s40, s15, 20
	s_add_i32 s41, s22, 20
	s_add_i32 s42, s15, 24
	s_add_i32 s43, s22, 24
	s_add_i32 s15, s15, 28
	s_add_i32 s22, s22, 28
	v_add_u32_e32 v132, s12, v107
	v_or_b32_e32 v108, s23, v1
	v_or_b32_e32 v109, s24, v0
	v_or_b32_e32 v110, s25, v1
	v_or_b32_e32 v111, s26, v0
	v_or_b32_e32 v112, s27, v1
	v_or_b32_e32 v113, s30, v0
	v_or_b32_e32 v114, s36, v1
	v_or_b32_e32 v115, s37, v0
	v_or_b32_e32 v116, s40, v1
	v_or_b32_e32 v117, s41, v0
	v_or_b32_e32 v118, s42, v1
	v_or_b32_e32 v119, s43, v0
	v_or_b32_e32 v120, s15, v1
	v_or_b32_e32 v121, s22, v0
	v_add_u32_e32 v130, s4, v106
	v_ashrrev_i32_e32 v133, 31, v132
	v_add_u32_e32 v134, s4, v108
	v_add_u32_e32 v136, s12, v109
	v_add_u32_e32 v138, s4, v110
	v_add_u32_e32 v140, s12, v111
	v_add_u32_e32 v142, s4, v112
	v_add_u32_e32 v144, s12, v113
	v_add_u32_e32 v146, s4, v114
	v_add_u32_e32 v148, s12, v115
	v_add_u32_e32 v150, s4, v116
	v_add_u32_e32 v152, s12, v117
	v_add_u32_e32 v154, s4, v118
	v_add_u32_e32 v156, s12, v119
	v_add_u32_e32 v158, s4, v120
	v_add_u32_e32 v160, s12, v121
	v_ashrrev_i32_e32 v131, 31, v130
	v_lshlrev_b64 v[132:133], 12, v[132:133]
	v_ashrrev_i32_e32 v137, 31, v136
	v_ashrrev_i32_e32 v135, 31, v134
	v_ashrrev_i32_e32 v141, 31, v140
	v_ashrrev_i32_e32 v139, 31, v138
	v_ashrrev_i32_e32 v145, 31, v144
	v_ashrrev_i32_e32 v143, 31, v142
	v_ashrrev_i32_e32 v149, 31, v148
	v_ashrrev_i32_e32 v147, 31, v146
	v_ashrrev_i32_e32 v153, 31, v152
	v_ashrrev_i32_e32 v151, 31, v150
	v_ashrrev_i32_e32 v157, 31, v156
	v_ashrrev_i32_e32 v155, 31, v154
	v_ashrrev_i32_e32 v161, 31, v160
	v_ashrrev_i32_e32 v159, 31, v158
	v_lshlrev_b64 v[130:131], 12, v[130:131]
	v_lshl_add_u64 v[132:133], v[50:51], 0, v[132:133]
	v_lshlrev_b64 v[134:135], 12, v[134:135]
	v_lshlrev_b64 v[136:137], 12, v[136:137]
	v_lshlrev_b64 v[138:139], 12, v[138:139]
	v_lshlrev_b64 v[140:141], 12, v[140:141]
	v_lshlrev_b64 v[142:143], 12, v[142:143]
	v_lshlrev_b64 v[144:145], 12, v[144:145]
	v_lshlrev_b64 v[146:147], 12, v[146:147]
	v_lshlrev_b64 v[148:149], 12, v[148:149]
	v_lshlrev_b64 v[150:151], 12, v[150:151]
	v_lshlrev_b64 v[152:153], 12, v[152:153]
	v_lshlrev_b64 v[154:155], 12, v[154:155]
	v_lshlrev_b64 v[156:157], 12, v[156:157]
	v_lshlrev_b64 v[158:159], 12, v[158:159]
	v_lshlrev_b64 v[160:161], 12, v[160:161]
	v_lshl_add_u64 v[130:131], v[50:51], 0, v[130:131]
	v_lshl_add_u64 v[136:137], v[50:51], 0, v[136:137]
	v_lshl_add_u64 v[134:135], v[50:51], 0, v[134:135]
	v_lshl_add_u64 v[140:141], v[50:51], 0, v[140:141]
	v_lshl_add_u64 v[138:139], v[50:51], 0, v[138:139]
	v_lshl_add_u64 v[144:145], v[50:51], 0, v[144:145]
	v_lshl_add_u64 v[142:143], v[50:51], 0, v[142:143]
	v_lshl_add_u64 v[148:149], v[50:51], 0, v[148:149]
	v_lshl_add_u64 v[146:147], v[50:51], 0, v[146:147]
	v_lshl_add_u64 v[152:153], v[50:51], 0, v[152:153]
	v_lshl_add_u64 v[150:151], v[50:51], 0, v[150:151]
	v_lshl_add_u64 v[156:157], v[50:51], 0, v[156:157]
	v_lshl_add_u64 v[154:155], v[50:51], 0, v[154:155]
	v_lshl_add_u64 v[160:161], v[50:51], 0, v[160:161]
	v_lshl_add_u64 v[158:159], v[50:51], 0, v[158:159]
	global_load_dword v122, v[132:133], off
	global_load_dword v123, v[130:131], off
	global_load_dword v124, v[136:137], off
	global_load_dword v125, v[134:135], off
	global_load_dword v126, v[140:141], off
	global_load_dword v127, v[138:139], off
	global_load_dword v162, v[144:145], off
	global_load_dword v163, v[142:143], off
	global_load_dword v164, v[148:149], off
	global_load_dword v165, v[146:147], off
	global_load_dword v166, v[152:153], off
	global_load_dword v167, v[150:151], off
	global_load_dword v168, v[156:157], off
	global_load_dword v169, v[154:155], off
	global_load_dword v170, v[160:161], off
	global_load_dword v171, v[158:159], off
	v_mad_u64_u32 v[52:53], s[22:23], v9, s78, v[4:5]
	v_mad_u64_u32 v[54:55], s[22:23], v7, s78, v[4:5]
	v_mad_u64_u32 v[56:57], s[22:23], v13, s78, v[4:5]
	v_mad_u64_u32 v[58:59], s[22:23], v11, s78, v[4:5]
	v_mad_u64_u32 v[60:61], s[22:23], v19, s78, v[4:5]
	v_mad_u64_u32 v[62:63], s[22:23], v15, s78, v[4:5]
	v_mad_u64_u32 v[64:65], s[22:23], v43, s78, v[4:5]
	v_mad_u64_u32 v[66:67], s[22:23], v41, s78, v[4:5]
	v_mad_u64_u32 v[68:69], s[22:23], v47, s78, v[4:5]
	v_mad_u64_u32 v[70:71], s[22:23], v45, s78, v[4:5]
	v_mad_u64_u32 v[72:73], s[22:23], v82, s78, v[4:5]
	v_mad_u64_u32 v[74:75], s[22:23], v49, s78, v[4:5]
	v_mad_u64_u32 v[76:77], s[22:23], v87, s78, v[4:5]
	v_mad_u64_u32 v[78:79], s[22:23], v86, s78, v[4:5]
	v_mad_u64_u32 v[80:81], s[22:23], v89, s78, v[4:5]
	v_mad_u64_u32 v[84:85], s[22:23], v88, s78, v[4:5]
	s_waitcnt vmcnt(31)
	ds_write_b32 v52, v90
	s_waitcnt vmcnt(30)
	ds_write_b32 v54, v91
	s_waitcnt vmcnt(29)
	ds_write_b32 v56, v92
	s_waitcnt vmcnt(28)
	ds_write_b32 v58, v93
	s_waitcnt vmcnt(27)
	ds_write_b32 v60, v94
	s_waitcnt vmcnt(26)
	ds_write_b32 v62, v95
	s_waitcnt vmcnt(25)
	ds_write_b32 v64, v96
	s_waitcnt vmcnt(24)
	ds_write_b32 v66, v97
	s_waitcnt vmcnt(23)
	ds_write_b32 v68, v98
	s_waitcnt vmcnt(22)
	ds_write_b32 v70, v99
	s_waitcnt vmcnt(21)
	ds_write_b32 v72, v100
	s_waitcnt vmcnt(20)
	ds_write_b32 v74, v101
	s_waitcnt vmcnt(19)
	ds_write_b32 v76, v102
	s_waitcnt vmcnt(18)
	ds_write_b32 v78, v103
	s_waitcnt vmcnt(17)
	ds_write_b32 v80, v104
	s_waitcnt vmcnt(16)
	ds_write_b32 v84, v105
	v_mad_u64_u32 v[130:131], s[22:23], v107, s78, v[4:5]
	v_mad_u64_u32 v[132:133], s[22:23], v106, s78, v[4:5]
	v_mad_u64_u32 v[134:135], s[22:23], v109, s78, v[4:5]
	v_mad_u64_u32 v[136:137], s[22:23], v108, s78, v[4:5]
	v_mad_u64_u32 v[138:139], s[22:23], v111, s78, v[4:5]
	v_mad_u64_u32 v[140:141], s[22:23], v110, s78, v[4:5]
	v_mad_u64_u32 v[142:143], s[22:23], v113, s78, v[4:5]
	v_mad_u64_u32 v[144:145], s[22:23], v112, s78, v[4:5]
	v_mad_u64_u32 v[146:147], s[22:23], v115, s78, v[4:5]
	v_mad_u64_u32 v[148:149], s[22:23], v114, s78, v[4:5]
	v_mad_u64_u32 v[150:151], s[22:23], v117, s78, v[4:5]
	v_mad_u64_u32 v[152:153], s[22:23], v116, s78, v[4:5]
	v_mad_u64_u32 v[154:155], s[22:23], v119, s78, v[4:5]
	v_mad_u64_u32 v[156:157], s[22:23], v118, s78, v[4:5]
	v_mad_u64_u32 v[158:159], s[22:23], v121, s78, v[4:5]
	v_mad_u64_u32 v[160:161], s[22:23], v120, s78, v[4:5]
	s_waitcnt vmcnt(15)
	ds_write_b32 v130, v122
	s_waitcnt vmcnt(14)
	ds_write_b32 v132, v123
	s_waitcnt vmcnt(13)
	ds_write_b32 v134, v124
	s_waitcnt vmcnt(12)
	ds_write_b32 v136, v125
	s_waitcnt vmcnt(11)
	ds_write_b32 v138, v126
	s_waitcnt vmcnt(10)
	ds_write_b32 v140, v127
	s_waitcnt vmcnt(9)
	ds_write_b32 v142, v162
	s_waitcnt vmcnt(8)
	ds_write_b32 v144, v163
	s_waitcnt vmcnt(7)
	ds_write_b32 v146, v164
	s_waitcnt vmcnt(6)
	ds_write_b32 v148, v165
	s_waitcnt vmcnt(5)
	ds_write_b32 v150, v166
	s_waitcnt vmcnt(4)
	ds_write_b32 v152, v167
	s_waitcnt vmcnt(3)
	ds_write_b32 v154, v168
	s_waitcnt vmcnt(2)
	ds_write_b32 v156, v169
	s_waitcnt vmcnt(1)
	ds_write_b32 v158, v170
	s_waitcnt vmcnt(0)
	ds_write_b32 v160, v171
	s_add_i32 s5, s5, 16
	s_add_i32 s0, s0, 16
	s_add_i32 s13, s13, -16
	s_add_i32 s13, s13, -16
	s_cmp_lg_u32 s13, 0
	s_waitcnt lgkmcnt(0)
	ds_read2_b32 v[54:55], v5 offset1:8
	ds_read2_b32 v[58:59], v5 offset0:33 offset1:41
	ds_read2_b32 v[60:61], v5 offset0:66 offset1:74
	ds_read2_b32 v[62:63], v5 offset0:99 offset1:107
	ds_read2_b32 v[64:65], v5 offset0:132 offset1:140
	s_waitcnt lgkmcnt(4)
	v_bfe_u32 v7, v54, 16, 1
	v_add3_u32 v7, v54, v7, s33
	s_waitcnt lgkmcnt(3)
	v_bfe_u32 v9, v58, 16, 1
	v_lshrrev_b32_e32 v7, 16, v7
	v_add3_u32 v9, v58, v9, s33
	ds_read2_b32 v[66:67], v5 offset0:165 offset1:173
	v_and_or_b32 v50, v9, s69, v7
	s_waitcnt lgkmcnt(3)
	v_bfe_u32 v7, v60, 16, 1
	v_add3_u32 v7, v60, v7, s33
	s_waitcnt lgkmcnt(2)
	v_bfe_u32 v9, v62, 16, 1
	ds_read2_b32 v[68:69], v5 offset0:198 offset1:206
	v_lshrrev_b32_e32 v7, 16, v7
	v_add3_u32 v9, v62, v9, s33
	ds_read2_b32 v[70:71], v5 offset0:231 offset1:239
	v_and_or_b32 v51, v9, s69, v7
	s_waitcnt lgkmcnt(3)
	v_bfe_u32 v7, v64, 16, 1
	s_mul_i32 s4, s14, 0x1600
	v_add3_u32 v7, v64, v7, s33
	s_waitcnt lgkmcnt(2)
	v_bfe_u32 v9, v66, 16, 1
	s_mul_hi_i32 s0, s14, 0x1600
	s_add_u32 s14, s39, s4
	v_lshrrev_b32_e32 v7, 16, v7
	v_add3_u32 v9, v66, v9, s33
	s_addc_u32 s0, s44, s0
	s_ashr_i32 s13, s12, 31
	v_and_or_b32 v52, v9, s69, v7
	s_waitcnt lgkmcnt(1)
	v_bfe_u32 v7, v68, 16, 1
	s_lshl_b64 s[4:5], s[12:13], 1
	v_add3_u32 v7, v68, v7, s33
	s_waitcnt lgkmcnt(0)
	v_bfe_u32 v9, v70, 16, 1
	s_add_u32 s4, s14, s4
	v_lshrrev_b32_e32 v7, 16, v7
	v_add3_u32 v9, v70, v9, s33
	s_addc_u32 s5, s0, s5
	v_lshlrev_b32_e32 v128, 1, v6
	v_and_or_b32 v53, v9, s69, v7
	v_bfe_u32 v7, v55, 16, 1
	v_lshl_add_u64 v[56:57], s[4:5], 0, v[128:129]
	v_lshlrev_b32_e32 v128, 1, v18
	v_add3_u32 v7, v55, v7, s33
	v_bfe_u32 v9, v59, 16, 1
	v_lshl_add_u64 v[56:57], v[56:57], 0, v[128:129]
	v_lshrrev_b32_e32 v7, 16, v7
	v_add3_u32 v9, v59, v9, s33
	global_store_dwordx4 v[56:57], v[50:53], off
	s_mov_b32 s0, 0xb000
	v_add_co_u32_e32 v58, vcc, s0, v56
	v_and_or_b32 v50, v9, s69, v7
	v_bfe_u32 v7, v61, 16, 1
	v_add3_u32 v7, v61, v7, s33
	v_bfe_u32 v9, v63, 16, 1
	v_lshrrev_b32_e32 v7, 16, v7
	v_add3_u32 v9, v63, v9, s33
	v_and_or_b32 v51, v9, s69, v7
	v_bfe_u32 v7, v65, 16, 1
	v_add3_u32 v7, v65, v7, s33
	v_bfe_u32 v9, v67, 16, 1
	v_lshrrev_b32_e32 v7, 16, v7
	v_add3_u32 v9, v67, v9, s33
	v_and_or_b32 v52, v9, s69, v7
	v_bfe_u32 v7, v69, 16, 1
	v_add3_u32 v7, v69, v7, s33
	v_bfe_u32 v9, v71, 16, 1
	v_lshrrev_b32_e32 v7, 16, v7
	v_add3_u32 v9, v71, v9, s33
	v_and_or_b32 v53, v9, s69, v7
	ds_read2_b32 v[54:55], v5 offset0:16 offset1:24
	v_addc_co_u32_e32 v59, vcc, 0, v57, vcc
	global_store_dwordx4 v[58:59], v[50:53], off
	ds_read2_b32 v[58:59], v5 offset0:49 offset1:57
	ds_read2_b32 v[60:61], v5 offset0:82 offset1:90
	ds_read2_b32 v[62:63], v5 offset0:115 offset1:123
	s_waitcnt lgkmcnt(3)
	v_bfe_u32 v7, v54, 16, 1
	v_add3_u32 v7, v54, v7, s33
	s_waitcnt lgkmcnt(2)
	v_bfe_u32 v9, v58, 16, 1
	ds_read2_b32 v[64:65], v5 offset0:148 offset1:156
	v_lshrrev_b32_e32 v7, 16, v7
	v_add3_u32 v9, v58, v9, s33
	ds_read2_b32 v[66:67], v5 offset0:181 offset1:189
	v_and_or_b32 v50, v9, s69, v7
	s_waitcnt lgkmcnt(3)
	v_bfe_u32 v7, v60, 16, 1
	v_add3_u32 v7, v60, v7, s33
	s_waitcnt lgkmcnt(2)
	v_bfe_u32 v9, v62, 16, 1
	ds_read2_b32 v[68:69], v5 offset0:214 offset1:222
	v_lshrrev_b32_e32 v7, 16, v7
	v_add3_u32 v9, v62, v9, s33
	ds_read2_b32 v[70:71], v5 offset0:247 offset1:255
	v_and_or_b32 v51, v9, s69, v7
	s_waitcnt lgkmcnt(3)
	v_bfe_u32 v7, v64, 16, 1
	v_add3_u32 v7, v64, v7, s33
	s_waitcnt lgkmcnt(2)
	v_bfe_u32 v9, v66, 16, 1
	v_lshrrev_b32_e32 v7, 16, v7
	v_add3_u32 v9, v66, v9, s33
	v_and_or_b32 v52, v9, s69, v7
	s_waitcnt lgkmcnt(1)
	v_bfe_u32 v7, v68, 16, 1
	v_add3_u32 v7, v68, v7, s33
	s_waitcnt lgkmcnt(0)
	v_bfe_u32 v9, v70, 16, 1
	v_lshrrev_b32_e32 v7, 16, v7
	v_add3_u32 v9, v70, v9, s33
	v_and_or_b32 v53, v9, s69, v7
	s_mov_b32 s0, 0x16000
	v_bfe_u32 v7, v55, 16, 1
	v_add_co_u32_e32 v72, vcc, s0, v56
	v_add3_u32 v7, v55, v7, s33
	v_bfe_u32 v9, v59, 16, 1
	v_addc_co_u32_e32 v73, vcc, 0, v57, vcc
	v_lshrrev_b32_e32 v7, 16, v7
	v_add3_u32 v9, v59, v9, s33
	global_store_dwordx4 v[72:73], v[50:53], off
	v_add_co_u32_e32 v54, vcc, 0x21000, v56
	s_nop 0
	v_and_or_b32 v50, v9, s69, v7
	v_bfe_u32 v7, v61, 16, 1
	v_add3_u32 v7, v61, v7, s33
	v_bfe_u32 v9, v63, 16, 1
	v_lshrrev_b32_e32 v7, 16, v7
	v_add3_u32 v9, v63, v9, s33
	v_and_or_b32 v51, v9, s69, v7
	v_bfe_u32 v7, v65, 16, 1
	v_add3_u32 v7, v65, v7, s33
	v_bfe_u32 v9, v67, 16, 1
	v_lshrrev_b32_e32 v7, 16, v7
	v_add3_u32 v9, v67, v9, s33
	v_and_or_b32 v52, v9, s69, v7
	v_bfe_u32 v7, v69, 16, 1
	v_add3_u32 v7, v69, v7, s33
	v_bfe_u32 v9, v71, 16, 1
	v_lshrrev_b32_e32 v7, 16, v7
	v_add3_u32 v9, v71, v9, s33
	v_and_or_b32 v53, v9, s69, v7
	v_addc_co_u32_e32 v55, vcc, 0, v57, vcc
	global_store_dwordx4 v[54:55], v[50:53], off
	s_waitcnt lgkmcnt(0)
	s_mov_b32 s0, s1
	s_andn2_b64 vcc, exec, s[10:11]
	s_mov_b64 s[10:11], -1
	s_cbranch_vccnz .LBB0_744

.LBB0_700:
	s_lshl_b32 s23, s5, 1
	s_lshl_b32 s24, s13, 1
	v_or_b32_e32 v7, s23, v1
	v_or_b32_e32 v9, s24, v0
	s_add_i32 s25, s23, 4
	s_add_i32 s26, s24, 4
	s_add_i32 s27, s23, 8
	s_add_i32 s30, s24, 8
	s_add_i32 s36, s23, 12
	s_add_i32 s37, s24, 12
	s_add_i32 s40, s23, 16
	s_add_i32 s41, s24, 16
	s_add_i32 s42, s23, 20
	s_add_i32 s43, s24, 20
	s_add_i32 s52, s23, 24
	s_add_i32 s53, s24, 24
	s_add_i32 s23, s23, 28
	s_add_i32 s24, s24, 28
	v_add_u32_e32 v11, s4, v7
	v_add_u32_e32 v13, s12, v9
	v_or_b32_e32 v15, s25, v1
	v_or_b32_e32 v19, s26, v0
	v_or_b32_e32 v41, s27, v1
	v_or_b32_e32 v43, s30, v0
	v_or_b32_e32 v45, s36, v1
	v_or_b32_e32 v47, s37, v0
	v_or_b32_e32 v49, s40, v1
	v_or_b32_e32 v82, s41, v0
	v_or_b32_e32 v86, s42, v1
	v_or_b32_e32 v87, s43, v0
	v_or_b32_e32 v88, s52, v1
	v_or_b32_e32 v89, s53, v0
	v_or_b32_e32 v90, s23, v1
	v_or_b32_e32 v91, s24, v0
	v_mad_i64_i32 v[52:53], s[24:25], v13, s68, v[50:51]
	v_mad_i64_i32 v[54:55], s[24:25], v11, s68, v[50:51]
	v_add_u32_e32 v11, s4, v15
	v_add_u32_e32 v13, s12, v19
	v_add_u32_e32 v62, s4, v41
	v_add_u32_e32 v60, s12, v43
	v_add_u32_e32 v66, s4, v45
	v_add_u32_e32 v64, s12, v47
	v_add_u32_e32 v70, s4, v49
	v_add_u32_e32 v68, s12, v82
	v_add_u32_e32 v74, s4, v86
	v_add_u32_e32 v72, s12, v87
	v_add_u32_e32 v78, s4, v88
	v_add_u32_e32 v76, s12, v89
	v_add_u32_e32 v84, s4, v90
	v_add_u32_e32 v80, s12, v91
	v_mad_i64_i32 v[56:57], s[24:25], v13, s68, v[50:51]
	v_mad_i64_i32 v[58:59], s[24:25], v11, s68, v[50:51]
	v_mad_i64_i32 v[60:61], s[24:25], v60, s68, v[50:51]
	v_mad_i64_i32 v[62:63], s[24:25], v62, s68, v[50:51]
	v_mad_i64_i32 v[64:65], s[24:25], v64, s68, v[50:51]
	v_mad_i64_i32 v[66:67], s[24:25], v66, s68, v[50:51]
	v_mad_i64_i32 v[68:69], s[24:25], v68, s68, v[50:51]
	v_mad_i64_i32 v[70:71], s[24:25], v70, s68, v[50:51]
	v_mad_i64_i32 v[72:73], s[24:25], v72, s68, v[50:51]
	v_mad_i64_i32 v[74:75], s[24:25], v74, s68, v[50:51]
	v_mad_i64_i32 v[76:77], s[24:25], v76, s68, v[50:51]
	v_mad_i64_i32 v[78:79], s[24:25], v78, s68, v[50:51]
	v_mad_i64_i32 v[80:81], s[24:25], v80, s68, v[50:51]
	v_mad_i64_i32 v[84:85], s[24:25], v84, s68, v[50:51]
	global_load_dword v11, v[52:53], off
	global_load_dword v13, v[54:55], off
	global_load_dword v92, v[56:57], off
	global_load_dword v93, v[58:59], off
	global_load_dword v94, v[60:61], off
	global_load_dword v95, v[62:63], off
	global_load_dword v96, v[64:65], off
	global_load_dword v97, v[66:67], off
	global_load_dword v98, v[68:69], off
	global_load_dword v99, v[70:71], off
	global_load_dword v100, v[72:73], off
	global_load_dword v101, v[74:75], off
	global_load_dword v102, v[76:77], off
	global_load_dword v103, v[78:79], off
	global_load_dword v104, v[80:81], off
	global_load_dword v105, v[84:85], off
	s_add_i32 s13, s13, 16
	s_add_i32 s5, s5, 16
	s_lshl_b32 s23, s5, 1
	s_lshl_b32 s24, s13, 1
	v_or_b32_e32 v106, s23, v1
	v_or_b32_e32 v107, s24, v0
	s_add_i32 s25, s23, 4
	s_add_i32 s26, s24, 4
	s_add_i32 s27, s23, 8
	s_add_i32 s30, s24, 8
	s_add_i32 s36, s23, 12
	s_add_i32 s37, s24, 12
	s_add_i32 s40, s23, 16
	s_add_i32 s41, s24, 16
	s_add_i32 s42, s23, 20
	s_add_i32 s43, s24, 20
	s_add_i32 s52, s23, 24
	s_add_i32 s53, s24, 24
	s_add_i32 s23, s23, 28
	s_add_i32 s24, s24, 28
	v_add_u32_e32 v108, s4, v106
	v_add_u32_e32 v109, s12, v107
	v_or_b32_e32 v110, s25, v1
	v_or_b32_e32 v111, s26, v0
	v_or_b32_e32 v112, s27, v1
	v_or_b32_e32 v113, s30, v0
	v_or_b32_e32 v114, s36, v1
	v_or_b32_e32 v115, s37, v0
	v_or_b32_e32 v116, s40, v1
	v_or_b32_e32 v117, s41, v0
	v_or_b32_e32 v118, s42, v1
	v_or_b32_e32 v119, s43, v0
	v_or_b32_e32 v120, s52, v1
	v_or_b32_e32 v121, s53, v0
	v_or_b32_e32 v122, s23, v1
	v_or_b32_e32 v123, s24, v0
	v_mad_i64_i32 v[130:131], s[24:25], v109, s68, v[50:51]
	v_mad_i64_i32 v[132:133], s[24:25], v108, s68, v[50:51]
	v_add_u32_e32 v108, s4, v110
	v_add_u32_e32 v109, s12, v111
	v_add_u32_e32 v140, s4, v112
	v_add_u32_e32 v138, s12, v113
	v_add_u32_e32 v144, s4, v114
	v_add_u32_e32 v142, s12, v115
	v_add_u32_e32 v148, s4, v116
	v_add_u32_e32 v146, s12, v117
	v_add_u32_e32 v152, s4, v118
	v_add_u32_e32 v150, s12, v119
	v_add_u32_e32 v156, s4, v120
	v_add_u32_e32 v154, s12, v121
	v_add_u32_e32 v160, s4, v122
	v_add_u32_e32 v158, s12, v123
	v_mad_i64_i32 v[134:135], s[24:25], v109, s68, v[50:51]
	v_mad_i64_i32 v[136:137], s[24:25], v108, s68, v[50:51]
	v_mad_i64_i32 v[138:139], s[24:25], v138, s68, v[50:51]
	v_mad_i64_i32 v[140:141], s[24:25], v140, s68, v[50:51]
	v_mad_i64_i32 v[142:143], s[24:25], v142, s68, v[50:51]
	v_mad_i64_i32 v[144:145], s[24:25], v144, s68, v[50:51]
	v_mad_i64_i32 v[146:147], s[24:25], v146, s68, v[50:51]
	v_mad_i64_i32 v[148:149], s[24:25], v148, s68, v[50:51]
	v_mad_i64_i32 v[150:151], s[24:25], v150, s68, v[50:51]
	v_mad_i64_i32 v[152:153], s[24:25], v152, s68, v[50:51]
	v_mad_i64_i32 v[154:155], s[24:25], v154, s68, v[50:51]
	v_mad_i64_i32 v[156:157], s[24:25], v156, s68, v[50:51]
	v_mad_i64_i32 v[158:159], s[24:25], v158, s68, v[50:51]
	v_mad_i64_i32 v[160:161], s[24:25], v160, s68, v[50:51]
	global_load_dword v108, v[130:131], off
	global_load_dword v109, v[132:133], off
	global_load_dword v124, v[134:135], off
	global_load_dword v125, v[136:137], off
	global_load_dword v126, v[138:139], off
	global_load_dword v127, v[140:141], off
	global_load_dword v162, v[142:143], off
	global_load_dword v163, v[144:145], off
	global_load_dword v164, v[146:147], off
	global_load_dword v165, v[148:149], off
	global_load_dword v166, v[150:151], off
	global_load_dword v167, v[152:153], off
	global_load_dword v168, v[154:155], off
	global_load_dword v169, v[156:157], off
	global_load_dword v170, v[158:159], off
	global_load_dword v171, v[160:161], off
	v_mad_u64_u32 v[52:53], s[24:25], v9, s78, v[4:5]
	v_mad_u64_u32 v[54:55], s[24:25], v7, s78, v[4:5]
	v_mad_u64_u32 v[56:57], s[24:25], v19, s78, v[4:5]
	v_mad_u64_u32 v[58:59], s[24:25], v15, s78, v[4:5]
	v_mad_u64_u32 v[60:61], s[24:25], v43, s78, v[4:5]
	v_mad_u64_u32 v[62:63], s[24:25], v41, s78, v[4:5]
	v_mad_u64_u32 v[64:65], s[24:25], v47, s78, v[4:5]
	v_mad_u64_u32 v[66:67], s[24:25], v45, s78, v[4:5]
	v_mad_u64_u32 v[68:69], s[24:25], v82, s78, v[4:5]
	v_mad_u64_u32 v[70:71], s[24:25], v49, s78, v[4:5]
	v_mad_u64_u32 v[72:73], s[24:25], v87, s78, v[4:5]
	v_mad_u64_u32 v[74:75], s[24:25], v86, s78, v[4:5]
	v_mad_u64_u32 v[76:77], s[24:25], v89, s78, v[4:5]
	v_mad_u64_u32 v[78:79], s[24:25], v88, s78, v[4:5]
	v_mad_u64_u32 v[80:81], s[24:25], v91, s78, v[4:5]
	v_mad_u64_u32 v[84:85], s[24:25], v90, s78, v[4:5]
	s_waitcnt vmcnt(31)
	ds_write_b32 v52, v11
	s_waitcnt vmcnt(30)
	ds_write_b32 v54, v13
	s_waitcnt vmcnt(29)
	ds_write_b32 v56, v92
	s_waitcnt vmcnt(28)
	ds_write_b32 v58, v93
	s_waitcnt vmcnt(27)
	ds_write_b32 v60, v94
	s_waitcnt vmcnt(26)
	ds_write_b32 v62, v95
	s_waitcnt vmcnt(25)
	ds_write_b32 v64, v96
	s_waitcnt vmcnt(24)
	ds_write_b32 v66, v97
	s_waitcnt vmcnt(23)
	ds_write_b32 v68, v98
	s_waitcnt vmcnt(22)
	ds_write_b32 v70, v99
	s_waitcnt vmcnt(21)
	ds_write_b32 v72, v100
	s_waitcnt vmcnt(20)
	ds_write_b32 v74, v101
	s_waitcnt vmcnt(19)
	ds_write_b32 v76, v102
	s_waitcnt vmcnt(18)
	ds_write_b32 v78, v103
	s_waitcnt vmcnt(17)
	ds_write_b32 v80, v104
	s_waitcnt vmcnt(16)
	ds_write_b32 v84, v105
	v_mad_u64_u32 v[130:131], s[24:25], v107, s78, v[4:5]
	v_mad_u64_u32 v[132:133], s[24:25], v106, s78, v[4:5]
	v_mad_u64_u32 v[134:135], s[24:25], v111, s78, v[4:5]
	v_mad_u64_u32 v[136:137], s[24:25], v110, s78, v[4:5]
	v_mad_u64_u32 v[138:139], s[24:25], v113, s78, v[4:5]
	v_mad_u64_u32 v[140:141], s[24:25], v112, s78, v[4:5]
	v_mad_u64_u32 v[142:143], s[24:25], v115, s78, v[4:5]
	v_mad_u64_u32 v[144:145], s[24:25], v114, s78, v[4:5]
	v_mad_u64_u32 v[146:147], s[24:25], v117, s78, v[4:5]
	v_mad_u64_u32 v[148:149], s[24:25], v116, s78, v[4:5]
	v_mad_u64_u32 v[150:151], s[24:25], v119, s78, v[4:5]
	v_mad_u64_u32 v[152:153], s[24:25], v118, s78, v[4:5]
	v_mad_u64_u32 v[154:155], s[24:25], v121, s78, v[4:5]
	v_mad_u64_u32 v[156:157], s[24:25], v120, s78, v[4:5]
	v_mad_u64_u32 v[158:159], s[24:25], v123, s78, v[4:5]
	v_mad_u64_u32 v[160:161], s[24:25], v122, s78, v[4:5]
	s_waitcnt vmcnt(15)
	ds_write_b32 v130, v108
	s_waitcnt vmcnt(14)
	ds_write_b32 v132, v109
	s_waitcnt vmcnt(13)
	ds_write_b32 v134, v124
	s_waitcnt vmcnt(12)
	ds_write_b32 v136, v125
	s_waitcnt vmcnt(11)
	ds_write_b32 v138, v126
	s_waitcnt vmcnt(10)
	ds_write_b32 v140, v127
	s_waitcnt vmcnt(9)
	ds_write_b32 v142, v162
	s_waitcnt vmcnt(8)
	ds_write_b32 v144, v163
	s_waitcnt vmcnt(7)
	ds_write_b32 v146, v164
	s_waitcnt vmcnt(6)
	ds_write_b32 v148, v165
	s_waitcnt vmcnt(5)
	ds_write_b32 v150, v166
	s_waitcnt vmcnt(4)
	ds_write_b32 v152, v167
	s_waitcnt vmcnt(3)
	ds_write_b32 v154, v168
	s_waitcnt vmcnt(2)
	ds_write_b32 v156, v169
	s_waitcnt vmcnt(1)
	ds_write_b32 v158, v170
	s_waitcnt vmcnt(0)
	ds_write_b32 v160, v171
	s_add_i32 s13, s13, 16
	s_add_i32 s5, s5, 16
	s_add_i32 s22, s22, -16
	s_add_i32 s22, s22, -16
	s_cmp_lg_u32 s22, 0
	s_waitcnt lgkmcnt(0)
	ds_read2_b32 v[54:55], v5 offset1:8
	ds_read2_b32 v[58:59], v5 offset0:33 offset1:41
	ds_read2_b32 v[60:61], v5 offset0:66 offset1:74
	ds_read2_b32 v[62:63], v5 offset0:99 offset1:107
	ds_read2_b32 v[64:65], v5 offset0:132 offset1:140
	s_waitcnt lgkmcnt(4)
	v_bfe_u32 v7, v54, 16, 1
	v_add3_u32 v7, v54, v7, s33
	s_waitcnt lgkmcnt(3)
	v_bfe_u32 v9, v58, 16, 1
	v_lshrrev_b32_e32 v7, 16, v7
	v_add3_u32 v9, v58, v9, s33
	ds_read2_b32 v[66:67], v5 offset0:165 offset1:173
	v_and_or_b32 v50, v9, s69, v7
	s_waitcnt lgkmcnt(3)
	v_bfe_u32 v7, v60, 16, 1
	s_add_i32 s4, s14, 0xfffffb00
	v_add3_u32 v7, v60, v7, s33
	s_waitcnt lgkmcnt(2)
	v_bfe_u32 v9, v62, 16, 1
	ds_read2_b32 v[68:69], v5 offset0:198 offset1:206
	s_cmp_lt_i32 s1, 40
	v_lshrrev_b32_e32 v7, 16, v7
	v_add3_u32 v9, v62, v9, s33
	ds_read2_b32 v[70:71], v5 offset0:231 offset1:239
	s_cselect_b32 s5, s15, 0
	s_cselect_b32 s4, s14, s4
	v_and_or_b32 v51, v9, s69, v7
	s_waitcnt lgkmcnt(3)
	v_bfe_u32 v7, v64, 16, 1
	s_cselect_b32 s1, s35, s62
	s_cselect_b32 s13, s38, s63
	s_lshl_b64 s[4:5], s[4:5], 11
	v_add3_u32 v7, v64, v7, s33
	s_waitcnt lgkmcnt(2)
	v_bfe_u32 v9, v66, 16, 1
	s_add_u32 s1, s1, s4
	v_lshrrev_b32_e32 v7, 16, v7
	v_add3_u32 v9, v66, v9, s33
	s_addc_u32 s14, s13, s5
	s_ashr_i32 s13, s12, 31
	v_and_or_b32 v52, v9, s69, v7
	s_waitcnt lgkmcnt(1)
	v_bfe_u32 v7, v68, 16, 1
	s_lshl_b64 s[4:5], s[12:13], 1
	v_add3_u32 v7, v68, v7, s33
	s_waitcnt lgkmcnt(0)
	v_bfe_u32 v9, v70, 16, 1
	s_add_u32 s4, s1, s4
	v_lshrrev_b32_e32 v7, 16, v7
	v_add3_u32 v9, v70, v9, s33
	s_addc_u32 s5, s14, s5
	v_lshlrev_b32_e32 v128, 1, v6
	v_and_or_b32 v53, v9, s69, v7
	v_bfe_u32 v7, v55, 16, 1
	v_lshl_add_u64 v[56:57], s[4:5], 0, v[128:129]
	v_lshlrev_b32_e32 v128, 1, v8
	v_add3_u32 v7, v55, v7, s33
	v_bfe_u32 v9, v59, 16, 1
	v_lshl_add_u64 v[72:73], v[56:57], 0, v[128:129]
	v_lshrrev_b32_e32 v7, 16, v7
	v_add3_u32 v9, v59, v9, s33
	global_store_dwordx4 v[72:73], v[50:53], off
	v_lshlrev_b32_e32 v128, 1, v10
	ds_read2_b32 v[54:55], v5 offset0:16 offset1:24
	v_and_or_b32 v50, v9, s69, v7
	v_bfe_u32 v7, v61, 16, 1
	v_add3_u32 v7, v61, v7, s33
	v_bfe_u32 v9, v63, 16, 1
	v_lshrrev_b32_e32 v7, 16, v7
	v_add3_u32 v9, v63, v9, s33
	v_and_or_b32 v51, v9, s69, v7
	v_bfe_u32 v7, v65, 16, 1
	v_add3_u32 v7, v65, v7, s33
	v_bfe_u32 v9, v67, 16, 1
	v_lshrrev_b32_e32 v7, 16, v7
	v_add3_u32 v9, v67, v9, s33
	v_and_or_b32 v52, v9, s69, v7
	v_bfe_u32 v7, v69, 16, 1
	v_add3_u32 v7, v69, v7, s33
	v_bfe_u32 v9, v71, 16, 1
	v_lshrrev_b32_e32 v7, 16, v7
	v_add3_u32 v9, v71, v9, s33
	v_and_or_b32 v53, v9, s69, v7
	v_lshl_add_u64 v[58:59], v[56:57], 0, v[128:129]
	global_store_dwordx4 v[58:59], v[50:53], off
	ds_read2_b32 v[58:59], v5 offset0:49 offset1:57
	ds_read2_b32 v[60:61], v5 offset0:82 offset1:90
	ds_read2_b32 v[62:63], v5 offset0:115 offset1:123
	s_waitcnt lgkmcnt(3)
	v_bfe_u32 v7, v54, 16, 1
	v_add3_u32 v7, v54, v7, s33
	s_waitcnt lgkmcnt(2)
	v_bfe_u32 v9, v58, 16, 1
	ds_read2_b32 v[64:65], v5 offset0:148 offset1:156
	v_lshrrev_b32_e32 v7, 16, v7
	v_add3_u32 v9, v58, v9, s33
	ds_read2_b32 v[66:67], v5 offset0:181 offset1:189
	v_and_or_b32 v50, v9, s69, v7
	s_waitcnt lgkmcnt(3)
	v_bfe_u32 v7, v60, 16, 1
	v_add3_u32 v7, v60, v7, s33
	s_waitcnt lgkmcnt(2)
	v_bfe_u32 v9, v62, 16, 1
	ds_read2_b32 v[68:69], v5 offset0:214 offset1:222
	v_lshrrev_b32_e32 v7, 16, v7
	v_add3_u32 v9, v62, v9, s33
	ds_read2_b32 v[70:71], v5 offset0:247 offset1:255
	v_and_or_b32 v51, v9, s69, v7
	s_waitcnt lgkmcnt(3)
	v_bfe_u32 v7, v64, 16, 1
	v_add3_u32 v7, v64, v7, s33
	s_waitcnt lgkmcnt(2)
	v_bfe_u32 v9, v66, 16, 1
	v_lshrrev_b32_e32 v7, 16, v7
	v_add3_u32 v9, v66, v9, s33
	v_and_or_b32 v52, v9, s69, v7
	s_waitcnt lgkmcnt(1)
	v_bfe_u32 v7, v68, 16, 1
	v_add3_u32 v7, v68, v7, s33
	s_waitcnt lgkmcnt(0)
	v_bfe_u32 v9, v70, 16, 1
	v_lshrrev_b32_e32 v7, 16, v7
	v_add3_u32 v9, v70, v9, s33
	v_and_or_b32 v53, v9, s69, v7
	v_bfe_u32 v7, v55, 16, 1
	v_lshlrev_b32_e32 v128, 1, v12
	v_add3_u32 v7, v55, v7, s33
	v_bfe_u32 v9, v59, 16, 1
	v_lshl_add_u64 v[72:73], v[56:57], 0, v[128:129]
	v_lshrrev_b32_e32 v7, 16, v7
	v_add3_u32 v9, v59, v9, s33
	global_store_dwordx4 v[72:73], v[50:53], off
	v_lshlrev_b32_e32 v128, 1, v14
	v_lshl_add_u64 v[54:55], v[56:57], 0, v[128:129]
	v_and_or_b32 v50, v9, s69, v7
	v_bfe_u32 v7, v61, 16, 1
	v_add3_u32 v7, v61, v7, s33
	v_bfe_u32 v9, v63, 16, 1
	v_lshrrev_b32_e32 v7, 16, v7
	v_add3_u32 v9, v63, v9, s33
	v_and_or_b32 v51, v9, s69, v7
	v_bfe_u32 v7, v65, 16, 1
	v_add3_u32 v7, v65, v7, s33
	v_bfe_u32 v9, v67, 16, 1
	v_lshrrev_b32_e32 v7, 16, v7
	v_add3_u32 v9, v67, v9, s33
	v_and_or_b32 v52, v9, s69, v7
	v_bfe_u32 v7, v69, 16, 1
	v_add3_u32 v7, v69, v7, s33
	v_bfe_u32 v9, v71, 16, 1
	v_lshrrev_b32_e32 v7, 16, v7
	v_add3_u32 v9, v71, v9, s33
	v_and_or_b32 v53, v9, s69, v7
	global_store_dwordx4 v[54:55], v[50:53], off
	s_waitcnt lgkmcnt(0)
	s_mov_b32 s1, s0
	s_andn2_b64 vcc, exec, s[10:11]
	s_mov_b64 s[10:11], -1
	s_cbranch_vccnz .LBB0_706

.LBB0_704:
	s_lshl_b32 s14, s1, 1
	s_lshl_b32 s15, s5, 1
	v_or_b32_e32 v7, s14, v1
	v_or_b32_e32 v9, s15, v0
	s_add_i32 s22, s14, 4
	s_add_i32 s23, s15, 4
	s_add_i32 s24, s14, 8
	s_add_i32 s25, s15, 8
	s_add_i32 s26, s14, 12
	s_add_i32 s27, s15, 12
	s_add_i32 s30, s14, 16
	s_add_i32 s36, s15, 16
	s_add_i32 s37, s14, 20
	s_add_i32 s40, s15, 20
	s_add_i32 s41, s14, 24
	s_add_i32 s42, s15, 24
	s_add_i32 s14, s14, 28
	s_add_i32 s15, s15, 28
	v_add_u32_e32 v54, s10, v9
	v_or_b32_e32 v11, s22, v1
	v_or_b32_e32 v13, s23, v0
	v_or_b32_e32 v15, s24, v1
	v_or_b32_e32 v19, s25, v0
	v_or_b32_e32 v41, s26, v1
	v_or_b32_e32 v43, s27, v0
	v_or_b32_e32 v45, s30, v1
	v_or_b32_e32 v47, s36, v0
	v_or_b32_e32 v49, s37, v1
	v_or_b32_e32 v82, s40, v0
	v_or_b32_e32 v86, s41, v1
	v_or_b32_e32 v87, s42, v0
	v_or_b32_e32 v88, s14, v1
	v_or_b32_e32 v89, s15, v0
	v_add_u32_e32 v52, s4, v7
	v_ashrrev_i32_e32 v55, 31, v54
	v_add_u32_e32 v56, s4, v11
	v_add_u32_e32 v58, s10, v13
	v_add_u32_e32 v60, s4, v15
	v_add_u32_e32 v62, s10, v19
	v_add_u32_e32 v64, s4, v41
	v_add_u32_e32 v66, s10, v43
	v_add_u32_e32 v68, s4, v45
	v_add_u32_e32 v70, s10, v47
	v_add_u32_e32 v72, s4, v49
	v_add_u32_e32 v74, s10, v82
	v_add_u32_e32 v76, s4, v86
	v_add_u32_e32 v78, s10, v87
	v_add_u32_e32 v80, s4, v88
	v_add_u32_e32 v84, s10, v89
	v_ashrrev_i32_e32 v53, 31, v52
	v_lshlrev_b64 v[54:55], 12, v[54:55]
	v_ashrrev_i32_e32 v59, 31, v58
	v_ashrrev_i32_e32 v57, 31, v56
	v_ashrrev_i32_e32 v63, 31, v62
	v_ashrrev_i32_e32 v61, 31, v60
	v_ashrrev_i32_e32 v67, 31, v66
	v_ashrrev_i32_e32 v65, 31, v64
	v_ashrrev_i32_e32 v71, 31, v70
	v_ashrrev_i32_e32 v69, 31, v68
	v_ashrrev_i32_e32 v75, 31, v74
	v_ashrrev_i32_e32 v73, 31, v72
	v_ashrrev_i32_e32 v79, 31, v78
	v_ashrrev_i32_e32 v77, 31, v76
	v_ashrrev_i32_e32 v85, 31, v84
	v_ashrrev_i32_e32 v81, 31, v80
	v_lshlrev_b64 v[52:53], 12, v[52:53]
	v_lshl_add_u64 v[54:55], v[50:51], 0, v[54:55]
	v_lshlrev_b64 v[56:57], 12, v[56:57]
	v_lshlrev_b64 v[58:59], 12, v[58:59]
	v_lshlrev_b64 v[60:61], 12, v[60:61]
	v_lshlrev_b64 v[62:63], 12, v[62:63]
	v_lshlrev_b64 v[64:65], 12, v[64:65]
	v_lshlrev_b64 v[66:67], 12, v[66:67]
	v_lshlrev_b64 v[68:69], 12, v[68:69]
	v_lshlrev_b64 v[70:71], 12, v[70:71]
	v_lshlrev_b64 v[72:73], 12, v[72:73]
	v_lshlrev_b64 v[74:75], 12, v[74:75]
	v_lshlrev_b64 v[76:77], 12, v[76:77]
	v_lshlrev_b64 v[78:79], 12, v[78:79]
	v_lshlrev_b64 v[80:81], 12, v[80:81]
	v_lshlrev_b64 v[84:85], 12, v[84:85]
	v_lshl_add_u64 v[52:53], v[50:51], 0, v[52:53]
	v_lshl_add_u64 v[58:59], v[50:51], 0, v[58:59]
	v_lshl_add_u64 v[56:57], v[50:51], 0, v[56:57]
	v_lshl_add_u64 v[62:63], v[50:51], 0, v[62:63]
	v_lshl_add_u64 v[60:61], v[50:51], 0, v[60:61]
	v_lshl_add_u64 v[66:67], v[50:51], 0, v[66:67]
	v_lshl_add_u64 v[64:65], v[50:51], 0, v[64:65]
	v_lshl_add_u64 v[70:71], v[50:51], 0, v[70:71]
	v_lshl_add_u64 v[68:69], v[50:51], 0, v[68:69]
	v_lshl_add_u64 v[74:75], v[50:51], 0, v[74:75]
	v_lshl_add_u64 v[72:73], v[50:51], 0, v[72:73]
	v_lshl_add_u64 v[78:79], v[50:51], 0, v[78:79]
	v_lshl_add_u64 v[76:77], v[50:51], 0, v[76:77]
	v_lshl_add_u64 v[84:85], v[50:51], 0, v[84:85]
	v_lshl_add_u64 v[80:81], v[50:51], 0, v[80:81]
	global_load_dword v90, v[54:55], off
	global_load_dword v91, v[52:53], off
	global_load_dword v92, v[58:59], off
	global_load_dword v93, v[56:57], off
	global_load_dword v94, v[62:63], off
	global_load_dword v95, v[60:61], off
	global_load_dword v96, v[66:67], off
	global_load_dword v97, v[64:65], off
	global_load_dword v98, v[70:71], off
	global_load_dword v99, v[68:69], off
	global_load_dword v100, v[74:75], off
	global_load_dword v101, v[72:73], off
	global_load_dword v102, v[78:79], off
	global_load_dword v103, v[76:77], off
	global_load_dword v104, v[84:85], off
	global_load_dword v105, v[80:81], off
	s_add_i32 s5, s5, 16
	s_add_i32 s1, s1, 16
	s_lshl_b32 s14, s1, 1
	s_lshl_b32 s15, s5, 1
	v_or_b32_e32 v106, s14, v1
	v_or_b32_e32 v107, s15, v0
	s_add_i32 s22, s14, 4
	s_add_i32 s23, s15, 4
	s_add_i32 s24, s14, 8
	s_add_i32 s25, s15, 8
	s_add_i32 s26, s14, 12
	s_add_i32 s27, s15, 12
	s_add_i32 s30, s14, 16
	s_add_i32 s36, s15, 16
	s_add_i32 s37, s14, 20
	s_add_i32 s40, s15, 20
	s_add_i32 s41, s14, 24
	s_add_i32 s42, s15, 24
	s_add_i32 s14, s14, 28
	s_add_i32 s15, s15, 28
	v_add_u32_e32 v132, s10, v107
	v_or_b32_e32 v108, s22, v1
	v_or_b32_e32 v109, s23, v0
	v_or_b32_e32 v110, s24, v1
	v_or_b32_e32 v111, s25, v0
	v_or_b32_e32 v112, s26, v1
	v_or_b32_e32 v113, s27, v0
	v_or_b32_e32 v114, s30, v1
	v_or_b32_e32 v115, s36, v0
	v_or_b32_e32 v116, s37, v1
	v_or_b32_e32 v117, s40, v0
	v_or_b32_e32 v118, s41, v1
	v_or_b32_e32 v119, s42, v0
	v_or_b32_e32 v120, s14, v1
	v_or_b32_e32 v121, s15, v0
	v_add_u32_e32 v130, s4, v106
	v_ashrrev_i32_e32 v133, 31, v132
	v_add_u32_e32 v134, s4, v108
	v_add_u32_e32 v136, s10, v109
	v_add_u32_e32 v138, s4, v110
	v_add_u32_e32 v140, s10, v111
	v_add_u32_e32 v142, s4, v112
	v_add_u32_e32 v144, s10, v113
	v_add_u32_e32 v146, s4, v114
	v_add_u32_e32 v148, s10, v115
	v_add_u32_e32 v150, s4, v116
	v_add_u32_e32 v152, s10, v117
	v_add_u32_e32 v154, s4, v118
	v_add_u32_e32 v156, s10, v119
	v_add_u32_e32 v158, s4, v120
	v_add_u32_e32 v160, s10, v121
	v_ashrrev_i32_e32 v131, 31, v130
	v_lshlrev_b64 v[132:133], 12, v[132:133]
	v_ashrrev_i32_e32 v137, 31, v136
	v_ashrrev_i32_e32 v135, 31, v134
	v_ashrrev_i32_e32 v141, 31, v140
	v_ashrrev_i32_e32 v139, 31, v138
	v_ashrrev_i32_e32 v145, 31, v144
	v_ashrrev_i32_e32 v143, 31, v142
	v_ashrrev_i32_e32 v149, 31, v148
	v_ashrrev_i32_e32 v147, 31, v146
	v_ashrrev_i32_e32 v153, 31, v152
	v_ashrrev_i32_e32 v151, 31, v150
	v_ashrrev_i32_e32 v157, 31, v156
	v_ashrrev_i32_e32 v155, 31, v154
	v_ashrrev_i32_e32 v161, 31, v160
	v_ashrrev_i32_e32 v159, 31, v158
	v_lshlrev_b64 v[130:131], 12, v[130:131]
	v_lshl_add_u64 v[132:133], v[50:51], 0, v[132:133]
	v_lshlrev_b64 v[134:135], 12, v[134:135]
	v_lshlrev_b64 v[136:137], 12, v[136:137]
	v_lshlrev_b64 v[138:139], 12, v[138:139]
	v_lshlrev_b64 v[140:141], 12, v[140:141]
	v_lshlrev_b64 v[142:143], 12, v[142:143]
	v_lshlrev_b64 v[144:145], 12, v[144:145]
	v_lshlrev_b64 v[146:147], 12, v[146:147]
	v_lshlrev_b64 v[148:149], 12, v[148:149]
	v_lshlrev_b64 v[150:151], 12, v[150:151]
	v_lshlrev_b64 v[152:153], 12, v[152:153]
	v_lshlrev_b64 v[154:155], 12, v[154:155]
	v_lshlrev_b64 v[156:157], 12, v[156:157]
	v_lshlrev_b64 v[158:159], 12, v[158:159]
	v_lshlrev_b64 v[160:161], 12, v[160:161]
	v_lshl_add_u64 v[130:131], v[50:51], 0, v[130:131]
	v_lshl_add_u64 v[136:137], v[50:51], 0, v[136:137]
	v_lshl_add_u64 v[134:135], v[50:51], 0, v[134:135]
	v_lshl_add_u64 v[140:141], v[50:51], 0, v[140:141]
	v_lshl_add_u64 v[138:139], v[50:51], 0, v[138:139]
	v_lshl_add_u64 v[144:145], v[50:51], 0, v[144:145]
	v_lshl_add_u64 v[142:143], v[50:51], 0, v[142:143]
	v_lshl_add_u64 v[148:149], v[50:51], 0, v[148:149]
	v_lshl_add_u64 v[146:147], v[50:51], 0, v[146:147]
	v_lshl_add_u64 v[152:153], v[50:51], 0, v[152:153]
	v_lshl_add_u64 v[150:151], v[50:51], 0, v[150:151]
	v_lshl_add_u64 v[156:157], v[50:51], 0, v[156:157]
	v_lshl_add_u64 v[154:155], v[50:51], 0, v[154:155]
	v_lshl_add_u64 v[160:161], v[50:51], 0, v[160:161]
	v_lshl_add_u64 v[158:159], v[50:51], 0, v[158:159]
	global_load_dword v122, v[132:133], off
	global_load_dword v123, v[130:131], off
	global_load_dword v124, v[136:137], off
	global_load_dword v125, v[134:135], off
	global_load_dword v126, v[140:141], off
	global_load_dword v127, v[138:139], off
	global_load_dword v162, v[144:145], off
	global_load_dword v163, v[142:143], off
	global_load_dword v164, v[148:149], off
	global_load_dword v165, v[146:147], off
	global_load_dword v166, v[152:153], off
	global_load_dword v167, v[150:151], off
	global_load_dword v168, v[156:157], off
	global_load_dword v169, v[154:155], off
	global_load_dword v170, v[160:161], off
	global_load_dword v171, v[158:159], off
	v_mad_u64_u32 v[52:53], s[14:15], v9, s78, v[4:5]
	v_mad_u64_u32 v[54:55], s[14:15], v7, s78, v[4:5]
	v_mad_u64_u32 v[56:57], s[14:15], v13, s78, v[4:5]
	v_mad_u64_u32 v[58:59], s[14:15], v11, s78, v[4:5]
	v_mad_u64_u32 v[60:61], s[14:15], v19, s78, v[4:5]
	v_mad_u64_u32 v[62:63], s[14:15], v15, s78, v[4:5]
	v_mad_u64_u32 v[64:65], s[14:15], v43, s78, v[4:5]
	v_mad_u64_u32 v[66:67], s[14:15], v41, s78, v[4:5]
	v_mad_u64_u32 v[68:69], s[14:15], v47, s78, v[4:5]
	v_mad_u64_u32 v[70:71], s[14:15], v45, s78, v[4:5]
	v_mad_u64_u32 v[72:73], s[14:15], v82, s78, v[4:5]
	v_mad_u64_u32 v[74:75], s[14:15], v49, s78, v[4:5]
	v_mad_u64_u32 v[76:77], s[14:15], v87, s78, v[4:5]
	v_mad_u64_u32 v[78:79], s[14:15], v86, s78, v[4:5]
	v_mad_u64_u32 v[80:81], s[14:15], v89, s78, v[4:5]
	v_mad_u64_u32 v[84:85], s[14:15], v88, s78, v[4:5]
	s_waitcnt vmcnt(31)
	ds_write_b32 v52, v90
	s_waitcnt vmcnt(30)
	ds_write_b32 v54, v91
	s_waitcnt vmcnt(29)
	ds_write_b32 v56, v92
	s_waitcnt vmcnt(28)
	ds_write_b32 v58, v93
	s_waitcnt vmcnt(27)
	ds_write_b32 v60, v94
	s_waitcnt vmcnt(26)
	ds_write_b32 v62, v95
	s_waitcnt vmcnt(25)
	ds_write_b32 v64, v96
	s_waitcnt vmcnt(24)
	ds_write_b32 v66, v97
	s_waitcnt vmcnt(23)
	ds_write_b32 v68, v98
	s_waitcnt vmcnt(22)
	ds_write_b32 v70, v99
	s_waitcnt vmcnt(21)
	ds_write_b32 v72, v100
	s_waitcnt vmcnt(20)
	ds_write_b32 v74, v101
	s_waitcnt vmcnt(19)
	ds_write_b32 v76, v102
	s_waitcnt vmcnt(18)
	ds_write_b32 v78, v103
	s_waitcnt vmcnt(17)
	ds_write_b32 v80, v104
	s_waitcnt vmcnt(16)
	ds_write_b32 v84, v105
	v_mad_u64_u32 v[130:131], s[14:15], v107, s78, v[4:5]
	v_mad_u64_u32 v[132:133], s[14:15], v106, s78, v[4:5]
	v_mad_u64_u32 v[134:135], s[14:15], v109, s78, v[4:5]
	v_mad_u64_u32 v[136:137], s[14:15], v108, s78, v[4:5]
	v_mad_u64_u32 v[138:139], s[14:15], v111, s78, v[4:5]
	v_mad_u64_u32 v[140:141], s[14:15], v110, s78, v[4:5]
	v_mad_u64_u32 v[142:143], s[14:15], v113, s78, v[4:5]
	v_mad_u64_u32 v[144:145], s[14:15], v112, s78, v[4:5]
	v_mad_u64_u32 v[146:147], s[14:15], v115, s78, v[4:5]
	v_mad_u64_u32 v[148:149], s[14:15], v114, s78, v[4:5]
	v_mad_u64_u32 v[150:151], s[14:15], v117, s78, v[4:5]
	v_mad_u64_u32 v[152:153], s[14:15], v116, s78, v[4:5]
	v_mad_u64_u32 v[154:155], s[14:15], v119, s78, v[4:5]
	v_mad_u64_u32 v[156:157], s[14:15], v118, s78, v[4:5]
	v_mad_u64_u32 v[158:159], s[14:15], v121, s78, v[4:5]
	v_mad_u64_u32 v[160:161], s[14:15], v120, s78, v[4:5]
	s_waitcnt vmcnt(15)
	ds_write_b32 v130, v122
	s_waitcnt vmcnt(14)
	ds_write_b32 v132, v123
	s_waitcnt vmcnt(13)
	ds_write_b32 v134, v124
	s_waitcnt vmcnt(12)
	ds_write_b32 v136, v125
	s_waitcnt vmcnt(11)
	ds_write_b32 v138, v126
	s_waitcnt vmcnt(10)
	ds_write_b32 v140, v127
	s_waitcnt vmcnt(9)
	ds_write_b32 v142, v162
	s_waitcnt vmcnt(8)
	ds_write_b32 v144, v163
	s_waitcnt vmcnt(7)
	ds_write_b32 v146, v164
	s_waitcnt vmcnt(6)
	ds_write_b32 v148, v165
	s_waitcnt vmcnt(5)
	ds_write_b32 v150, v166
	s_waitcnt vmcnt(4)
	ds_write_b32 v152, v167
	s_waitcnt vmcnt(3)
	ds_write_b32 v154, v168
	s_waitcnt vmcnt(2)
	ds_write_b32 v156, v169
	s_waitcnt vmcnt(1)
	ds_write_b32 v158, v170
	s_waitcnt vmcnt(0)
	ds_write_b32 v160, v171
	s_add_i32 s5, s5, 16
	s_add_i32 s1, s1, 16
	s_add_i32 s11, s11, -16
	s_add_i32 s11, s11, -16
	s_cmp_lg_u32 s11, 0
	s_waitcnt lgkmcnt(0)
	ds_read2_b32 v[54:55], v5 offset1:8
	ds_read2_b32 v[58:59], v5 offset0:33 offset1:41
	ds_read2_b32 v[60:61], v5 offset0:66 offset1:74
	ds_read2_b32 v[62:63], v5 offset0:99 offset1:107
	ds_read2_b32 v[64:65], v5 offset0:132 offset1:140
	s_waitcnt lgkmcnt(4)
	v_bfe_u32 v7, v54, 16, 1
	v_add3_u32 v7, v54, v7, s33
	s_waitcnt lgkmcnt(3)
	v_bfe_u32 v9, v58, 16, 1
	v_lshrrev_b32_e32 v7, 16, v7
	v_add3_u32 v9, v58, v9, s33
	ds_read2_b32 v[66:67], v5 offset0:165 offset1:173
	v_and_or_b32 v50, v9, s69, v7
	s_waitcnt lgkmcnt(3)
	v_bfe_u32 v7, v60, 16, 1
	v_add3_u32 v7, v60, v7, s33
	s_waitcnt lgkmcnt(2)
	v_bfe_u32 v9, v62, 16, 1
	ds_read2_b32 v[68:69], v5 offset0:198 offset1:206
	v_lshrrev_b32_e32 v7, 16, v7
	v_add3_u32 v9, v62, v9, s33
	ds_read2_b32 v[70:71], v5 offset0:231 offset1:239
	v_and_or_b32 v51, v9, s69, v7
	s_waitcnt lgkmcnt(3)
	v_bfe_u32 v7, v64, 16, 1
	s_lshl_b64 s[4:5], s[12:13], 11
	v_add3_u32 v7, v64, v7, s33
	s_waitcnt lgkmcnt(2)
	v_bfe_u32 v9, v66, 16, 1
	s_add_u32 s1, s64, s4
	v_lshrrev_b32_e32 v7, 16, v7
	v_add3_u32 v9, v66, v9, s33
	s_addc_u32 s12, s65, s5
	s_ashr_i32 s11, s10, 31
	v_and_or_b32 v52, v9, s69, v7
	s_waitcnt lgkmcnt(1)
	v_bfe_u32 v7, v68, 16, 1
	s_lshl_b64 s[4:5], s[10:11], 1
	v_add3_u32 v7, v68, v7, s33
	s_waitcnt lgkmcnt(0)
	v_bfe_u32 v9, v70, 16, 1
	s_add_u32 s4, s1, s4
	v_lshrrev_b32_e32 v7, 16, v7
	v_add3_u32 v9, v70, v9, s33
	s_addc_u32 s5, s12, s5
	v_lshlrev_b32_e32 v128, 1, v6
	v_and_or_b32 v53, v9, s69, v7
	v_bfe_u32 v7, v55, 16, 1
	v_lshl_add_u64 v[56:57], s[4:5], 0, v[128:129]
	v_lshlrev_b32_e32 v128, 1, v8
	v_add3_u32 v7, v55, v7, s33
	v_bfe_u32 v9, v59, 16, 1
	v_lshl_add_u64 v[72:73], v[56:57], 0, v[128:129]
	v_lshrrev_b32_e32 v7, 16, v7
	v_add3_u32 v9, v59, v9, s33
	global_store_dwordx4 v[72:73], v[50:53], off
	v_lshlrev_b32_e32 v128, 1, v10
	ds_read2_b32 v[54:55], v5 offset0:16 offset1:24
	v_and_or_b32 v50, v9, s69, v7
	v_bfe_u32 v7, v61, 16, 1
	v_add3_u32 v7, v61, v7, s33
	v_bfe_u32 v9, v63, 16, 1
	v_lshrrev_b32_e32 v7, 16, v7
	v_add3_u32 v9, v63, v9, s33
	v_and_or_b32 v51, v9, s69, v7
	v_bfe_u32 v7, v65, 16, 1
	v_add3_u32 v7, v65, v7, s33
	v_bfe_u32 v9, v67, 16, 1
	v_lshrrev_b32_e32 v7, 16, v7
	v_add3_u32 v9, v67, v9, s33
	v_and_or_b32 v52, v9, s69, v7
	v_bfe_u32 v7, v69, 16, 1
	v_add3_u32 v7, v69, v7, s33
	v_bfe_u32 v9, v71, 16, 1
	v_lshrrev_b32_e32 v7, 16, v7
	v_add3_u32 v9, v71, v9, s33
	v_and_or_b32 v53, v9, s69, v7
	v_lshl_add_u64 v[58:59], v[56:57], 0, v[128:129]
	global_store_dwordx4 v[58:59], v[50:53], off
	ds_read2_b32 v[58:59], v5 offset0:49 offset1:57
	ds_read2_b32 v[60:61], v5 offset0:82 offset1:90
	ds_read2_b32 v[62:63], v5 offset0:115 offset1:123
	s_waitcnt lgkmcnt(3)
	v_bfe_u32 v7, v54, 16, 1
	v_add3_u32 v7, v54, v7, s33
	s_waitcnt lgkmcnt(2)
	v_bfe_u32 v9, v58, 16, 1
	ds_read2_b32 v[64:65], v5 offset0:148 offset1:156
	v_lshrrev_b32_e32 v7, 16, v7
	v_add3_u32 v9, v58, v9, s33
	ds_read2_b32 v[66:67], v5 offset0:181 offset1:189
	v_and_or_b32 v50, v9, s69, v7
	s_waitcnt lgkmcnt(3)
	v_bfe_u32 v7, v60, 16, 1
	v_add3_u32 v7, v60, v7, s33
	s_waitcnt lgkmcnt(2)
	v_bfe_u32 v9, v62, 16, 1
	ds_read2_b32 v[68:69], v5 offset0:214 offset1:222
	v_lshrrev_b32_e32 v7, 16, v7
	v_add3_u32 v9, v62, v9, s33
	ds_read2_b32 v[70:71], v5 offset0:247 offset1:255
	v_and_or_b32 v51, v9, s69, v7
	s_waitcnt lgkmcnt(3)
	v_bfe_u32 v7, v64, 16, 1
	v_add3_u32 v7, v64, v7, s33
	s_waitcnt lgkmcnt(2)
	v_bfe_u32 v9, v66, 16, 1
	v_lshrrev_b32_e32 v7, 16, v7
	v_add3_u32 v9, v66, v9, s33
	v_and_or_b32 v52, v9, s69, v7
	s_waitcnt lgkmcnt(1)
	v_bfe_u32 v7, v68, 16, 1
	v_add3_u32 v7, v68, v7, s33
	s_waitcnt lgkmcnt(0)
	v_bfe_u32 v9, v70, 16, 1
	v_lshrrev_b32_e32 v7, 16, v7
	v_add3_u32 v9, v70, v9, s33
	v_and_or_b32 v53, v9, s69, v7
	v_bfe_u32 v7, v55, 16, 1
	v_lshlrev_b32_e32 v128, 1, v12
	v_add3_u32 v7, v55, v7, s33
	v_bfe_u32 v9, v59, 16, 1
	v_lshl_add_u64 v[72:73], v[56:57], 0, v[128:129]
	v_lshrrev_b32_e32 v7, 16, v7
	v_add3_u32 v9, v59, v9, s33
	global_store_dwordx4 v[72:73], v[50:53], off
	v_lshlrev_b32_e32 v128, 1, v14
	v_lshl_add_u64 v[54:55], v[56:57], 0, v[128:129]
	v_and_or_b32 v50, v9, s69, v7
	v_bfe_u32 v7, v61, 16, 1
	v_add3_u32 v7, v61, v7, s33
	v_bfe_u32 v9, v63, 16, 1
	v_lshrrev_b32_e32 v7, 16, v7
	v_add3_u32 v9, v63, v9, s33
	v_and_or_b32 v51, v9, s69, v7
	v_bfe_u32 v7, v65, 16, 1
	v_add3_u32 v7, v65, v7, s33
	v_bfe_u32 v9, v67, 16, 1
	v_lshrrev_b32_e32 v7, 16, v7
	v_add3_u32 v9, v67, v9, s33
	v_and_or_b32 v52, v9, s69, v7
	v_bfe_u32 v7, v69, 16, 1
	v_add3_u32 v7, v69, v7, s33
	v_bfe_u32 v9, v71, 16, 1
	v_lshrrev_b32_e32 v7, 16, v7
	v_add3_u32 v9, v71, v9, s33
	v_and_or_b32 v53, v9, s69, v7
	global_store_dwordx4 v[54:55], v[50:53], off
	s_waitcnt lgkmcnt(0)
	s_mov_b64 s[10:11], -1

.LBB0_712:
	s_lshl_b32 s23, s5, 1
	s_lshl_b32 s24, s13, 1
	v_or_b32_e32 v7, s23, v1
	v_or_b32_e32 v9, s24, v0
	s_add_i32 s25, s23, 4
	s_add_i32 s26, s24, 4
	s_add_i32 s27, s23, 8
	s_add_i32 s30, s24, 8
	s_add_i32 s36, s23, 12
	s_add_i32 s37, s24, 12
	s_add_i32 s40, s23, 16
	s_add_i32 s41, s24, 16
	s_add_i32 s42, s23, 20
	s_add_i32 s43, s24, 20
	s_add_i32 s52, s23, 24
	s_add_i32 s53, s24, 24
	s_add_i32 s23, s23, 28
	s_add_i32 s24, s24, 28
	v_add_u32_e32 v11, s4, v7
	v_add_u32_e32 v13, s12, v9
	v_or_b32_e32 v15, s25, v1
	v_or_b32_e32 v19, s26, v0
	v_or_b32_e32 v41, s27, v1
	v_or_b32_e32 v43, s30, v0
	v_or_b32_e32 v45, s36, v1
	v_or_b32_e32 v47, s37, v0
	v_or_b32_e32 v49, s40, v1
	v_or_b32_e32 v82, s41, v0
	v_or_b32_e32 v86, s42, v1
	v_or_b32_e32 v87, s43, v0
	v_or_b32_e32 v88, s52, v1
	v_or_b32_e32 v89, s53, v0
	v_or_b32_e32 v90, s23, v1
	v_or_b32_e32 v91, s24, v0
	v_mad_i64_i32 v[52:53], s[24:25], v13, s55, v[50:51]
	v_mad_i64_i32 v[54:55], s[24:25], v11, s55, v[50:51]
	v_add_u32_e32 v11, s4, v15
	v_add_u32_e32 v13, s12, v19
	v_add_u32_e32 v62, s4, v41
	v_add_u32_e32 v60, s12, v43
	v_add_u32_e32 v66, s4, v45
	v_add_u32_e32 v64, s12, v47
	v_add_u32_e32 v70, s4, v49
	v_add_u32_e32 v68, s12, v82
	v_add_u32_e32 v74, s4, v86
	v_add_u32_e32 v72, s12, v87
	v_add_u32_e32 v78, s4, v88
	v_add_u32_e32 v76, s12, v89
	v_add_u32_e32 v84, s4, v90
	v_add_u32_e32 v80, s12, v91
	v_mad_i64_i32 v[56:57], s[24:25], v13, s55, v[50:51]
	v_mad_i64_i32 v[58:59], s[24:25], v11, s55, v[50:51]
	v_mad_i64_i32 v[60:61], s[24:25], v60, s55, v[50:51]
	v_mad_i64_i32 v[62:63], s[24:25], v62, s55, v[50:51]
	v_mad_i64_i32 v[64:65], s[24:25], v64, s55, v[50:51]
	v_mad_i64_i32 v[66:67], s[24:25], v66, s55, v[50:51]
	v_mad_i64_i32 v[68:69], s[24:25], v68, s55, v[50:51]
	v_mad_i64_i32 v[70:71], s[24:25], v70, s55, v[50:51]
	v_mad_i64_i32 v[72:73], s[24:25], v72, s55, v[50:51]
	v_mad_i64_i32 v[74:75], s[24:25], v74, s55, v[50:51]
	v_mad_i64_i32 v[76:77], s[24:25], v76, s55, v[50:51]
	v_mad_i64_i32 v[78:79], s[24:25], v78, s55, v[50:51]
	v_mad_i64_i32 v[80:81], s[24:25], v80, s55, v[50:51]
	v_mad_i64_i32 v[84:85], s[24:25], v84, s55, v[50:51]
	global_load_dword v11, v[52:53], off
	global_load_dword v13, v[54:55], off
	global_load_dword v92, v[56:57], off
	global_load_dword v93, v[58:59], off
	global_load_dword v94, v[60:61], off
	global_load_dword v95, v[62:63], off
	global_load_dword v96, v[64:65], off
	global_load_dword v97, v[66:67], off
	global_load_dword v98, v[68:69], off
	global_load_dword v99, v[70:71], off
	global_load_dword v100, v[72:73], off
	global_load_dword v101, v[74:75], off
	global_load_dword v102, v[76:77], off
	global_load_dword v103, v[78:79], off
	global_load_dword v104, v[80:81], off
	global_load_dword v105, v[84:85], off
	s_add_i32 s13, s13, 16
	s_add_i32 s5, s5, 16
	s_lshl_b32 s23, s5, 1
	s_lshl_b32 s24, s13, 1
	v_or_b32_e32 v106, s23, v1
	v_or_b32_e32 v107, s24, v0
	s_add_i32 s25, s23, 4
	s_add_i32 s26, s24, 4
	s_add_i32 s27, s23, 8
	s_add_i32 s30, s24, 8
	s_add_i32 s36, s23, 12
	s_add_i32 s37, s24, 12
	s_add_i32 s40, s23, 16
	s_add_i32 s41, s24, 16
	s_add_i32 s42, s23, 20
	s_add_i32 s43, s24, 20
	s_add_i32 s52, s23, 24
	s_add_i32 s53, s24, 24
	s_add_i32 s23, s23, 28
	s_add_i32 s24, s24, 28
	v_add_u32_e32 v108, s4, v106
	v_add_u32_e32 v109, s12, v107
	v_or_b32_e32 v110, s25, v1
	v_or_b32_e32 v111, s26, v0
	v_or_b32_e32 v112, s27, v1
	v_or_b32_e32 v113, s30, v0
	v_or_b32_e32 v114, s36, v1
	v_or_b32_e32 v115, s37, v0
	v_or_b32_e32 v116, s40, v1
	v_or_b32_e32 v117, s41, v0
	v_or_b32_e32 v118, s42, v1
	v_or_b32_e32 v119, s43, v0
	v_or_b32_e32 v120, s52, v1
	v_or_b32_e32 v121, s53, v0
	v_or_b32_e32 v122, s23, v1
	v_or_b32_e32 v123, s24, v0
	v_mad_i64_i32 v[130:131], s[24:25], v109, s55, v[50:51]
	v_mad_i64_i32 v[132:133], s[24:25], v108, s55, v[50:51]
	v_add_u32_e32 v108, s4, v110
	v_add_u32_e32 v109, s12, v111
	v_add_u32_e32 v140, s4, v112
	v_add_u32_e32 v138, s12, v113
	v_add_u32_e32 v144, s4, v114
	v_add_u32_e32 v142, s12, v115
	v_add_u32_e32 v148, s4, v116
	v_add_u32_e32 v146, s12, v117
	v_add_u32_e32 v152, s4, v118
	v_add_u32_e32 v150, s12, v119
	v_add_u32_e32 v156, s4, v120
	v_add_u32_e32 v154, s12, v121
	v_add_u32_e32 v160, s4, v122
	v_add_u32_e32 v158, s12, v123
	v_mad_i64_i32 v[134:135], s[24:25], v109, s55, v[50:51]
	v_mad_i64_i32 v[136:137], s[24:25], v108, s55, v[50:51]
	v_mad_i64_i32 v[138:139], s[24:25], v138, s55, v[50:51]
	v_mad_i64_i32 v[140:141], s[24:25], v140, s55, v[50:51]
	v_mad_i64_i32 v[142:143], s[24:25], v142, s55, v[50:51]
	v_mad_i64_i32 v[144:145], s[24:25], v144, s55, v[50:51]
	v_mad_i64_i32 v[146:147], s[24:25], v146, s55, v[50:51]
	v_mad_i64_i32 v[148:149], s[24:25], v148, s55, v[50:51]
	v_mad_i64_i32 v[150:151], s[24:25], v150, s55, v[50:51]
	v_mad_i64_i32 v[152:153], s[24:25], v152, s55, v[50:51]
	v_mad_i64_i32 v[154:155], s[24:25], v154, s55, v[50:51]
	v_mad_i64_i32 v[156:157], s[24:25], v156, s55, v[50:51]
	v_mad_i64_i32 v[158:159], s[24:25], v158, s55, v[50:51]
	v_mad_i64_i32 v[160:161], s[24:25], v160, s55, v[50:51]
	global_load_dword v108, v[130:131], off
	global_load_dword v109, v[132:133], off
	global_load_dword v124, v[134:135], off
	global_load_dword v125, v[136:137], off
	global_load_dword v126, v[138:139], off
	global_load_dword v127, v[140:141], off
	global_load_dword v162, v[142:143], off
	global_load_dword v163, v[144:145], off
	global_load_dword v164, v[146:147], off
	global_load_dword v165, v[148:149], off
	global_load_dword v166, v[150:151], off
	global_load_dword v167, v[152:153], off
	global_load_dword v168, v[154:155], off
	global_load_dword v169, v[156:157], off
	global_load_dword v170, v[158:159], off
	global_load_dword v171, v[160:161], off
	v_mad_u64_u32 v[52:53], s[24:25], v9, s78, v[4:5]
	v_mad_u64_u32 v[54:55], s[24:25], v7, s78, v[4:5]
	v_mad_u64_u32 v[56:57], s[24:25], v19, s78, v[4:5]
	v_mad_u64_u32 v[58:59], s[24:25], v15, s78, v[4:5]
	v_mad_u64_u32 v[60:61], s[24:25], v43, s78, v[4:5]
	v_mad_u64_u32 v[62:63], s[24:25], v41, s78, v[4:5]
	v_mad_u64_u32 v[64:65], s[24:25], v47, s78, v[4:5]
	v_mad_u64_u32 v[66:67], s[24:25], v45, s78, v[4:5]
	v_mad_u64_u32 v[68:69], s[24:25], v82, s78, v[4:5]
	v_mad_u64_u32 v[70:71], s[24:25], v49, s78, v[4:5]
	v_mad_u64_u32 v[72:73], s[24:25], v87, s78, v[4:5]
	v_mad_u64_u32 v[74:75], s[24:25], v86, s78, v[4:5]
	v_mad_u64_u32 v[76:77], s[24:25], v89, s78, v[4:5]
	v_mad_u64_u32 v[78:79], s[24:25], v88, s78, v[4:5]
	v_mad_u64_u32 v[80:81], s[24:25], v91, s78, v[4:5]
	v_mad_u64_u32 v[84:85], s[24:25], v90, s78, v[4:5]
	s_waitcnt vmcnt(31)
	ds_write_b32 v52, v11
	s_waitcnt vmcnt(30)
	ds_write_b32 v54, v13
	s_waitcnt vmcnt(29)
	ds_write_b32 v56, v92
	s_waitcnt vmcnt(28)
	ds_write_b32 v58, v93
	s_waitcnt vmcnt(27)
	ds_write_b32 v60, v94
	s_waitcnt vmcnt(26)
	ds_write_b32 v62, v95
	s_waitcnt vmcnt(25)
	ds_write_b32 v64, v96
	s_waitcnt vmcnt(24)
	ds_write_b32 v66, v97
	s_waitcnt vmcnt(23)
	ds_write_b32 v68, v98
	s_waitcnt vmcnt(22)
	ds_write_b32 v70, v99
	s_waitcnt vmcnt(21)
	ds_write_b32 v72, v100
	s_waitcnt vmcnt(20)
	ds_write_b32 v74, v101
	s_waitcnt vmcnt(19)
	ds_write_b32 v76, v102
	s_waitcnt vmcnt(18)
	ds_write_b32 v78, v103
	s_waitcnt vmcnt(17)
	ds_write_b32 v80, v104
	s_waitcnt vmcnt(16)
	ds_write_b32 v84, v105
	v_mad_u64_u32 v[130:131], s[24:25], v107, s78, v[4:5]
	v_mad_u64_u32 v[132:133], s[24:25], v106, s78, v[4:5]
	v_mad_u64_u32 v[134:135], s[24:25], v111, s78, v[4:5]
	v_mad_u64_u32 v[136:137], s[24:25], v110, s78, v[4:5]
	v_mad_u64_u32 v[138:139], s[24:25], v113, s78, v[4:5]
	v_mad_u64_u32 v[140:141], s[24:25], v112, s78, v[4:5]
	v_mad_u64_u32 v[142:143], s[24:25], v115, s78, v[4:5]
	v_mad_u64_u32 v[144:145], s[24:25], v114, s78, v[4:5]
	v_mad_u64_u32 v[146:147], s[24:25], v117, s78, v[4:5]
	v_mad_u64_u32 v[148:149], s[24:25], v116, s78, v[4:5]
	v_mad_u64_u32 v[150:151], s[24:25], v119, s78, v[4:5]
	v_mad_u64_u32 v[152:153], s[24:25], v118, s78, v[4:5]
	v_mad_u64_u32 v[154:155], s[24:25], v121, s78, v[4:5]
	v_mad_u64_u32 v[156:157], s[24:25], v120, s78, v[4:5]
	v_mad_u64_u32 v[158:159], s[24:25], v123, s78, v[4:5]
	v_mad_u64_u32 v[160:161], s[24:25], v122, s78, v[4:5]
	s_waitcnt vmcnt(15)
	ds_write_b32 v130, v108
	s_waitcnt vmcnt(14)
	ds_write_b32 v132, v109
	s_waitcnt vmcnt(13)
	ds_write_b32 v134, v124
	s_waitcnt vmcnt(12)
	ds_write_b32 v136, v125
	s_waitcnt vmcnt(11)
	ds_write_b32 v138, v126
	s_waitcnt vmcnt(10)
	ds_write_b32 v140, v127
	s_waitcnt vmcnt(9)
	ds_write_b32 v142, v162
	s_waitcnt vmcnt(8)
	ds_write_b32 v144, v163
	s_waitcnt vmcnt(7)
	ds_write_b32 v146, v164
	s_waitcnt vmcnt(6)
	ds_write_b32 v148, v165
	s_waitcnt vmcnt(5)
	ds_write_b32 v150, v166
	s_waitcnt vmcnt(4)
	ds_write_b32 v152, v167
	s_waitcnt vmcnt(3)
	ds_write_b32 v154, v168
	s_waitcnt vmcnt(2)
	ds_write_b32 v156, v169
	s_waitcnt vmcnt(1)
	ds_write_b32 v158, v170
	s_waitcnt vmcnt(0)
	ds_write_b32 v160, v171
	s_add_i32 s13, s13, 16
	s_add_i32 s5, s5, 16
	s_add_i32 s22, s22, -16
	s_add_i32 s22, s22, -16
	s_cmp_lg_u32 s22, 0
	s_waitcnt lgkmcnt(0)
	ds_read2_b32 v[54:55], v5 offset1:8
	ds_read2_b32 v[58:59], v5 offset0:33 offset1:41
	ds_read2_b32 v[60:61], v5 offset0:66 offset1:74
	ds_read2_b32 v[62:63], v5 offset0:99 offset1:107
	ds_read2_b32 v[64:65], v5 offset0:132 offset1:140
	s_waitcnt lgkmcnt(4)
	v_bfe_u32 v7, v54, 16, 1
	v_add3_u32 v7, v54, v7, s33
	s_waitcnt lgkmcnt(3)
	v_bfe_u32 v9, v58, 16, 1
	v_lshrrev_b32_e32 v7, 16, v7
	v_add3_u32 v9, v58, v9, s33
	ds_read2_b32 v[66:67], v5 offset0:165 offset1:173
	v_and_or_b32 v50, v9, s69, v7
	s_waitcnt lgkmcnt(3)
	v_bfe_u32 v7, v60, 16, 1
	s_add_i32 s4, s14, 0xfffff800
	v_add3_u32 v7, v60, v7, s33
	s_waitcnt lgkmcnt(2)
	v_bfe_u32 v9, v62, 16, 1
	ds_read2_b32 v[68:69], v5 offset0:198 offset1:206
	s_cmp_lt_i32 s1, 64
	v_lshrrev_b32_e32 v7, 16, v7
	v_add3_u32 v9, v62, v9, s33
	ds_read2_b32 v[70:71], v5 offset0:231 offset1:239
	s_cselect_b32 s5, s15, 0
	s_cselect_b32 s4, s14, s4
	v_and_or_b32 v51, v9, s69, v7
	s_waitcnt lgkmcnt(3)
	v_bfe_u32 v7, v64, 16, 1
	s_cselect_b32 s1, s35, s45
	s_cselect_b32 s13, s38, s46
	s_lshl_b64 s[4:5], s[4:5], 11
	v_add3_u32 v7, v64, v7, s33
	s_waitcnt lgkmcnt(2)
	v_bfe_u32 v9, v66, 16, 1
	s_add_u32 s1, s1, s4
	v_lshrrev_b32_e32 v7, 16, v7
	v_add3_u32 v9, v66, v9, s33
	s_addc_u32 s14, s13, s5
	s_ashr_i32 s13, s12, 31
	v_and_or_b32 v52, v9, s69, v7
	s_waitcnt lgkmcnt(1)
	v_bfe_u32 v7, v68, 16, 1
	s_lshl_b64 s[4:5], s[12:13], 1
	v_add3_u32 v7, v68, v7, s33
	s_waitcnt lgkmcnt(0)
	v_bfe_u32 v9, v70, 16, 1
	s_add_u32 s4, s1, s4
	v_lshrrev_b32_e32 v7, 16, v7
	v_add3_u32 v9, v70, v9, s33
	s_addc_u32 s5, s14, s5
	v_lshlrev_b32_e32 v128, 1, v6
	v_and_or_b32 v53, v9, s69, v7
	v_bfe_u32 v7, v55, 16, 1
	v_lshl_add_u64 v[56:57], s[4:5], 0, v[128:129]
	v_lshlrev_b32_e32 v128, 1, v8
	v_add3_u32 v7, v55, v7, s33
	v_bfe_u32 v9, v59, 16, 1
	v_lshl_add_u64 v[72:73], v[56:57], 0, v[128:129]
	v_lshrrev_b32_e32 v7, 16, v7
	v_add3_u32 v9, v59, v9, s33
	global_store_dwordx4 v[72:73], v[50:53], off
	v_lshlrev_b32_e32 v128, 1, v10
	ds_read2_b32 v[54:55], v5 offset0:16 offset1:24
	v_and_or_b32 v50, v9, s69, v7
	v_bfe_u32 v7, v61, 16, 1
	v_add3_u32 v7, v61, v7, s33
	v_bfe_u32 v9, v63, 16, 1
	v_lshrrev_b32_e32 v7, 16, v7
	v_add3_u32 v9, v63, v9, s33
	v_and_or_b32 v51, v9, s69, v7
	v_bfe_u32 v7, v65, 16, 1
	v_add3_u32 v7, v65, v7, s33
	v_bfe_u32 v9, v67, 16, 1
	v_lshrrev_b32_e32 v7, 16, v7
	v_add3_u32 v9, v67, v9, s33
	v_and_or_b32 v52, v9, s69, v7
	v_bfe_u32 v7, v69, 16, 1
	v_add3_u32 v7, v69, v7, s33
	v_bfe_u32 v9, v71, 16, 1
	v_lshrrev_b32_e32 v7, 16, v7
	v_add3_u32 v9, v71, v9, s33
	v_and_or_b32 v53, v9, s69, v7
	v_lshl_add_u64 v[58:59], v[56:57], 0, v[128:129]
	global_store_dwordx4 v[58:59], v[50:53], off
	ds_read2_b32 v[58:59], v5 offset0:49 offset1:57
	ds_read2_b32 v[60:61], v5 offset0:82 offset1:90
	ds_read2_b32 v[62:63], v5 offset0:115 offset1:123
	s_waitcnt lgkmcnt(3)
	v_bfe_u32 v7, v54, 16, 1
	v_add3_u32 v7, v54, v7, s33
	s_waitcnt lgkmcnt(2)
	v_bfe_u32 v9, v58, 16, 1
	ds_read2_b32 v[64:65], v5 offset0:148 offset1:156
	v_lshrrev_b32_e32 v7, 16, v7
	v_add3_u32 v9, v58, v9, s33
	ds_read2_b32 v[66:67], v5 offset0:181 offset1:189
	v_and_or_b32 v50, v9, s69, v7
	s_waitcnt lgkmcnt(3)
	v_bfe_u32 v7, v60, 16, 1
	v_add3_u32 v7, v60, v7, s33
	s_waitcnt lgkmcnt(2)
	v_bfe_u32 v9, v62, 16, 1
	ds_read2_b32 v[68:69], v5 offset0:214 offset1:222
	v_lshrrev_b32_e32 v7, 16, v7
	v_add3_u32 v9, v62, v9, s33
	ds_read2_b32 v[70:71], v5 offset0:247 offset1:255
	v_and_or_b32 v51, v9, s69, v7
	s_waitcnt lgkmcnt(3)
	v_bfe_u32 v7, v64, 16, 1
	v_add3_u32 v7, v64, v7, s33
	s_waitcnt lgkmcnt(2)
	v_bfe_u32 v9, v66, 16, 1
	v_lshrrev_b32_e32 v7, 16, v7
	v_add3_u32 v9, v66, v9, s33
	v_and_or_b32 v52, v9, s69, v7
	s_waitcnt lgkmcnt(1)
	v_bfe_u32 v7, v68, 16, 1
	v_add3_u32 v7, v68, v7, s33
	s_waitcnt lgkmcnt(0)
	v_bfe_u32 v9, v70, 16, 1
	v_lshrrev_b32_e32 v7, 16, v7
	v_add3_u32 v9, v70, v9, s33
	v_and_or_b32 v53, v9, s69, v7
	v_bfe_u32 v7, v55, 16, 1
	v_lshlrev_b32_e32 v128, 1, v12
	v_add3_u32 v7, v55, v7, s33
	v_bfe_u32 v9, v59, 16, 1
	v_lshl_add_u64 v[72:73], v[56:57], 0, v[128:129]
	v_lshrrev_b32_e32 v7, 16, v7
	v_add3_u32 v9, v59, v9, s33
	global_store_dwordx4 v[72:73], v[50:53], off
	v_lshlrev_b32_e32 v128, 1, v14
	v_lshl_add_u64 v[54:55], v[56:57], 0, v[128:129]
	v_and_or_b32 v50, v9, s69, v7
	v_bfe_u32 v7, v61, 16, 1
	v_add3_u32 v7, v61, v7, s33
	v_bfe_u32 v9, v63, 16, 1
	v_lshrrev_b32_e32 v7, 16, v7
	v_add3_u32 v9, v63, v9, s33
	v_and_or_b32 v51, v9, s69, v7
	v_bfe_u32 v7, v65, 16, 1
	v_add3_u32 v7, v65, v7, s33
	v_bfe_u32 v9, v67, 16, 1
	v_lshrrev_b32_e32 v7, 16, v7
	v_add3_u32 v9, v67, v9, s33
	v_and_or_b32 v52, v9, s69, v7
	v_bfe_u32 v7, v69, 16, 1
	v_add3_u32 v7, v69, v7, s33
	v_bfe_u32 v9, v71, 16, 1
	v_lshrrev_b32_e32 v7, 16, v7
	v_add3_u32 v9, v71, v9, s33
	v_and_or_b32 v53, v9, s69, v7
	global_store_dwordx4 v[54:55], v[50:53], off
	s_waitcnt lgkmcnt(0)
	s_mov_b32 s1, s0
	s_andn2_b64 vcc, exec, s[10:11]
	s_mov_b64 s[10:11], -1
	s_cbranch_vccnz .LBB0_718

.LBB0_716:
	s_lshl_b32 s14, s1, 1
	s_lshl_b32 s15, s5, 1
	v_or_b32_e32 v7, s14, v1
	v_or_b32_e32 v9, s15, v0
	s_add_i32 s22, s14, 4
	s_add_i32 s23, s15, 4
	s_add_i32 s24, s14, 8
	s_add_i32 s25, s15, 8
	s_add_i32 s26, s14, 12
	s_add_i32 s27, s15, 12
	s_add_i32 s30, s14, 16
	s_add_i32 s36, s15, 16
	s_add_i32 s37, s14, 20
	s_add_i32 s40, s15, 20
	s_add_i32 s41, s14, 24
	s_add_i32 s42, s15, 24
	s_add_i32 s14, s14, 28
	s_add_i32 s15, s15, 28
	v_add_u32_e32 v54, s10, v9
	v_or_b32_e32 v11, s22, v1
	v_or_b32_e32 v13, s23, v0
	v_or_b32_e32 v15, s24, v1
	v_or_b32_e32 v19, s25, v0
	v_or_b32_e32 v41, s26, v1
	v_or_b32_e32 v43, s27, v0
	v_or_b32_e32 v45, s30, v1
	v_or_b32_e32 v47, s36, v0
	v_or_b32_e32 v49, s37, v1
	v_or_b32_e32 v82, s40, v0
	v_or_b32_e32 v86, s41, v1
	v_or_b32_e32 v87, s42, v0
	v_or_b32_e32 v88, s14, v1
	v_or_b32_e32 v89, s15, v0
	v_add_u32_e32 v52, s4, v7
	v_ashrrev_i32_e32 v55, 31, v54
	v_add_u32_e32 v56, s4, v11
	v_add_u32_e32 v58, s10, v13
	v_add_u32_e32 v60, s4, v15
	v_add_u32_e32 v62, s10, v19
	v_add_u32_e32 v64, s4, v41
	v_add_u32_e32 v66, s10, v43
	v_add_u32_e32 v68, s4, v45
	v_add_u32_e32 v70, s10, v47
	v_add_u32_e32 v72, s4, v49
	v_add_u32_e32 v74, s10, v82
	v_add_u32_e32 v76, s4, v86
	v_add_u32_e32 v78, s10, v87
	v_add_u32_e32 v80, s4, v88
	v_add_u32_e32 v84, s10, v89
	v_ashrrev_i32_e32 v53, 31, v52
	v_lshlrev_b64 v[54:55], 12, v[54:55]
	v_ashrrev_i32_e32 v59, 31, v58
	v_ashrrev_i32_e32 v57, 31, v56
	v_ashrrev_i32_e32 v63, 31, v62
	v_ashrrev_i32_e32 v61, 31, v60
	v_ashrrev_i32_e32 v67, 31, v66
	v_ashrrev_i32_e32 v65, 31, v64
	v_ashrrev_i32_e32 v71, 31, v70
	v_ashrrev_i32_e32 v69, 31, v68
	v_ashrrev_i32_e32 v75, 31, v74
	v_ashrrev_i32_e32 v73, 31, v72
	v_ashrrev_i32_e32 v79, 31, v78
	v_ashrrev_i32_e32 v77, 31, v76
	v_ashrrev_i32_e32 v85, 31, v84
	v_ashrrev_i32_e32 v81, 31, v80
	v_lshlrev_b64 v[52:53], 12, v[52:53]
	v_lshl_add_u64 v[54:55], v[50:51], 0, v[54:55]
	v_lshlrev_b64 v[56:57], 12, v[56:57]
	v_lshlrev_b64 v[58:59], 12, v[58:59]
	v_lshlrev_b64 v[60:61], 12, v[60:61]
	v_lshlrev_b64 v[62:63], 12, v[62:63]
	v_lshlrev_b64 v[64:65], 12, v[64:65]
	v_lshlrev_b64 v[66:67], 12, v[66:67]
	v_lshlrev_b64 v[68:69], 12, v[68:69]
	v_lshlrev_b64 v[70:71], 12, v[70:71]
	v_lshlrev_b64 v[72:73], 12, v[72:73]
	v_lshlrev_b64 v[74:75], 12, v[74:75]
	v_lshlrev_b64 v[76:77], 12, v[76:77]
	v_lshlrev_b64 v[78:79], 12, v[78:79]
	v_lshlrev_b64 v[80:81], 12, v[80:81]
	v_lshlrev_b64 v[84:85], 12, v[84:85]
	v_lshl_add_u64 v[52:53], v[50:51], 0, v[52:53]
	v_lshl_add_u64 v[58:59], v[50:51], 0, v[58:59]
	v_lshl_add_u64 v[56:57], v[50:51], 0, v[56:57]
	v_lshl_add_u64 v[62:63], v[50:51], 0, v[62:63]
	v_lshl_add_u64 v[60:61], v[50:51], 0, v[60:61]
	v_lshl_add_u64 v[66:67], v[50:51], 0, v[66:67]
	v_lshl_add_u64 v[64:65], v[50:51], 0, v[64:65]
	v_lshl_add_u64 v[70:71], v[50:51], 0, v[70:71]
	v_lshl_add_u64 v[68:69], v[50:51], 0, v[68:69]
	v_lshl_add_u64 v[74:75], v[50:51], 0, v[74:75]
	v_lshl_add_u64 v[72:73], v[50:51], 0, v[72:73]
	v_lshl_add_u64 v[78:79], v[50:51], 0, v[78:79]
	v_lshl_add_u64 v[76:77], v[50:51], 0, v[76:77]
	v_lshl_add_u64 v[84:85], v[50:51], 0, v[84:85]
	v_lshl_add_u64 v[80:81], v[50:51], 0, v[80:81]
	global_load_dword v90, v[54:55], off
	global_load_dword v91, v[52:53], off
	global_load_dword v92, v[58:59], off
	global_load_dword v93, v[56:57], off
	global_load_dword v94, v[62:63], off
	global_load_dword v95, v[60:61], off
	global_load_dword v96, v[66:67], off
	global_load_dword v97, v[64:65], off
	global_load_dword v98, v[70:71], off
	global_load_dword v99, v[68:69], off
	global_load_dword v100, v[74:75], off
	global_load_dword v101, v[72:73], off
	global_load_dword v102, v[78:79], off
	global_load_dword v103, v[76:77], off
	global_load_dword v104, v[84:85], off
	global_load_dword v105, v[80:81], off
	s_add_i32 s5, s5, 16
	s_add_i32 s1, s1, 16
	s_lshl_b32 s14, s1, 1
	s_lshl_b32 s15, s5, 1
	v_or_b32_e32 v106, s14, v1
	v_or_b32_e32 v107, s15, v0
	s_add_i32 s22, s14, 4
	s_add_i32 s23, s15, 4
	s_add_i32 s24, s14, 8
	s_add_i32 s25, s15, 8
	s_add_i32 s26, s14, 12
	s_add_i32 s27, s15, 12
	s_add_i32 s30, s14, 16
	s_add_i32 s36, s15, 16
	s_add_i32 s37, s14, 20
	s_add_i32 s40, s15, 20
	s_add_i32 s41, s14, 24
	s_add_i32 s42, s15, 24
	s_add_i32 s14, s14, 28
	s_add_i32 s15, s15, 28
	v_add_u32_e32 v132, s10, v107
	v_or_b32_e32 v108, s22, v1
	v_or_b32_e32 v109, s23, v0
	v_or_b32_e32 v110, s24, v1
	v_or_b32_e32 v111, s25, v0
	v_or_b32_e32 v112, s26, v1
	v_or_b32_e32 v113, s27, v0
	v_or_b32_e32 v114, s30, v1
	v_or_b32_e32 v115, s36, v0
	v_or_b32_e32 v116, s37, v1
	v_or_b32_e32 v117, s40, v0
	v_or_b32_e32 v118, s41, v1
	v_or_b32_e32 v119, s42, v0
	v_or_b32_e32 v120, s14, v1
	v_or_b32_e32 v121, s15, v0
	v_add_u32_e32 v130, s4, v106
	v_ashrrev_i32_e32 v133, 31, v132
	v_add_u32_e32 v134, s4, v108
	v_add_u32_e32 v136, s10, v109
	v_add_u32_e32 v138, s4, v110
	v_add_u32_e32 v140, s10, v111
	v_add_u32_e32 v142, s4, v112
	v_add_u32_e32 v144, s10, v113
	v_add_u32_e32 v146, s4, v114
	v_add_u32_e32 v148, s10, v115
	v_add_u32_e32 v150, s4, v116
	v_add_u32_e32 v152, s10, v117
	v_add_u32_e32 v154, s4, v118
	v_add_u32_e32 v156, s10, v119
	v_add_u32_e32 v158, s4, v120
	v_add_u32_e32 v160, s10, v121
	v_ashrrev_i32_e32 v131, 31, v130
	v_lshlrev_b64 v[132:133], 12, v[132:133]
	v_ashrrev_i32_e32 v137, 31, v136
	v_ashrrev_i32_e32 v135, 31, v134
	v_ashrrev_i32_e32 v141, 31, v140
	v_ashrrev_i32_e32 v139, 31, v138
	v_ashrrev_i32_e32 v145, 31, v144
	v_ashrrev_i32_e32 v143, 31, v142
	v_ashrrev_i32_e32 v149, 31, v148
	v_ashrrev_i32_e32 v147, 31, v146
	v_ashrrev_i32_e32 v153, 31, v152
	v_ashrrev_i32_e32 v151, 31, v150
	v_ashrrev_i32_e32 v157, 31, v156
	v_ashrrev_i32_e32 v155, 31, v154
	v_ashrrev_i32_e32 v161, 31, v160
	v_ashrrev_i32_e32 v159, 31, v158
	v_lshlrev_b64 v[130:131], 12, v[130:131]
	v_lshl_add_u64 v[132:133], v[50:51], 0, v[132:133]
	v_lshlrev_b64 v[134:135], 12, v[134:135]
	v_lshlrev_b64 v[136:137], 12, v[136:137]
	v_lshlrev_b64 v[138:139], 12, v[138:139]
	v_lshlrev_b64 v[140:141], 12, v[140:141]
	v_lshlrev_b64 v[142:143], 12, v[142:143]
	v_lshlrev_b64 v[144:145], 12, v[144:145]
	v_lshlrev_b64 v[146:147], 12, v[146:147]
	v_lshlrev_b64 v[148:149], 12, v[148:149]
	v_lshlrev_b64 v[150:151], 12, v[150:151]
	v_lshlrev_b64 v[152:153], 12, v[152:153]
	v_lshlrev_b64 v[154:155], 12, v[154:155]
	v_lshlrev_b64 v[156:157], 12, v[156:157]
	v_lshlrev_b64 v[158:159], 12, v[158:159]
	v_lshlrev_b64 v[160:161], 12, v[160:161]
	v_lshl_add_u64 v[130:131], v[50:51], 0, v[130:131]
	v_lshl_add_u64 v[136:137], v[50:51], 0, v[136:137]
	v_lshl_add_u64 v[134:135], v[50:51], 0, v[134:135]
	v_lshl_add_u64 v[140:141], v[50:51], 0, v[140:141]
	v_lshl_add_u64 v[138:139], v[50:51], 0, v[138:139]
	v_lshl_add_u64 v[144:145], v[50:51], 0, v[144:145]
	v_lshl_add_u64 v[142:143], v[50:51], 0, v[142:143]
	v_lshl_add_u64 v[148:149], v[50:51], 0, v[148:149]
	v_lshl_add_u64 v[146:147], v[50:51], 0, v[146:147]
	v_lshl_add_u64 v[152:153], v[50:51], 0, v[152:153]
	v_lshl_add_u64 v[150:151], v[50:51], 0, v[150:151]
	v_lshl_add_u64 v[156:157], v[50:51], 0, v[156:157]
	v_lshl_add_u64 v[154:155], v[50:51], 0, v[154:155]
	v_lshl_add_u64 v[160:161], v[50:51], 0, v[160:161]
	v_lshl_add_u64 v[158:159], v[50:51], 0, v[158:159]
	global_load_dword v122, v[132:133], off
	global_load_dword v123, v[130:131], off
	global_load_dword v124, v[136:137], off
	global_load_dword v125, v[134:135], off
	global_load_dword v126, v[140:141], off
	global_load_dword v127, v[138:139], off
	global_load_dword v162, v[144:145], off
	global_load_dword v163, v[142:143], off
	global_load_dword v164, v[148:149], off
	global_load_dword v165, v[146:147], off
	global_load_dword v166, v[152:153], off
	global_load_dword v167, v[150:151], off
	global_load_dword v168, v[156:157], off
	global_load_dword v169, v[154:155], off
	global_load_dword v170, v[160:161], off
	global_load_dword v171, v[158:159], off
	v_mad_u64_u32 v[52:53], s[14:15], v9, s78, v[4:5]
	v_mad_u64_u32 v[54:55], s[14:15], v7, s78, v[4:5]
	v_mad_u64_u32 v[56:57], s[14:15], v13, s78, v[4:5]
	v_mad_u64_u32 v[58:59], s[14:15], v11, s78, v[4:5]
	v_mad_u64_u32 v[60:61], s[14:15], v19, s78, v[4:5]
	v_mad_u64_u32 v[62:63], s[14:15], v15, s78, v[4:5]
	v_mad_u64_u32 v[64:65], s[14:15], v43, s78, v[4:5]
	v_mad_u64_u32 v[66:67], s[14:15], v41, s78, v[4:5]
	v_mad_u64_u32 v[68:69], s[14:15], v47, s78, v[4:5]
	v_mad_u64_u32 v[70:71], s[14:15], v45, s78, v[4:5]
	v_mad_u64_u32 v[72:73], s[14:15], v82, s78, v[4:5]
	v_mad_u64_u32 v[74:75], s[14:15], v49, s78, v[4:5]
	v_mad_u64_u32 v[76:77], s[14:15], v87, s78, v[4:5]
	v_mad_u64_u32 v[78:79], s[14:15], v86, s78, v[4:5]
	v_mad_u64_u32 v[80:81], s[14:15], v89, s78, v[4:5]
	v_mad_u64_u32 v[84:85], s[14:15], v88, s78, v[4:5]
	s_waitcnt vmcnt(31)
	ds_write_b32 v52, v90
	s_waitcnt vmcnt(30)
	ds_write_b32 v54, v91
	s_waitcnt vmcnt(29)
	ds_write_b32 v56, v92
	s_waitcnt vmcnt(28)
	ds_write_b32 v58, v93
	s_waitcnt vmcnt(27)
	ds_write_b32 v60, v94
	s_waitcnt vmcnt(26)
	ds_write_b32 v62, v95
	s_waitcnt vmcnt(25)
	ds_write_b32 v64, v96
	s_waitcnt vmcnt(24)
	ds_write_b32 v66, v97
	s_waitcnt vmcnt(23)
	ds_write_b32 v68, v98
	s_waitcnt vmcnt(22)
	ds_write_b32 v70, v99
	s_waitcnt vmcnt(21)
	ds_write_b32 v72, v100
	s_waitcnt vmcnt(20)
	ds_write_b32 v74, v101
	s_waitcnt vmcnt(19)
	ds_write_b32 v76, v102
	s_waitcnt vmcnt(18)
	ds_write_b32 v78, v103
	s_waitcnt vmcnt(17)
	ds_write_b32 v80, v104
	s_waitcnt vmcnt(16)
	ds_write_b32 v84, v105
	v_mad_u64_u32 v[130:131], s[14:15], v107, s78, v[4:5]
	v_mad_u64_u32 v[132:133], s[14:15], v106, s78, v[4:5]
	v_mad_u64_u32 v[134:135], s[14:15], v109, s78, v[4:5]
	v_mad_u64_u32 v[136:137], s[14:15], v108, s78, v[4:5]
	v_mad_u64_u32 v[138:139], s[14:15], v111, s78, v[4:5]
	v_mad_u64_u32 v[140:141], s[14:15], v110, s78, v[4:5]
	v_mad_u64_u32 v[142:143], s[14:15], v113, s78, v[4:5]
	v_mad_u64_u32 v[144:145], s[14:15], v112, s78, v[4:5]
	v_mad_u64_u32 v[146:147], s[14:15], v115, s78, v[4:5]
	v_mad_u64_u32 v[148:149], s[14:15], v114, s78, v[4:5]
	v_mad_u64_u32 v[150:151], s[14:15], v117, s78, v[4:5]
	v_mad_u64_u32 v[152:153], s[14:15], v116, s78, v[4:5]
	v_mad_u64_u32 v[154:155], s[14:15], v119, s78, v[4:5]
	v_mad_u64_u32 v[156:157], s[14:15], v118, s78, v[4:5]
	v_mad_u64_u32 v[158:159], s[14:15], v121, s78, v[4:5]
	v_mad_u64_u32 v[160:161], s[14:15], v120, s78, v[4:5]
	s_waitcnt vmcnt(15)
	ds_write_b32 v130, v122
	s_waitcnt vmcnt(14)
	ds_write_b32 v132, v123
	s_waitcnt vmcnt(13)
	ds_write_b32 v134, v124
	s_waitcnt vmcnt(12)
	ds_write_b32 v136, v125
	s_waitcnt vmcnt(11)
	ds_write_b32 v138, v126
	s_waitcnt vmcnt(10)
	ds_write_b32 v140, v127
	s_waitcnt vmcnt(9)
	ds_write_b32 v142, v162
	s_waitcnt vmcnt(8)
	ds_write_b32 v144, v163
	s_waitcnt vmcnt(7)
	ds_write_b32 v146, v164
	s_waitcnt vmcnt(6)
	ds_write_b32 v148, v165
	s_waitcnt vmcnt(5)
	ds_write_b32 v150, v166
	s_waitcnt vmcnt(4)
	ds_write_b32 v152, v167
	s_waitcnt vmcnt(3)
	ds_write_b32 v154, v168
	s_waitcnt vmcnt(2)
	ds_write_b32 v156, v169
	s_waitcnt vmcnt(1)
	ds_write_b32 v158, v170
	s_waitcnt vmcnt(0)
	ds_write_b32 v160, v171
	s_add_i32 s5, s5, 16
	s_add_i32 s1, s1, 16
	s_add_i32 s11, s11, -16
	s_add_i32 s11, s11, -16
	s_cmp_lg_u32 s11, 0
	s_waitcnt lgkmcnt(0)
	ds_read2_b32 v[54:55], v5 offset1:8
	ds_read2_b32 v[58:59], v5 offset0:33 offset1:41
	ds_read2_b32 v[60:61], v5 offset0:66 offset1:74
	ds_read2_b32 v[62:63], v5 offset0:99 offset1:107
	ds_read2_b32 v[64:65], v5 offset0:132 offset1:140
	s_waitcnt lgkmcnt(4)
	v_bfe_u32 v7, v54, 16, 1
	v_add3_u32 v7, v54, v7, s33
	s_waitcnt lgkmcnt(3)
	v_bfe_u32 v9, v58, 16, 1
	v_lshrrev_b32_e32 v7, 16, v7
	v_add3_u32 v9, v58, v9, s33
	ds_read2_b32 v[66:67], v5 offset0:165 offset1:173
	v_and_or_b32 v50, v9, s69, v7
	s_waitcnt lgkmcnt(3)
	v_bfe_u32 v7, v60, 16, 1
	v_add3_u32 v7, v60, v7, s33
	s_waitcnt lgkmcnt(2)
	v_bfe_u32 v9, v62, 16, 1
	ds_read2_b32 v[68:69], v5 offset0:198 offset1:206
	v_lshrrev_b32_e32 v7, 16, v7
	v_add3_u32 v9, v62, v9, s33
	ds_read2_b32 v[70:71], v5 offset0:231 offset1:239
	v_and_or_b32 v51, v9, s69, v7
	s_waitcnt lgkmcnt(3)
	v_bfe_u32 v7, v64, 16, 1
	s_lshl_b64 s[4:5], s[12:13], 11
	v_add3_u32 v7, v64, v7, s33
	s_waitcnt lgkmcnt(2)
	v_bfe_u32 v9, v66, 16, 1
	s_add_u32 s1, s47, s4
	v_lshrrev_b32_e32 v7, 16, v7
	v_add3_u32 v9, v66, v9, s33
	s_addc_u32 s12, s48, s5
	s_ashr_i32 s11, s10, 31
	v_and_or_b32 v52, v9, s69, v7
	s_waitcnt lgkmcnt(1)
	v_bfe_u32 v7, v68, 16, 1
	s_lshl_b64 s[4:5], s[10:11], 1
	v_add3_u32 v7, v68, v7, s33
	s_waitcnt lgkmcnt(0)
	v_bfe_u32 v9, v70, 16, 1
	s_add_u32 s4, s1, s4
	v_lshrrev_b32_e32 v7, 16, v7
	v_add3_u32 v9, v70, v9, s33
	s_addc_u32 s5, s12, s5
	v_lshlrev_b32_e32 v128, 1, v6
	v_and_or_b32 v53, v9, s69, v7
	v_bfe_u32 v7, v55, 16, 1
	v_lshl_add_u64 v[56:57], s[4:5], 0, v[128:129]
	v_lshlrev_b32_e32 v128, 1, v8
	v_add3_u32 v7, v55, v7, s33
	v_bfe_u32 v9, v59, 16, 1
	v_lshl_add_u64 v[72:73], v[56:57], 0, v[128:129]
	v_lshrrev_b32_e32 v7, 16, v7
	v_add3_u32 v9, v59, v9, s33
	global_store_dwordx4 v[72:73], v[50:53], off
	v_lshlrev_b32_e32 v128, 1, v10
	ds_read2_b32 v[54:55], v5 offset0:16 offset1:24
	v_and_or_b32 v50, v9, s69, v7
	v_bfe_u32 v7, v61, 16, 1
	v_add3_u32 v7, v61, v7, s33
	v_bfe_u32 v9, v63, 16, 1
	v_lshrrev_b32_e32 v7, 16, v7
	v_add3_u32 v9, v63, v9, s33
	v_and_or_b32 v51, v9, s69, v7
	v_bfe_u32 v7, v65, 16, 1
	v_add3_u32 v7, v65, v7, s33
	v_bfe_u32 v9, v67, 16, 1
	v_lshrrev_b32_e32 v7, 16, v7
	v_add3_u32 v9, v67, v9, s33
	v_and_or_b32 v52, v9, s69, v7
	v_bfe_u32 v7, v69, 16, 1
	v_add3_u32 v7, v69, v7, s33
	v_bfe_u32 v9, v71, 16, 1
	v_lshrrev_b32_e32 v7, 16, v7
	v_add3_u32 v9, v71, v9, s33
	v_and_or_b32 v53, v9, s69, v7
	v_lshl_add_u64 v[58:59], v[56:57], 0, v[128:129]
	global_store_dwordx4 v[58:59], v[50:53], off
	ds_read2_b32 v[58:59], v5 offset0:49 offset1:57
	ds_read2_b32 v[60:61], v5 offset0:82 offset1:90
	ds_read2_b32 v[62:63], v5 offset0:115 offset1:123
	s_waitcnt lgkmcnt(3)
	v_bfe_u32 v7, v54, 16, 1
	v_add3_u32 v7, v54, v7, s33
	s_waitcnt lgkmcnt(2)
	v_bfe_u32 v9, v58, 16, 1
	ds_read2_b32 v[64:65], v5 offset0:148 offset1:156
	v_lshrrev_b32_e32 v7, 16, v7
	v_add3_u32 v9, v58, v9, s33
	ds_read2_b32 v[66:67], v5 offset0:181 offset1:189
	v_and_or_b32 v50, v9, s69, v7
	s_waitcnt lgkmcnt(3)
	v_bfe_u32 v7, v60, 16, 1
	v_add3_u32 v7, v60, v7, s33
	s_waitcnt lgkmcnt(2)
	v_bfe_u32 v9, v62, 16, 1
	ds_read2_b32 v[68:69], v5 offset0:214 offset1:222
	v_lshrrev_b32_e32 v7, 16, v7
	v_add3_u32 v9, v62, v9, s33
	ds_read2_b32 v[70:71], v5 offset0:247 offset1:255
	v_and_or_b32 v51, v9, s69, v7
	s_waitcnt lgkmcnt(3)
	v_bfe_u32 v7, v64, 16, 1
	v_add3_u32 v7, v64, v7, s33
	s_waitcnt lgkmcnt(2)
	v_bfe_u32 v9, v66, 16, 1
	v_lshrrev_b32_e32 v7, 16, v7
	v_add3_u32 v9, v66, v9, s33
	v_and_or_b32 v52, v9, s69, v7
	s_waitcnt lgkmcnt(1)
	v_bfe_u32 v7, v68, 16, 1
	v_add3_u32 v7, v68, v7, s33
	s_waitcnt lgkmcnt(0)
	v_bfe_u32 v9, v70, 16, 1
	v_lshrrev_b32_e32 v7, 16, v7
	v_add3_u32 v9, v70, v9, s33
	v_and_or_b32 v53, v9, s69, v7
	v_bfe_u32 v7, v55, 16, 1
	v_lshlrev_b32_e32 v128, 1, v12
	v_add3_u32 v7, v55, v7, s33
	v_bfe_u32 v9, v59, 16, 1
	v_lshl_add_u64 v[72:73], v[56:57], 0, v[128:129]
	v_lshrrev_b32_e32 v7, 16, v7
	v_add3_u32 v9, v59, v9, s33
	global_store_dwordx4 v[72:73], v[50:53], off
	v_lshlrev_b32_e32 v128, 1, v14
	v_lshl_add_u64 v[54:55], v[56:57], 0, v[128:129]
	v_and_or_b32 v50, v9, s69, v7
	v_bfe_u32 v7, v61, 16, 1
	v_add3_u32 v7, v61, v7, s33
	v_bfe_u32 v9, v63, 16, 1
	v_lshrrev_b32_e32 v7, 16, v7
	v_add3_u32 v9, v63, v9, s33
	v_and_or_b32 v51, v9, s69, v7
	v_bfe_u32 v7, v65, 16, 1
	v_add3_u32 v7, v65, v7, s33
	v_bfe_u32 v9, v67, 16, 1
	v_lshrrev_b32_e32 v7, 16, v7
	v_add3_u32 v9, v67, v9, s33
	v_and_or_b32 v52, v9, s69, v7
	v_bfe_u32 v7, v69, 16, 1
	v_add3_u32 v7, v69, v7, s33
	v_bfe_u32 v9, v71, 16, 1
	v_lshrrev_b32_e32 v7, 16, v7
	v_add3_u32 v9, v71, v9, s33
	v_and_or_b32 v53, v9, s69, v7
	global_store_dwordx4 v[54:55], v[50:53], off
	s_waitcnt lgkmcnt(0)
	s_mov_b64 s[10:11], -1

.LBB0_724:
	s_lshl_b32 s22, s4, 1
	s_lshl_b32 s23, s5, 1
	v_or_b32_e32 v7, s22, v1
	v_or_b32_e32 v9, s23, v0
	s_add_i32 s24, s22, 4
	s_add_i32 s25, s23, 4
	s_add_i32 s26, s22, 8
	s_add_i32 s27, s23, 8
	s_add_i32 s30, s22, 12
	s_add_i32 s36, s23, 12
	s_add_i32 s37, s22, 16
	s_add_i32 s40, s23, 16
	s_add_i32 s41, s22, 20
	s_add_i32 s42, s23, 20
	s_add_i32 s43, s22, 24
	s_add_i32 s52, s23, 24
	s_add_i32 s22, s22, 28
	s_add_i32 s23, s23, 28
	v_add_u32_e32 v11, s1, v7
	v_add_u32_e32 v13, s12, v9
	v_or_b32_e32 v15, s24, v1
	v_or_b32_e32 v19, s25, v0
	v_or_b32_e32 v41, s26, v1
	v_or_b32_e32 v43, s27, v0
	v_or_b32_e32 v45, s30, v1
	v_or_b32_e32 v47, s36, v0
	v_or_b32_e32 v49, s37, v1
	v_or_b32_e32 v82, s40, v0
	v_or_b32_e32 v86, s41, v1
	v_or_b32_e32 v87, s42, v0
	v_or_b32_e32 v88, s43, v1
	v_or_b32_e32 v89, s52, v0
	v_or_b32_e32 v90, s22, v1
	v_or_b32_e32 v91, s23, v0
	v_mad_i64_i32 v[52:53], s[22:23], v13, s79, v[50:51]
	v_mad_i64_i32 v[54:55], s[22:23], v11, s79, v[50:51]
	v_add_u32_e32 v11, s1, v15
	v_add_u32_e32 v13, s12, v19
	v_add_u32_e32 v62, s1, v41
	v_add_u32_e32 v60, s12, v43
	v_add_u32_e32 v66, s1, v45
	v_add_u32_e32 v64, s12, v47
	v_add_u32_e32 v70, s1, v49
	v_add_u32_e32 v68, s12, v82
	v_add_u32_e32 v74, s1, v86
	v_add_u32_e32 v72, s12, v87
	v_add_u32_e32 v78, s1, v88
	v_add_u32_e32 v76, s12, v89
	v_add_u32_e32 v84, s1, v90
	v_add_u32_e32 v80, s12, v91
	v_mad_i64_i32 v[56:57], s[22:23], v13, s79, v[50:51]
	v_mad_i64_i32 v[58:59], s[22:23], v11, s79, v[50:51]
	v_mad_i64_i32 v[60:61], s[22:23], v60, s79, v[50:51]
	v_mad_i64_i32 v[62:63], s[22:23], v62, s79, v[50:51]
	v_mad_i64_i32 v[64:65], s[22:23], v64, s79, v[50:51]
	v_mad_i64_i32 v[66:67], s[22:23], v66, s79, v[50:51]
	v_mad_i64_i32 v[68:69], s[22:23], v68, s79, v[50:51]
	v_mad_i64_i32 v[70:71], s[22:23], v70, s79, v[50:51]
	v_mad_i64_i32 v[72:73], s[22:23], v72, s79, v[50:51]
	v_mad_i64_i32 v[74:75], s[22:23], v74, s79, v[50:51]
	v_mad_i64_i32 v[76:77], s[22:23], v76, s79, v[50:51]
	v_mad_i64_i32 v[78:79], s[22:23], v78, s79, v[50:51]
	v_mad_i64_i32 v[80:81], s[22:23], v80, s79, v[50:51]
	v_mad_i64_i32 v[84:85], s[22:23], v84, s79, v[50:51]
	global_load_dword v11, v[52:53], off
	global_load_dword v13, v[54:55], off
	global_load_dword v92, v[56:57], off
	global_load_dword v93, v[58:59], off
	global_load_dword v94, v[60:61], off
	global_load_dword v95, v[62:63], off
	global_load_dword v96, v[64:65], off
	global_load_dword v97, v[66:67], off
	global_load_dword v98, v[68:69], off
	global_load_dword v99, v[70:71], off
	global_load_dword v100, v[72:73], off
	global_load_dword v101, v[74:75], off
	global_load_dword v102, v[76:77], off
	global_load_dword v103, v[78:79], off
	global_load_dword v104, v[80:81], off
	global_load_dword v105, v[84:85], off
	s_add_i32 s5, s5, 16
	s_add_i32 s4, s4, 16
	s_lshl_b32 s22, s4, 1
	s_lshl_b32 s23, s5, 1
	v_or_b32_e32 v106, s22, v1
	v_or_b32_e32 v107, s23, v0
	s_add_i32 s24, s22, 4
	s_add_i32 s25, s23, 4
	s_add_i32 s26, s22, 8
	s_add_i32 s27, s23, 8
	s_add_i32 s30, s22, 12
	s_add_i32 s36, s23, 12
	s_add_i32 s37, s22, 16
	s_add_i32 s40, s23, 16
	s_add_i32 s41, s22, 20
	s_add_i32 s42, s23, 20
	s_add_i32 s43, s22, 24
	s_add_i32 s52, s23, 24
	s_add_i32 s22, s22, 28
	s_add_i32 s23, s23, 28
	v_add_u32_e32 v108, s1, v106
	v_add_u32_e32 v109, s12, v107
	v_or_b32_e32 v110, s24, v1
	v_or_b32_e32 v111, s25, v0
	v_or_b32_e32 v112, s26, v1
	v_or_b32_e32 v113, s27, v0
	v_or_b32_e32 v114, s30, v1
	v_or_b32_e32 v115, s36, v0
	v_or_b32_e32 v116, s37, v1
	v_or_b32_e32 v117, s40, v0
	v_or_b32_e32 v118, s41, v1
	v_or_b32_e32 v119, s42, v0
	v_or_b32_e32 v120, s43, v1
	v_or_b32_e32 v121, s52, v0
	v_or_b32_e32 v122, s22, v1
	v_or_b32_e32 v123, s23, v0
	v_mad_i64_i32 v[130:131], s[22:23], v109, s79, v[50:51]
	v_mad_i64_i32 v[132:133], s[22:23], v108, s79, v[50:51]
	v_add_u32_e32 v108, s1, v110
	v_add_u32_e32 v109, s12, v111
	v_add_u32_e32 v140, s1, v112
	v_add_u32_e32 v138, s12, v113
	v_add_u32_e32 v144, s1, v114
	v_add_u32_e32 v142, s12, v115
	v_add_u32_e32 v148, s1, v116
	v_add_u32_e32 v146, s12, v117
	v_add_u32_e32 v152, s1, v118
	v_add_u32_e32 v150, s12, v119
	v_add_u32_e32 v156, s1, v120
	v_add_u32_e32 v154, s12, v121
	v_add_u32_e32 v160, s1, v122
	v_add_u32_e32 v158, s12, v123
	v_mad_i64_i32 v[134:135], s[22:23], v109, s79, v[50:51]
	v_mad_i64_i32 v[136:137], s[22:23], v108, s79, v[50:51]
	v_mad_i64_i32 v[138:139], s[22:23], v138, s79, v[50:51]
	v_mad_i64_i32 v[140:141], s[22:23], v140, s79, v[50:51]
	v_mad_i64_i32 v[142:143], s[22:23], v142, s79, v[50:51]
	v_mad_i64_i32 v[144:145], s[22:23], v144, s79, v[50:51]
	v_mad_i64_i32 v[146:147], s[22:23], v146, s79, v[50:51]
	v_mad_i64_i32 v[148:149], s[22:23], v148, s79, v[50:51]
	v_mad_i64_i32 v[150:151], s[22:23], v150, s79, v[50:51]
	v_mad_i64_i32 v[152:153], s[22:23], v152, s79, v[50:51]
	v_mad_i64_i32 v[154:155], s[22:23], v154, s79, v[50:51]
	v_mad_i64_i32 v[156:157], s[22:23], v156, s79, v[50:51]
	v_mad_i64_i32 v[158:159], s[22:23], v158, s79, v[50:51]
	v_mad_i64_i32 v[160:161], s[22:23], v160, s79, v[50:51]
	global_load_dword v108, v[130:131], off
	global_load_dword v109, v[132:133], off
	global_load_dword v124, v[134:135], off
	global_load_dword v125, v[136:137], off
	global_load_dword v126, v[138:139], off
	global_load_dword v127, v[140:141], off
	global_load_dword v162, v[142:143], off
	global_load_dword v163, v[144:145], off
	global_load_dword v164, v[146:147], off
	global_load_dword v165, v[148:149], off
	global_load_dword v166, v[150:151], off
	global_load_dword v167, v[152:153], off
	global_load_dword v168, v[154:155], off
	global_load_dword v169, v[156:157], off
	global_load_dword v170, v[158:159], off
	global_load_dword v171, v[160:161], off
	v_mad_u64_u32 v[52:53], s[22:23], v9, s78, v[4:5]
	v_mad_u64_u32 v[54:55], s[22:23], v7, s78, v[4:5]
	v_mad_u64_u32 v[56:57], s[22:23], v19, s78, v[4:5]
	v_mad_u64_u32 v[58:59], s[22:23], v15, s78, v[4:5]
	v_mad_u64_u32 v[60:61], s[22:23], v43, s78, v[4:5]
	v_mad_u64_u32 v[62:63], s[22:23], v41, s78, v[4:5]
	v_mad_u64_u32 v[64:65], s[22:23], v47, s78, v[4:5]
	v_mad_u64_u32 v[66:67], s[22:23], v45, s78, v[4:5]
	v_mad_u64_u32 v[68:69], s[22:23], v82, s78, v[4:5]
	v_mad_u64_u32 v[70:71], s[22:23], v49, s78, v[4:5]
	v_mad_u64_u32 v[72:73], s[22:23], v87, s78, v[4:5]
	v_mad_u64_u32 v[74:75], s[22:23], v86, s78, v[4:5]
	v_mad_u64_u32 v[76:77], s[22:23], v89, s78, v[4:5]
	v_mad_u64_u32 v[78:79], s[22:23], v88, s78, v[4:5]
	v_mad_u64_u32 v[80:81], s[22:23], v91, s78, v[4:5]
	v_mad_u64_u32 v[84:85], s[22:23], v90, s78, v[4:5]
	s_waitcnt vmcnt(31)
	ds_write_b32 v52, v11
	s_waitcnt vmcnt(30)
	ds_write_b32 v54, v13
	s_waitcnt vmcnt(29)
	ds_write_b32 v56, v92
	s_waitcnt vmcnt(28)
	ds_write_b32 v58, v93
	s_waitcnt vmcnt(27)
	ds_write_b32 v60, v94
	s_waitcnt vmcnt(26)
	ds_write_b32 v62, v95
	s_waitcnt vmcnt(25)
	ds_write_b32 v64, v96
	s_waitcnt vmcnt(24)
	ds_write_b32 v66, v97
	s_waitcnt vmcnt(23)
	ds_write_b32 v68, v98
	s_waitcnt vmcnt(22)
	ds_write_b32 v70, v99
	s_waitcnt vmcnt(21)
	ds_write_b32 v72, v100
	s_waitcnt vmcnt(20)
	ds_write_b32 v74, v101
	s_waitcnt vmcnt(19)
	ds_write_b32 v76, v102
	s_waitcnt vmcnt(18)
	ds_write_b32 v78, v103
	s_waitcnt vmcnt(17)
	ds_write_b32 v80, v104
	s_waitcnt vmcnt(16)
	ds_write_b32 v84, v105
	v_mad_u64_u32 v[130:131], s[22:23], v107, s78, v[4:5]
	v_mad_u64_u32 v[132:133], s[22:23], v106, s78, v[4:5]
	v_mad_u64_u32 v[134:135], s[22:23], v111, s78, v[4:5]
	v_mad_u64_u32 v[136:137], s[22:23], v110, s78, v[4:5]
	v_mad_u64_u32 v[138:139], s[22:23], v113, s78, v[4:5]
	v_mad_u64_u32 v[140:141], s[22:23], v112, s78, v[4:5]
	v_mad_u64_u32 v[142:143], s[22:23], v115, s78, v[4:5]
	v_mad_u64_u32 v[144:145], s[22:23], v114, s78, v[4:5]
	v_mad_u64_u32 v[146:147], s[22:23], v117, s78, v[4:5]
	v_mad_u64_u32 v[148:149], s[22:23], v116, s78, v[4:5]
	v_mad_u64_u32 v[150:151], s[22:23], v119, s78, v[4:5]
	v_mad_u64_u32 v[152:153], s[22:23], v118, s78, v[4:5]
	v_mad_u64_u32 v[154:155], s[22:23], v121, s78, v[4:5]
	v_mad_u64_u32 v[156:157], s[22:23], v120, s78, v[4:5]
	v_mad_u64_u32 v[158:159], s[22:23], v123, s78, v[4:5]
	v_mad_u64_u32 v[160:161], s[22:23], v122, s78, v[4:5]
	s_waitcnt vmcnt(15)
	ds_write_b32 v130, v108
	s_waitcnt vmcnt(14)
	ds_write_b32 v132, v109
	s_waitcnt vmcnt(13)
	ds_write_b32 v134, v124
	s_waitcnt vmcnt(12)
	ds_write_b32 v136, v125
	s_waitcnt vmcnt(11)
	ds_write_b32 v138, v126
	s_waitcnt vmcnt(10)
	ds_write_b32 v140, v127
	s_waitcnt vmcnt(9)
	ds_write_b32 v142, v162
	s_waitcnt vmcnt(8)
	ds_write_b32 v144, v163
	s_waitcnt vmcnt(7)
	ds_write_b32 v146, v164
	s_waitcnt vmcnt(6)
	ds_write_b32 v148, v165
	s_waitcnt vmcnt(5)
	ds_write_b32 v150, v166
	s_waitcnt vmcnt(4)
	ds_write_b32 v152, v167
	s_waitcnt vmcnt(3)
	ds_write_b32 v154, v168
	s_waitcnt vmcnt(2)
	ds_write_b32 v156, v169
	s_waitcnt vmcnt(1)
	ds_write_b32 v158, v170
	s_waitcnt vmcnt(0)
	ds_write_b32 v160, v171
	s_add_i32 s5, s5, 16
	s_add_i32 s4, s4, 16
	s_add_i32 s13, s13, -16
	s_add_i32 s13, s13, -16
	s_cmp_lg_u32 s13, 0
	s_waitcnt lgkmcnt(0)
	ds_read2_b32 v[54:55], v5 offset1:8
	ds_read2_b32 v[58:59], v5 offset0:33 offset1:41
	ds_read2_b32 v[60:61], v5 offset0:66 offset1:74
	ds_read2_b32 v[62:63], v5 offset0:99 offset1:107
	ds_read2_b32 v[64:65], v5 offset0:132 offset1:140
	s_waitcnt lgkmcnt(4)
	v_bfe_u32 v7, v54, 16, 1
	v_add3_u32 v7, v54, v7, s33
	s_waitcnt lgkmcnt(3)
	v_bfe_u32 v9, v58, 16, 1
	v_lshrrev_b32_e32 v7, 16, v7
	v_add3_u32 v9, v58, v9, s33
	ds_read2_b32 v[66:67], v5 offset0:165 offset1:173
	v_and_or_b32 v50, v9, s69, v7
	s_waitcnt lgkmcnt(3)
	v_bfe_u32 v7, v60, 16, 1
	v_add3_u32 v7, v60, v7, s33
	s_waitcnt lgkmcnt(2)
	v_bfe_u32 v9, v62, 16, 1
	ds_read2_b32 v[68:69], v5 offset0:198 offset1:206
	v_lshrrev_b32_e32 v7, 16, v7
	v_add3_u32 v9, v62, v9, s33
	ds_read2_b32 v[70:71], v5 offset0:231 offset1:239
	v_and_or_b32 v51, v9, s69, v7
	s_waitcnt lgkmcnt(3)
	v_bfe_u32 v7, v64, 16, 1
	s_lshl_b64 s[4:5], s[14:15], 11
	v_add3_u32 v7, v64, v7, s33
	s_waitcnt lgkmcnt(2)
	v_bfe_u32 v9, v66, 16, 1
	s_add_u32 s1, s35, s4
	v_lshrrev_b32_e32 v7, 16, v7
	v_add3_u32 v9, v66, v9, s33
	s_addc_u32 s14, s38, s5
	s_ashr_i32 s13, s12, 31
	v_and_or_b32 v52, v9, s69, v7
	s_waitcnt lgkmcnt(1)
	v_bfe_u32 v7, v68, 16, 1
	s_lshl_b64 s[4:5], s[12:13], 1
	v_add3_u32 v7, v68, v7, s33
	s_waitcnt lgkmcnt(0)
	v_bfe_u32 v9, v70, 16, 1
	s_add_u32 s4, s1, s4
	v_lshrrev_b32_e32 v7, 16, v7
	v_add3_u32 v9, v70, v9, s33
	s_addc_u32 s5, s14, s5
	v_lshlrev_b32_e32 v128, 1, v6
	v_and_or_b32 v53, v9, s69, v7
	v_bfe_u32 v7, v55, 16, 1
	v_lshl_add_u64 v[56:57], s[4:5], 0, v[128:129]
	v_lshlrev_b32_e32 v128, 1, v8
	v_add3_u32 v7, v55, v7, s33
	v_bfe_u32 v9, v59, 16, 1
	v_lshl_add_u64 v[72:73], v[56:57], 0, v[128:129]
	v_lshrrev_b32_e32 v7, 16, v7
	v_add3_u32 v9, v59, v9, s33
	global_store_dwordx4 v[72:73], v[50:53], off
	v_lshlrev_b32_e32 v128, 1, v10
	ds_read2_b32 v[54:55], v5 offset0:16 offset1:24
	v_and_or_b32 v50, v9, s69, v7
	v_bfe_u32 v7, v61, 16, 1
	v_add3_u32 v7, v61, v7, s33
	v_bfe_u32 v9, v63, 16, 1
	v_lshrrev_b32_e32 v7, 16, v7
	v_add3_u32 v9, v63, v9, s33
	v_and_or_b32 v51, v9, s69, v7
	v_bfe_u32 v7, v65, 16, 1
	v_add3_u32 v7, v65, v7, s33
	v_bfe_u32 v9, v67, 16, 1
	v_lshrrev_b32_e32 v7, 16, v7
	v_add3_u32 v9, v67, v9, s33
	v_and_or_b32 v52, v9, s69, v7
	v_bfe_u32 v7, v69, 16, 1
	v_add3_u32 v7, v69, v7, s33
	v_bfe_u32 v9, v71, 16, 1
	v_lshrrev_b32_e32 v7, 16, v7
	v_add3_u32 v9, v71, v9, s33
	v_and_or_b32 v53, v9, s69, v7
	v_lshl_add_u64 v[58:59], v[56:57], 0, v[128:129]
	global_store_dwordx4 v[58:59], v[50:53], off
	ds_read2_b32 v[58:59], v5 offset0:49 offset1:57
	ds_read2_b32 v[60:61], v5 offset0:82 offset1:90
	ds_read2_b32 v[62:63], v5 offset0:115 offset1:123
	s_waitcnt lgkmcnt(3)
	v_bfe_u32 v7, v54, 16, 1
	v_add3_u32 v7, v54, v7, s33
	s_waitcnt lgkmcnt(2)
	v_bfe_u32 v9, v58, 16, 1
	ds_read2_b32 v[64:65], v5 offset0:148 offset1:156
	v_lshrrev_b32_e32 v7, 16, v7
	v_add3_u32 v9, v58, v9, s33
	ds_read2_b32 v[66:67], v5 offset0:181 offset1:189
	v_and_or_b32 v50, v9, s69, v7
	s_waitcnt lgkmcnt(3)
	v_bfe_u32 v7, v60, 16, 1
	v_add3_u32 v7, v60, v7, s33
	s_waitcnt lgkmcnt(2)
	v_bfe_u32 v9, v62, 16, 1
	ds_read2_b32 v[68:69], v5 offset0:214 offset1:222
	v_lshrrev_b32_e32 v7, 16, v7
	v_add3_u32 v9, v62, v9, s33
	ds_read2_b32 v[70:71], v5 offset0:247 offset1:255
	v_and_or_b32 v51, v9, s69, v7
	s_waitcnt lgkmcnt(3)
	v_bfe_u32 v7, v64, 16, 1
	v_add3_u32 v7, v64, v7, s33
	s_waitcnt lgkmcnt(2)
	v_bfe_u32 v9, v66, 16, 1
	v_lshrrev_b32_e32 v7, 16, v7
	v_add3_u32 v9, v66, v9, s33
	v_and_or_b32 v52, v9, s69, v7
	s_waitcnt lgkmcnt(1)
	v_bfe_u32 v7, v68, 16, 1
	v_add3_u32 v7, v68, v7, s33
	s_waitcnt lgkmcnt(0)
	v_bfe_u32 v9, v70, 16, 1
	v_lshrrev_b32_e32 v7, 16, v7
	v_add3_u32 v9, v70, v9, s33
	v_and_or_b32 v53, v9, s69, v7
	v_bfe_u32 v7, v55, 16, 1
	v_lshlrev_b32_e32 v128, 1, v12
	v_add3_u32 v7, v55, v7, s33
	v_bfe_u32 v9, v59, 16, 1
	v_lshl_add_u64 v[72:73], v[56:57], 0, v[128:129]
	v_lshrrev_b32_e32 v7, 16, v7
	v_add3_u32 v9, v59, v9, s33
	global_store_dwordx4 v[72:73], v[50:53], off
	v_lshlrev_b32_e32 v128, 1, v14
	v_lshl_add_u64 v[54:55], v[56:57], 0, v[128:129]
	v_and_or_b32 v50, v9, s69, v7
	v_bfe_u32 v7, v61, 16, 1
	v_add3_u32 v7, v61, v7, s33
	v_bfe_u32 v9, v63, 16, 1
	v_lshrrev_b32_e32 v7, 16, v7
	v_add3_u32 v9, v63, v9, s33
	v_and_or_b32 v51, v9, s69, v7
	v_bfe_u32 v7, v65, 16, 1
	v_add3_u32 v7, v65, v7, s33
	v_bfe_u32 v9, v67, 16, 1
	v_lshrrev_b32_e32 v7, 16, v7
	v_add3_u32 v9, v67, v9, s33
	v_and_or_b32 v52, v9, s69, v7
	v_bfe_u32 v7, v69, 16, 1
	v_add3_u32 v7, v69, v7, s33
	v_bfe_u32 v9, v71, 16, 1
	v_lshrrev_b32_e32 v7, 16, v7
	v_add3_u32 v9, v71, v9, s33
	v_and_or_b32 v53, v9, s69, v7
	global_store_dwordx4 v[54:55], v[50:53], off
	s_waitcnt lgkmcnt(0)
	s_mov_b32 s1, s0
	s_andn2_b64 vcc, exec, s[10:11]
	s_mov_b64 s[10:11], -1
	s_cbranch_vccnz .LBB0_744

.LBB0_731:
	s_lshl_b32 s15, s4, 1
	s_lshl_b32 s22, s5, 1
	v_or_b32_e32 v7, s15, v1
	v_or_b32_e32 v9, s22, v0
	s_add_i32 s23, s15, 4
	s_add_i32 s24, s22, 4
	s_add_i32 s25, s15, 8
	s_add_i32 s26, s22, 8
	s_add_i32 s27, s15, 12
	s_add_i32 s30, s22, 12
	s_add_i32 s36, s15, 16
	s_add_i32 s37, s22, 16
	s_add_i32 s40, s15, 20
	s_add_i32 s41, s22, 20
	s_add_i32 s42, s15, 24
	s_add_i32 s43, s22, 24
	s_add_i32 s15, s15, 28
	s_add_i32 s22, s22, 28
	v_add_u32_e32 v11, s0, v7
	v_add_u32_e32 v13, s12, v9
	v_or_b32_e32 v15, s23, v1
	v_or_b32_e32 v19, s24, v0
	v_or_b32_e32 v41, s25, v1
	v_or_b32_e32 v43, s26, v0
	v_or_b32_e32 v45, s27, v1
	v_or_b32_e32 v47, s30, v0
	v_or_b32_e32 v49, s36, v1
	v_or_b32_e32 v82, s37, v0
	v_or_b32_e32 v86, s40, v1
	v_or_b32_e32 v87, s41, v0
	v_or_b32_e32 v88, s42, v1
	v_or_b32_e32 v89, s43, v0
	v_or_b32_e32 v90, s15, v1
	v_or_b32_e32 v91, s22, v0
	v_mad_i64_i32 v[52:53], s[22:23], v13, s68, v[50:51]
	v_mad_i64_i32 v[54:55], s[22:23], v11, s68, v[50:51]
	v_add_u32_e32 v11, s0, v15
	v_add_u32_e32 v13, s12, v19
	v_add_u32_e32 v62, s0, v41
	v_add_u32_e32 v60, s12, v43
	v_add_u32_e32 v66, s0, v45
	v_add_u32_e32 v64, s12, v47
	v_add_u32_e32 v70, s0, v49
	v_add_u32_e32 v68, s12, v82
	v_add_u32_e32 v74, s0, v86
	v_add_u32_e32 v72, s12, v87
	v_add_u32_e32 v78, s0, v88
	v_add_u32_e32 v76, s12, v89
	v_add_u32_e32 v84, s0, v90
	v_add_u32_e32 v80, s12, v91
	v_mad_i64_i32 v[56:57], s[22:23], v13, s68, v[50:51]
	v_mad_i64_i32 v[58:59], s[22:23], v11, s68, v[50:51]
	v_mad_i64_i32 v[60:61], s[22:23], v60, s68, v[50:51]
	v_mad_i64_i32 v[62:63], s[22:23], v62, s68, v[50:51]
	v_mad_i64_i32 v[64:65], s[22:23], v64, s68, v[50:51]
	v_mad_i64_i32 v[66:67], s[22:23], v66, s68, v[50:51]
	v_mad_i64_i32 v[68:69], s[22:23], v68, s68, v[50:51]
	v_mad_i64_i32 v[70:71], s[22:23], v70, s68, v[50:51]
	v_mad_i64_i32 v[72:73], s[22:23], v72, s68, v[50:51]
	v_mad_i64_i32 v[74:75], s[22:23], v74, s68, v[50:51]
	v_mad_i64_i32 v[76:77], s[22:23], v76, s68, v[50:51]
	v_mad_i64_i32 v[78:79], s[22:23], v78, s68, v[50:51]
	v_mad_i64_i32 v[80:81], s[22:23], v80, s68, v[50:51]
	v_mad_i64_i32 v[84:85], s[22:23], v84, s68, v[50:51]
	global_load_dword v11, v[52:53], off
	global_load_dword v13, v[54:55], off
	global_load_dword v92, v[56:57], off
	global_load_dword v93, v[58:59], off
	global_load_dword v94, v[60:61], off
	global_load_dword v95, v[62:63], off
	global_load_dword v96, v[64:65], off
	global_load_dword v97, v[66:67], off
	global_load_dword v98, v[68:69], off
	global_load_dword v99, v[70:71], off
	global_load_dword v100, v[72:73], off
	global_load_dword v101, v[74:75], off
	global_load_dword v102, v[76:77], off
	global_load_dword v103, v[78:79], off
	global_load_dword v104, v[80:81], off
	global_load_dword v105, v[84:85], off
	s_add_i32 s5, s5, 16
	s_add_i32 s4, s4, 16
	s_lshl_b32 s15, s4, 1
	s_lshl_b32 s22, s5, 1
	v_or_b32_e32 v106, s15, v1
	v_or_b32_e32 v107, s22, v0
	s_add_i32 s23, s15, 4
	s_add_i32 s24, s22, 4
	s_add_i32 s25, s15, 8
	s_add_i32 s26, s22, 8
	s_add_i32 s27, s15, 12
	s_add_i32 s30, s22, 12
	s_add_i32 s36, s15, 16
	s_add_i32 s37, s22, 16
	s_add_i32 s40, s15, 20
	s_add_i32 s41, s22, 20
	s_add_i32 s42, s15, 24
	s_add_i32 s43, s22, 24
	s_add_i32 s15, s15, 28
	s_add_i32 s22, s22, 28
	v_add_u32_e32 v108, s0, v106
	v_add_u32_e32 v109, s12, v107
	v_or_b32_e32 v110, s23, v1
	v_or_b32_e32 v111, s24, v0
	v_or_b32_e32 v112, s25, v1
	v_or_b32_e32 v113, s26, v0
	v_or_b32_e32 v114, s27, v1
	v_or_b32_e32 v115, s30, v0
	v_or_b32_e32 v116, s36, v1
	v_or_b32_e32 v117, s37, v0
	v_or_b32_e32 v118, s40, v1
	v_or_b32_e32 v119, s41, v0
	v_or_b32_e32 v120, s42, v1
	v_or_b32_e32 v121, s43, v0
	v_or_b32_e32 v122, s15, v1
	v_or_b32_e32 v123, s22, v0
	v_mad_i64_i32 v[130:131], s[22:23], v109, s68, v[50:51]
	v_mad_i64_i32 v[132:133], s[22:23], v108, s68, v[50:51]
	v_add_u32_e32 v108, s0, v110
	v_add_u32_e32 v109, s12, v111
	v_add_u32_e32 v140, s0, v112
	v_add_u32_e32 v138, s12, v113
	v_add_u32_e32 v144, s0, v114
	v_add_u32_e32 v142, s12, v115
	v_add_u32_e32 v148, s0, v116
	v_add_u32_e32 v146, s12, v117
	v_add_u32_e32 v152, s0, v118
	v_add_u32_e32 v150, s12, v119
	v_add_u32_e32 v156, s0, v120
	v_add_u32_e32 v154, s12, v121
	v_add_u32_e32 v160, s0, v122
	v_add_u32_e32 v158, s12, v123
	v_mad_i64_i32 v[134:135], s[22:23], v109, s68, v[50:51]
	v_mad_i64_i32 v[136:137], s[22:23], v108, s68, v[50:51]
	v_mad_i64_i32 v[138:139], s[22:23], v138, s68, v[50:51]
	v_mad_i64_i32 v[140:141], s[22:23], v140, s68, v[50:51]
	v_mad_i64_i32 v[142:143], s[22:23], v142, s68, v[50:51]
	v_mad_i64_i32 v[144:145], s[22:23], v144, s68, v[50:51]
	v_mad_i64_i32 v[146:147], s[22:23], v146, s68, v[50:51]
	v_mad_i64_i32 v[148:149], s[22:23], v148, s68, v[50:51]
	v_mad_i64_i32 v[150:151], s[22:23], v150, s68, v[50:51]
	v_mad_i64_i32 v[152:153], s[22:23], v152, s68, v[50:51]
	v_mad_i64_i32 v[154:155], s[22:23], v154, s68, v[50:51]
	v_mad_i64_i32 v[156:157], s[22:23], v156, s68, v[50:51]
	v_mad_i64_i32 v[158:159], s[22:23], v158, s68, v[50:51]
	v_mad_i64_i32 v[160:161], s[22:23], v160, s68, v[50:51]
	global_load_dword v108, v[130:131], off
	global_load_dword v109, v[132:133], off
	global_load_dword v124, v[134:135], off
	global_load_dword v125, v[136:137], off
	global_load_dword v126, v[138:139], off
	global_load_dword v127, v[140:141], off
	global_load_dword v162, v[142:143], off
	global_load_dword v163, v[144:145], off
	global_load_dword v164, v[146:147], off
	global_load_dword v165, v[148:149], off
	global_load_dword v166, v[150:151], off
	global_load_dword v167, v[152:153], off
	global_load_dword v168, v[154:155], off
	global_load_dword v169, v[156:157], off
	global_load_dword v170, v[158:159], off
	global_load_dword v171, v[160:161], off
	v_mad_u64_u32 v[52:53], s[22:23], v9, s78, v[4:5]
	v_mad_u64_u32 v[54:55], s[22:23], v7, s78, v[4:5]
	v_mad_u64_u32 v[56:57], s[22:23], v19, s78, v[4:5]
	v_mad_u64_u32 v[58:59], s[22:23], v15, s78, v[4:5]
	v_mad_u64_u32 v[60:61], s[22:23], v43, s78, v[4:5]
	v_mad_u64_u32 v[62:63], s[22:23], v41, s78, v[4:5]
	v_mad_u64_u32 v[64:65], s[22:23], v47, s78, v[4:5]
	v_mad_u64_u32 v[66:67], s[22:23], v45, s78, v[4:5]
	v_mad_u64_u32 v[68:69], s[22:23], v82, s78, v[4:5]
	v_mad_u64_u32 v[70:71], s[22:23], v49, s78, v[4:5]
	v_mad_u64_u32 v[72:73], s[22:23], v87, s78, v[4:5]
	v_mad_u64_u32 v[74:75], s[22:23], v86, s78, v[4:5]
	v_mad_u64_u32 v[76:77], s[22:23], v89, s78, v[4:5]
	v_mad_u64_u32 v[78:79], s[22:23], v88, s78, v[4:5]
	v_mad_u64_u32 v[80:81], s[22:23], v91, s78, v[4:5]
	v_mad_u64_u32 v[84:85], s[22:23], v90, s78, v[4:5]
	s_waitcnt vmcnt(31)
	ds_write_b32 v52, v11
	s_waitcnt vmcnt(30)
	ds_write_b32 v54, v13
	s_waitcnt vmcnt(29)
	ds_write_b32 v56, v92
	s_waitcnt vmcnt(28)
	ds_write_b32 v58, v93
	s_waitcnt vmcnt(27)
	ds_write_b32 v60, v94
	s_waitcnt vmcnt(26)
	ds_write_b32 v62, v95
	s_waitcnt vmcnt(25)
	ds_write_b32 v64, v96
	s_waitcnt vmcnt(24)
	ds_write_b32 v66, v97
	s_waitcnt vmcnt(23)
	ds_write_b32 v68, v98
	s_waitcnt vmcnt(22)
	ds_write_b32 v70, v99
	s_waitcnt vmcnt(21)
	ds_write_b32 v72, v100
	s_waitcnt vmcnt(20)
	ds_write_b32 v74, v101
	s_waitcnt vmcnt(19)
	ds_write_b32 v76, v102
	s_waitcnt vmcnt(18)
	ds_write_b32 v78, v103
	s_waitcnt vmcnt(17)
	ds_write_b32 v80, v104
	s_waitcnt vmcnt(16)
	ds_write_b32 v84, v105
	v_mad_u64_u32 v[130:131], s[22:23], v107, s78, v[4:5]
	v_mad_u64_u32 v[132:133], s[22:23], v106, s78, v[4:5]
	v_mad_u64_u32 v[134:135], s[22:23], v111, s78, v[4:5]
	v_mad_u64_u32 v[136:137], s[22:23], v110, s78, v[4:5]
	v_mad_u64_u32 v[138:139], s[22:23], v113, s78, v[4:5]
	v_mad_u64_u32 v[140:141], s[22:23], v112, s78, v[4:5]
	v_mad_u64_u32 v[142:143], s[22:23], v115, s78, v[4:5]
	v_mad_u64_u32 v[144:145], s[22:23], v114, s78, v[4:5]
	v_mad_u64_u32 v[146:147], s[22:23], v117, s78, v[4:5]
	v_mad_u64_u32 v[148:149], s[22:23], v116, s78, v[4:5]
	v_mad_u64_u32 v[150:151], s[22:23], v119, s78, v[4:5]
	v_mad_u64_u32 v[152:153], s[22:23], v118, s78, v[4:5]
	v_mad_u64_u32 v[154:155], s[22:23], v121, s78, v[4:5]
	v_mad_u64_u32 v[156:157], s[22:23], v120, s78, v[4:5]
	v_mad_u64_u32 v[158:159], s[22:23], v123, s78, v[4:5]
	v_mad_u64_u32 v[160:161], s[22:23], v122, s78, v[4:5]
	s_waitcnt vmcnt(15)
	ds_write_b32 v130, v108
	s_waitcnt vmcnt(14)
	ds_write_b32 v132, v109
	s_waitcnt vmcnt(13)
	ds_write_b32 v134, v124
	s_waitcnt vmcnt(12)
	ds_write_b32 v136, v125
	s_waitcnt vmcnt(11)
	ds_write_b32 v138, v126
	s_waitcnt vmcnt(10)
	ds_write_b32 v140, v127
	s_waitcnt vmcnt(9)
	ds_write_b32 v142, v162
	s_waitcnt vmcnt(8)
	ds_write_b32 v144, v163
	s_waitcnt vmcnt(7)
	ds_write_b32 v146, v164
	s_waitcnt vmcnt(6)
	ds_write_b32 v148, v165
	s_waitcnt vmcnt(5)
	ds_write_b32 v150, v166
	s_waitcnt vmcnt(4)
	ds_write_b32 v152, v167
	s_waitcnt vmcnt(3)
	ds_write_b32 v154, v168
	s_waitcnt vmcnt(2)
	ds_write_b32 v156, v169
	s_waitcnt vmcnt(1)
	ds_write_b32 v158, v170
	s_waitcnt vmcnt(0)
	ds_write_b32 v160, v171
	s_add_i32 s5, s5, 16
	s_add_i32 s4, s4, 16
	s_add_i32 s13, s13, -16
	s_add_i32 s13, s13, -16
	s_cmp_lg_u32 s13, 0
	s_waitcnt lgkmcnt(0)
	ds_read2_b32 v[54:55], v5 offset1:8
	ds_read2_b32 v[58:59], v5 offset0:33 offset1:41
	ds_read2_b32 v[60:61], v5 offset0:66 offset1:74
	ds_read2_b32 v[62:63], v5 offset0:99 offset1:107
	ds_read2_b32 v[64:65], v5 offset0:132 offset1:140
	s_waitcnt lgkmcnt(4)
	v_bfe_u32 v7, v54, 16, 1
	v_add3_u32 v7, v54, v7, s33
	s_waitcnt lgkmcnt(3)
	v_bfe_u32 v9, v58, 16, 1
	v_lshrrev_b32_e32 v7, 16, v7
	v_add3_u32 v9, v58, v9, s33
	ds_read2_b32 v[66:67], v5 offset0:165 offset1:173
	v_and_or_b32 v50, v9, s69, v7
	s_waitcnt lgkmcnt(3)
	v_bfe_u32 v7, v60, 16, 1
	v_add3_u32 v7, v60, v7, s33
	s_waitcnt lgkmcnt(2)
	v_bfe_u32 v9, v62, 16, 1
	ds_read2_b32 v[68:69], v5 offset0:198 offset1:206
	v_lshrrev_b32_e32 v7, 16, v7
	v_add3_u32 v9, v62, v9, s33
	ds_read2_b32 v[70:71], v5 offset0:231 offset1:239
	v_and_or_b32 v51, v9, s69, v7
	s_waitcnt lgkmcnt(3)
	v_bfe_u32 v7, v64, 16, 1
	s_mul_i32 s4, s14, 0x300
	v_add3_u32 v7, v64, v7, s33
	s_waitcnt lgkmcnt(2)
	v_bfe_u32 v9, v66, 16, 1
	s_mul_hi_i32 s0, s14, 0x300
	s_add_u32 s14, s49, s4
	v_lshrrev_b32_e32 v7, 16, v7
	v_add3_u32 v9, v66, v9, s33
	s_addc_u32 s0, s50, s0
	s_ashr_i32 s13, s12, 31
	v_and_or_b32 v52, v9, s69, v7
	s_waitcnt lgkmcnt(1)
	v_bfe_u32 v7, v68, 16, 1
	s_lshl_b64 s[4:5], s[12:13], 1
	v_add3_u32 v7, v68, v7, s33
	s_waitcnt lgkmcnt(0)
	v_bfe_u32 v9, v70, 16, 1
	s_add_u32 s4, s14, s4
	v_lshrrev_b32_e32 v7, 16, v7
	v_add3_u32 v9, v70, v9, s33
	s_addc_u32 s5, s0, s5
	v_lshlrev_b32_e32 v128, 1, v6
	v_and_or_b32 v53, v9, s69, v7
	v_bfe_u32 v7, v55, 16, 1
	v_lshl_add_u64 v[56:57], s[4:5], 0, v[128:129]
	v_mov_b32_e32 v41, v129
	v_add3_u32 v7, v55, v7, s33
	v_bfe_u32 v9, v59, 16, 1
	v_lshl_add_u64 v[56:57], v[56:57], 0, v[40:41]
	v_lshrrev_b32_e32 v7, 16, v7
	v_add3_u32 v9, v59, v9, s33
	global_store_dwordx4 v[56:57], v[50:53], off
	s_movk_i32 s0, 0x1000
	v_add_co_u32_e32 v58, vcc, s0, v56
	v_and_or_b32 v50, v9, s69, v7
	v_bfe_u32 v7, v61, 16, 1
	v_add3_u32 v7, v61, v7, s33
	v_bfe_u32 v9, v63, 16, 1
	v_lshrrev_b32_e32 v7, 16, v7
	v_add3_u32 v9, v63, v9, s33
	v_and_or_b32 v51, v9, s69, v7
	v_bfe_u32 v7, v65, 16, 1
	v_add3_u32 v7, v65, v7, s33
	v_bfe_u32 v9, v67, 16, 1
	v_lshrrev_b32_e32 v7, 16, v7
	v_add3_u32 v9, v67, v9, s33
	v_and_or_b32 v52, v9, s69, v7
	v_bfe_u32 v7, v69, 16, 1
	v_add3_u32 v7, v69, v7, s33
	v_bfe_u32 v9, v71, 16, 1
	v_lshrrev_b32_e32 v7, 16, v7
	v_add3_u32 v9, v71, v9, s33
	v_and_or_b32 v53, v9, s69, v7
	ds_read2_b32 v[54:55], v5 offset0:16 offset1:24
	v_addc_co_u32_e32 v59, vcc, 0, v57, vcc
	global_store_dwordx4 v[58:59], v[50:53], off offset:2048
	ds_read2_b32 v[58:59], v5 offset0:49 offset1:57
	ds_read2_b32 v[60:61], v5 offset0:82 offset1:90
	ds_read2_b32 v[62:63], v5 offset0:115 offset1:123
	s_waitcnt lgkmcnt(3)
	v_bfe_u32 v7, v54, 16, 1
	v_add3_u32 v7, v54, v7, s33
	s_waitcnt lgkmcnt(2)
	v_bfe_u32 v9, v58, 16, 1
	ds_read2_b32 v[64:65], v5 offset0:148 offset1:156
	v_lshrrev_b32_e32 v7, 16, v7
	v_add3_u32 v9, v58, v9, s33
	ds_read2_b32 v[66:67], v5 offset0:181 offset1:189
	v_and_or_b32 v50, v9, s69, v7
	s_waitcnt lgkmcnt(3)
	v_bfe_u32 v7, v60, 16, 1
	v_add3_u32 v7, v60, v7, s33
	s_waitcnt lgkmcnt(2)
	v_bfe_u32 v9, v62, 16, 1
	ds_read2_b32 v[68:69], v5 offset0:214 offset1:222
	v_lshrrev_b32_e32 v7, 16, v7
	v_add3_u32 v9, v62, v9, s33
	ds_read2_b32 v[70:71], v5 offset0:247 offset1:255
	v_and_or_b32 v51, v9, s69, v7
	s_waitcnt lgkmcnt(3)
	v_bfe_u32 v7, v64, 16, 1
	v_add3_u32 v7, v64, v7, s33
	s_waitcnt lgkmcnt(2)
	v_bfe_u32 v9, v66, 16, 1
	v_lshrrev_b32_e32 v7, 16, v7
	v_add3_u32 v9, v66, v9, s33
	v_and_or_b32 v52, v9, s69, v7
	s_waitcnt lgkmcnt(1)
	v_bfe_u32 v7, v68, 16, 1
	v_add3_u32 v7, v68, v7, s33
	s_waitcnt lgkmcnt(0)
	v_bfe_u32 v9, v70, 16, 1
	v_lshrrev_b32_e32 v7, 16, v7
	v_add3_u32 v9, v70, v9, s33
	v_and_or_b32 v53, v9, s69, v7
	s_movk_i32 s0, 0x3000
	v_bfe_u32 v7, v55, 16, 1
	v_add_co_u32_e32 v72, vcc, s0, v56
	v_add3_u32 v7, v55, v7, s33
	v_bfe_u32 v9, v59, 16, 1
	v_addc_co_u32_e32 v73, vcc, 0, v57, vcc
	v_lshrrev_b32_e32 v7, 16, v7
	v_add3_u32 v9, v59, v9, s33
	global_store_dwordx4 v[72:73], v[50:53], off
	v_add_co_u32_e32 v54, vcc, 0x4000, v56
	s_nop 0
	v_and_or_b32 v50, v9, s69, v7
	v_bfe_u32 v7, v61, 16, 1
	v_add3_u32 v7, v61, v7, s33
	v_bfe_u32 v9, v63, 16, 1
	v_lshrrev_b32_e32 v7, 16, v7
	v_add3_u32 v9, v63, v9, s33
	v_and_or_b32 v51, v9, s69, v7
	v_bfe_u32 v7, v65, 16, 1
	v_add3_u32 v7, v65, v7, s33
	v_bfe_u32 v9, v67, 16, 1
	v_lshrrev_b32_e32 v7, 16, v7
	v_add3_u32 v9, v67, v9, s33
	v_and_or_b32 v52, v9, s69, v7
	v_bfe_u32 v7, v69, 16, 1
	v_add3_u32 v7, v69, v7, s33
	v_bfe_u32 v9, v71, 16, 1
	v_lshrrev_b32_e32 v7, 16, v7
	v_add3_u32 v9, v71, v9, s33
	v_and_or_b32 v53, v9, s69, v7
	v_addc_co_u32_e32 v55, vcc, 0, v57, vcc
	global_store_dwordx4 v[54:55], v[50:53], off offset:2048
	s_waitcnt lgkmcnt(0)
	s_mov_b32 s0, s1
	s_andn2_b64 vcc, exec, s[10:11]
	s_mov_b64 s[10:11], -1
	s_cbranch_vccnz .LBB0_744

.LBB0_738:
	s_lshl_b32 s22, s5, 1
	s_lshl_b32 s23, s13, 1
	v_or_b32_e32 v7, s22, v1
	v_or_b32_e32 v9, s23, v0
	s_add_i32 s24, s22, 4
	s_add_i32 s25, s23, 4
	s_add_i32 s26, s22, 8
	s_add_i32 s27, s23, 8
	s_add_i32 s30, s22, 12
	s_add_i32 s36, s23, 12
	s_add_i32 s37, s22, 16
	s_add_i32 s40, s23, 16
	s_add_i32 s41, s22, 20
	s_add_i32 s42, s23, 20
	s_add_i32 s43, s22, 24
	s_add_i32 s52, s23, 24
	s_add_i32 s22, s22, 28
	s_add_i32 s23, s23, 28
	v_add_u32_e32 v54, s12, v9
	v_or_b32_e32 v11, s24, v1
	v_or_b32_e32 v13, s25, v0
	v_or_b32_e32 v15, s26, v1
	v_or_b32_e32 v19, s27, v0
	v_or_b32_e32 v41, s30, v1
	v_or_b32_e32 v43, s36, v0
	v_or_b32_e32 v45, s37, v1
	v_or_b32_e32 v47, s40, v0
	v_or_b32_e32 v49, s41, v1
	v_or_b32_e32 v82, s42, v0
	v_or_b32_e32 v86, s43, v1
	v_or_b32_e32 v87, s52, v0
	v_or_b32_e32 v88, s22, v1
	v_or_b32_e32 v89, s23, v0
	v_add_u32_e32 v52, s4, v7
	v_ashrrev_i32_e32 v55, 31, v54
	v_add_u32_e32 v56, s4, v11
	v_add_u32_e32 v58, s12, v13
	v_add_u32_e32 v60, s4, v15
	v_add_u32_e32 v62, s12, v19
	v_add_u32_e32 v64, s4, v41
	v_add_u32_e32 v66, s12, v43
	v_add_u32_e32 v68, s4, v45
	v_add_u32_e32 v70, s12, v47
	v_add_u32_e32 v72, s4, v49
	v_add_u32_e32 v74, s12, v82
	v_add_u32_e32 v76, s4, v86
	v_add_u32_e32 v78, s12, v87
	v_add_u32_e32 v80, s4, v88
	v_add_u32_e32 v84, s12, v89
	v_ashrrev_i32_e32 v53, 31, v52
	v_lshlrev_b64 v[54:55], 13, v[54:55]
	v_ashrrev_i32_e32 v59, 31, v58
	v_ashrrev_i32_e32 v57, 31, v56
	v_ashrrev_i32_e32 v63, 31, v62
	v_ashrrev_i32_e32 v61, 31, v60
	v_ashrrev_i32_e32 v67, 31, v66
	v_ashrrev_i32_e32 v65, 31, v64
	v_ashrrev_i32_e32 v71, 31, v70
	v_ashrrev_i32_e32 v69, 31, v68
	v_ashrrev_i32_e32 v75, 31, v74
	v_ashrrev_i32_e32 v73, 31, v72
	v_ashrrev_i32_e32 v79, 31, v78
	v_ashrrev_i32_e32 v77, 31, v76
	v_ashrrev_i32_e32 v85, 31, v84
	v_ashrrev_i32_e32 v81, 31, v80
	v_lshlrev_b64 v[52:53], 13, v[52:53]
	v_lshl_add_u64 v[54:55], v[50:51], 0, v[54:55]
	v_lshlrev_b64 v[56:57], 13, v[56:57]
	v_lshlrev_b64 v[58:59], 13, v[58:59]
	v_lshlrev_b64 v[60:61], 13, v[60:61]
	v_lshlrev_b64 v[62:63], 13, v[62:63]
	v_lshlrev_b64 v[64:65], 13, v[64:65]
	v_lshlrev_b64 v[66:67], 13, v[66:67]
	v_lshlrev_b64 v[68:69], 13, v[68:69]
	v_lshlrev_b64 v[70:71], 13, v[70:71]
	v_lshlrev_b64 v[72:73], 13, v[72:73]
	v_lshlrev_b64 v[74:75], 13, v[74:75]
	v_lshlrev_b64 v[76:77], 13, v[76:77]
	v_lshlrev_b64 v[78:79], 13, v[78:79]
	v_lshlrev_b64 v[80:81], 13, v[80:81]
	v_lshlrev_b64 v[84:85], 13, v[84:85]
	v_lshl_add_u64 v[52:53], v[50:51], 0, v[52:53]
	v_lshl_add_u64 v[58:59], v[50:51], 0, v[58:59]
	v_lshl_add_u64 v[56:57], v[50:51], 0, v[56:57]
	v_lshl_add_u64 v[62:63], v[50:51], 0, v[62:63]
	v_lshl_add_u64 v[60:61], v[50:51], 0, v[60:61]
	v_lshl_add_u64 v[66:67], v[50:51], 0, v[66:67]
	v_lshl_add_u64 v[64:65], v[50:51], 0, v[64:65]
	v_lshl_add_u64 v[70:71], v[50:51], 0, v[70:71]
	v_lshl_add_u64 v[68:69], v[50:51], 0, v[68:69]
	v_lshl_add_u64 v[74:75], v[50:51], 0, v[74:75]
	v_lshl_add_u64 v[72:73], v[50:51], 0, v[72:73]
	v_lshl_add_u64 v[78:79], v[50:51], 0, v[78:79]
	v_lshl_add_u64 v[76:77], v[50:51], 0, v[76:77]
	v_lshl_add_u64 v[84:85], v[50:51], 0, v[84:85]
	v_lshl_add_u64 v[80:81], v[50:51], 0, v[80:81]
	global_load_dword v90, v[54:55], off
	global_load_dword v91, v[52:53], off
	global_load_dword v92, v[58:59], off
	global_load_dword v93, v[56:57], off
	global_load_dword v94, v[62:63], off
	global_load_dword v95, v[60:61], off
	global_load_dword v96, v[66:67], off
	global_load_dword v97, v[64:65], off
	global_load_dword v98, v[70:71], off
	global_load_dword v99, v[68:69], off
	global_load_dword v100, v[74:75], off
	global_load_dword v101, v[72:73], off
	global_load_dword v102, v[78:79], off
	global_load_dword v103, v[76:77], off
	global_load_dword v104, v[84:85], off
	global_load_dword v105, v[80:81], off
	s_add_i32 s13, s13, 16
	s_add_i32 s5, s5, 16
	s_lshl_b32 s22, s5, 1
	s_lshl_b32 s23, s13, 1
	v_or_b32_e32 v106, s22, v1
	v_or_b32_e32 v107, s23, v0
	s_add_i32 s24, s22, 4
	s_add_i32 s25, s23, 4
	s_add_i32 s26, s22, 8
	s_add_i32 s27, s23, 8
	s_add_i32 s30, s22, 12
	s_add_i32 s36, s23, 12
	s_add_i32 s37, s22, 16
	s_add_i32 s40, s23, 16
	s_add_i32 s41, s22, 20
	s_add_i32 s42, s23, 20
	s_add_i32 s43, s22, 24
	s_add_i32 s52, s23, 24
	s_add_i32 s22, s22, 28
	s_add_i32 s23, s23, 28
	v_add_u32_e32 v132, s12, v107
	v_or_b32_e32 v108, s24, v1
	v_or_b32_e32 v109, s25, v0
	v_or_b32_e32 v110, s26, v1
	v_or_b32_e32 v111, s27, v0
	v_or_b32_e32 v112, s30, v1
	v_or_b32_e32 v113, s36, v0
	v_or_b32_e32 v114, s37, v1
	v_or_b32_e32 v115, s40, v0
	v_or_b32_e32 v116, s41, v1
	v_or_b32_e32 v117, s42, v0
	v_or_b32_e32 v118, s43, v1
	v_or_b32_e32 v119, s52, v0
	v_or_b32_e32 v120, s22, v1
	v_or_b32_e32 v121, s23, v0
	v_add_u32_e32 v130, s4, v106
	v_ashrrev_i32_e32 v133, 31, v132
	v_add_u32_e32 v134, s4, v108
	v_add_u32_e32 v136, s12, v109
	v_add_u32_e32 v138, s4, v110
	v_add_u32_e32 v140, s12, v111
	v_add_u32_e32 v142, s4, v112
	v_add_u32_e32 v144, s12, v113
	v_add_u32_e32 v146, s4, v114
	v_add_u32_e32 v148, s12, v115
	v_add_u32_e32 v150, s4, v116
	v_add_u32_e32 v152, s12, v117
	v_add_u32_e32 v154, s4, v118
	v_add_u32_e32 v156, s12, v119
	v_add_u32_e32 v158, s4, v120
	v_add_u32_e32 v160, s12, v121
	v_ashrrev_i32_e32 v131, 31, v130
	v_lshlrev_b64 v[132:133], 13, v[132:133]
	v_ashrrev_i32_e32 v137, 31, v136
	v_ashrrev_i32_e32 v135, 31, v134
	v_ashrrev_i32_e32 v141, 31, v140
	v_ashrrev_i32_e32 v139, 31, v138
	v_ashrrev_i32_e32 v145, 31, v144
	v_ashrrev_i32_e32 v143, 31, v142
	v_ashrrev_i32_e32 v149, 31, v148
	v_ashrrev_i32_e32 v147, 31, v146
	v_ashrrev_i32_e32 v153, 31, v152
	v_ashrrev_i32_e32 v151, 31, v150
	v_ashrrev_i32_e32 v157, 31, v156
	v_ashrrev_i32_e32 v155, 31, v154
	v_ashrrev_i32_e32 v161, 31, v160
	v_ashrrev_i32_e32 v159, 31, v158
	v_lshlrev_b64 v[130:131], 13, v[130:131]
	v_lshl_add_u64 v[132:133], v[50:51], 0, v[132:133]
	v_lshlrev_b64 v[134:135], 13, v[134:135]
	v_lshlrev_b64 v[136:137], 13, v[136:137]
	v_lshlrev_b64 v[138:139], 13, v[138:139]
	v_lshlrev_b64 v[140:141], 13, v[140:141]
	v_lshlrev_b64 v[142:143], 13, v[142:143]
	v_lshlrev_b64 v[144:145], 13, v[144:145]
	v_lshlrev_b64 v[146:147], 13, v[146:147]
	v_lshlrev_b64 v[148:149], 13, v[148:149]
	v_lshlrev_b64 v[150:151], 13, v[150:151]
	v_lshlrev_b64 v[152:153], 13, v[152:153]
	v_lshlrev_b64 v[154:155], 13, v[154:155]
	v_lshlrev_b64 v[156:157], 13, v[156:157]
	v_lshlrev_b64 v[158:159], 13, v[158:159]
	v_lshlrev_b64 v[160:161], 13, v[160:161]
	v_lshl_add_u64 v[130:131], v[50:51], 0, v[130:131]
	v_lshl_add_u64 v[136:137], v[50:51], 0, v[136:137]
	v_lshl_add_u64 v[134:135], v[50:51], 0, v[134:135]
	v_lshl_add_u64 v[140:141], v[50:51], 0, v[140:141]
	v_lshl_add_u64 v[138:139], v[50:51], 0, v[138:139]
	v_lshl_add_u64 v[144:145], v[50:51], 0, v[144:145]
	v_lshl_add_u64 v[142:143], v[50:51], 0, v[142:143]
	v_lshl_add_u64 v[148:149], v[50:51], 0, v[148:149]
	v_lshl_add_u64 v[146:147], v[50:51], 0, v[146:147]
	v_lshl_add_u64 v[152:153], v[50:51], 0, v[152:153]
	v_lshl_add_u64 v[150:151], v[50:51], 0, v[150:151]
	v_lshl_add_u64 v[156:157], v[50:51], 0, v[156:157]
	v_lshl_add_u64 v[154:155], v[50:51], 0, v[154:155]
	v_lshl_add_u64 v[160:161], v[50:51], 0, v[160:161]
	v_lshl_add_u64 v[158:159], v[50:51], 0, v[158:159]
	global_load_dword v122, v[132:133], off
	global_load_dword v123, v[130:131], off
	global_load_dword v124, v[136:137], off
	global_load_dword v125, v[134:135], off
	global_load_dword v126, v[140:141], off
	global_load_dword v127, v[138:139], off
	global_load_dword v162, v[144:145], off
	global_load_dword v163, v[142:143], off
	global_load_dword v164, v[148:149], off
	global_load_dword v165, v[146:147], off
	global_load_dword v166, v[152:153], off
	global_load_dword v167, v[150:151], off
	global_load_dword v168, v[156:157], off
	global_load_dword v169, v[154:155], off
	global_load_dword v170, v[160:161], off
	global_load_dword v171, v[158:159], off
	v_mad_u64_u32 v[52:53], s[22:23], v9, s78, v[4:5]
	v_mad_u64_u32 v[54:55], s[22:23], v7, s78, v[4:5]
	v_mad_u64_u32 v[56:57], s[22:23], v13, s78, v[4:5]
	v_mad_u64_u32 v[58:59], s[22:23], v11, s78, v[4:5]
	v_mad_u64_u32 v[60:61], s[22:23], v19, s78, v[4:5]
	v_mad_u64_u32 v[62:63], s[22:23], v15, s78, v[4:5]
	v_mad_u64_u32 v[64:65], s[22:23], v43, s78, v[4:5]
	v_mad_u64_u32 v[66:67], s[22:23], v41, s78, v[4:5]
	v_mad_u64_u32 v[68:69], s[22:23], v47, s78, v[4:5]
	v_mad_u64_u32 v[70:71], s[22:23], v45, s78, v[4:5]
	v_mad_u64_u32 v[72:73], s[22:23], v82, s78, v[4:5]
	v_mad_u64_u32 v[74:75], s[22:23], v49, s78, v[4:5]
	v_mad_u64_u32 v[76:77], s[22:23], v87, s78, v[4:5]
	v_mad_u64_u32 v[78:79], s[22:23], v86, s78, v[4:5]
	v_mad_u64_u32 v[80:81], s[22:23], v89, s78, v[4:5]
	v_mad_u64_u32 v[84:85], s[22:23], v88, s78, v[4:5]
	s_waitcnt vmcnt(31)
	ds_write_b32 v52, v90
	s_waitcnt vmcnt(30)
	ds_write_b32 v54, v91
	s_waitcnt vmcnt(29)
	ds_write_b32 v56, v92
	s_waitcnt vmcnt(28)
	ds_write_b32 v58, v93
	s_waitcnt vmcnt(27)
	ds_write_b32 v60, v94
	s_waitcnt vmcnt(26)
	ds_write_b32 v62, v95
	s_waitcnt vmcnt(25)
	ds_write_b32 v64, v96
	s_waitcnt vmcnt(24)
	ds_write_b32 v66, v97
	s_waitcnt vmcnt(23)
	ds_write_b32 v68, v98
	s_waitcnt vmcnt(22)
	ds_write_b32 v70, v99
	s_waitcnt vmcnt(21)
	ds_write_b32 v72, v100
	s_waitcnt vmcnt(20)
	ds_write_b32 v74, v101
	s_waitcnt vmcnt(19)
	ds_write_b32 v76, v102
	s_waitcnt vmcnt(18)
	ds_write_b32 v78, v103
	s_waitcnt vmcnt(17)
	ds_write_b32 v80, v104
	s_waitcnt vmcnt(16)
	ds_write_b32 v84, v105
	v_mad_u64_u32 v[130:131], s[22:23], v107, s78, v[4:5]
	v_mad_u64_u32 v[132:133], s[22:23], v106, s78, v[4:5]
	v_mad_u64_u32 v[134:135], s[22:23], v109, s78, v[4:5]
	v_mad_u64_u32 v[136:137], s[22:23], v108, s78, v[4:5]
	v_mad_u64_u32 v[138:139], s[22:23], v111, s78, v[4:5]
	v_mad_u64_u32 v[140:141], s[22:23], v110, s78, v[4:5]
	v_mad_u64_u32 v[142:143], s[22:23], v113, s78, v[4:5]
	v_mad_u64_u32 v[144:145], s[22:23], v112, s78, v[4:5]
	v_mad_u64_u32 v[146:147], s[22:23], v115, s78, v[4:5]
	v_mad_u64_u32 v[148:149], s[22:23], v114, s78, v[4:5]
	v_mad_u64_u32 v[150:151], s[22:23], v117, s78, v[4:5]
	v_mad_u64_u32 v[152:153], s[22:23], v116, s78, v[4:5]
	v_mad_u64_u32 v[154:155], s[22:23], v119, s78, v[4:5]
	v_mad_u64_u32 v[156:157], s[22:23], v118, s78, v[4:5]
	v_mad_u64_u32 v[158:159], s[22:23], v121, s78, v[4:5]
	v_mad_u64_u32 v[160:161], s[22:23], v120, s78, v[4:5]
	s_waitcnt vmcnt(15)
	ds_write_b32 v130, v122
	s_waitcnt vmcnt(14)
	ds_write_b32 v132, v123
	s_waitcnt vmcnt(13)
	ds_write_b32 v134, v124
	s_waitcnt vmcnt(12)
	ds_write_b32 v136, v125
	s_waitcnt vmcnt(11)
	ds_write_b32 v138, v126
	s_waitcnt vmcnt(10)
	ds_write_b32 v140, v127
	s_waitcnt vmcnt(9)
	ds_write_b32 v142, v162
	s_waitcnt vmcnt(8)
	ds_write_b32 v144, v163
	s_waitcnt vmcnt(7)
	ds_write_b32 v146, v164
	s_waitcnt vmcnt(6)
	ds_write_b32 v148, v165
	s_waitcnt vmcnt(5)
	ds_write_b32 v150, v166
	s_waitcnt vmcnt(4)
	ds_write_b32 v152, v167
	s_waitcnt vmcnt(3)
	ds_write_b32 v154, v168
	s_waitcnt vmcnt(2)
	ds_write_b32 v156, v169
	s_waitcnt vmcnt(1)
	ds_write_b32 v158, v170
	s_waitcnt vmcnt(0)
	ds_write_b32 v160, v171
	s_add_i32 s13, s13, 16
	s_add_i32 s5, s5, 16
	s_add_i32 s15, s15, -16
	s_add_i32 s15, s15, -16
	s_cmp_lg_u32 s15, 0
	s_bfe_i32 s4, s1, 0x80000
	s_bfe_u32 s4, s4, 0x3000c
	s_waitcnt lgkmcnt(0)
	s_add_i32 s1, s1, s4
	s_bfe_u32 s4, s14, 0x80017
	ds_read2_b32 v[54:55], v5 offset1:8
	s_bfe_i32 s1, s1, 0x80000
	s_add_i32 s4, s14, s4
	ds_read2_b32 v[58:59], v5 offset0:33 offset1:41
	s_sext_i32_i16 s1, s1
	s_and_b32 s4, s4, 0xff00
	s_sub_i32 s4, s14, s4
	s_lshl_b32 s1, s1, 4
	ds_read2_b32 v[60:61], v5 offset0:66 offset1:74
	s_sext_i32_i16 s4, s4
	s_and_b32 s1, s1, 0xffffff80
	ds_read2_b32 v[62:63], v5 offset0:99 offset1:107
	s_add_i32 s1, s1, s4
	s_waitcnt lgkmcnt(3)
	v_bfe_u32 v7, v54, 16, 1
	s_add_i32 s5, s1, 0xffffff80
	v_add3_u32 v7, v54, v7, s33
	s_waitcnt lgkmcnt(2)
	v_bfe_u32 v9, v58, 16, 1
	ds_read2_b32 v[64:65], v5 offset0:132 offset1:140
	s_cmpk_lt_i32 s4, 0x80
	v_lshrrev_b32_e32 v7, 16, v7
	v_add3_u32 v9, v58, v9, s33
	ds_read2_b32 v[66:67], v5 offset0:165 offset1:173
	s_cselect_b32 s4, s1, s5
	s_mov_b32 s1, 0x23a0000
	v_and_or_b32 v50, v9, s69, v7
	s_waitcnt lgkmcnt(3)
	v_bfe_u32 v7, v60, 16, 1
	s_cselect_b32 s1, s1, 0x2420000
	s_ashr_i32 s5, s4, 31
	v_add3_u32 v7, v60, v7, s33
	s_waitcnt lgkmcnt(2)
	v_bfe_u32 v9, v62, 16, 1
	ds_read2_b32 v[68:69], v5 offset0:198 offset1:206
	s_lshl_b64 s[4:5], s[4:5], 9
	v_lshrrev_b32_e32 v7, 16, v7
	v_add3_u32 v9, v62, v9, s33
	ds_read2_b32 v[70:71], v5 offset0:231 offset1:239
	s_add_u32 s1, s17, s1
	v_and_or_b32 v51, v9, s69, v7
	s_waitcnt lgkmcnt(3)
	v_bfe_u32 v7, v64, 16, 1
	s_addc_u32 s13, s29, 0
	v_add3_u32 v7, v64, v7, s33
	s_waitcnt lgkmcnt(2)
	v_bfe_u32 v9, v66, 16, 1
	s_add_u32 s1, s1, s4
	v_lshrrev_b32_e32 v7, 16, v7
	v_add3_u32 v9, v66, v9, s33
	s_addc_u32 s14, s13, s5
	s_ashr_i32 s13, s12, 31
	v_and_or_b32 v52, v9, s69, v7
	s_waitcnt lgkmcnt(1)
	v_bfe_u32 v7, v68, 16, 1
	s_lshl_b64 s[4:5], s[12:13], 1
	v_add3_u32 v7, v68, v7, s33
	s_waitcnt lgkmcnt(0)
	v_bfe_u32 v9, v70, 16, 1
	s_add_u32 s4, s1, s4
	v_lshrrev_b32_e32 v7, 16, v7
	v_add3_u32 v9, v70, v9, s33
	s_addc_u32 s5, s14, s5
	v_lshlrev_b32_e32 v128, 1, v6
	v_and_or_b32 v53, v9, s69, v7
	v_bfe_u32 v7, v55, 16, 1
	v_lshl_add_u64 v[56:57], s[4:5], 0, v[128:129]
	v_mov_b32_e32 v43, v129
	v_add3_u32 v7, v55, v7, s33
	v_bfe_u32 v9, v59, 16, 1
	v_lshl_add_u64 v[72:73], v[56:57], 0, v[42:43]
	v_lshrrev_b32_e32 v7, 16, v7
	v_add3_u32 v9, v59, v9, s33
	global_store_dwordx4 v[72:73], v[50:53], off
	v_mov_b32_e32 v45, v129
	ds_read2_b32 v[54:55], v5 offset0:16 offset1:24
	v_and_or_b32 v50, v9, s69, v7
	v_bfe_u32 v7, v61, 16, 1
	v_add3_u32 v7, v61, v7, s33
	v_bfe_u32 v9, v63, 16, 1
	v_lshrrev_b32_e32 v7, 16, v7
	v_add3_u32 v9, v63, v9, s33
	v_and_or_b32 v51, v9, s69, v7
	v_bfe_u32 v7, v65, 16, 1
	v_add3_u32 v7, v65, v7, s33
	v_bfe_u32 v9, v67, 16, 1
	v_lshrrev_b32_e32 v7, 16, v7
	v_add3_u32 v9, v67, v9, s33
	v_and_or_b32 v52, v9, s69, v7
	v_bfe_u32 v7, v69, 16, 1
	v_add3_u32 v7, v69, v7, s33
	v_bfe_u32 v9, v71, 16, 1
	v_lshrrev_b32_e32 v7, 16, v7
	v_add3_u32 v9, v71, v9, s33
	v_and_or_b32 v53, v9, s69, v7
	v_lshl_add_u64 v[58:59], v[56:57], 0, v[44:45]
	global_store_dwordx4 v[58:59], v[50:53], off
	ds_read2_b32 v[58:59], v5 offset0:49 offset1:57
	ds_read2_b32 v[60:61], v5 offset0:82 offset1:90
	ds_read2_b32 v[62:63], v5 offset0:115 offset1:123
	s_waitcnt lgkmcnt(3)
	v_bfe_u32 v7, v54, 16, 1
	v_add3_u32 v7, v54, v7, s33
	s_waitcnt lgkmcnt(2)
	v_bfe_u32 v9, v58, 16, 1
	ds_read2_b32 v[64:65], v5 offset0:148 offset1:156
	v_lshrrev_b32_e32 v7, 16, v7
	v_add3_u32 v9, v58, v9, s33
	ds_read2_b32 v[66:67], v5 offset0:181 offset1:189
	v_and_or_b32 v50, v9, s69, v7
	s_waitcnt lgkmcnt(3)
	v_bfe_u32 v7, v60, 16, 1
	v_add3_u32 v7, v60, v7, s33
	s_waitcnt lgkmcnt(2)
	v_bfe_u32 v9, v62, 16, 1
	ds_read2_b32 v[68:69], v5 offset0:214 offset1:222
	v_lshrrev_b32_e32 v7, 16, v7
	v_add3_u32 v9, v62, v9, s33
	ds_read2_b32 v[70:71], v5 offset0:247 offset1:255
	v_and_or_b32 v51, v9, s69, v7
	s_waitcnt lgkmcnt(3)
	v_bfe_u32 v7, v64, 16, 1
	v_add3_u32 v7, v64, v7, s33
	s_waitcnt lgkmcnt(2)
	v_bfe_u32 v9, v66, 16, 1
	v_lshrrev_b32_e32 v7, 16, v7
	v_add3_u32 v9, v66, v9, s33
	v_and_or_b32 v52, v9, s69, v7
	s_waitcnt lgkmcnt(1)
	v_bfe_u32 v7, v68, 16, 1
	v_add3_u32 v7, v68, v7, s33
	s_waitcnt lgkmcnt(0)
	v_bfe_u32 v9, v70, 16, 1
	v_lshrrev_b32_e32 v7, 16, v7
	v_add3_u32 v9, v70, v9, s33
	v_and_or_b32 v53, v9, s69, v7
	v_bfe_u32 v7, v55, 16, 1
	v_mov_b32_e32 v47, v129
	v_add3_u32 v7, v55, v7, s33
	v_bfe_u32 v9, v59, 16, 1
	v_lshl_add_u64 v[72:73], v[56:57], 0, v[46:47]
	v_lshrrev_b32_e32 v7, 16, v7
	v_add3_u32 v9, v59, v9, s33
	global_store_dwordx4 v[72:73], v[50:53], off
	v_mov_b32_e32 v49, v129
	v_lshl_add_u64 v[54:55], v[56:57], 0, v[48:49]
	v_and_or_b32 v50, v9, s69, v7
	v_bfe_u32 v7, v61, 16, 1
	v_add3_u32 v7, v61, v7, s33
	v_bfe_u32 v9, v63, 16, 1
	v_lshrrev_b32_e32 v7, 16, v7
	v_add3_u32 v9, v63, v9, s33
	v_and_or_b32 v51, v9, s69, v7
	v_bfe_u32 v7, v65, 16, 1
	v_add3_u32 v7, v65, v7, s33
	v_bfe_u32 v9, v67, 16, 1
	v_lshrrev_b32_e32 v7, 16, v7
	v_add3_u32 v9, v67, v9, s33
	v_and_or_b32 v52, v9, s69, v7
	v_bfe_u32 v7, v69, 16, 1
	v_add3_u32 v7, v69, v7, s33
	v_bfe_u32 v9, v71, 16, 1
	v_lshrrev_b32_e32 v7, 16, v7
	v_add3_u32 v9, v71, v9, s33
	v_and_or_b32 v53, v9, s69, v7
	global_store_dwordx4 v[54:55], v[50:53], off
	s_waitcnt lgkmcnt(0)
	s_mov_b32 s1, s0
	s_andn2_b64 vcc, exec, s[10:11]
	s_mov_b64 s[10:11], -1
	s_cbranch_vccnz .LBB0_744

.LBB0_742:
	s_lshl_b32 s11, s0, 1
	s_lshl_b32 s14, s4, 1
	v_or_b32_e32 v7, s11, v1
	v_or_b32_e32 v9, s14, v0
	s_add_i32 s15, s11, 4
	s_add_i32 s22, s14, 4
	s_add_i32 s23, s11, 8
	s_add_i32 s24, s14, 8
	s_add_i32 s25, s11, 12
	s_add_i32 s26, s14, 12
	s_add_i32 s27, s11, 16
	s_add_i32 s30, s14, 16
	s_add_i32 s36, s11, 20
	s_add_i32 s37, s14, 20
	s_add_i32 s40, s11, 24
	s_add_i32 s41, s14, 24
	s_add_i32 s11, s11, 28
	s_add_i32 s14, s14, 28
	v_add_u32_e32 v54, s10, v9
	v_or_b32_e32 v11, s15, v1
	v_or_b32_e32 v13, s22, v0
	v_or_b32_e32 v15, s23, v1
	v_or_b32_e32 v19, s24, v0
	v_or_b32_e32 v41, s25, v1
	v_or_b32_e32 v43, s26, v0
	v_or_b32_e32 v45, s27, v1
	v_or_b32_e32 v47, s30, v0
	v_or_b32_e32 v49, s36, v1
	v_or_b32_e32 v82, s37, v0
	v_or_b32_e32 v86, s40, v1
	v_or_b32_e32 v87, s41, v0
	v_or_b32_e32 v88, s11, v1
	v_or_b32_e32 v89, s14, v0
	v_add_u32_e32 v52, s1, v7
	v_ashrrev_i32_e32 v55, 31, v54
	v_add_u32_e32 v56, s1, v11
	v_add_u32_e32 v58, s10, v13
	v_add_u32_e32 v60, s1, v15
	v_add_u32_e32 v62, s10, v19
	v_add_u32_e32 v64, s1, v41
	v_add_u32_e32 v66, s10, v43
	v_add_u32_e32 v68, s1, v45
	v_add_u32_e32 v70, s10, v47
	v_add_u32_e32 v72, s1, v49
	v_add_u32_e32 v74, s10, v82
	v_add_u32_e32 v76, s1, v86
	v_add_u32_e32 v78, s10, v87
	v_add_u32_e32 v80, s1, v88
	v_add_u32_e32 v84, s10, v89
	v_ashrrev_i32_e32 v53, 31, v52
	v_lshlrev_b64 v[54:55], 12, v[54:55]
	v_ashrrev_i32_e32 v59, 31, v58
	v_ashrrev_i32_e32 v57, 31, v56
	v_ashrrev_i32_e32 v63, 31, v62
	v_ashrrev_i32_e32 v61, 31, v60
	v_ashrrev_i32_e32 v67, 31, v66
	v_ashrrev_i32_e32 v65, 31, v64
	v_ashrrev_i32_e32 v71, 31, v70
	v_ashrrev_i32_e32 v69, 31, v68
	v_ashrrev_i32_e32 v75, 31, v74
	v_ashrrev_i32_e32 v73, 31, v72
	v_ashrrev_i32_e32 v79, 31, v78
	v_ashrrev_i32_e32 v77, 31, v76
	v_ashrrev_i32_e32 v85, 31, v84
	v_ashrrev_i32_e32 v81, 31, v80
	v_lshlrev_b64 v[52:53], 12, v[52:53]
	v_lshl_add_u64 v[54:55], v[50:51], 0, v[54:55]
	v_lshlrev_b64 v[56:57], 12, v[56:57]
	v_lshlrev_b64 v[58:59], 12, v[58:59]
	v_lshlrev_b64 v[60:61], 12, v[60:61]
	v_lshlrev_b64 v[62:63], 12, v[62:63]
	v_lshlrev_b64 v[64:65], 12, v[64:65]
	v_lshlrev_b64 v[66:67], 12, v[66:67]
	v_lshlrev_b64 v[68:69], 12, v[68:69]
	v_lshlrev_b64 v[70:71], 12, v[70:71]
	v_lshlrev_b64 v[72:73], 12, v[72:73]
	v_lshlrev_b64 v[74:75], 12, v[74:75]
	v_lshlrev_b64 v[76:77], 12, v[76:77]
	v_lshlrev_b64 v[78:79], 12, v[78:79]
	v_lshlrev_b64 v[80:81], 12, v[80:81]
	v_lshlrev_b64 v[84:85], 12, v[84:85]
	v_lshl_add_u64 v[52:53], v[50:51], 0, v[52:53]
	v_lshl_add_u64 v[58:59], v[50:51], 0, v[58:59]
	v_lshl_add_u64 v[56:57], v[50:51], 0, v[56:57]
	v_lshl_add_u64 v[62:63], v[50:51], 0, v[62:63]
	v_lshl_add_u64 v[60:61], v[50:51], 0, v[60:61]
	v_lshl_add_u64 v[66:67], v[50:51], 0, v[66:67]
	v_lshl_add_u64 v[64:65], v[50:51], 0, v[64:65]
	v_lshl_add_u64 v[70:71], v[50:51], 0, v[70:71]
	v_lshl_add_u64 v[68:69], v[50:51], 0, v[68:69]
	v_lshl_add_u64 v[74:75], v[50:51], 0, v[74:75]
	v_lshl_add_u64 v[72:73], v[50:51], 0, v[72:73]
	v_lshl_add_u64 v[78:79], v[50:51], 0, v[78:79]
	v_lshl_add_u64 v[76:77], v[50:51], 0, v[76:77]
	v_lshl_add_u64 v[84:85], v[50:51], 0, v[84:85]
	v_lshl_add_u64 v[80:81], v[50:51], 0, v[80:81]
	global_load_dword v90, v[54:55], off
	global_load_dword v91, v[52:53], off
	global_load_dword v92, v[58:59], off
	global_load_dword v93, v[56:57], off
	global_load_dword v94, v[62:63], off
	global_load_dword v95, v[60:61], off
	global_load_dword v96, v[66:67], off
	global_load_dword v97, v[64:65], off
	global_load_dword v98, v[70:71], off
	global_load_dword v99, v[68:69], off
	global_load_dword v100, v[74:75], off
	global_load_dword v101, v[72:73], off
	global_load_dword v102, v[78:79], off
	global_load_dword v103, v[76:77], off
	global_load_dword v104, v[84:85], off
	global_load_dword v105, v[80:81], off
	s_add_i32 s4, s4, 16
	s_add_i32 s0, s0, 16
	s_lshl_b32 s11, s0, 1
	s_lshl_b32 s14, s4, 1
	v_or_b32_e32 v106, s11, v1
	v_or_b32_e32 v107, s14, v0
	s_add_i32 s15, s11, 4
	s_add_i32 s22, s14, 4
	s_add_i32 s23, s11, 8
	s_add_i32 s24, s14, 8
	s_add_i32 s25, s11, 12
	s_add_i32 s26, s14, 12
	s_add_i32 s27, s11, 16
	s_add_i32 s30, s14, 16
	s_add_i32 s36, s11, 20
	s_add_i32 s37, s14, 20
	s_add_i32 s40, s11, 24
	s_add_i32 s41, s14, 24
	s_add_i32 s11, s11, 28
	s_add_i32 s14, s14, 28
	v_add_u32_e32 v132, s10, v107
	v_or_b32_e32 v108, s15, v1
	v_or_b32_e32 v109, s22, v0
	v_or_b32_e32 v110, s23, v1
	v_or_b32_e32 v111, s24, v0
	v_or_b32_e32 v112, s25, v1
	v_or_b32_e32 v113, s26, v0
	v_or_b32_e32 v114, s27, v1
	v_or_b32_e32 v115, s30, v0
	v_or_b32_e32 v116, s36, v1
	v_or_b32_e32 v117, s37, v0
	v_or_b32_e32 v118, s40, v1
	v_or_b32_e32 v119, s41, v0
	v_or_b32_e32 v120, s11, v1
	v_or_b32_e32 v121, s14, v0
	v_add_u32_e32 v130, s1, v106
	v_ashrrev_i32_e32 v133, 31, v132
	v_add_u32_e32 v134, s1, v108
	v_add_u32_e32 v136, s10, v109
	v_add_u32_e32 v138, s1, v110
	v_add_u32_e32 v140, s10, v111
	v_add_u32_e32 v142, s1, v112
	v_add_u32_e32 v144, s10, v113
	v_add_u32_e32 v146, s1, v114
	v_add_u32_e32 v148, s10, v115
	v_add_u32_e32 v150, s1, v116
	v_add_u32_e32 v152, s10, v117
	v_add_u32_e32 v154, s1, v118
	v_add_u32_e32 v156, s10, v119
	v_add_u32_e32 v158, s1, v120
	v_add_u32_e32 v160, s10, v121
	v_ashrrev_i32_e32 v131, 31, v130
	v_lshlrev_b64 v[132:133], 12, v[132:133]
	v_ashrrev_i32_e32 v137, 31, v136
	v_ashrrev_i32_e32 v135, 31, v134
	v_ashrrev_i32_e32 v141, 31, v140
	v_ashrrev_i32_e32 v139, 31, v138
	v_ashrrev_i32_e32 v145, 31, v144
	v_ashrrev_i32_e32 v143, 31, v142
	v_ashrrev_i32_e32 v149, 31, v148
	v_ashrrev_i32_e32 v147, 31, v146
	v_ashrrev_i32_e32 v153, 31, v152
	v_ashrrev_i32_e32 v151, 31, v150
	v_ashrrev_i32_e32 v157, 31, v156
	v_ashrrev_i32_e32 v155, 31, v154
	v_ashrrev_i32_e32 v161, 31, v160
	v_ashrrev_i32_e32 v159, 31, v158
	v_lshlrev_b64 v[130:131], 12, v[130:131]
	v_lshl_add_u64 v[132:133], v[50:51], 0, v[132:133]
	v_lshlrev_b64 v[134:135], 12, v[134:135]
	v_lshlrev_b64 v[136:137], 12, v[136:137]
	v_lshlrev_b64 v[138:139], 12, v[138:139]
	v_lshlrev_b64 v[140:141], 12, v[140:141]
	v_lshlrev_b64 v[142:143], 12, v[142:143]
	v_lshlrev_b64 v[144:145], 12, v[144:145]
	v_lshlrev_b64 v[146:147], 12, v[146:147]
	v_lshlrev_b64 v[148:149], 12, v[148:149]
	v_lshlrev_b64 v[150:151], 12, v[150:151]
	v_lshlrev_b64 v[152:153], 12, v[152:153]
	v_lshlrev_b64 v[154:155], 12, v[154:155]
	v_lshlrev_b64 v[156:157], 12, v[156:157]
	v_lshlrev_b64 v[158:159], 12, v[158:159]
	v_lshlrev_b64 v[160:161], 12, v[160:161]
	v_lshl_add_u64 v[130:131], v[50:51], 0, v[130:131]
	v_lshl_add_u64 v[136:137], v[50:51], 0, v[136:137]
	v_lshl_add_u64 v[134:135], v[50:51], 0, v[134:135]
	v_lshl_add_u64 v[140:141], v[50:51], 0, v[140:141]
	v_lshl_add_u64 v[138:139], v[50:51], 0, v[138:139]
	v_lshl_add_u64 v[144:145], v[50:51], 0, v[144:145]
	v_lshl_add_u64 v[142:143], v[50:51], 0, v[142:143]
	v_lshl_add_u64 v[148:149], v[50:51], 0, v[148:149]
	v_lshl_add_u64 v[146:147], v[50:51], 0, v[146:147]
	v_lshl_add_u64 v[152:153], v[50:51], 0, v[152:153]
	v_lshl_add_u64 v[150:151], v[50:51], 0, v[150:151]
	v_lshl_add_u64 v[156:157], v[50:51], 0, v[156:157]
	v_lshl_add_u64 v[154:155], v[50:51], 0, v[154:155]
	v_lshl_add_u64 v[160:161], v[50:51], 0, v[160:161]
	v_lshl_add_u64 v[158:159], v[50:51], 0, v[158:159]
	global_load_dword v122, v[132:133], off
	global_load_dword v123, v[130:131], off
	global_load_dword v124, v[136:137], off
	global_load_dword v125, v[134:135], off
	global_load_dword v126, v[140:141], off
	global_load_dword v127, v[138:139], off
	global_load_dword v162, v[144:145], off
	global_load_dword v163, v[142:143], off
	global_load_dword v164, v[148:149], off
	global_load_dword v165, v[146:147], off
	global_load_dword v166, v[152:153], off
	global_load_dword v167, v[150:151], off
	global_load_dword v168, v[156:157], off
	global_load_dword v169, v[154:155], off
	global_load_dword v170, v[160:161], off
	global_load_dword v171, v[158:159], off
	v_mad_u64_u32 v[52:53], s[14:15], v9, s78, v[4:5]
	v_mad_u64_u32 v[54:55], s[14:15], v7, s78, v[4:5]
	v_mad_u64_u32 v[56:57], s[14:15], v13, s78, v[4:5]
	v_mad_u64_u32 v[58:59], s[14:15], v11, s78, v[4:5]
	v_mad_u64_u32 v[60:61], s[14:15], v19, s78, v[4:5]
	v_mad_u64_u32 v[62:63], s[14:15], v15, s78, v[4:5]
	v_mad_u64_u32 v[64:65], s[14:15], v43, s78, v[4:5]
	v_mad_u64_u32 v[66:67], s[14:15], v41, s78, v[4:5]
	v_mad_u64_u32 v[68:69], s[14:15], v47, s78, v[4:5]
	v_mad_u64_u32 v[70:71], s[14:15], v45, s78, v[4:5]
	v_mad_u64_u32 v[72:73], s[14:15], v82, s78, v[4:5]
	v_mad_u64_u32 v[74:75], s[14:15], v49, s78, v[4:5]
	v_mad_u64_u32 v[76:77], s[14:15], v87, s78, v[4:5]
	v_mad_u64_u32 v[78:79], s[14:15], v86, s78, v[4:5]
	v_mad_u64_u32 v[80:81], s[14:15], v89, s78, v[4:5]
	v_mad_u64_u32 v[84:85], s[14:15], v88, s78, v[4:5]
	s_waitcnt vmcnt(31)
	ds_write_b32 v52, v90
	s_waitcnt vmcnt(30)
	ds_write_b32 v54, v91
	s_waitcnt vmcnt(29)
	ds_write_b32 v56, v92
	s_waitcnt vmcnt(28)
	ds_write_b32 v58, v93
	s_waitcnt vmcnt(27)
	ds_write_b32 v60, v94
	s_waitcnt vmcnt(26)
	ds_write_b32 v62, v95
	s_waitcnt vmcnt(25)
	ds_write_b32 v64, v96
	s_waitcnt vmcnt(24)
	ds_write_b32 v66, v97
	s_waitcnt vmcnt(23)
	ds_write_b32 v68, v98
	s_waitcnt vmcnt(22)
	ds_write_b32 v70, v99
	s_waitcnt vmcnt(21)
	ds_write_b32 v72, v100
	s_waitcnt vmcnt(20)
	ds_write_b32 v74, v101
	s_waitcnt vmcnt(19)
	ds_write_b32 v76, v102
	s_waitcnt vmcnt(18)
	ds_write_b32 v78, v103
	s_waitcnt vmcnt(17)
	ds_write_b32 v80, v104
	s_waitcnt vmcnt(16)
	ds_write_b32 v84, v105
	v_mad_u64_u32 v[130:131], s[14:15], v107, s78, v[4:5]
	v_mad_u64_u32 v[132:133], s[14:15], v106, s78, v[4:5]
	v_mad_u64_u32 v[134:135], s[14:15], v109, s78, v[4:5]
	v_mad_u64_u32 v[136:137], s[14:15], v108, s78, v[4:5]
	v_mad_u64_u32 v[138:139], s[14:15], v111, s78, v[4:5]
	v_mad_u64_u32 v[140:141], s[14:15], v110, s78, v[4:5]
	v_mad_u64_u32 v[142:143], s[14:15], v113, s78, v[4:5]
	v_mad_u64_u32 v[144:145], s[14:15], v112, s78, v[4:5]
	v_mad_u64_u32 v[146:147], s[14:15], v115, s78, v[4:5]
	v_mad_u64_u32 v[148:149], s[14:15], v114, s78, v[4:5]
	v_mad_u64_u32 v[150:151], s[14:15], v117, s78, v[4:5]
	v_mad_u64_u32 v[152:153], s[14:15], v116, s78, v[4:5]
	v_mad_u64_u32 v[154:155], s[14:15], v119, s78, v[4:5]
	v_mad_u64_u32 v[156:157], s[14:15], v118, s78, v[4:5]
	v_mad_u64_u32 v[158:159], s[14:15], v121, s78, v[4:5]
	v_mad_u64_u32 v[160:161], s[14:15], v120, s78, v[4:5]
	s_waitcnt vmcnt(15)
	ds_write_b32 v130, v122
	s_waitcnt vmcnt(14)
	ds_write_b32 v132, v123
	s_waitcnt vmcnt(13)
	ds_write_b32 v134, v124
	s_waitcnt vmcnt(12)
	ds_write_b32 v136, v125
	s_waitcnt vmcnt(11)
	ds_write_b32 v138, v126
	s_waitcnt vmcnt(10)
	ds_write_b32 v140, v127
	s_waitcnt vmcnt(9)
	ds_write_b32 v142, v162
	s_waitcnt vmcnt(8)
	ds_write_b32 v144, v163
	s_waitcnt vmcnt(7)
	ds_write_b32 v146, v164
	s_waitcnt vmcnt(6)
	ds_write_b32 v148, v165
	s_waitcnt vmcnt(5)
	ds_write_b32 v150, v166
	s_waitcnt vmcnt(4)
	ds_write_b32 v152, v167
	s_waitcnt vmcnt(3)
	ds_write_b32 v154, v168
	s_waitcnt vmcnt(2)
	ds_write_b32 v156, v169
	s_waitcnt vmcnt(1)
	ds_write_b32 v158, v170
	s_waitcnt vmcnt(0)
	ds_write_b32 v160, v171
	s_add_i32 s4, s4, 16
	s_add_i32 s0, s0, 16
	s_add_i32 s5, s5, -16
	s_add_i32 s5, s5, -16
	s_cmp_lg_u32 s5, 0
	s_waitcnt lgkmcnt(0)
	ds_read2_b32 v[54:55], v5 offset1:8
	ds_read2_b32 v[58:59], v5 offset0:33 offset1:41
	ds_read2_b32 v[60:61], v5 offset0:66 offset1:74
	ds_read2_b32 v[62:63], v5 offset0:99 offset1:107
	ds_read2_b32 v[64:65], v5 offset0:132 offset1:140
	s_waitcnt lgkmcnt(4)
	v_bfe_u32 v7, v54, 16, 1
	v_add3_u32 v7, v54, v7, s33
	s_waitcnt lgkmcnt(3)
	v_bfe_u32 v9, v58, 16, 1
	v_lshrrev_b32_e32 v7, 16, v7
	v_add3_u32 v9, v58, v9, s33
	ds_read2_b32 v[66:67], v5 offset0:165 offset1:173
	v_and_or_b32 v50, v9, s69, v7
	s_waitcnt lgkmcnt(3)
	v_bfe_u32 v7, v60, 16, 1
	v_add3_u32 v7, v60, v7, s33
	s_waitcnt lgkmcnt(2)
	v_bfe_u32 v9, v62, 16, 1
	ds_read2_b32 v[68:69], v5 offset0:198 offset1:206
	v_lshrrev_b32_e32 v7, 16, v7
	v_add3_u32 v9, v62, v9, s33
	ds_read2_b32 v[70:71], v5 offset0:231 offset1:239
	v_and_or_b32 v51, v9, s69, v7
	s_waitcnt lgkmcnt(3)
	v_bfe_u32 v7, v64, 16, 1
	s_lshl_b64 s[0:1], s[12:13], 11
	v_add3_u32 v7, v64, v7, s33
	s_waitcnt lgkmcnt(2)
	v_bfe_u32 v9, v66, 16, 1
	s_add_u32 s4, s51, s0
	v_lshrrev_b32_e32 v7, 16, v7
	v_add3_u32 v9, v66, v9, s33
	s_addc_u32 s5, s61, s1
	s_ashr_i32 s11, s10, 31
	v_and_or_b32 v52, v9, s69, v7
	s_waitcnt lgkmcnt(1)
	v_bfe_u32 v7, v68, 16, 1
	s_lshl_b64 s[0:1], s[10:11], 1
	v_add3_u32 v7, v68, v7, s33
	s_waitcnt lgkmcnt(0)
	v_bfe_u32 v9, v70, 16, 1
	s_add_u32 s0, s4, s0
	v_lshrrev_b32_e32 v7, 16, v7
	v_add3_u32 v9, v70, v9, s33
	s_addc_u32 s1, s5, s1
	v_lshlrev_b32_e32 v128, 1, v6
	v_and_or_b32 v53, v9, s69, v7
	v_bfe_u32 v7, v55, 16, 1
	v_lshl_add_u64 v[56:57], s[0:1], 0, v[128:129]
	v_lshlrev_b32_e32 v128, 1, v8
	v_add3_u32 v7, v55, v7, s33
	v_bfe_u32 v9, v59, 16, 1
	v_lshl_add_u64 v[72:73], v[56:57], 0, v[128:129]
	v_lshrrev_b32_e32 v7, 16, v7
	v_add3_u32 v9, v59, v9, s33
	global_store_dwordx4 v[72:73], v[50:53], off
	v_lshlrev_b32_e32 v128, 1, v10
	ds_read2_b32 v[54:55], v5 offset0:16 offset1:24
	v_and_or_b32 v50, v9, s69, v7
	v_bfe_u32 v7, v61, 16, 1
	v_add3_u32 v7, v61, v7, s33
	v_bfe_u32 v9, v63, 16, 1
	v_lshrrev_b32_e32 v7, 16, v7
	v_add3_u32 v9, v63, v9, s33
	v_and_or_b32 v51, v9, s69, v7
	v_bfe_u32 v7, v65, 16, 1
	v_add3_u32 v7, v65, v7, s33
	v_bfe_u32 v9, v67, 16, 1
	v_lshrrev_b32_e32 v7, 16, v7
	v_add3_u32 v9, v67, v9, s33
	v_and_or_b32 v52, v9, s69, v7
	v_bfe_u32 v7, v69, 16, 1
	v_add3_u32 v7, v69, v7, s33
	v_bfe_u32 v9, v71, 16, 1
	v_lshrrev_b32_e32 v7, 16, v7
	v_add3_u32 v9, v71, v9, s33
	v_and_or_b32 v53, v9, s69, v7
	v_lshl_add_u64 v[58:59], v[56:57], 0, v[128:129]
	global_store_dwordx4 v[58:59], v[50:53], off
	ds_read2_b32 v[58:59], v5 offset0:49 offset1:57
	ds_read2_b32 v[60:61], v5 offset0:82 offset1:90
	ds_read2_b32 v[62:63], v5 offset0:115 offset1:123
	s_waitcnt lgkmcnt(3)
	v_bfe_u32 v7, v54, 16, 1
	v_add3_u32 v7, v54, v7, s33
	s_waitcnt lgkmcnt(2)
	v_bfe_u32 v9, v58, 16, 1
	ds_read2_b32 v[64:65], v5 offset0:148 offset1:156
	v_lshrrev_b32_e32 v7, 16, v7
	v_add3_u32 v9, v58, v9, s33
	ds_read2_b32 v[66:67], v5 offset0:181 offset1:189
	v_and_or_b32 v50, v9, s69, v7
	s_waitcnt lgkmcnt(3)
	v_bfe_u32 v7, v60, 16, 1
	v_add3_u32 v7, v60, v7, s33
	s_waitcnt lgkmcnt(2)
	v_bfe_u32 v9, v62, 16, 1
	ds_read2_b32 v[68:69], v5 offset0:214 offset1:222
	v_lshrrev_b32_e32 v7, 16, v7
	v_add3_u32 v9, v62, v9, s33
	ds_read2_b32 v[70:71], v5 offset0:247 offset1:255
	v_and_or_b32 v51, v9, s69, v7
	s_waitcnt lgkmcnt(3)
	v_bfe_u32 v7, v64, 16, 1
	v_add3_u32 v7, v64, v7, s33
	s_waitcnt lgkmcnt(2)
	v_bfe_u32 v9, v66, 16, 1
	v_lshrrev_b32_e32 v7, 16, v7
	v_add3_u32 v9, v66, v9, s33
	v_and_or_b32 v52, v9, s69, v7
	s_waitcnt lgkmcnt(1)
	v_bfe_u32 v7, v68, 16, 1
	v_add3_u32 v7, v68, v7, s33
	s_waitcnt lgkmcnt(0)
	v_bfe_u32 v9, v70, 16, 1
	v_lshrrev_b32_e32 v7, 16, v7
	v_add3_u32 v9, v70, v9, s33
	v_and_or_b32 v53, v9, s69, v7
	v_bfe_u32 v7, v55, 16, 1
	v_lshlrev_b32_e32 v128, 1, v12
	v_add3_u32 v7, v55, v7, s33
	v_bfe_u32 v9, v59, 16, 1
	v_lshl_add_u64 v[72:73], v[56:57], 0, v[128:129]
	v_lshrrev_b32_e32 v7, 16, v7
	v_add3_u32 v9, v59, v9, s33
	global_store_dwordx4 v[72:73], v[50:53], off
	v_lshlrev_b32_e32 v128, 1, v14
	v_lshl_add_u64 v[54:55], v[56:57], 0, v[128:129]
	v_and_or_b32 v50, v9, s69, v7
	v_bfe_u32 v7, v61, 16, 1
	v_add3_u32 v7, v61, v7, s33
	v_bfe_u32 v9, v63, 16, 1
	v_lshrrev_b32_e32 v7, 16, v7
	v_add3_u32 v9, v63, v9, s33
	v_and_or_b32 v51, v9, s69, v7
	v_bfe_u32 v7, v65, 16, 1
	v_add3_u32 v7, v65, v7, s33
	v_bfe_u32 v9, v67, 16, 1
	v_lshrrev_b32_e32 v7, 16, v7
	v_add3_u32 v9, v67, v9, s33
	v_and_or_b32 v52, v9, s69, v7
	v_bfe_u32 v7, v69, 16, 1
	v_add3_u32 v7, v69, v7, s33
	v_bfe_u32 v9, v71, 16, 1
	v_lshrrev_b32_e32 v7, 16, v7
	v_add3_u32 v9, v71, v9, s33
	v_and_or_b32 v53, v9, s69, v7
	global_store_dwordx4 v[54:55], v[50:53], off
	s_waitcnt lgkmcnt(0)
	s_mov_b64 s[10:11], -1

.LBB0_784:
	s_lshl_b32 s9, s3, 1
	s_lshl_b32 s10, s4, 1
	v_or_b32_e32 v7, s9, v1
	v_or_b32_e32 v9, s10, v2
	s_add_i32 s11, s9, 4
	s_add_i32 s28, s10, 4
	s_add_i32 s29, s9, 8
	s_add_i32 s30, s10, 8
	s_add_i32 s36, s9, 12
	s_add_i32 s37, s10, 12
	s_add_i32 s38, s9, 16
	s_add_i32 s39, s10, 16
	s_add_i32 s40, s9, 20
	s_add_i32 s41, s10, 20
	s_add_i32 s42, s9, 24
	s_add_i32 s43, s10, 24
	s_add_i32 s9, s9, 28
	s_add_i32 s10, s10, 28
	v_add_u32_e32 v11, s1, v7
	v_add_u32_e32 v13, s2, v9
	v_or_b32_e32 v15, s11, v1
	v_or_b32_e32 v17, s28, v2
	v_or_b32_e32 v21, s29, v1
	v_or_b32_e32 v35, s30, v2
	v_or_b32_e32 v37, s36, v1
	v_or_b32_e32 v39, s37, v2
	v_or_b32_e32 v41, s38, v1
	v_or_b32_e32 v43, s39, v2
	v_or_b32_e32 v78, s40, v1
	v_or_b32_e32 v79, s41, v2
	v_or_b32_e32 v80, s42, v1
	v_or_b32_e32 v81, s43, v2
	v_or_b32_e32 v82, s9, v1
	v_or_b32_e32 v83, s10, v2
	v_mad_i64_i32 v[46:47], s[10:11], v13, s80, v[44:45]
	v_mad_i64_i32 v[48:49], s[10:11], v11, s80, v[44:45]
	v_add_u32_e32 v11, s1, v15
	v_add_u32_e32 v13, s2, v17
	v_add_u32_e32 v56, s1, v21
	v_add_u32_e32 v54, s2, v35
	v_add_u32_e32 v60, s1, v37
	v_add_u32_e32 v58, s2, v39
	v_add_u32_e32 v64, s1, v41
	v_add_u32_e32 v62, s2, v43
	v_add_u32_e32 v68, s1, v78
	v_add_u32_e32 v66, s2, v79
	v_add_u32_e32 v72, s1, v80
	v_add_u32_e32 v70, s2, v81
	v_add_u32_e32 v76, s1, v82
	v_add_u32_e32 v74, s2, v83
	v_mad_i64_i32 v[50:51], s[10:11], v13, s80, v[44:45]
	v_mad_i64_i32 v[52:53], s[10:11], v11, s80, v[44:45]
	v_mad_i64_i32 v[54:55], s[10:11], v54, s80, v[44:45]
	v_mad_i64_i32 v[56:57], s[10:11], v56, s80, v[44:45]
	v_mad_i64_i32 v[58:59], s[10:11], v58, s80, v[44:45]
	v_mad_i64_i32 v[60:61], s[10:11], v60, s80, v[44:45]
	v_mad_i64_i32 v[62:63], s[10:11], v62, s80, v[44:45]
	v_mad_i64_i32 v[64:65], s[10:11], v64, s80, v[44:45]
	v_mad_i64_i32 v[66:67], s[10:11], v66, s80, v[44:45]
	v_mad_i64_i32 v[68:69], s[10:11], v68, s80, v[44:45]
	v_mad_i64_i32 v[70:71], s[10:11], v70, s80, v[44:45]
	v_mad_i64_i32 v[72:73], s[10:11], v72, s80, v[44:45]
	v_mad_i64_i32 v[74:75], s[10:11], v74, s80, v[44:45]
	v_mad_i64_i32 v[76:77], s[10:11], v76, s80, v[44:45]
	global_load_dword v11, v[46:47], off
	global_load_dword v13, v[48:49], off
	global_load_dword v84, v[50:51], off
	global_load_dword v85, v[52:53], off
	global_load_dword v86, v[54:55], off
	global_load_dword v87, v[56:57], off
	global_load_dword v88, v[58:59], off
	global_load_dword v89, v[60:61], off
	global_load_dword v90, v[62:63], off
	global_load_dword v91, v[64:65], off
	global_load_dword v92, v[66:67], off
	global_load_dword v93, v[68:69], off
	global_load_dword v94, v[70:71], off
	global_load_dword v95, v[72:73], off
	global_load_dword v96, v[74:75], off
	global_load_dword v97, v[76:77], off
	s_add_i32 s4, s4, 16
	s_add_i32 s3, s3, 16
	s_lshl_b32 s9, s3, 1
	s_lshl_b32 s10, s4, 1
	v_or_b32_e32 v106, s9, v1
	v_or_b32_e32 v107, s10, v2
	s_add_i32 s11, s9, 4
	s_add_i32 s28, s10, 4
	s_add_i32 s29, s9, 8
	s_add_i32 s30, s10, 8
	s_add_i32 s36, s9, 12
	s_add_i32 s37, s10, 12
	s_add_i32 s38, s9, 16
	s_add_i32 s39, s10, 16
	s_add_i32 s40, s9, 20
	s_add_i32 s41, s10, 20
	s_add_i32 s42, s9, 24
	s_add_i32 s43, s10, 24
	s_add_i32 s9, s9, 28
	s_add_i32 s10, s10, 28
	v_add_u32_e32 v108, s1, v106
	v_add_u32_e32 v109, s2, v107
	v_or_b32_e32 v110, s11, v1
	v_or_b32_e32 v111, s28, v2
	v_or_b32_e32 v112, s29, v1
	v_or_b32_e32 v113, s30, v2
	v_or_b32_e32 v114, s36, v1
	v_or_b32_e32 v115, s37, v2
	v_or_b32_e32 v116, s38, v1
	v_or_b32_e32 v117, s39, v2
	v_or_b32_e32 v118, s40, v1
	v_or_b32_e32 v119, s41, v2
	v_or_b32_e32 v120, s42, v1
	v_or_b32_e32 v121, s43, v2
	v_or_b32_e32 v122, s9, v1
	v_or_b32_e32 v123, s10, v2
	v_mad_i64_i32 v[130:131], s[10:11], v109, s80, v[44:45]
	v_mad_i64_i32 v[132:133], s[10:11], v108, s80, v[44:45]
	v_add_u32_e32 v108, s1, v110
	v_add_u32_e32 v109, s2, v111
	v_add_u32_e32 v140, s1, v112
	v_add_u32_e32 v138, s2, v113
	v_add_u32_e32 v144, s1, v114
	v_add_u32_e32 v142, s2, v115
	v_add_u32_e32 v148, s1, v116
	v_add_u32_e32 v146, s2, v117
	v_add_u32_e32 v152, s1, v118
	v_add_u32_e32 v150, s2, v119
	v_add_u32_e32 v156, s1, v120
	v_add_u32_e32 v154, s2, v121
	v_add_u32_e32 v160, s1, v122
	v_add_u32_e32 v158, s2, v123
	v_mad_i64_i32 v[134:135], s[10:11], v109, s80, v[44:45]
	v_mad_i64_i32 v[136:137], s[10:11], v108, s80, v[44:45]
	v_mad_i64_i32 v[138:139], s[10:11], v138, s80, v[44:45]
	v_mad_i64_i32 v[140:141], s[10:11], v140, s80, v[44:45]
	v_mad_i64_i32 v[142:143], s[10:11], v142, s80, v[44:45]
	v_mad_i64_i32 v[144:145], s[10:11], v144, s80, v[44:45]
	v_mad_i64_i32 v[146:147], s[10:11], v146, s80, v[44:45]
	v_mad_i64_i32 v[148:149], s[10:11], v148, s80, v[44:45]
	v_mad_i64_i32 v[150:151], s[10:11], v150, s80, v[44:45]
	v_mad_i64_i32 v[152:153], s[10:11], v152, s80, v[44:45]
	v_mad_i64_i32 v[154:155], s[10:11], v154, s80, v[44:45]
	v_mad_i64_i32 v[156:157], s[10:11], v156, s80, v[44:45]
	v_mad_i64_i32 v[158:159], s[10:11], v158, s80, v[44:45]
	v_mad_i64_i32 v[160:161], s[10:11], v160, s80, v[44:45]
	global_load_dword v108, v[130:131], off
	global_load_dword v109, v[132:133], off
	global_load_dword v124, v[134:135], off
	global_load_dword v125, v[136:137], off
	global_load_dword v126, v[138:139], off
	global_load_dword v127, v[140:141], off
	global_load_dword v162, v[142:143], off
	global_load_dword v163, v[144:145], off
	global_load_dword v164, v[146:147], off
	global_load_dword v165, v[148:149], off
	global_load_dword v166, v[150:151], off
	global_load_dword v167, v[152:153], off
	global_load_dword v168, v[154:155], off
	global_load_dword v169, v[156:157], off
	global_load_dword v170, v[158:159], off
	global_load_dword v171, v[160:161], off
	v_mad_u64_u32 v[46:47], s[10:11], v9, s78, v[6:7]
	v_mad_u64_u32 v[48:49], s[10:11], v7, s78, v[6:7]
	v_mad_u64_u32 v[50:51], s[10:11], v17, s78, v[6:7]
	v_mad_u64_u32 v[52:53], s[10:11], v15, s78, v[6:7]
	v_mad_u64_u32 v[54:55], s[10:11], v35, s78, v[6:7]
	v_mad_u64_u32 v[56:57], s[10:11], v21, s78, v[6:7]
	v_mad_u64_u32 v[58:59], s[10:11], v39, s78, v[6:7]
	v_mad_u64_u32 v[60:61], s[10:11], v37, s78, v[6:7]
	v_mad_u64_u32 v[62:63], s[10:11], v43, s78, v[6:7]
	v_mad_u64_u32 v[64:65], s[10:11], v41, s78, v[6:7]
	v_mad_u64_u32 v[66:67], s[10:11], v79, s78, v[6:7]
	v_mad_u64_u32 v[68:69], s[10:11], v78, s78, v[6:7]
	v_mad_u64_u32 v[70:71], s[10:11], v81, s78, v[6:7]
	v_mad_u64_u32 v[72:73], s[10:11], v80, s78, v[6:7]
	v_mad_u64_u32 v[74:75], s[10:11], v83, s78, v[6:7]
	v_mad_u64_u32 v[76:77], s[10:11], v82, s78, v[6:7]
	s_waitcnt vmcnt(31)
	ds_write_b32 v46, v11
	s_waitcnt vmcnt(30)
	ds_write_b32 v48, v13
	s_waitcnt vmcnt(29)
	ds_write_b32 v50, v84
	s_waitcnt vmcnt(28)
	ds_write_b32 v52, v85
	s_waitcnt vmcnt(27)
	ds_write_b32 v54, v86
	s_waitcnt vmcnt(26)
	ds_write_b32 v56, v87
	s_waitcnt vmcnt(25)
	ds_write_b32 v58, v88
	s_waitcnt vmcnt(24)
	ds_write_b32 v60, v89
	s_waitcnt vmcnt(23)
	ds_write_b32 v62, v90
	s_waitcnt vmcnt(22)
	ds_write_b32 v64, v91
	s_waitcnt vmcnt(21)
	ds_write_b32 v66, v92
	s_waitcnt vmcnt(20)
	ds_write_b32 v68, v93
	s_waitcnt vmcnt(19)
	ds_write_b32 v70, v94
	s_waitcnt vmcnt(18)
	ds_write_b32 v72, v95
	s_waitcnt vmcnt(17)
	ds_write_b32 v74, v96
	s_waitcnt vmcnt(16)
	ds_write_b32 v76, v97
	v_mad_u64_u32 v[130:131], s[10:11], v107, s78, v[6:7]
	v_mad_u64_u32 v[132:133], s[10:11], v106, s78, v[6:7]
	v_mad_u64_u32 v[134:135], s[10:11], v111, s78, v[6:7]
	v_mad_u64_u32 v[136:137], s[10:11], v110, s78, v[6:7]
	v_mad_u64_u32 v[138:139], s[10:11], v113, s78, v[6:7]
	v_mad_u64_u32 v[140:141], s[10:11], v112, s78, v[6:7]
	v_mad_u64_u32 v[142:143], s[10:11], v115, s78, v[6:7]
	v_mad_u64_u32 v[144:145], s[10:11], v114, s78, v[6:7]
	v_mad_u64_u32 v[146:147], s[10:11], v117, s78, v[6:7]
	v_mad_u64_u32 v[148:149], s[10:11], v116, s78, v[6:7]
	v_mad_u64_u32 v[150:151], s[10:11], v119, s78, v[6:7]
	v_mad_u64_u32 v[152:153], s[10:11], v118, s78, v[6:7]
	v_mad_u64_u32 v[154:155], s[10:11], v121, s78, v[6:7]
	v_mad_u64_u32 v[156:157], s[10:11], v120, s78, v[6:7]
	v_mad_u64_u32 v[158:159], s[10:11], v123, s78, v[6:7]
	v_mad_u64_u32 v[160:161], s[10:11], v122, s78, v[6:7]
	s_waitcnt vmcnt(15)
	ds_write_b32 v130, v108
	s_waitcnt vmcnt(14)
	ds_write_b32 v132, v109
	s_waitcnt vmcnt(13)
	ds_write_b32 v134, v124
	s_waitcnt vmcnt(12)
	ds_write_b32 v136, v125
	s_waitcnt vmcnt(11)
	ds_write_b32 v138, v126
	s_waitcnt vmcnt(10)
	ds_write_b32 v140, v127
	s_waitcnt vmcnt(9)
	ds_write_b32 v142, v162
	s_waitcnt vmcnt(8)
	ds_write_b32 v144, v163
	s_waitcnt vmcnt(7)
	ds_write_b32 v146, v164
	s_waitcnt vmcnt(6)
	ds_write_b32 v148, v165
	s_waitcnt vmcnt(5)
	ds_write_b32 v150, v166
	s_waitcnt vmcnt(4)
	ds_write_b32 v152, v167
	s_waitcnt vmcnt(3)
	ds_write_b32 v154, v168
	s_waitcnt vmcnt(2)
	ds_write_b32 v156, v169
	s_waitcnt vmcnt(1)
	ds_write_b32 v158, v170
	s_waitcnt vmcnt(0)
	ds_write_b32 v160, v171
	s_add_i32 s4, s4, 16
	s_add_i32 s3, s3, 16
	s_add_i32 s5, s5, -16
	s_add_i32 s5, s5, -16
	s_cmp_lg_u32 s5, 0
	s_waitcnt lgkmcnt(0)
	s_add_i32 s1, s8, 0xf500
	ds_read2_b32 v[48:49], v3 offset1:8
	s_cmpk_lt_i32 s0, 0x58
	ds_read2_b32 v[52:53], v3 offset0:33 offset1:41
	s_cselect_b32 s0, s8, s1
	s_sext_i32_i16 s1, s0
	ds_read2_b32 v[54:55], v3 offset0:66 offset1:74
	s_cselect_b32 s3, 0, 0x80
	s_bfe_u32 s1, s1, 0x70018
	ds_read2_b32 v[56:57], v3 offset0:99 offset1:107
	s_add_i32 s1, s0, s1
	s_waitcnt lgkmcnt(3)
	v_bfe_u32 v7, v48, 16, 1
	s_sext_i32_i16 s4, s1
	s_and_b32 s1, s1, 0xff80
	v_add3_u32 v7, v48, v7, s33
	s_waitcnt lgkmcnt(2)
	v_bfe_u32 v9, v52, 16, 1
	ds_read2_b32 v[58:59], v3 offset0:132 offset1:140
	s_sub_i32 s0, s0, s1
	v_lshrrev_b32_e32 v7, 16, v7
	v_add3_u32 v9, v52, v9, s33
	ds_read2_b32 v[60:61], v3 offset0:165 offset1:173
	s_lshl_b32 s4, s4, 1
	s_sext_i32_i16 s0, s0
	v_and_or_b32 v44, v9, s69, v7
	s_waitcnt lgkmcnt(3)
	v_bfe_u32 v7, v54, 16, 1
	s_and_b32 s4, s4, 0xffffff00
	s_add_i32 s0, s3, s0
	v_add3_u32 v7, v54, v7, s33
	s_waitcnt lgkmcnt(2)
	v_bfe_u32 v9, v56, 16, 1
	ds_read2_b32 v[62:63], v3 offset0:198 offset1:206
	s_add_i32 s0, s0, s4
	v_lshrrev_b32_e32 v7, 16, v7
	v_add3_u32 v9, v56, v9, s33
	ds_read2_b32 v[64:65], v3 offset0:231 offset1:239
	s_ashr_i32 s1, s0, 31
	v_and_or_b32 v45, v9, s69, v7
	s_waitcnt lgkmcnt(3)
	v_bfe_u32 v7, v58, 16, 1
	s_lshl_b64 s[0:1], s[0:1], 11
	v_add3_u32 v7, v58, v7, s33
	s_waitcnt lgkmcnt(2)
	v_bfe_u32 v9, v60, 16, 1
	s_add_u32 s4, s13, s0
	v_lshrrev_b32_e32 v7, 16, v7
	v_add3_u32 v9, v60, v9, s33
	s_addc_u32 s5, s14, s1
	s_ashr_i32 s3, s2, 31
	v_and_or_b32 v46, v9, s69, v7
	s_waitcnt lgkmcnt(1)
	v_bfe_u32 v7, v62, 16, 1
	s_lshl_b64 s[0:1], s[2:3], 1
	v_add3_u32 v7, v62, v7, s33
	s_waitcnt lgkmcnt(0)
	v_bfe_u32 v9, v64, 16, 1
	s_add_u32 s0, s4, s0
	v_lshrrev_b32_e32 v7, 16, v7
	v_add3_u32 v9, v64, v9, s33
	s_addc_u32 s1, s5, s1
	v_lshlrev_b32_e32 v128, 1, v8
	v_and_or_b32 v47, v9, s69, v7
	v_bfe_u32 v7, v49, 16, 1
	v_lshl_add_u64 v[50:51], s[0:1], 0, v[128:129]
	v_lshlrev_b32_e32 v128, 1, v10
	v_add3_u32 v7, v49, v7, s33
	v_bfe_u32 v9, v53, 16, 1
	v_lshl_add_u64 v[66:67], v[50:51], 0, v[128:129]
	v_lshrrev_b32_e32 v7, 16, v7
	v_add3_u32 v9, v53, v9, s33
	global_store_dwordx4 v[66:67], v[44:47], off
	v_lshlrev_b32_e32 v128, 1, v12
	ds_read2_b32 v[48:49], v3 offset0:16 offset1:24
	v_and_or_b32 v44, v9, s69, v7
	v_bfe_u32 v7, v55, 16, 1
	v_add3_u32 v7, v55, v7, s33
	v_bfe_u32 v9, v57, 16, 1
	v_lshrrev_b32_e32 v7, 16, v7
	v_add3_u32 v9, v57, v9, s33
	v_and_or_b32 v45, v9, s69, v7
	v_bfe_u32 v7, v59, 16, 1
	v_add3_u32 v7, v59, v7, s33
	v_bfe_u32 v9, v61, 16, 1
	v_lshrrev_b32_e32 v7, 16, v7
	v_add3_u32 v9, v61, v9, s33
	v_and_or_b32 v46, v9, s69, v7
	v_bfe_u32 v7, v63, 16, 1
	v_add3_u32 v7, v63, v7, s33
	v_bfe_u32 v9, v65, 16, 1
	v_lshrrev_b32_e32 v7, 16, v7
	v_add3_u32 v9, v65, v9, s33
	v_and_or_b32 v47, v9, s69, v7
	v_lshl_add_u64 v[52:53], v[50:51], 0, v[128:129]
	global_store_dwordx4 v[52:53], v[44:47], off
	ds_read2_b32 v[52:53], v3 offset0:49 offset1:57
	ds_read2_b32 v[54:55], v3 offset0:82 offset1:90
	ds_read2_b32 v[56:57], v3 offset0:115 offset1:123
	s_waitcnt lgkmcnt(3)
	v_bfe_u32 v7, v48, 16, 1
	v_add3_u32 v7, v48, v7, s33
	s_waitcnt lgkmcnt(2)
	v_bfe_u32 v9, v52, 16, 1
	ds_read2_b32 v[58:59], v3 offset0:148 offset1:156
	v_lshrrev_b32_e32 v7, 16, v7
	v_add3_u32 v9, v52, v9, s33
	ds_read2_b32 v[60:61], v3 offset0:181 offset1:189
	v_and_or_b32 v44, v9, s69, v7
	s_waitcnt lgkmcnt(3)
	v_bfe_u32 v7, v54, 16, 1
	v_add3_u32 v7, v54, v7, s33
	s_waitcnt lgkmcnt(2)
	v_bfe_u32 v9, v56, 16, 1
	ds_read2_b32 v[62:63], v3 offset0:214 offset1:222
	v_lshrrev_b32_e32 v7, 16, v7
	v_add3_u32 v9, v56, v9, s33
	ds_read2_b32 v[64:65], v3 offset0:247 offset1:255
	v_and_or_b32 v45, v9, s69, v7
	s_waitcnt lgkmcnt(3)
	v_bfe_u32 v7, v58, 16, 1
	v_add3_u32 v7, v58, v7, s33
	s_waitcnt lgkmcnt(2)
	v_bfe_u32 v9, v60, 16, 1
	v_lshrrev_b32_e32 v7, 16, v7
	v_add3_u32 v9, v60, v9, s33
	v_and_or_b32 v46, v9, s69, v7
	s_waitcnt lgkmcnt(1)
	v_bfe_u32 v7, v62, 16, 1
	v_add3_u32 v7, v62, v7, s33
	s_waitcnt lgkmcnt(0)
	v_bfe_u32 v9, v64, 16, 1
	v_lshrrev_b32_e32 v7, 16, v7
	v_add3_u32 v9, v64, v9, s33
	v_and_or_b32 v47, v9, s69, v7
	v_bfe_u32 v7, v49, 16, 1
	v_lshlrev_b32_e32 v128, 1, v14
	v_add3_u32 v7, v49, v7, s33
	v_bfe_u32 v9, v53, 16, 1
	v_lshl_add_u64 v[66:67], v[50:51], 0, v[128:129]
	v_lshrrev_b32_e32 v7, 16, v7
	v_add3_u32 v9, v53, v9, s33
	global_store_dwordx4 v[66:67], v[44:47], off
	v_lshlrev_b32_e32 v128, 1, v16
	v_lshl_add_u64 v[48:49], v[50:51], 0, v[128:129]
	v_and_or_b32 v44, v9, s69, v7
	v_bfe_u32 v7, v55, 16, 1
	v_add3_u32 v7, v55, v7, s33
	v_bfe_u32 v9, v57, 16, 1
	v_lshrrev_b32_e32 v7, 16, v7
	v_add3_u32 v9, v57, v9, s33
	v_and_or_b32 v45, v9, s69, v7
	v_bfe_u32 v7, v59, 16, 1
	v_add3_u32 v7, v59, v7, s33
	v_bfe_u32 v9, v61, 16, 1
	v_lshrrev_b32_e32 v7, 16, v7
	v_add3_u32 v9, v61, v9, s33
	v_and_or_b32 v46, v9, s69, v7
	v_bfe_u32 v7, v63, 16, 1
	v_add3_u32 v7, v63, v7, s33
	v_bfe_u32 v9, v65, 16, 1
	v_lshrrev_b32_e32 v7, 16, v7
	v_add3_u32 v9, v65, v9, s33
	v_and_or_b32 v47, v9, s69, v7
	global_store_dwordx4 v[48:49], v[44:47], off
	s_waitcnt lgkmcnt(0)
	s_mov_b32 s0, s12
	s_mov_b64 s[2:3], -1
	s_andn2_b64 vcc, exec, s[6:7]
	s_mov_b64 s[6:7], -1
	s_cbranch_vccnz .LBB0_832

.LBB0_791:
	s_lshl_b32 s11, s1, 1
	s_lshl_b32 s28, s5, 1
	v_or_b32_e32 v7, s11, v1
	v_or_b32_e32 v9, s28, v2
	s_add_i32 s29, s11, 4
	s_add_i32 s30, s28, 4
	s_add_i32 s36, s11, 8
	s_add_i32 s37, s28, 8
	s_add_i32 s38, s11, 12
	s_add_i32 s39, s28, 12
	s_add_i32 s40, s11, 16
	s_add_i32 s41, s28, 16
	s_add_i32 s42, s11, 20
	s_add_i32 s43, s28, 20
	s_add_i32 s44, s11, 24
	s_add_i32 s45, s28, 24
	s_add_i32 s11, s11, 28
	s_add_i32 s28, s28, 28
	v_add_u32_e32 v48, s8, v9
	v_or_b32_e32 v11, s29, v1
	v_or_b32_e32 v13, s30, v2
	v_or_b32_e32 v15, s36, v1
	v_or_b32_e32 v17, s37, v2
	v_or_b32_e32 v21, s38, v1
	v_or_b32_e32 v35, s39, v2
	v_or_b32_e32 v37, s40, v1
	v_or_b32_e32 v39, s41, v2
	v_or_b32_e32 v41, s42, v1
	v_or_b32_e32 v43, s43, v2
	v_or_b32_e32 v78, s44, v1
	v_or_b32_e32 v79, s45, v2
	v_or_b32_e32 v80, s11, v1
	v_or_b32_e32 v81, s28, v2
	v_add_u32_e32 v46, s4, v7
	v_ashrrev_i32_e32 v49, 31, v48
	v_add_u32_e32 v50, s4, v11
	v_add_u32_e32 v52, s8, v13
	v_add_u32_e32 v54, s4, v15
	v_add_u32_e32 v56, s8, v17
	v_add_u32_e32 v58, s4, v21
	v_add_u32_e32 v60, s8, v35
	v_add_u32_e32 v62, s4, v37
	v_add_u32_e32 v64, s8, v39
	v_add_u32_e32 v66, s4, v41
	v_add_u32_e32 v68, s8, v43
	v_add_u32_e32 v70, s4, v78
	v_add_u32_e32 v72, s8, v79
	v_add_u32_e32 v74, s4, v80
	v_add_u32_e32 v76, s8, v81
	v_ashrrev_i32_e32 v47, 31, v46
	v_lshlrev_b64 v[48:49], 12, v[48:49]
	v_ashrrev_i32_e32 v53, 31, v52
	v_ashrrev_i32_e32 v51, 31, v50
	v_ashrrev_i32_e32 v57, 31, v56
	v_ashrrev_i32_e32 v55, 31, v54
	v_ashrrev_i32_e32 v61, 31, v60
	v_ashrrev_i32_e32 v59, 31, v58
	v_ashrrev_i32_e32 v65, 31, v64
	v_ashrrev_i32_e32 v63, 31, v62
	v_ashrrev_i32_e32 v69, 31, v68
	v_ashrrev_i32_e32 v67, 31, v66
	v_ashrrev_i32_e32 v73, 31, v72
	v_ashrrev_i32_e32 v71, 31, v70
	v_ashrrev_i32_e32 v77, 31, v76
	v_ashrrev_i32_e32 v75, 31, v74
	v_lshlrev_b64 v[46:47], 12, v[46:47]
	v_lshl_add_u64 v[48:49], v[44:45], 0, v[48:49]
	v_lshlrev_b64 v[50:51], 12, v[50:51]
	v_lshlrev_b64 v[52:53], 12, v[52:53]
	v_lshlrev_b64 v[54:55], 12, v[54:55]
	v_lshlrev_b64 v[56:57], 12, v[56:57]
	v_lshlrev_b64 v[58:59], 12, v[58:59]
	v_lshlrev_b64 v[60:61], 12, v[60:61]
	v_lshlrev_b64 v[62:63], 12, v[62:63]
	v_lshlrev_b64 v[64:65], 12, v[64:65]
	v_lshlrev_b64 v[66:67], 12, v[66:67]
	v_lshlrev_b64 v[68:69], 12, v[68:69]
	v_lshlrev_b64 v[70:71], 12, v[70:71]
	v_lshlrev_b64 v[72:73], 12, v[72:73]
	v_lshlrev_b64 v[74:75], 12, v[74:75]
	v_lshlrev_b64 v[76:77], 12, v[76:77]
	v_lshl_add_u64 v[46:47], v[44:45], 0, v[46:47]
	v_lshl_add_u64 v[52:53], v[44:45], 0, v[52:53]
	v_lshl_add_u64 v[50:51], v[44:45], 0, v[50:51]
	v_lshl_add_u64 v[56:57], v[44:45], 0, v[56:57]
	v_lshl_add_u64 v[54:55], v[44:45], 0, v[54:55]
	v_lshl_add_u64 v[60:61], v[44:45], 0, v[60:61]
	v_lshl_add_u64 v[58:59], v[44:45], 0, v[58:59]
	v_lshl_add_u64 v[64:65], v[44:45], 0, v[64:65]
	v_lshl_add_u64 v[62:63], v[44:45], 0, v[62:63]
	v_lshl_add_u64 v[68:69], v[44:45], 0, v[68:69]
	v_lshl_add_u64 v[66:67], v[44:45], 0, v[66:67]
	v_lshl_add_u64 v[72:73], v[44:45], 0, v[72:73]
	v_lshl_add_u64 v[70:71], v[44:45], 0, v[70:71]
	v_lshl_add_u64 v[76:77], v[44:45], 0, v[76:77]
	v_lshl_add_u64 v[74:75], v[44:45], 0, v[74:75]
	global_load_dword v82, v[48:49], off
	global_load_dword v83, v[46:47], off
	global_load_dword v84, v[52:53], off
	global_load_dword v85, v[50:51], off
	global_load_dword v86, v[56:57], off
	global_load_dword v87, v[54:55], off
	global_load_dword v88, v[60:61], off
	global_load_dword v89, v[58:59], off
	global_load_dword v90, v[64:65], off
	global_load_dword v91, v[62:63], off
	global_load_dword v92, v[68:69], off
	global_load_dword v93, v[66:67], off
	global_load_dword v94, v[72:73], off
	global_load_dword v95, v[70:71], off
	global_load_dword v96, v[76:77], off
	global_load_dword v97, v[74:75], off
	s_add_i32 s5, s5, 16
	s_add_i32 s1, s1, 16
	s_lshl_b32 s11, s1, 1
	s_lshl_b32 s28, s5, 1
	v_or_b32_e32 v106, s11, v1
	v_or_b32_e32 v107, s28, v2
	s_add_i32 s29, s11, 4
	s_add_i32 s30, s28, 4
	s_add_i32 s36, s11, 8
	s_add_i32 s37, s28, 8
	s_add_i32 s38, s11, 12
	s_add_i32 s39, s28, 12
	s_add_i32 s40, s11, 16
	s_add_i32 s41, s28, 16
	s_add_i32 s42, s11, 20
	s_add_i32 s43, s28, 20
	s_add_i32 s44, s11, 24
	s_add_i32 s45, s28, 24
	s_add_i32 s11, s11, 28
	s_add_i32 s28, s28, 28
	v_add_u32_e32 v132, s8, v107
	v_or_b32_e32 v108, s29, v1
	v_or_b32_e32 v109, s30, v2
	v_or_b32_e32 v110, s36, v1
	v_or_b32_e32 v111, s37, v2
	v_or_b32_e32 v112, s38, v1
	v_or_b32_e32 v113, s39, v2
	v_or_b32_e32 v114, s40, v1
	v_or_b32_e32 v115, s41, v2
	v_or_b32_e32 v116, s42, v1
	v_or_b32_e32 v117, s43, v2
	v_or_b32_e32 v118, s44, v1
	v_or_b32_e32 v119, s45, v2
	v_or_b32_e32 v120, s11, v1
	v_or_b32_e32 v121, s28, v2
	v_add_u32_e32 v130, s4, v106
	v_ashrrev_i32_e32 v133, 31, v132
	v_add_u32_e32 v134, s4, v108
	v_add_u32_e32 v136, s8, v109
	v_add_u32_e32 v138, s4, v110
	v_add_u32_e32 v140, s8, v111
	v_add_u32_e32 v142, s4, v112
	v_add_u32_e32 v144, s8, v113
	v_add_u32_e32 v146, s4, v114
	v_add_u32_e32 v148, s8, v115
	v_add_u32_e32 v150, s4, v116
	v_add_u32_e32 v152, s8, v117
	v_add_u32_e32 v154, s4, v118
	v_add_u32_e32 v156, s8, v119
	v_add_u32_e32 v158, s4, v120
	v_add_u32_e32 v160, s8, v121
	v_ashrrev_i32_e32 v131, 31, v130
	v_lshlrev_b64 v[132:133], 12, v[132:133]
	v_ashrrev_i32_e32 v137, 31, v136
	v_ashrrev_i32_e32 v135, 31, v134
	v_ashrrev_i32_e32 v141, 31, v140
	v_ashrrev_i32_e32 v139, 31, v138
	v_ashrrev_i32_e32 v145, 31, v144
	v_ashrrev_i32_e32 v143, 31, v142
	v_ashrrev_i32_e32 v149, 31, v148
	v_ashrrev_i32_e32 v147, 31, v146
	v_ashrrev_i32_e32 v153, 31, v152
	v_ashrrev_i32_e32 v151, 31, v150
	v_ashrrev_i32_e32 v157, 31, v156
	v_ashrrev_i32_e32 v155, 31, v154
	v_ashrrev_i32_e32 v161, 31, v160
	v_ashrrev_i32_e32 v159, 31, v158
	v_lshlrev_b64 v[130:131], 12, v[130:131]
	v_lshl_add_u64 v[132:133], v[44:45], 0, v[132:133]
	v_lshlrev_b64 v[134:135], 12, v[134:135]
	v_lshlrev_b64 v[136:137], 12, v[136:137]
	v_lshlrev_b64 v[138:139], 12, v[138:139]
	v_lshlrev_b64 v[140:141], 12, v[140:141]
	v_lshlrev_b64 v[142:143], 12, v[142:143]
	v_lshlrev_b64 v[144:145], 12, v[144:145]
	v_lshlrev_b64 v[146:147], 12, v[146:147]
	v_lshlrev_b64 v[148:149], 12, v[148:149]
	v_lshlrev_b64 v[150:151], 12, v[150:151]
	v_lshlrev_b64 v[152:153], 12, v[152:153]
	v_lshlrev_b64 v[154:155], 12, v[154:155]
	v_lshlrev_b64 v[156:157], 12, v[156:157]
	v_lshlrev_b64 v[158:159], 12, v[158:159]
	v_lshlrev_b64 v[160:161], 12, v[160:161]
	v_lshl_add_u64 v[130:131], v[44:45], 0, v[130:131]
	v_lshl_add_u64 v[136:137], v[44:45], 0, v[136:137]
	v_lshl_add_u64 v[134:135], v[44:45], 0, v[134:135]
	v_lshl_add_u64 v[140:141], v[44:45], 0, v[140:141]
	v_lshl_add_u64 v[138:139], v[44:45], 0, v[138:139]
	v_lshl_add_u64 v[144:145], v[44:45], 0, v[144:145]
	v_lshl_add_u64 v[142:143], v[44:45], 0, v[142:143]
	v_lshl_add_u64 v[148:149], v[44:45], 0, v[148:149]
	v_lshl_add_u64 v[146:147], v[44:45], 0, v[146:147]
	v_lshl_add_u64 v[152:153], v[44:45], 0, v[152:153]
	v_lshl_add_u64 v[150:151], v[44:45], 0, v[150:151]
	v_lshl_add_u64 v[156:157], v[44:45], 0, v[156:157]
	v_lshl_add_u64 v[154:155], v[44:45], 0, v[154:155]
	v_lshl_add_u64 v[160:161], v[44:45], 0, v[160:161]
	v_lshl_add_u64 v[158:159], v[44:45], 0, v[158:159]
	global_load_dword v122, v[132:133], off
	global_load_dword v123, v[130:131], off
	global_load_dword v124, v[136:137], off
	global_load_dword v125, v[134:135], off
	global_load_dword v126, v[140:141], off
	global_load_dword v127, v[138:139], off
	global_load_dword v162, v[144:145], off
	global_load_dword v163, v[142:143], off
	global_load_dword v164, v[148:149], off
	global_load_dword v165, v[146:147], off
	global_load_dword v166, v[152:153], off
	global_load_dword v167, v[150:151], off
	global_load_dword v168, v[156:157], off
	global_load_dword v169, v[154:155], off
	global_load_dword v170, v[160:161], off
	global_load_dword v171, v[158:159], off
	v_mad_u64_u32 v[46:47], s[28:29], v9, s78, v[6:7]
	v_mad_u64_u32 v[48:49], s[28:29], v7, s78, v[6:7]
	v_mad_u64_u32 v[50:51], s[28:29], v13, s78, v[6:7]
	v_mad_u64_u32 v[52:53], s[28:29], v11, s78, v[6:7]
	v_mad_u64_u32 v[54:55], s[28:29], v17, s78, v[6:7]
	v_mad_u64_u32 v[56:57], s[28:29], v15, s78, v[6:7]
	v_mad_u64_u32 v[58:59], s[28:29], v35, s78, v[6:7]
	v_mad_u64_u32 v[60:61], s[28:29], v21, s78, v[6:7]
	v_mad_u64_u32 v[62:63], s[28:29], v39, s78, v[6:7]
	v_mad_u64_u32 v[64:65], s[28:29], v37, s78, v[6:7]
	v_mad_u64_u32 v[66:67], s[28:29], v43, s78, v[6:7]
	v_mad_u64_u32 v[68:69], s[28:29], v41, s78, v[6:7]
	v_mad_u64_u32 v[70:71], s[28:29], v79, s78, v[6:7]
	v_mad_u64_u32 v[72:73], s[28:29], v78, s78, v[6:7]
	v_mad_u64_u32 v[74:75], s[28:29], v81, s78, v[6:7]
	v_mad_u64_u32 v[76:77], s[28:29], v80, s78, v[6:7]
	s_waitcnt vmcnt(31)
	ds_write_b32 v46, v82
	s_waitcnt vmcnt(30)
	ds_write_b32 v48, v83
	s_waitcnt vmcnt(29)
	ds_write_b32 v50, v84
	s_waitcnt vmcnt(28)
	ds_write_b32 v52, v85
	s_waitcnt vmcnt(27)
	ds_write_b32 v54, v86
	s_waitcnt vmcnt(26)
	ds_write_b32 v56, v87
	s_waitcnt vmcnt(25)
	ds_write_b32 v58, v88
	s_waitcnt vmcnt(24)
	ds_write_b32 v60, v89
	s_waitcnt vmcnt(23)
	ds_write_b32 v62, v90
	s_waitcnt vmcnt(22)
	ds_write_b32 v64, v91
	s_waitcnt vmcnt(21)
	ds_write_b32 v66, v92
	s_waitcnt vmcnt(20)
	ds_write_b32 v68, v93
	s_waitcnt vmcnt(19)
	ds_write_b32 v70, v94
	s_waitcnt vmcnt(18)
	ds_write_b32 v72, v95
	s_waitcnt vmcnt(17)
	ds_write_b32 v74, v96
	s_waitcnt vmcnt(16)
	ds_write_b32 v76, v97
	v_mad_u64_u32 v[130:131], s[28:29], v107, s78, v[6:7]
	v_mad_u64_u32 v[132:133], s[28:29], v106, s78, v[6:7]
	v_mad_u64_u32 v[134:135], s[28:29], v109, s78, v[6:7]
	v_mad_u64_u32 v[136:137], s[28:29], v108, s78, v[6:7]
	v_mad_u64_u32 v[138:139], s[28:29], v111, s78, v[6:7]
	v_mad_u64_u32 v[140:141], s[28:29], v110, s78, v[6:7]
	v_mad_u64_u32 v[142:143], s[28:29], v113, s78, v[6:7]
	v_mad_u64_u32 v[144:145], s[28:29], v112, s78, v[6:7]
	v_mad_u64_u32 v[146:147], s[28:29], v115, s78, v[6:7]
	v_mad_u64_u32 v[148:149], s[28:29], v114, s78, v[6:7]
	v_mad_u64_u32 v[150:151], s[28:29], v117, s78, v[6:7]
	v_mad_u64_u32 v[152:153], s[28:29], v116, s78, v[6:7]
	v_mad_u64_u32 v[154:155], s[28:29], v119, s78, v[6:7]
	v_mad_u64_u32 v[156:157], s[28:29], v118, s78, v[6:7]
	v_mad_u64_u32 v[158:159], s[28:29], v121, s78, v[6:7]
	v_mad_u64_u32 v[160:161], s[28:29], v120, s78, v[6:7]
	s_waitcnt vmcnt(15)
	ds_write_b32 v130, v122
	s_waitcnt vmcnt(14)
	ds_write_b32 v132, v123
	s_waitcnt vmcnt(13)
	ds_write_b32 v134, v124
	s_waitcnt vmcnt(12)
	ds_write_b32 v136, v125
	s_waitcnt vmcnt(11)
	ds_write_b32 v138, v126
	s_waitcnt vmcnt(10)
	ds_write_b32 v140, v127
	s_waitcnt vmcnt(9)
	ds_write_b32 v142, v162
	s_waitcnt vmcnt(8)
	ds_write_b32 v144, v163
	s_waitcnt vmcnt(7)
	ds_write_b32 v146, v164
	s_waitcnt vmcnt(6)
	ds_write_b32 v148, v165
	s_waitcnt vmcnt(5)
	ds_write_b32 v150, v166
	s_waitcnt vmcnt(4)
	ds_write_b32 v152, v167
	s_waitcnt vmcnt(3)
	ds_write_b32 v154, v168
	s_waitcnt vmcnt(2)
	ds_write_b32 v156, v169
	s_waitcnt vmcnt(1)
	ds_write_b32 v158, v170
	s_waitcnt vmcnt(0)
	ds_write_b32 v160, v171
	s_add_i32 s5, s5, 16
	s_add_i32 s1, s1, 16
	s_add_i32 s9, s9, -16
	s_add_i32 s9, s9, -16
	s_cmp_lg_u32 s9, 0
	s_waitcnt lgkmcnt(0)
	ds_read2_b32 v[48:49], v3 offset1:8
	ds_read2_b32 v[52:53], v3 offset0:33 offset1:41
	ds_read2_b32 v[54:55], v3 offset0:66 offset1:74
	ds_read2_b32 v[56:57], v3 offset0:99 offset1:107
	ds_read2_b32 v[58:59], v3 offset0:132 offset1:140
	s_waitcnt lgkmcnt(4)
	v_bfe_u32 v7, v48, 16, 1
	v_add3_u32 v7, v48, v7, s33
	s_waitcnt lgkmcnt(3)
	v_bfe_u32 v9, v52, 16, 1
	v_lshrrev_b32_e32 v7, 16, v7
	v_add3_u32 v9, v52, v9, s33
	ds_read2_b32 v[60:61], v3 offset0:165 offset1:173
	v_and_or_b32 v44, v9, s69, v7
	s_waitcnt lgkmcnt(3)
	v_bfe_u32 v7, v54, 16, 1
	v_add3_u32 v7, v54, v7, s33
	s_waitcnt lgkmcnt(2)
	v_bfe_u32 v9, v56, 16, 1
	ds_read2_b32 v[62:63], v3 offset0:198 offset1:206
	v_lshrrev_b32_e32 v7, 16, v7
	v_add3_u32 v9, v56, v9, s33
	ds_read2_b32 v[64:65], v3 offset0:231 offset1:239
	v_and_or_b32 v45, v9, s69, v7
	s_waitcnt lgkmcnt(3)
	v_bfe_u32 v7, v58, 16, 1
	s_mul_i32 s4, s10, 0x1600
	v_add3_u32 v7, v58, v7, s33
	s_waitcnt lgkmcnt(2)
	v_bfe_u32 v9, v60, 16, 1
	s_mul_hi_i32 s1, s10, 0x1600
	s_add_u32 s10, s18, s4
	v_lshrrev_b32_e32 v7, 16, v7
	v_add3_u32 v9, v60, v9, s33
	s_addc_u32 s1, s19, s1
	s_ashr_i32 s9, s8, 31
	v_and_or_b32 v46, v9, s69, v7
	s_waitcnt lgkmcnt(1)
	v_bfe_u32 v7, v62, 16, 1
	s_lshl_b64 s[4:5], s[8:9], 1
	v_add3_u32 v7, v62, v7, s33
	s_waitcnt lgkmcnt(0)
	v_bfe_u32 v9, v64, 16, 1
	s_add_u32 s4, s10, s4
	v_lshrrev_b32_e32 v7, 16, v7
	v_add3_u32 v9, v64, v9, s33
	s_addc_u32 s5, s1, s5
	v_lshlrev_b32_e32 v128, 1, v8
	v_and_or_b32 v47, v9, s69, v7
	v_bfe_u32 v7, v49, 16, 1
	v_lshl_add_u64 v[50:51], s[4:5], 0, v[128:129]
	v_lshlrev_b32_e32 v128, 1, v20
	v_add3_u32 v7, v49, v7, s33
	v_bfe_u32 v9, v53, 16, 1
	v_lshl_add_u64 v[50:51], v[50:51], 0, v[128:129]
	v_lshrrev_b32_e32 v7, 16, v7
	v_add3_u32 v9, v53, v9, s33
	global_store_dwordx4 v[50:51], v[44:47], off
	v_add_co_u32_e32 v52, vcc, s47, v50
	s_nop 0
	v_and_or_b32 v44, v9, s69, v7
	v_bfe_u32 v7, v55, 16, 1
	v_add3_u32 v7, v55, v7, s33
	v_bfe_u32 v9, v57, 16, 1
	v_lshrrev_b32_e32 v7, 16, v7
	v_add3_u32 v9, v57, v9, s33
	v_and_or_b32 v45, v9, s69, v7
	v_bfe_u32 v7, v59, 16, 1
	v_add3_u32 v7, v59, v7, s33
	v_bfe_u32 v9, v61, 16, 1
	v_lshrrev_b32_e32 v7, 16, v7
	v_add3_u32 v9, v61, v9, s33
	v_and_or_b32 v46, v9, s69, v7
	v_bfe_u32 v7, v63, 16, 1
	v_add3_u32 v7, v63, v7, s33
	v_bfe_u32 v9, v65, 16, 1
	v_lshrrev_b32_e32 v7, 16, v7
	v_add3_u32 v9, v65, v9, s33
	v_and_or_b32 v47, v9, s69, v7
	ds_read2_b32 v[48:49], v3 offset0:16 offset1:24
	v_addc_co_u32_e32 v53, vcc, 0, v51, vcc
	global_store_dwordx4 v[52:53], v[44:47], off
	ds_read2_b32 v[52:53], v3 offset0:49 offset1:57
	ds_read2_b32 v[54:55], v3 offset0:82 offset1:90
	ds_read2_b32 v[56:57], v3 offset0:115 offset1:123
	s_waitcnt lgkmcnt(3)
	v_bfe_u32 v7, v48, 16, 1
	v_add3_u32 v7, v48, v7, s33
	s_waitcnt lgkmcnt(2)
	v_bfe_u32 v9, v52, 16, 1
	ds_read2_b32 v[58:59], v3 offset0:148 offset1:156
	v_lshrrev_b32_e32 v7, 16, v7
	v_add3_u32 v9, v52, v9, s33
	ds_read2_b32 v[60:61], v3 offset0:181 offset1:189
	v_and_or_b32 v44, v9, s69, v7
	s_waitcnt lgkmcnt(3)
	v_bfe_u32 v7, v54, 16, 1
	v_add3_u32 v7, v54, v7, s33
	s_waitcnt lgkmcnt(2)
	v_bfe_u32 v9, v56, 16, 1
	ds_read2_b32 v[62:63], v3 offset0:214 offset1:222
	v_lshrrev_b32_e32 v7, 16, v7
	v_add3_u32 v9, v56, v9, s33
	ds_read2_b32 v[64:65], v3 offset0:247 offset1:255
	v_and_or_b32 v45, v9, s69, v7
	s_waitcnt lgkmcnt(3)
	v_bfe_u32 v7, v58, 16, 1
	v_add3_u32 v7, v58, v7, s33
	s_waitcnt lgkmcnt(2)
	v_bfe_u32 v9, v60, 16, 1
	v_lshrrev_b32_e32 v7, 16, v7
	v_add3_u32 v9, v60, v9, s33
	v_and_or_b32 v46, v9, s69, v7
	s_waitcnt lgkmcnt(1)
	v_bfe_u32 v7, v62, 16, 1
	v_add3_u32 v7, v62, v7, s33
	s_waitcnt lgkmcnt(0)
	v_bfe_u32 v9, v64, 16, 1
	v_lshrrev_b32_e32 v7, 16, v7
	v_add3_u32 v9, v64, v9, s33
	v_and_or_b32 v47, v9, s69, v7
	v_bfe_u32 v7, v49, 16, 1
	v_add_co_u32_e32 v66, vcc, s48, v50
	v_add3_u32 v7, v49, v7, s33
	v_bfe_u32 v9, v53, 16, 1
	v_addc_co_u32_e32 v67, vcc, 0, v51, vcc
	v_lshrrev_b32_e32 v7, 16, v7
	v_add3_u32 v9, v53, v9, s33
	global_store_dwordx4 v[66:67], v[44:47], off
	v_add_co_u32_e32 v48, vcc, 0x21000, v50
	s_nop 0
	v_and_or_b32 v44, v9, s69, v7
	v_bfe_u32 v7, v55, 16, 1
	v_add3_u32 v7, v55, v7, s33
	v_bfe_u32 v9, v57, 16, 1
	v_lshrrev_b32_e32 v7, 16, v7
	v_add3_u32 v9, v57, v9, s33
	v_and_or_b32 v45, v9, s69, v7
	v_bfe_u32 v7, v59, 16, 1
	v_add3_u32 v7, v59, v7, s33
	v_bfe_u32 v9, v61, 16, 1
	v_lshrrev_b32_e32 v7, 16, v7
	v_add3_u32 v9, v61, v9, s33
	v_and_or_b32 v46, v9, s69, v7
	v_bfe_u32 v7, v63, 16, 1
	v_add3_u32 v7, v63, v7, s33
	v_bfe_u32 v9, v65, 16, 1
	v_lshrrev_b32_e32 v7, 16, v7
	v_add3_u32 v9, v65, v9, s33
	v_and_or_b32 v47, v9, s69, v7
	v_addc_co_u32_e32 v49, vcc, 0, v51, vcc
	global_store_dwordx4 v[48:49], v[44:47], off
	s_waitcnt lgkmcnt(0)
	s_mov_b32 s1, s0
	s_andn2_b64 vcc, exec, s[6:7]
	s_mov_b64 s[6:7], -1
	s_cbranch_vccnz .LBB0_832

.LBB0_798:
	s_lshl_b32 s28, s5, 1
	s_lshl_b32 s29, s9, 1
	v_or_b32_e32 v7, s28, v1
	v_or_b32_e32 v9, s29, v2
	s_add_i32 s30, s28, 4
	s_add_i32 s36, s29, 4
	s_add_i32 s37, s28, 8
	s_add_i32 s38, s29, 8
	s_add_i32 s39, s28, 12
	s_add_i32 s40, s29, 12
	s_add_i32 s41, s28, 16
	s_add_i32 s42, s29, 16
	s_add_i32 s43, s28, 20
	s_add_i32 s44, s29, 20
	s_add_i32 s45, s28, 24
	s_add_i32 s46, s29, 24
	s_add_i32 s28, s28, 28
	s_add_i32 s29, s29, 28
	v_add_u32_e32 v11, s4, v7
	v_add_u32_e32 v13, s8, v9
	v_or_b32_e32 v15, s30, v1
	v_or_b32_e32 v17, s36, v2
	v_or_b32_e32 v21, s37, v1
	v_or_b32_e32 v35, s38, v2
	v_or_b32_e32 v37, s39, v1
	v_or_b32_e32 v39, s40, v2
	v_or_b32_e32 v41, s41, v1
	v_or_b32_e32 v43, s42, v2
	v_or_b32_e32 v78, s43, v1
	v_or_b32_e32 v79, s44, v2
	v_or_b32_e32 v80, s45, v1
	v_or_b32_e32 v81, s46, v2
	v_or_b32_e32 v82, s28, v1
	v_or_b32_e32 v83, s29, v2
	v_mad_i64_i32 v[46:47], s[28:29], v13, s80, v[44:45]
	v_mad_i64_i32 v[48:49], s[28:29], v11, s80, v[44:45]
	v_add_u32_e32 v11, s4, v15
	v_add_u32_e32 v13, s8, v17
	v_add_u32_e32 v56, s4, v21
	v_add_u32_e32 v54, s8, v35
	v_add_u32_e32 v60, s4, v37
	v_add_u32_e32 v58, s8, v39
	v_add_u32_e32 v64, s4, v41
	v_add_u32_e32 v62, s8, v43
	v_add_u32_e32 v68, s4, v78
	v_add_u32_e32 v66, s8, v79
	v_add_u32_e32 v72, s4, v80
	v_add_u32_e32 v70, s8, v81
	v_add_u32_e32 v76, s4, v82
	v_add_u32_e32 v74, s8, v83
	v_mad_i64_i32 v[50:51], s[28:29], v13, s80, v[44:45]
	v_mad_i64_i32 v[52:53], s[28:29], v11, s80, v[44:45]
	v_mad_i64_i32 v[54:55], s[28:29], v54, s80, v[44:45]
	v_mad_i64_i32 v[56:57], s[28:29], v56, s80, v[44:45]
	v_mad_i64_i32 v[58:59], s[28:29], v58, s80, v[44:45]
	v_mad_i64_i32 v[60:61], s[28:29], v60, s80, v[44:45]
	v_mad_i64_i32 v[62:63], s[28:29], v62, s80, v[44:45]
	v_mad_i64_i32 v[64:65], s[28:29], v64, s80, v[44:45]
	v_mad_i64_i32 v[66:67], s[28:29], v66, s80, v[44:45]
	v_mad_i64_i32 v[68:69], s[28:29], v68, s80, v[44:45]
	v_mad_i64_i32 v[70:71], s[28:29], v70, s80, v[44:45]
	v_mad_i64_i32 v[72:73], s[28:29], v72, s80, v[44:45]
	v_mad_i64_i32 v[74:75], s[28:29], v74, s80, v[44:45]
	v_mad_i64_i32 v[76:77], s[28:29], v76, s80, v[44:45]
	global_load_dword v11, v[46:47], off
	global_load_dword v13, v[48:49], off
	global_load_dword v84, v[50:51], off
	global_load_dword v85, v[52:53], off
	global_load_dword v86, v[54:55], off
	global_load_dword v87, v[56:57], off
	global_load_dword v88, v[58:59], off
	global_load_dword v89, v[60:61], off
	global_load_dword v90, v[62:63], off
	global_load_dword v91, v[64:65], off
	global_load_dword v92, v[66:67], off
	global_load_dword v93, v[68:69], off
	global_load_dword v94, v[70:71], off
	global_load_dword v95, v[72:73], off
	global_load_dword v96, v[74:75], off
	global_load_dword v97, v[76:77], off
	s_add_i32 s9, s9, 16
	s_add_i32 s5, s5, 16
	s_lshl_b32 s28, s5, 1
	s_lshl_b32 s29, s9, 1
	v_or_b32_e32 v106, s28, v1
	v_or_b32_e32 v107, s29, v2
	s_add_i32 s30, s28, 4
	s_add_i32 s36, s29, 4
	s_add_i32 s37, s28, 8
	s_add_i32 s38, s29, 8
	s_add_i32 s39, s28, 12
	s_add_i32 s40, s29, 12
	s_add_i32 s41, s28, 16
	s_add_i32 s42, s29, 16
	s_add_i32 s43, s28, 20
	s_add_i32 s44, s29, 20
	s_add_i32 s45, s28, 24
	s_add_i32 s46, s29, 24
	s_add_i32 s28, s28, 28
	s_add_i32 s29, s29, 28
	v_add_u32_e32 v108, s4, v106
	v_add_u32_e32 v109, s8, v107
	v_or_b32_e32 v110, s30, v1
	v_or_b32_e32 v111, s36, v2
	v_or_b32_e32 v112, s37, v1
	v_or_b32_e32 v113, s38, v2
	v_or_b32_e32 v114, s39, v1
	v_or_b32_e32 v115, s40, v2
	v_or_b32_e32 v116, s41, v1
	v_or_b32_e32 v117, s42, v2
	v_or_b32_e32 v118, s43, v1
	v_or_b32_e32 v119, s44, v2
	v_or_b32_e32 v120, s45, v1
	v_or_b32_e32 v121, s46, v2
	v_or_b32_e32 v122, s28, v1
	v_or_b32_e32 v123, s29, v2
	v_mad_i64_i32 v[130:131], s[28:29], v109, s80, v[44:45]
	v_mad_i64_i32 v[132:133], s[28:29], v108, s80, v[44:45]
	v_add_u32_e32 v108, s4, v110
	v_add_u32_e32 v109, s8, v111
	v_add_u32_e32 v140, s4, v112
	v_add_u32_e32 v138, s8, v113
	v_add_u32_e32 v144, s4, v114
	v_add_u32_e32 v142, s8, v115
	v_add_u32_e32 v148, s4, v116
	v_add_u32_e32 v146, s8, v117
	v_add_u32_e32 v152, s4, v118
	v_add_u32_e32 v150, s8, v119
	v_add_u32_e32 v156, s4, v120
	v_add_u32_e32 v154, s8, v121
	v_add_u32_e32 v160, s4, v122
	v_add_u32_e32 v158, s8, v123
	v_mad_i64_i32 v[134:135], s[28:29], v109, s80, v[44:45]
	v_mad_i64_i32 v[136:137], s[28:29], v108, s80, v[44:45]
	v_mad_i64_i32 v[138:139], s[28:29], v138, s80, v[44:45]
	v_mad_i64_i32 v[140:141], s[28:29], v140, s80, v[44:45]
	v_mad_i64_i32 v[142:143], s[28:29], v142, s80, v[44:45]
	v_mad_i64_i32 v[144:145], s[28:29], v144, s80, v[44:45]
	v_mad_i64_i32 v[146:147], s[28:29], v146, s80, v[44:45]
	v_mad_i64_i32 v[148:149], s[28:29], v148, s80, v[44:45]
	v_mad_i64_i32 v[150:151], s[28:29], v150, s80, v[44:45]
	v_mad_i64_i32 v[152:153], s[28:29], v152, s80, v[44:45]
	v_mad_i64_i32 v[154:155], s[28:29], v154, s80, v[44:45]
	v_mad_i64_i32 v[156:157], s[28:29], v156, s80, v[44:45]
	v_mad_i64_i32 v[158:159], s[28:29], v158, s80, v[44:45]
	v_mad_i64_i32 v[160:161], s[28:29], v160, s80, v[44:45]
	global_load_dword v108, v[130:131], off
	global_load_dword v109, v[132:133], off
	global_load_dword v124, v[134:135], off
	global_load_dword v125, v[136:137], off
	global_load_dword v126, v[138:139], off
	global_load_dword v127, v[140:141], off
	global_load_dword v162, v[142:143], off
	global_load_dword v163, v[144:145], off
	global_load_dword v164, v[146:147], off
	global_load_dword v165, v[148:149], off
	global_load_dword v166, v[150:151], off
	global_load_dword v167, v[152:153], off
	global_load_dword v168, v[154:155], off
	global_load_dword v169, v[156:157], off
	global_load_dword v170, v[158:159], off
	global_load_dword v171, v[160:161], off
	v_mad_u64_u32 v[46:47], s[28:29], v9, s78, v[6:7]
	v_mad_u64_u32 v[48:49], s[28:29], v7, s78, v[6:7]
	v_mad_u64_u32 v[50:51], s[28:29], v17, s78, v[6:7]
	v_mad_u64_u32 v[52:53], s[28:29], v15, s78, v[6:7]
	v_mad_u64_u32 v[54:55], s[28:29], v35, s78, v[6:7]
	v_mad_u64_u32 v[56:57], s[28:29], v21, s78, v[6:7]
	v_mad_u64_u32 v[58:59], s[28:29], v39, s78, v[6:7]
	v_mad_u64_u32 v[60:61], s[28:29], v37, s78, v[6:7]
	v_mad_u64_u32 v[62:63], s[28:29], v43, s78, v[6:7]
	v_mad_u64_u32 v[64:65], s[28:29], v41, s78, v[6:7]
	v_mad_u64_u32 v[66:67], s[28:29], v79, s78, v[6:7]
	v_mad_u64_u32 v[68:69], s[28:29], v78, s78, v[6:7]
	v_mad_u64_u32 v[70:71], s[28:29], v81, s78, v[6:7]
	v_mad_u64_u32 v[72:73], s[28:29], v80, s78, v[6:7]
	v_mad_u64_u32 v[74:75], s[28:29], v83, s78, v[6:7]
	v_mad_u64_u32 v[76:77], s[28:29], v82, s78, v[6:7]
	s_waitcnt vmcnt(31)
	ds_write_b32 v46, v11
	s_waitcnt vmcnt(30)
	ds_write_b32 v48, v13
	s_waitcnt vmcnt(29)
	ds_write_b32 v50, v84
	s_waitcnt vmcnt(28)
	ds_write_b32 v52, v85
	s_waitcnt vmcnt(27)
	ds_write_b32 v54, v86
	s_waitcnt vmcnt(26)
	ds_write_b32 v56, v87
	s_waitcnt vmcnt(25)
	ds_write_b32 v58, v88
	s_waitcnt vmcnt(24)
	ds_write_b32 v60, v89
	s_waitcnt vmcnt(23)
	ds_write_b32 v62, v90
	s_waitcnt vmcnt(22)
	ds_write_b32 v64, v91
	s_waitcnt vmcnt(21)
	ds_write_b32 v66, v92
	s_waitcnt vmcnt(20)
	ds_write_b32 v68, v93
	s_waitcnt vmcnt(19)
	ds_write_b32 v70, v94
	s_waitcnt vmcnt(18)
	ds_write_b32 v72, v95
	s_waitcnt vmcnt(17)
	ds_write_b32 v74, v96
	s_waitcnt vmcnt(16)
	ds_write_b32 v76, v97
	v_mad_u64_u32 v[130:131], s[28:29], v107, s78, v[6:7]
	v_mad_u64_u32 v[132:133], s[28:29], v106, s78, v[6:7]
	v_mad_u64_u32 v[134:135], s[28:29], v111, s78, v[6:7]
	v_mad_u64_u32 v[136:137], s[28:29], v110, s78, v[6:7]
	v_mad_u64_u32 v[138:139], s[28:29], v113, s78, v[6:7]
	v_mad_u64_u32 v[140:141], s[28:29], v112, s78, v[6:7]
	v_mad_u64_u32 v[142:143], s[28:29], v115, s78, v[6:7]
	v_mad_u64_u32 v[144:145], s[28:29], v114, s78, v[6:7]
	v_mad_u64_u32 v[146:147], s[28:29], v117, s78, v[6:7]
	v_mad_u64_u32 v[148:149], s[28:29], v116, s78, v[6:7]
	v_mad_u64_u32 v[150:151], s[28:29], v119, s78, v[6:7]
	v_mad_u64_u32 v[152:153], s[28:29], v118, s78, v[6:7]
	v_mad_u64_u32 v[154:155], s[28:29], v121, s78, v[6:7]
	v_mad_u64_u32 v[156:157], s[28:29], v120, s78, v[6:7]
	v_mad_u64_u32 v[158:159], s[28:29], v123, s78, v[6:7]
	v_mad_u64_u32 v[160:161], s[28:29], v122, s78, v[6:7]
	s_waitcnt vmcnt(15)
	ds_write_b32 v130, v108
	s_waitcnt vmcnt(14)
	ds_write_b32 v132, v109
	s_waitcnt vmcnt(13)
	ds_write_b32 v134, v124
	s_waitcnt vmcnt(12)
	ds_write_b32 v136, v125
	s_waitcnt vmcnt(11)
	ds_write_b32 v138, v126
	s_waitcnt vmcnt(10)
	ds_write_b32 v140, v127
	s_waitcnt vmcnt(9)
	ds_write_b32 v142, v162
	s_waitcnt vmcnt(8)
	ds_write_b32 v144, v163
	s_waitcnt vmcnt(7)
	ds_write_b32 v146, v164
	s_waitcnt vmcnt(6)
	ds_write_b32 v148, v165
	s_waitcnt vmcnt(5)
	ds_write_b32 v150, v166
	s_waitcnt vmcnt(4)
	ds_write_b32 v152, v167
	s_waitcnt vmcnt(3)
	ds_write_b32 v154, v168
	s_waitcnt vmcnt(2)
	ds_write_b32 v156, v169
	s_waitcnt vmcnt(1)
	ds_write_b32 v158, v170
	s_waitcnt vmcnt(0)
	ds_write_b32 v160, v171
	s_add_i32 s9, s9, 16
	s_add_i32 s5, s5, 16
	s_add_i32 s11, s11, -16
	s_add_i32 s11, s11, -16
	s_cmp_lg_u32 s11, 0
	s_waitcnt lgkmcnt(0)
	s_add_i32 s4, s10, 0xf500
	ds_read2_b32 v[48:49], v3 offset1:8
	s_cmpk_lt_i32 s0, 0x58
	ds_read2_b32 v[52:53], v3 offset0:33 offset1:41
	s_cselect_b32 s0, s10, s4
	s_sext_i32_i16 s4, s0
	ds_read2_b32 v[54:55], v3 offset0:66 offset1:74
	s_cselect_b32 s5, 0, 0x80
	s_bfe_u32 s4, s4, 0x70018
	ds_read2_b32 v[56:57], v3 offset0:99 offset1:107
	s_add_i32 s4, s0, s4
	s_waitcnt lgkmcnt(3)
	v_bfe_u32 v7, v48, 16, 1
	s_sext_i32_i16 s9, s4
	s_and_b32 s4, s4, 0xff80
	v_add3_u32 v7, v48, v7, s33
	s_waitcnt lgkmcnt(2)
	v_bfe_u32 v9, v52, 16, 1
	ds_read2_b32 v[58:59], v3 offset0:132 offset1:140
	s_sub_i32 s0, s0, s4
	v_lshrrev_b32_e32 v7, 16, v7
	v_add3_u32 v9, v52, v9, s33
	ds_read2_b32 v[60:61], v3 offset0:165 offset1:173
	s_lshl_b32 s9, s9, 1
	s_sext_i32_i16 s0, s0
	v_and_or_b32 v44, v9, s69, v7
	s_waitcnt lgkmcnt(3)
	v_bfe_u32 v7, v54, 16, 1
	s_and_b32 s9, s9, 0xffffff00
	s_add_i32 s0, s5, s0
	v_add3_u32 v7, v54, v7, s33
	s_waitcnt lgkmcnt(2)
	v_bfe_u32 v9, v56, 16, 1
	ds_read2_b32 v[62:63], v3 offset0:198 offset1:206
	s_add_i32 s4, s0, s9
	v_lshrrev_b32_e32 v7, 16, v7
	v_add3_u32 v9, v56, v9, s33
	ds_read2_b32 v[64:65], v3 offset0:231 offset1:239
	s_ashr_i32 s5, s4, 31
	v_and_or_b32 v45, v9, s69, v7
	s_waitcnt lgkmcnt(3)
	v_bfe_u32 v7, v58, 16, 1
	s_lshl_b64 s[4:5], s[4:5], 11
	v_add3_u32 v7, v58, v7, s33
	s_waitcnt lgkmcnt(2)
	v_bfe_u32 v9, v60, 16, 1
	s_add_u32 s0, s20, s4
	v_lshrrev_b32_e32 v7, 16, v7
	v_add3_u32 v9, v60, v9, s33
	s_addc_u32 s10, s21, s5
	s_ashr_i32 s9, s8, 31
	v_and_or_b32 v46, v9, s69, v7
	s_waitcnt lgkmcnt(1)
	v_bfe_u32 v7, v62, 16, 1
	s_lshl_b64 s[4:5], s[8:9], 1
	v_add3_u32 v7, v62, v7, s33
	s_waitcnt lgkmcnt(0)
	v_bfe_u32 v9, v64, 16, 1
	s_add_u32 s4, s0, s4
	v_lshrrev_b32_e32 v7, 16, v7
	v_add3_u32 v9, v64, v9, s33
	s_addc_u32 s5, s10, s5
	v_lshlrev_b32_e32 v128, 1, v8
	v_and_or_b32 v47, v9, s69, v7
	v_bfe_u32 v7, v49, 16, 1
	v_lshl_add_u64 v[50:51], s[4:5], 0, v[128:129]
	v_lshlrev_b32_e32 v128, 1, v10
	v_add3_u32 v7, v49, v7, s33
	v_bfe_u32 v9, v53, 16, 1
	v_lshl_add_u64 v[66:67], v[50:51], 0, v[128:129]
	v_lshrrev_b32_e32 v7, 16, v7
	v_add3_u32 v9, v53, v9, s33
	global_store_dwordx4 v[66:67], v[44:47], off
	v_lshlrev_b32_e32 v128, 1, v12
	ds_read2_b32 v[48:49], v3 offset0:16 offset1:24
	v_and_or_b32 v44, v9, s69, v7
	v_bfe_u32 v7, v55, 16, 1
	v_add3_u32 v7, v55, v7, s33
	v_bfe_u32 v9, v57, 16, 1
	v_lshrrev_b32_e32 v7, 16, v7
	v_add3_u32 v9, v57, v9, s33
	v_and_or_b32 v45, v9, s69, v7
	v_bfe_u32 v7, v59, 16, 1
	v_add3_u32 v7, v59, v7, s33
	v_bfe_u32 v9, v61, 16, 1
	v_lshrrev_b32_e32 v7, 16, v7
	v_add3_u32 v9, v61, v9, s33
	v_and_or_b32 v46, v9, s69, v7
	v_bfe_u32 v7, v63, 16, 1
	v_add3_u32 v7, v63, v7, s33
	v_bfe_u32 v9, v65, 16, 1
	v_lshrrev_b32_e32 v7, 16, v7
	v_add3_u32 v9, v65, v9, s33
	v_and_or_b32 v47, v9, s69, v7
	v_lshl_add_u64 v[52:53], v[50:51], 0, v[128:129]
	global_store_dwordx4 v[52:53], v[44:47], off
	ds_read2_b32 v[52:53], v3 offset0:49 offset1:57
	ds_read2_b32 v[54:55], v3 offset0:82 offset1:90
	ds_read2_b32 v[56:57], v3 offset0:115 offset1:123
	s_waitcnt lgkmcnt(3)
	v_bfe_u32 v7, v48, 16, 1
	v_add3_u32 v7, v48, v7, s33
	s_waitcnt lgkmcnt(2)
	v_bfe_u32 v9, v52, 16, 1
	ds_read2_b32 v[58:59], v3 offset0:148 offset1:156
	v_lshrrev_b32_e32 v7, 16, v7
	v_add3_u32 v9, v52, v9, s33
	ds_read2_b32 v[60:61], v3 offset0:181 offset1:189
	v_and_or_b32 v44, v9, s69, v7
	s_waitcnt lgkmcnt(3)
	v_bfe_u32 v7, v54, 16, 1
	v_add3_u32 v7, v54, v7, s33
	s_waitcnt lgkmcnt(2)
	v_bfe_u32 v9, v56, 16, 1
	ds_read2_b32 v[62:63], v3 offset0:214 offset1:222
	v_lshrrev_b32_e32 v7, 16, v7
	v_add3_u32 v9, v56, v9, s33
	ds_read2_b32 v[64:65], v3 offset0:247 offset1:255
	v_and_or_b32 v45, v9, s69, v7
	s_waitcnt lgkmcnt(3)
	v_bfe_u32 v7, v58, 16, 1
	v_add3_u32 v7, v58, v7, s33
	s_waitcnt lgkmcnt(2)
	v_bfe_u32 v9, v60, 16, 1
	v_lshrrev_b32_e32 v7, 16, v7
	v_add3_u32 v9, v60, v9, s33
	v_and_or_b32 v46, v9, s69, v7
	s_waitcnt lgkmcnt(1)
	v_bfe_u32 v7, v62, 16, 1
	v_add3_u32 v7, v62, v7, s33
	s_waitcnt lgkmcnt(0)
	v_bfe_u32 v9, v64, 16, 1
	v_lshrrev_b32_e32 v7, 16, v7
	v_add3_u32 v9, v64, v9, s33
	v_and_or_b32 v47, v9, s69, v7
	v_bfe_u32 v7, v49, 16, 1
	v_lshlrev_b32_e32 v128, 1, v14
	v_add3_u32 v7, v49, v7, s33
	v_bfe_u32 v9, v53, 16, 1
	v_lshl_add_u64 v[66:67], v[50:51], 0, v[128:129]
	v_lshrrev_b32_e32 v7, 16, v7
	v_add3_u32 v9, v53, v9, s33
	global_store_dwordx4 v[66:67], v[44:47], off
	v_lshlrev_b32_e32 v128, 1, v16
	v_lshl_add_u64 v[48:49], v[50:51], 0, v[128:129]
	v_and_or_b32 v44, v9, s69, v7
	v_bfe_u32 v7, v55, 16, 1
	v_add3_u32 v7, v55, v7, s33
	v_bfe_u32 v9, v57, 16, 1
	v_lshrrev_b32_e32 v7, 16, v7
	v_add3_u32 v9, v57, v9, s33
	v_and_or_b32 v45, v9, s69, v7
	v_bfe_u32 v7, v59, 16, 1
	v_add3_u32 v7, v59, v7, s33
	v_bfe_u32 v9, v61, 16, 1
	v_lshrrev_b32_e32 v7, 16, v7
	v_add3_u32 v9, v61, v9, s33
	v_and_or_b32 v46, v9, s69, v7
	v_bfe_u32 v7, v63, 16, 1
	v_add3_u32 v7, v63, v7, s33
	v_bfe_u32 v9, v65, 16, 1
	v_lshrrev_b32_e32 v7, 16, v7
	v_add3_u32 v9, v65, v9, s33
	v_and_or_b32 v47, v9, s69, v7
	global_store_dwordx4 v[48:49], v[44:47], off
	s_waitcnt lgkmcnt(0)
	s_mov_b32 s0, s1
	s_andn2_b64 vcc, exec, s[6:7]
	s_mov_b64 s[6:7], -1
	s_cbranch_vccnz .LBB0_832

.LBB0_805:
	s_lshl_b32 s11, s1, 1
	s_lshl_b32 s28, s5, 1
	v_or_b32_e32 v7, s11, v1
	v_or_b32_e32 v9, s28, v2
	s_add_i32 s29, s11, 4
	s_add_i32 s30, s28, 4
	s_add_i32 s36, s11, 8
	s_add_i32 s37, s28, 8
	s_add_i32 s38, s11, 12
	s_add_i32 s39, s28, 12
	s_add_i32 s40, s11, 16
	s_add_i32 s41, s28, 16
	s_add_i32 s42, s11, 20
	s_add_i32 s43, s28, 20
	s_add_i32 s44, s11, 24
	s_add_i32 s45, s28, 24
	s_add_i32 s11, s11, 28
	s_add_i32 s28, s28, 28
	v_add_u32_e32 v48, s8, v9
	v_or_b32_e32 v11, s29, v1
	v_or_b32_e32 v13, s30, v2
	v_or_b32_e32 v15, s36, v1
	v_or_b32_e32 v17, s37, v2
	v_or_b32_e32 v21, s38, v1
	v_or_b32_e32 v35, s39, v2
	v_or_b32_e32 v37, s40, v1
	v_or_b32_e32 v39, s41, v2
	v_or_b32_e32 v41, s42, v1
	v_or_b32_e32 v43, s43, v2
	v_or_b32_e32 v78, s44, v1
	v_or_b32_e32 v79, s45, v2
	v_or_b32_e32 v80, s11, v1
	v_or_b32_e32 v81, s28, v2
	v_add_u32_e32 v46, s4, v7
	v_ashrrev_i32_e32 v49, 31, v48
	v_add_u32_e32 v50, s4, v11
	v_add_u32_e32 v52, s8, v13
	v_add_u32_e32 v54, s4, v15
	v_add_u32_e32 v56, s8, v17
	v_add_u32_e32 v58, s4, v21
	v_add_u32_e32 v60, s8, v35
	v_add_u32_e32 v62, s4, v37
	v_add_u32_e32 v64, s8, v39
	v_add_u32_e32 v66, s4, v41
	v_add_u32_e32 v68, s8, v43
	v_add_u32_e32 v70, s4, v78
	v_add_u32_e32 v72, s8, v79
	v_add_u32_e32 v74, s4, v80
	v_add_u32_e32 v76, s8, v81
	v_ashrrev_i32_e32 v47, 31, v46
	v_lshlrev_b64 v[48:49], 12, v[48:49]
	v_ashrrev_i32_e32 v53, 31, v52
	v_ashrrev_i32_e32 v51, 31, v50
	v_ashrrev_i32_e32 v57, 31, v56
	v_ashrrev_i32_e32 v55, 31, v54
	v_ashrrev_i32_e32 v61, 31, v60
	v_ashrrev_i32_e32 v59, 31, v58
	v_ashrrev_i32_e32 v65, 31, v64
	v_ashrrev_i32_e32 v63, 31, v62
	v_ashrrev_i32_e32 v69, 31, v68
	v_ashrrev_i32_e32 v67, 31, v66
	v_ashrrev_i32_e32 v73, 31, v72
	v_ashrrev_i32_e32 v71, 31, v70
	v_ashrrev_i32_e32 v77, 31, v76
	v_ashrrev_i32_e32 v75, 31, v74
	v_lshlrev_b64 v[46:47], 12, v[46:47]
	v_lshl_add_u64 v[48:49], v[44:45], 0, v[48:49]
	v_lshlrev_b64 v[50:51], 12, v[50:51]
	v_lshlrev_b64 v[52:53], 12, v[52:53]
	v_lshlrev_b64 v[54:55], 12, v[54:55]
	v_lshlrev_b64 v[56:57], 12, v[56:57]
	v_lshlrev_b64 v[58:59], 12, v[58:59]
	v_lshlrev_b64 v[60:61], 12, v[60:61]
	v_lshlrev_b64 v[62:63], 12, v[62:63]
	v_lshlrev_b64 v[64:65], 12, v[64:65]
	v_lshlrev_b64 v[66:67], 12, v[66:67]
	v_lshlrev_b64 v[68:69], 12, v[68:69]
	v_lshlrev_b64 v[70:71], 12, v[70:71]
	v_lshlrev_b64 v[72:73], 12, v[72:73]
	v_lshlrev_b64 v[74:75], 12, v[74:75]
	v_lshlrev_b64 v[76:77], 12, v[76:77]
	v_lshl_add_u64 v[46:47], v[44:45], 0, v[46:47]
	v_lshl_add_u64 v[52:53], v[44:45], 0, v[52:53]
	v_lshl_add_u64 v[50:51], v[44:45], 0, v[50:51]
	v_lshl_add_u64 v[56:57], v[44:45], 0, v[56:57]
	v_lshl_add_u64 v[54:55], v[44:45], 0, v[54:55]
	v_lshl_add_u64 v[60:61], v[44:45], 0, v[60:61]
	v_lshl_add_u64 v[58:59], v[44:45], 0, v[58:59]
	v_lshl_add_u64 v[64:65], v[44:45], 0, v[64:65]
	v_lshl_add_u64 v[62:63], v[44:45], 0, v[62:63]
	v_lshl_add_u64 v[68:69], v[44:45], 0, v[68:69]
	v_lshl_add_u64 v[66:67], v[44:45], 0, v[66:67]
	v_lshl_add_u64 v[72:73], v[44:45], 0, v[72:73]
	v_lshl_add_u64 v[70:71], v[44:45], 0, v[70:71]
	v_lshl_add_u64 v[76:77], v[44:45], 0, v[76:77]
	v_lshl_add_u64 v[74:75], v[44:45], 0, v[74:75]
	global_load_dword v82, v[48:49], off
	global_load_dword v83, v[46:47], off
	global_load_dword v84, v[52:53], off
	global_load_dword v85, v[50:51], off
	global_load_dword v86, v[56:57], off
	global_load_dword v87, v[54:55], off
	global_load_dword v88, v[60:61], off
	global_load_dword v89, v[58:59], off
	global_load_dword v90, v[64:65], off
	global_load_dword v91, v[62:63], off
	global_load_dword v92, v[68:69], off
	global_load_dword v93, v[66:67], off
	global_load_dword v94, v[72:73], off
	global_load_dword v95, v[70:71], off
	global_load_dword v96, v[76:77], off
	global_load_dword v97, v[74:75], off
	s_add_i32 s5, s5, 16
	s_add_i32 s1, s1, 16
	s_lshl_b32 s11, s1, 1
	s_lshl_b32 s28, s5, 1
	v_or_b32_e32 v106, s11, v1
	v_or_b32_e32 v107, s28, v2
	s_add_i32 s29, s11, 4
	s_add_i32 s30, s28, 4
	s_add_i32 s36, s11, 8
	s_add_i32 s37, s28, 8
	s_add_i32 s38, s11, 12
	s_add_i32 s39, s28, 12
	s_add_i32 s40, s11, 16
	s_add_i32 s41, s28, 16
	s_add_i32 s42, s11, 20
	s_add_i32 s43, s28, 20
	s_add_i32 s44, s11, 24
	s_add_i32 s45, s28, 24
	s_add_i32 s11, s11, 28
	s_add_i32 s28, s28, 28
	v_add_u32_e32 v132, s8, v107
	v_or_b32_e32 v108, s29, v1
	v_or_b32_e32 v109, s30, v2
	v_or_b32_e32 v110, s36, v1
	v_or_b32_e32 v111, s37, v2
	v_or_b32_e32 v112, s38, v1
	v_or_b32_e32 v113, s39, v2
	v_or_b32_e32 v114, s40, v1
	v_or_b32_e32 v115, s41, v2
	v_or_b32_e32 v116, s42, v1
	v_or_b32_e32 v117, s43, v2
	v_or_b32_e32 v118, s44, v1
	v_or_b32_e32 v119, s45, v2
	v_or_b32_e32 v120, s11, v1
	v_or_b32_e32 v121, s28, v2
	v_add_u32_e32 v130, s4, v106
	v_ashrrev_i32_e32 v133, 31, v132
	v_add_u32_e32 v134, s4, v108
	v_add_u32_e32 v136, s8, v109
	v_add_u32_e32 v138, s4, v110
	v_add_u32_e32 v140, s8, v111
	v_add_u32_e32 v142, s4, v112
	v_add_u32_e32 v144, s8, v113
	v_add_u32_e32 v146, s4, v114
	v_add_u32_e32 v148, s8, v115
	v_add_u32_e32 v150, s4, v116
	v_add_u32_e32 v152, s8, v117
	v_add_u32_e32 v154, s4, v118
	v_add_u32_e32 v156, s8, v119
	v_add_u32_e32 v158, s4, v120
	v_add_u32_e32 v160, s8, v121
	v_ashrrev_i32_e32 v131, 31, v130
	v_lshlrev_b64 v[132:133], 12, v[132:133]
	v_ashrrev_i32_e32 v137, 31, v136
	v_ashrrev_i32_e32 v135, 31, v134
	v_ashrrev_i32_e32 v141, 31, v140
	v_ashrrev_i32_e32 v139, 31, v138
	v_ashrrev_i32_e32 v145, 31, v144
	v_ashrrev_i32_e32 v143, 31, v142
	v_ashrrev_i32_e32 v149, 31, v148
	v_ashrrev_i32_e32 v147, 31, v146
	v_ashrrev_i32_e32 v153, 31, v152
	v_ashrrev_i32_e32 v151, 31, v150
	v_ashrrev_i32_e32 v157, 31, v156
	v_ashrrev_i32_e32 v155, 31, v154
	v_ashrrev_i32_e32 v161, 31, v160
	v_ashrrev_i32_e32 v159, 31, v158
	v_lshlrev_b64 v[130:131], 12, v[130:131]
	v_lshl_add_u64 v[132:133], v[44:45], 0, v[132:133]
	v_lshlrev_b64 v[134:135], 12, v[134:135]
	v_lshlrev_b64 v[136:137], 12, v[136:137]
	v_lshlrev_b64 v[138:139], 12, v[138:139]
	v_lshlrev_b64 v[140:141], 12, v[140:141]
	v_lshlrev_b64 v[142:143], 12, v[142:143]
	v_lshlrev_b64 v[144:145], 12, v[144:145]
	v_lshlrev_b64 v[146:147], 12, v[146:147]
	v_lshlrev_b64 v[148:149], 12, v[148:149]
	v_lshlrev_b64 v[150:151], 12, v[150:151]
	v_lshlrev_b64 v[152:153], 12, v[152:153]
	v_lshlrev_b64 v[154:155], 12, v[154:155]
	v_lshlrev_b64 v[156:157], 12, v[156:157]
	v_lshlrev_b64 v[158:159], 12, v[158:159]
	v_lshlrev_b64 v[160:161], 12, v[160:161]
	v_lshl_add_u64 v[130:131], v[44:45], 0, v[130:131]
	v_lshl_add_u64 v[136:137], v[44:45], 0, v[136:137]
	v_lshl_add_u64 v[134:135], v[44:45], 0, v[134:135]
	v_lshl_add_u64 v[140:141], v[44:45], 0, v[140:141]
	v_lshl_add_u64 v[138:139], v[44:45], 0, v[138:139]
	v_lshl_add_u64 v[144:145], v[44:45], 0, v[144:145]
	v_lshl_add_u64 v[142:143], v[44:45], 0, v[142:143]
	v_lshl_add_u64 v[148:149], v[44:45], 0, v[148:149]
	v_lshl_add_u64 v[146:147], v[44:45], 0, v[146:147]
	v_lshl_add_u64 v[152:153], v[44:45], 0, v[152:153]
	v_lshl_add_u64 v[150:151], v[44:45], 0, v[150:151]
	v_lshl_add_u64 v[156:157], v[44:45], 0, v[156:157]
	v_lshl_add_u64 v[154:155], v[44:45], 0, v[154:155]
	v_lshl_add_u64 v[160:161], v[44:45], 0, v[160:161]
	v_lshl_add_u64 v[158:159], v[44:45], 0, v[158:159]
	global_load_dword v122, v[132:133], off
	global_load_dword v123, v[130:131], off
	global_load_dword v124, v[136:137], off
	global_load_dword v125, v[134:135], off
	global_load_dword v126, v[140:141], off
	global_load_dword v127, v[138:139], off
	global_load_dword v162, v[144:145], off
	global_load_dword v163, v[142:143], off
	global_load_dword v164, v[148:149], off
	global_load_dword v165, v[146:147], off
	global_load_dword v166, v[152:153], off
	global_load_dword v167, v[150:151], off
	global_load_dword v168, v[156:157], off
	global_load_dword v169, v[154:155], off
	global_load_dword v170, v[160:161], off
	global_load_dword v171, v[158:159], off
	v_mad_u64_u32 v[46:47], s[28:29], v9, s78, v[6:7]
	v_mad_u64_u32 v[48:49], s[28:29], v7, s78, v[6:7]
	v_mad_u64_u32 v[50:51], s[28:29], v13, s78, v[6:7]
	v_mad_u64_u32 v[52:53], s[28:29], v11, s78, v[6:7]
	v_mad_u64_u32 v[54:55], s[28:29], v17, s78, v[6:7]
	v_mad_u64_u32 v[56:57], s[28:29], v15, s78, v[6:7]
	v_mad_u64_u32 v[58:59], s[28:29], v35, s78, v[6:7]
	v_mad_u64_u32 v[60:61], s[28:29], v21, s78, v[6:7]
	v_mad_u64_u32 v[62:63], s[28:29], v39, s78, v[6:7]
	v_mad_u64_u32 v[64:65], s[28:29], v37, s78, v[6:7]
	v_mad_u64_u32 v[66:67], s[28:29], v43, s78, v[6:7]
	v_mad_u64_u32 v[68:69], s[28:29], v41, s78, v[6:7]
	v_mad_u64_u32 v[70:71], s[28:29], v79, s78, v[6:7]
	v_mad_u64_u32 v[72:73], s[28:29], v78, s78, v[6:7]
	v_mad_u64_u32 v[74:75], s[28:29], v81, s78, v[6:7]
	v_mad_u64_u32 v[76:77], s[28:29], v80, s78, v[6:7]
	s_waitcnt vmcnt(31)
	ds_write_b32 v46, v82
	s_waitcnt vmcnt(30)
	ds_write_b32 v48, v83
	s_waitcnt vmcnt(29)
	ds_write_b32 v50, v84
	s_waitcnt vmcnt(28)
	ds_write_b32 v52, v85
	s_waitcnt vmcnt(27)
	ds_write_b32 v54, v86
	s_waitcnt vmcnt(26)
	ds_write_b32 v56, v87
	s_waitcnt vmcnt(25)
	ds_write_b32 v58, v88
	s_waitcnt vmcnt(24)
	ds_write_b32 v60, v89
	s_waitcnt vmcnt(23)
	ds_write_b32 v62, v90
	s_waitcnt vmcnt(22)
	ds_write_b32 v64, v91
	s_waitcnt vmcnt(21)
	ds_write_b32 v66, v92
	s_waitcnt vmcnt(20)
	ds_write_b32 v68, v93
	s_waitcnt vmcnt(19)
	ds_write_b32 v70, v94
	s_waitcnt vmcnt(18)
	ds_write_b32 v72, v95
	s_waitcnt vmcnt(17)
	ds_write_b32 v74, v96
	s_waitcnt vmcnt(16)
	ds_write_b32 v76, v97
	v_mad_u64_u32 v[130:131], s[28:29], v107, s78, v[6:7]
	v_mad_u64_u32 v[132:133], s[28:29], v106, s78, v[6:7]
	v_mad_u64_u32 v[134:135], s[28:29], v109, s78, v[6:7]
	v_mad_u64_u32 v[136:137], s[28:29], v108, s78, v[6:7]
	v_mad_u64_u32 v[138:139], s[28:29], v111, s78, v[6:7]
	v_mad_u64_u32 v[140:141], s[28:29], v110, s78, v[6:7]
	v_mad_u64_u32 v[142:143], s[28:29], v113, s78, v[6:7]
	v_mad_u64_u32 v[144:145], s[28:29], v112, s78, v[6:7]
	v_mad_u64_u32 v[146:147], s[28:29], v115, s78, v[6:7]
	v_mad_u64_u32 v[148:149], s[28:29], v114, s78, v[6:7]
	v_mad_u64_u32 v[150:151], s[28:29], v117, s78, v[6:7]
	v_mad_u64_u32 v[152:153], s[28:29], v116, s78, v[6:7]
	v_mad_u64_u32 v[154:155], s[28:29], v119, s78, v[6:7]
	v_mad_u64_u32 v[156:157], s[28:29], v118, s78, v[6:7]
	v_mad_u64_u32 v[158:159], s[28:29], v121, s78, v[6:7]
	v_mad_u64_u32 v[160:161], s[28:29], v120, s78, v[6:7]
	s_waitcnt vmcnt(15)
	ds_write_b32 v130, v122
	s_waitcnt vmcnt(14)
	ds_write_b32 v132, v123
	s_waitcnt vmcnt(13)
	ds_write_b32 v134, v124
	s_waitcnt vmcnt(12)
	ds_write_b32 v136, v125
	s_waitcnt vmcnt(11)
	ds_write_b32 v138, v126
	s_waitcnt vmcnt(10)
	ds_write_b32 v140, v127
	s_waitcnt vmcnt(9)
	ds_write_b32 v142, v162
	s_waitcnt vmcnt(8)
	ds_write_b32 v144, v163
	s_waitcnt vmcnt(7)
	ds_write_b32 v146, v164
	s_waitcnt vmcnt(6)
	ds_write_b32 v148, v165
	s_waitcnt vmcnt(5)
	ds_write_b32 v150, v166
	s_waitcnt vmcnt(4)
	ds_write_b32 v152, v167
	s_waitcnt vmcnt(3)
	ds_write_b32 v154, v168
	s_waitcnt vmcnt(2)
	ds_write_b32 v156, v169
	s_waitcnt vmcnt(1)
	ds_write_b32 v158, v170
	s_waitcnt vmcnt(0)
	ds_write_b32 v160, v171
	s_add_i32 s5, s5, 16
	s_add_i32 s1, s1, 16
	s_add_i32 s9, s9, -16
	s_add_i32 s9, s9, -16
	s_cmp_lg_u32 s9, 0
	s_waitcnt lgkmcnt(0)
	ds_read2_b32 v[48:49], v3 offset1:8
	ds_read2_b32 v[52:53], v3 offset0:33 offset1:41
	ds_read2_b32 v[54:55], v3 offset0:66 offset1:74
	ds_read2_b32 v[56:57], v3 offset0:99 offset1:107
	ds_read2_b32 v[58:59], v3 offset0:132 offset1:140
	s_waitcnt lgkmcnt(4)
	v_bfe_u32 v7, v48, 16, 1
	v_add3_u32 v7, v48, v7, s33
	s_waitcnt lgkmcnt(3)
	v_bfe_u32 v9, v52, 16, 1
	v_lshrrev_b32_e32 v7, 16, v7
	v_add3_u32 v9, v52, v9, s33
	ds_read2_b32 v[60:61], v3 offset0:165 offset1:173
	v_and_or_b32 v44, v9, s69, v7
	s_waitcnt lgkmcnt(3)
	v_bfe_u32 v7, v54, 16, 1
	v_add3_u32 v7, v54, v7, s33
	s_waitcnt lgkmcnt(2)
	v_bfe_u32 v9, v56, 16, 1
	ds_read2_b32 v[62:63], v3 offset0:198 offset1:206
	v_lshrrev_b32_e32 v7, 16, v7
	v_add3_u32 v9, v56, v9, s33
	ds_read2_b32 v[64:65], v3 offset0:231 offset1:239
	v_and_or_b32 v45, v9, s69, v7
	s_waitcnt lgkmcnt(3)
	v_bfe_u32 v7, v58, 16, 1
	s_mul_i32 s4, s10, 0x1600
	v_add3_u32 v7, v58, v7, s33
	s_waitcnt lgkmcnt(2)
	v_bfe_u32 v9, v60, 16, 1
	s_mul_hi_i32 s1, s10, 0x1600
	s_add_u32 s10, s22, s4
	v_lshrrev_b32_e32 v7, 16, v7
	v_add3_u32 v9, v60, v9, s33
	s_addc_u32 s1, s23, s1
	s_ashr_i32 s9, s8, 31
	v_and_or_b32 v46, v9, s69, v7
	s_waitcnt lgkmcnt(1)
	v_bfe_u32 v7, v62, 16, 1
	s_lshl_b64 s[4:5], s[8:9], 1
	v_add3_u32 v7, v62, v7, s33
	s_waitcnt lgkmcnt(0)
	v_bfe_u32 v9, v64, 16, 1
	s_add_u32 s4, s10, s4
	v_lshrrev_b32_e32 v7, 16, v7
	v_add3_u32 v9, v64, v9, s33
	s_addc_u32 s5, s1, s5
	v_lshlrev_b32_e32 v128, 1, v8
	v_and_or_b32 v47, v9, s69, v7
	v_bfe_u32 v7, v49, 16, 1
	v_lshl_add_u64 v[50:51], s[4:5], 0, v[128:129]
	v_lshlrev_b32_e32 v128, 1, v20
	v_add3_u32 v7, v49, v7, s33
	v_bfe_u32 v9, v53, 16, 1
	v_lshl_add_u64 v[50:51], v[50:51], 0, v[128:129]
	v_lshrrev_b32_e32 v7, 16, v7
	v_add3_u32 v9, v53, v9, s33
	global_store_dwordx4 v[50:51], v[44:47], off
	v_add_co_u32_e32 v52, vcc, s47, v50
	s_nop 0
	v_and_or_b32 v44, v9, s69, v7
	v_bfe_u32 v7, v55, 16, 1
	v_add3_u32 v7, v55, v7, s33
	v_bfe_u32 v9, v57, 16, 1
	v_lshrrev_b32_e32 v7, 16, v7
	v_add3_u32 v9, v57, v9, s33
	v_and_or_b32 v45, v9, s69, v7
	v_bfe_u32 v7, v59, 16, 1
	v_add3_u32 v7, v59, v7, s33
	v_bfe_u32 v9, v61, 16, 1
	v_lshrrev_b32_e32 v7, 16, v7
	v_add3_u32 v9, v61, v9, s33
	v_and_or_b32 v46, v9, s69, v7
	v_bfe_u32 v7, v63, 16, 1
	v_add3_u32 v7, v63, v7, s33
	v_bfe_u32 v9, v65, 16, 1
	v_lshrrev_b32_e32 v7, 16, v7
	v_add3_u32 v9, v65, v9, s33
	v_and_or_b32 v47, v9, s69, v7
	ds_read2_b32 v[48:49], v3 offset0:16 offset1:24
	v_addc_co_u32_e32 v53, vcc, 0, v51, vcc
	global_store_dwordx4 v[52:53], v[44:47], off
	ds_read2_b32 v[52:53], v3 offset0:49 offset1:57
	ds_read2_b32 v[54:55], v3 offset0:82 offset1:90
	ds_read2_b32 v[56:57], v3 offset0:115 offset1:123
	s_waitcnt lgkmcnt(3)
	v_bfe_u32 v7, v48, 16, 1
	v_add3_u32 v7, v48, v7, s33
	s_waitcnt lgkmcnt(2)
	v_bfe_u32 v9, v52, 16, 1
	ds_read2_b32 v[58:59], v3 offset0:148 offset1:156
	v_lshrrev_b32_e32 v7, 16, v7
	v_add3_u32 v9, v52, v9, s33
	ds_read2_b32 v[60:61], v3 offset0:181 offset1:189
	v_and_or_b32 v44, v9, s69, v7
	s_waitcnt lgkmcnt(3)
	v_bfe_u32 v7, v54, 16, 1
	v_add3_u32 v7, v54, v7, s33
	s_waitcnt lgkmcnt(2)
	v_bfe_u32 v9, v56, 16, 1
	ds_read2_b32 v[62:63], v3 offset0:214 offset1:222
	v_lshrrev_b32_e32 v7, 16, v7
	v_add3_u32 v9, v56, v9, s33
	ds_read2_b32 v[64:65], v3 offset0:247 offset1:255
	v_and_or_b32 v45, v9, s69, v7
	s_waitcnt lgkmcnt(3)
	v_bfe_u32 v7, v58, 16, 1
	v_add3_u32 v7, v58, v7, s33
	s_waitcnt lgkmcnt(2)
	v_bfe_u32 v9, v60, 16, 1
	v_lshrrev_b32_e32 v7, 16, v7
	v_add3_u32 v9, v60, v9, s33
	v_and_or_b32 v46, v9, s69, v7
	s_waitcnt lgkmcnt(1)
	v_bfe_u32 v7, v62, 16, 1
	v_add3_u32 v7, v62, v7, s33
	s_waitcnt lgkmcnt(0)
	v_bfe_u32 v9, v64, 16, 1
	v_lshrrev_b32_e32 v7, 16, v7
	v_add3_u32 v9, v64, v9, s33
	v_and_or_b32 v47, v9, s69, v7
	v_bfe_u32 v7, v49, 16, 1
	v_add_co_u32_e32 v66, vcc, s48, v50
	v_add3_u32 v7, v49, v7, s33
	v_bfe_u32 v9, v53, 16, 1
	v_addc_co_u32_e32 v67, vcc, 0, v51, vcc
	v_lshrrev_b32_e32 v7, 16, v7
	v_add3_u32 v9, v53, v9, s33
	global_store_dwordx4 v[66:67], v[44:47], off
	v_add_co_u32_e32 v48, vcc, 0x21000, v50
	s_nop 0
	v_and_or_b32 v44, v9, s69, v7
	v_bfe_u32 v7, v55, 16, 1
	v_add3_u32 v7, v55, v7, s33
	v_bfe_u32 v9, v57, 16, 1
	v_lshrrev_b32_e32 v7, 16, v7
	v_add3_u32 v9, v57, v9, s33
	v_and_or_b32 v45, v9, s69, v7
	v_bfe_u32 v7, v59, 16, 1
	v_add3_u32 v7, v59, v7, s33
	v_bfe_u32 v9, v61, 16, 1
	v_lshrrev_b32_e32 v7, 16, v7
	v_add3_u32 v9, v61, v9, s33
	v_and_or_b32 v46, v9, s69, v7
	v_bfe_u32 v7, v63, 16, 1
	v_add3_u32 v7, v63, v7, s33
	v_bfe_u32 v9, v65, 16, 1
	v_lshrrev_b32_e32 v7, 16, v7
	v_add3_u32 v9, v65, v9, s33
	v_and_or_b32 v47, v9, s69, v7
	v_addc_co_u32_e32 v49, vcc, 0, v51, vcc
	global_store_dwordx4 v[48:49], v[44:47], off
	s_waitcnt lgkmcnt(0)
	s_mov_b32 s4, s0
	s_andn2_b64 vcc, exec, s[6:7]
	s_mov_b64 s[6:7], -1
	s_cbranch_vccnz .LBB0_832

.LBB0_812:
	s_lshl_b32 s28, s1, 1
	s_lshl_b32 s29, s5, 1
	v_or_b32_e32 v7, s28, v1
	v_or_b32_e32 v9, s29, v2
	s_add_i32 s30, s28, 4
	s_add_i32 s36, s29, 4
	s_add_i32 s37, s28, 8
	s_add_i32 s38, s29, 8
	s_add_i32 s39, s28, 12
	s_add_i32 s40, s29, 12
	s_add_i32 s41, s28, 16
	s_add_i32 s42, s29, 16
	s_add_i32 s43, s28, 20
	s_add_i32 s44, s29, 20
	s_add_i32 s45, s28, 24
	s_add_i32 s46, s29, 24
	s_add_i32 s28, s28, 28
	s_add_i32 s29, s29, 28
	v_add_u32_e32 v11, s0, v7
	v_add_u32_e32 v13, s8, v9
	v_or_b32_e32 v15, s30, v1
	v_or_b32_e32 v17, s36, v2
	v_or_b32_e32 v21, s37, v1
	v_or_b32_e32 v35, s38, v2
	v_or_b32_e32 v37, s39, v1
	v_or_b32_e32 v39, s40, v2
	v_or_b32_e32 v41, s41, v1
	v_or_b32_e32 v43, s42, v2
	v_or_b32_e32 v78, s43, v1
	v_or_b32_e32 v79, s44, v2
	v_or_b32_e32 v80, s45, v1
	v_or_b32_e32 v81, s46, v2
	v_or_b32_e32 v82, s28, v1
	v_or_b32_e32 v83, s29, v2
	v_mad_i64_i32 v[46:47], s[28:29], v13, s79, v[44:45]
	v_mad_i64_i32 v[48:49], s[28:29], v11, s79, v[44:45]
	v_add_u32_e32 v11, s0, v15
	v_add_u32_e32 v13, s8, v17
	v_add_u32_e32 v56, s0, v21
	v_add_u32_e32 v54, s8, v35
	v_add_u32_e32 v60, s0, v37
	v_add_u32_e32 v58, s8, v39
	v_add_u32_e32 v64, s0, v41
	v_add_u32_e32 v62, s8, v43
	v_add_u32_e32 v68, s0, v78
	v_add_u32_e32 v66, s8, v79
	v_add_u32_e32 v72, s0, v80
	v_add_u32_e32 v70, s8, v81
	v_add_u32_e32 v76, s0, v82
	v_add_u32_e32 v74, s8, v83
	v_mad_i64_i32 v[50:51], s[28:29], v13, s79, v[44:45]
	v_mad_i64_i32 v[52:53], s[28:29], v11, s79, v[44:45]
	v_mad_i64_i32 v[54:55], s[28:29], v54, s79, v[44:45]
	v_mad_i64_i32 v[56:57], s[28:29], v56, s79, v[44:45]
	v_mad_i64_i32 v[58:59], s[28:29], v58, s79, v[44:45]
	v_mad_i64_i32 v[60:61], s[28:29], v60, s79, v[44:45]
	v_mad_i64_i32 v[62:63], s[28:29], v62, s79, v[44:45]
	v_mad_i64_i32 v[64:65], s[28:29], v64, s79, v[44:45]
	v_mad_i64_i32 v[66:67], s[28:29], v66, s79, v[44:45]
	v_mad_i64_i32 v[68:69], s[28:29], v68, s79, v[44:45]
	v_mad_i64_i32 v[70:71], s[28:29], v70, s79, v[44:45]
	v_mad_i64_i32 v[72:73], s[28:29], v72, s79, v[44:45]
	v_mad_i64_i32 v[74:75], s[28:29], v74, s79, v[44:45]
	v_mad_i64_i32 v[76:77], s[28:29], v76, s79, v[44:45]
	global_load_dword v11, v[46:47], off
	global_load_dword v13, v[48:49], off
	global_load_dword v84, v[50:51], off
	global_load_dword v85, v[52:53], off
	global_load_dword v86, v[54:55], off
	global_load_dword v87, v[56:57], off
	global_load_dword v88, v[58:59], off
	global_load_dword v89, v[60:61], off
	global_load_dword v90, v[62:63], off
	global_load_dword v91, v[64:65], off
	global_load_dword v92, v[66:67], off
	global_load_dword v93, v[68:69], off
	global_load_dword v94, v[70:71], off
	global_load_dword v95, v[72:73], off
	global_load_dword v96, v[74:75], off
	global_load_dword v97, v[76:77], off
	s_add_i32 s5, s5, 16
	s_add_i32 s1, s1, 16
	s_lshl_b32 s28, s1, 1
	s_lshl_b32 s29, s5, 1
	v_or_b32_e32 v106, s28, v1
	v_or_b32_e32 v107, s29, v2
	s_add_i32 s30, s28, 4
	s_add_i32 s36, s29, 4
	s_add_i32 s37, s28, 8
	s_add_i32 s38, s29, 8
	s_add_i32 s39, s28, 12
	s_add_i32 s40, s29, 12
	s_add_i32 s41, s28, 16
	s_add_i32 s42, s29, 16
	s_add_i32 s43, s28, 20
	s_add_i32 s44, s29, 20
	s_add_i32 s45, s28, 24
	s_add_i32 s46, s29, 24
	s_add_i32 s28, s28, 28
	s_add_i32 s29, s29, 28
	v_add_u32_e32 v108, s0, v106
	v_add_u32_e32 v109, s8, v107
	v_or_b32_e32 v110, s30, v1
	v_or_b32_e32 v111, s36, v2
	v_or_b32_e32 v112, s37, v1
	v_or_b32_e32 v113, s38, v2
	v_or_b32_e32 v114, s39, v1
	v_or_b32_e32 v115, s40, v2
	v_or_b32_e32 v116, s41, v1
	v_or_b32_e32 v117, s42, v2
	v_or_b32_e32 v118, s43, v1
	v_or_b32_e32 v119, s44, v2
	v_or_b32_e32 v120, s45, v1
	v_or_b32_e32 v121, s46, v2
	v_or_b32_e32 v122, s28, v1
	v_or_b32_e32 v123, s29, v2
	v_mad_i64_i32 v[130:131], s[28:29], v109, s79, v[44:45]
	v_mad_i64_i32 v[132:133], s[28:29], v108, s79, v[44:45]
	v_add_u32_e32 v108, s0, v110
	v_add_u32_e32 v109, s8, v111
	v_add_u32_e32 v140, s0, v112
	v_add_u32_e32 v138, s8, v113
	v_add_u32_e32 v144, s0, v114
	v_add_u32_e32 v142, s8, v115
	v_add_u32_e32 v148, s0, v116
	v_add_u32_e32 v146, s8, v117
	v_add_u32_e32 v152, s0, v118
	v_add_u32_e32 v150, s8, v119
	v_add_u32_e32 v156, s0, v120
	v_add_u32_e32 v154, s8, v121
	v_add_u32_e32 v160, s0, v122
	v_add_u32_e32 v158, s8, v123
	v_mad_i64_i32 v[134:135], s[28:29], v109, s79, v[44:45]
	v_mad_i64_i32 v[136:137], s[28:29], v108, s79, v[44:45]
	v_mad_i64_i32 v[138:139], s[28:29], v138, s79, v[44:45]
	v_mad_i64_i32 v[140:141], s[28:29], v140, s79, v[44:45]
	v_mad_i64_i32 v[142:143], s[28:29], v142, s79, v[44:45]
	v_mad_i64_i32 v[144:145], s[28:29], v144, s79, v[44:45]
	v_mad_i64_i32 v[146:147], s[28:29], v146, s79, v[44:45]
	v_mad_i64_i32 v[148:149], s[28:29], v148, s79, v[44:45]
	v_mad_i64_i32 v[150:151], s[28:29], v150, s79, v[44:45]
	v_mad_i64_i32 v[152:153], s[28:29], v152, s79, v[44:45]
	v_mad_i64_i32 v[154:155], s[28:29], v154, s79, v[44:45]
	v_mad_i64_i32 v[156:157], s[28:29], v156, s79, v[44:45]
	v_mad_i64_i32 v[158:159], s[28:29], v158, s79, v[44:45]
	v_mad_i64_i32 v[160:161], s[28:29], v160, s79, v[44:45]
	global_load_dword v108, v[130:131], off
	global_load_dword v109, v[132:133], off
	global_load_dword v124, v[134:135], off
	global_load_dword v125, v[136:137], off
	global_load_dword v126, v[138:139], off
	global_load_dword v127, v[140:141], off
	global_load_dword v162, v[142:143], off
	global_load_dword v163, v[144:145], off
	global_load_dword v164, v[146:147], off
	global_load_dword v165, v[148:149], off
	global_load_dword v166, v[150:151], off
	global_load_dword v167, v[152:153], off
	global_load_dword v168, v[154:155], off
	global_load_dword v169, v[156:157], off
	global_load_dword v170, v[158:159], off
	global_load_dword v171, v[160:161], off
	v_mad_u64_u32 v[46:47], s[28:29], v9, s78, v[6:7]
	v_mad_u64_u32 v[48:49], s[28:29], v7, s78, v[6:7]
	v_mad_u64_u32 v[50:51], s[28:29], v17, s78, v[6:7]
	v_mad_u64_u32 v[52:53], s[28:29], v15, s78, v[6:7]
	v_mad_u64_u32 v[54:55], s[28:29], v35, s78, v[6:7]
	v_mad_u64_u32 v[56:57], s[28:29], v21, s78, v[6:7]
	v_mad_u64_u32 v[58:59], s[28:29], v39, s78, v[6:7]
	v_mad_u64_u32 v[60:61], s[28:29], v37, s78, v[6:7]
	v_mad_u64_u32 v[62:63], s[28:29], v43, s78, v[6:7]
	v_mad_u64_u32 v[64:65], s[28:29], v41, s78, v[6:7]
	v_mad_u64_u32 v[66:67], s[28:29], v79, s78, v[6:7]
	v_mad_u64_u32 v[68:69], s[28:29], v78, s78, v[6:7]
	v_mad_u64_u32 v[70:71], s[28:29], v81, s78, v[6:7]
	v_mad_u64_u32 v[72:73], s[28:29], v80, s78, v[6:7]
	v_mad_u64_u32 v[74:75], s[28:29], v83, s78, v[6:7]
	v_mad_u64_u32 v[76:77], s[28:29], v82, s78, v[6:7]
	s_waitcnt vmcnt(31)
	ds_write_b32 v46, v11
	s_waitcnt vmcnt(30)
	ds_write_b32 v48, v13
	s_waitcnt vmcnt(29)
	ds_write_b32 v50, v84
	s_waitcnt vmcnt(28)
	ds_write_b32 v52, v85
	s_waitcnt vmcnt(27)
	ds_write_b32 v54, v86
	s_waitcnt vmcnt(26)
	ds_write_b32 v56, v87
	s_waitcnt vmcnt(25)
	ds_write_b32 v58, v88
	s_waitcnt vmcnt(24)
	ds_write_b32 v60, v89
	s_waitcnt vmcnt(23)
	ds_write_b32 v62, v90
	s_waitcnt vmcnt(22)
	ds_write_b32 v64, v91
	s_waitcnt vmcnt(21)
	ds_write_b32 v66, v92
	s_waitcnt vmcnt(20)
	ds_write_b32 v68, v93
	s_waitcnt vmcnt(19)
	ds_write_b32 v70, v94
	s_waitcnt vmcnt(18)
	ds_write_b32 v72, v95
	s_waitcnt vmcnt(17)
	ds_write_b32 v74, v96
	s_waitcnt vmcnt(16)
	ds_write_b32 v76, v97
	v_mad_u64_u32 v[130:131], s[28:29], v107, s78, v[6:7]
	v_mad_u64_u32 v[132:133], s[28:29], v106, s78, v[6:7]
	v_mad_u64_u32 v[134:135], s[28:29], v111, s78, v[6:7]
	v_mad_u64_u32 v[136:137], s[28:29], v110, s78, v[6:7]
	v_mad_u64_u32 v[138:139], s[28:29], v113, s78, v[6:7]
	v_mad_u64_u32 v[140:141], s[28:29], v112, s78, v[6:7]
	v_mad_u64_u32 v[142:143], s[28:29], v115, s78, v[6:7]
	v_mad_u64_u32 v[144:145], s[28:29], v114, s78, v[6:7]
	v_mad_u64_u32 v[146:147], s[28:29], v117, s78, v[6:7]
	v_mad_u64_u32 v[148:149], s[28:29], v116, s78, v[6:7]
	v_mad_u64_u32 v[150:151], s[28:29], v119, s78, v[6:7]
	v_mad_u64_u32 v[152:153], s[28:29], v118, s78, v[6:7]
	v_mad_u64_u32 v[154:155], s[28:29], v121, s78, v[6:7]
	v_mad_u64_u32 v[156:157], s[28:29], v120, s78, v[6:7]
	v_mad_u64_u32 v[158:159], s[28:29], v123, s78, v[6:7]
	v_mad_u64_u32 v[160:161], s[28:29], v122, s78, v[6:7]
	s_waitcnt vmcnt(15)
	ds_write_b32 v130, v108
	s_waitcnt vmcnt(14)
	ds_write_b32 v132, v109
	s_waitcnt vmcnt(13)
	ds_write_b32 v134, v124
	s_waitcnt vmcnt(12)
	ds_write_b32 v136, v125
	s_waitcnt vmcnt(11)
	ds_write_b32 v138, v126
	s_waitcnt vmcnt(10)
	ds_write_b32 v140, v127
	s_waitcnt vmcnt(9)
	ds_write_b32 v142, v162
	s_waitcnt vmcnt(8)
	ds_write_b32 v144, v163
	s_waitcnt vmcnt(7)
	ds_write_b32 v146, v164
	s_waitcnt vmcnt(6)
	ds_write_b32 v148, v165
	s_waitcnt vmcnt(5)
	ds_write_b32 v150, v166
	s_waitcnt vmcnt(4)
	ds_write_b32 v152, v167
	s_waitcnt vmcnt(3)
	ds_write_b32 v154, v168
	s_waitcnt vmcnt(2)
	ds_write_b32 v156, v169
	s_waitcnt vmcnt(1)
	ds_write_b32 v158, v170
	s_waitcnt vmcnt(0)
	ds_write_b32 v160, v171
	s_add_i32 s5, s5, 16
	s_add_i32 s1, s1, 16
	s_add_i32 s9, s9, -16
	s_add_i32 s9, s9, -16
	s_cmp_lg_u32 s9, 0
	s_waitcnt lgkmcnt(0)
	ds_read2_b32 v[48:49], v3 offset1:8
	ds_read2_b32 v[52:53], v3 offset0:33 offset1:41
	ds_read2_b32 v[54:55], v3 offset0:66 offset1:74
	ds_read2_b32 v[56:57], v3 offset0:99 offset1:107
	ds_read2_b32 v[58:59], v3 offset0:132 offset1:140
	s_waitcnt lgkmcnt(4)
	v_bfe_u32 v7, v48, 16, 1
	v_add3_u32 v7, v48, v7, s33
	s_waitcnt lgkmcnt(3)
	v_bfe_u32 v9, v52, 16, 1
	v_lshrrev_b32_e32 v7, 16, v7
	v_add3_u32 v9, v52, v9, s33
	ds_read2_b32 v[60:61], v3 offset0:165 offset1:173
	v_and_or_b32 v44, v9, s69, v7
	s_waitcnt lgkmcnt(3)
	v_bfe_u32 v7, v54, 16, 1
	v_add3_u32 v7, v54, v7, s33
	s_waitcnt lgkmcnt(2)
	v_bfe_u32 v9, v56, 16, 1
	ds_read2_b32 v[62:63], v3 offset0:198 offset1:206
	v_lshrrev_b32_e32 v7, 16, v7
	v_add3_u32 v9, v56, v9, s33
	ds_read2_b32 v[64:65], v3 offset0:231 offset1:239
	v_and_or_b32 v45, v9, s69, v7
	s_waitcnt lgkmcnt(3)
	v_bfe_u32 v7, v58, 16, 1
	s_lshl_b64 s[0:1], s[10:11], 11
	v_add3_u32 v7, v58, v7, s33
	s_waitcnt lgkmcnt(2)
	v_bfe_u32 v9, v60, 16, 1
	s_add_u32 s5, s16, s0
	v_lshrrev_b32_e32 v7, 16, v7
	v_add3_u32 v9, v60, v9, s33
	s_addc_u32 s10, s17, s1
	s_ashr_i32 s9, s8, 31
	v_and_or_b32 v46, v9, s69, v7
	s_waitcnt lgkmcnt(1)
	v_bfe_u32 v7, v62, 16, 1
	s_lshl_b64 s[0:1], s[8:9], 1
	v_add3_u32 v7, v62, v7, s33
	s_waitcnt lgkmcnt(0)
	v_bfe_u32 v9, v64, 16, 1
	s_add_u32 s0, s5, s0
	v_lshrrev_b32_e32 v7, 16, v7
	v_add3_u32 v9, v64, v9, s33
	s_addc_u32 s1, s10, s1
	v_lshlrev_b32_e32 v128, 1, v8
	v_and_or_b32 v47, v9, s69, v7
	v_bfe_u32 v7, v49, 16, 1
	v_lshl_add_u64 v[50:51], s[0:1], 0, v[128:129]
	v_lshlrev_b32_e32 v128, 1, v10
	v_add3_u32 v7, v49, v7, s33
	v_bfe_u32 v9, v53, 16, 1
	v_lshl_add_u64 v[66:67], v[50:51], 0, v[128:129]
	v_lshrrev_b32_e32 v7, 16, v7
	v_add3_u32 v9, v53, v9, s33
	global_store_dwordx4 v[66:67], v[44:47], off
	v_lshlrev_b32_e32 v128, 1, v12
	ds_read2_b32 v[48:49], v3 offset0:16 offset1:24
	v_and_or_b32 v44, v9, s69, v7
	v_bfe_u32 v7, v55, 16, 1
	v_add3_u32 v7, v55, v7, s33
	v_bfe_u32 v9, v57, 16, 1
	v_lshrrev_b32_e32 v7, 16, v7
	v_add3_u32 v9, v57, v9, s33
	v_and_or_b32 v45, v9, s69, v7
	v_bfe_u32 v7, v59, 16, 1
	v_add3_u32 v7, v59, v7, s33
	v_bfe_u32 v9, v61, 16, 1
	v_lshrrev_b32_e32 v7, 16, v7
	v_add3_u32 v9, v61, v9, s33
	v_and_or_b32 v46, v9, s69, v7
	v_bfe_u32 v7, v63, 16, 1
	v_add3_u32 v7, v63, v7, s33
	v_bfe_u32 v9, v65, 16, 1
	v_lshrrev_b32_e32 v7, 16, v7
	v_add3_u32 v9, v65, v9, s33
	v_and_or_b32 v47, v9, s69, v7
	v_lshl_add_u64 v[52:53], v[50:51], 0, v[128:129]
	global_store_dwordx4 v[52:53], v[44:47], off
	ds_read2_b32 v[52:53], v3 offset0:49 offset1:57
	ds_read2_b32 v[54:55], v3 offset0:82 offset1:90
	ds_read2_b32 v[56:57], v3 offset0:115 offset1:123
	s_waitcnt lgkmcnt(3)
	v_bfe_u32 v7, v48, 16, 1
	v_add3_u32 v7, v48, v7, s33
	s_waitcnt lgkmcnt(2)
	v_bfe_u32 v9, v52, 16, 1
	ds_read2_b32 v[58:59], v3 offset0:148 offset1:156
	v_lshrrev_b32_e32 v7, 16, v7
	v_add3_u32 v9, v52, v9, s33
	ds_read2_b32 v[60:61], v3 offset0:181 offset1:189
	v_and_or_b32 v44, v9, s69, v7
	s_waitcnt lgkmcnt(3)
	v_bfe_u32 v7, v54, 16, 1
	v_add3_u32 v7, v54, v7, s33
	s_waitcnt lgkmcnt(2)
	v_bfe_u32 v9, v56, 16, 1
	ds_read2_b32 v[62:63], v3 offset0:214 offset1:222
	v_lshrrev_b32_e32 v7, 16, v7
	v_add3_u32 v9, v56, v9, s33
	ds_read2_b32 v[64:65], v3 offset0:247 offset1:255
	v_and_or_b32 v45, v9, s69, v7
	s_waitcnt lgkmcnt(3)
	v_bfe_u32 v7, v58, 16, 1
	v_add3_u32 v7, v58, v7, s33
	s_waitcnt lgkmcnt(2)
	v_bfe_u32 v9, v60, 16, 1
	v_lshrrev_b32_e32 v7, 16, v7
	v_add3_u32 v9, v60, v9, s33
	v_and_or_b32 v46, v9, s69, v7
	s_waitcnt lgkmcnt(1)
	v_bfe_u32 v7, v62, 16, 1
	v_add3_u32 v7, v62, v7, s33
	s_waitcnt lgkmcnt(0)
	v_bfe_u32 v9, v64, 16, 1
	v_lshrrev_b32_e32 v7, 16, v7
	v_add3_u32 v9, v64, v9, s33
	v_and_or_b32 v47, v9, s69, v7
	v_bfe_u32 v7, v49, 16, 1
	v_lshlrev_b32_e32 v128, 1, v14
	v_add3_u32 v7, v49, v7, s33
	v_bfe_u32 v9, v53, 16, 1
	v_lshl_add_u64 v[66:67], v[50:51], 0, v[128:129]
	v_lshrrev_b32_e32 v7, 16, v7
	v_add3_u32 v9, v53, v9, s33
	global_store_dwordx4 v[66:67], v[44:47], off
	v_lshlrev_b32_e32 v128, 1, v16
	v_lshl_add_u64 v[48:49], v[50:51], 0, v[128:129]
	v_and_or_b32 v44, v9, s69, v7
	v_bfe_u32 v7, v55, 16, 1
	v_add3_u32 v7, v55, v7, s33
	v_bfe_u32 v9, v57, 16, 1
	v_lshrrev_b32_e32 v7, 16, v7
	v_add3_u32 v9, v57, v9, s33
	v_and_or_b32 v45, v9, s69, v7
	v_bfe_u32 v7, v59, 16, 1
	v_add3_u32 v7, v59, v7, s33
	v_bfe_u32 v9, v61, 16, 1
	v_lshrrev_b32_e32 v7, 16, v7
	v_add3_u32 v9, v61, v9, s33
	v_and_or_b32 v46, v9, s69, v7
	v_bfe_u32 v7, v63, 16, 1
	v_add3_u32 v7, v63, v7, s33
	v_bfe_u32 v9, v65, 16, 1
	v_lshrrev_b32_e32 v7, 16, v7
	v_add3_u32 v9, v65, v9, s33
	v_and_or_b32 v47, v9, s69, v7
	global_store_dwordx4 v[48:49], v[44:47], off
	s_waitcnt lgkmcnt(0)
	s_mov_b32 s1, s4
	s_andn2_b64 vcc, exec, s[6:7]
	s_mov_b64 s[6:7], -1
	s_cbranch_vccnz .LBB0_832

.LBB0_819:
	s_lshl_b32 s11, s4, 1
	s_lshl_b32 s28, s5, 1
	v_or_b32_e32 v7, s11, v1
	v_or_b32_e32 v9, s28, v2
	s_add_i32 s29, s11, 4
	s_add_i32 s30, s28, 4
	s_add_i32 s36, s11, 8
	s_add_i32 s37, s28, 8
	s_add_i32 s38, s11, 12
	s_add_i32 s39, s28, 12
	s_add_i32 s40, s11, 16
	s_add_i32 s41, s28, 16
	s_add_i32 s42, s11, 20
	s_add_i32 s43, s28, 20
	s_add_i32 s44, s11, 24
	s_add_i32 s45, s28, 24
	s_add_i32 s11, s11, 28
	s_add_i32 s28, s28, 28
	v_add_u32_e32 v11, s0, v7
	v_add_u32_e32 v13, s8, v9
	v_or_b32_e32 v15, s29, v1
	v_or_b32_e32 v17, s30, v2
	v_or_b32_e32 v21, s36, v1
	v_or_b32_e32 v35, s37, v2
	v_or_b32_e32 v37, s38, v1
	v_or_b32_e32 v39, s39, v2
	v_or_b32_e32 v41, s40, v1
	v_or_b32_e32 v43, s41, v2
	v_or_b32_e32 v78, s42, v1
	v_or_b32_e32 v79, s43, v2
	v_or_b32_e32 v80, s44, v1
	v_or_b32_e32 v81, s45, v2
	v_or_b32_e32 v82, s11, v1
	v_or_b32_e32 v83, s28, v2
	v_mad_i64_i32 v[46:47], s[28:29], v13, s68, v[44:45]
	v_mad_i64_i32 v[48:49], s[28:29], v11, s68, v[44:45]
	v_add_u32_e32 v11, s0, v15
	v_add_u32_e32 v13, s8, v17
	v_add_u32_e32 v56, s0, v21
	v_add_u32_e32 v54, s8, v35
	v_add_u32_e32 v60, s0, v37
	v_add_u32_e32 v58, s8, v39
	v_add_u32_e32 v64, s0, v41
	v_add_u32_e32 v62, s8, v43
	v_add_u32_e32 v68, s0, v78
	v_add_u32_e32 v66, s8, v79
	v_add_u32_e32 v72, s0, v80
	v_add_u32_e32 v70, s8, v81
	v_add_u32_e32 v76, s0, v82
	v_add_u32_e32 v74, s8, v83
	v_mad_i64_i32 v[50:51], s[28:29], v13, s68, v[44:45]
	v_mad_i64_i32 v[52:53], s[28:29], v11, s68, v[44:45]
	v_mad_i64_i32 v[54:55], s[28:29], v54, s68, v[44:45]
	v_mad_i64_i32 v[56:57], s[28:29], v56, s68, v[44:45]
	v_mad_i64_i32 v[58:59], s[28:29], v58, s68, v[44:45]
	v_mad_i64_i32 v[60:61], s[28:29], v60, s68, v[44:45]
	v_mad_i64_i32 v[62:63], s[28:29], v62, s68, v[44:45]
	v_mad_i64_i32 v[64:65], s[28:29], v64, s68, v[44:45]
	v_mad_i64_i32 v[66:67], s[28:29], v66, s68, v[44:45]
	v_mad_i64_i32 v[68:69], s[28:29], v68, s68, v[44:45]
	v_mad_i64_i32 v[70:71], s[28:29], v70, s68, v[44:45]
	v_mad_i64_i32 v[72:73], s[28:29], v72, s68, v[44:45]
	v_mad_i64_i32 v[74:75], s[28:29], v74, s68, v[44:45]
	v_mad_i64_i32 v[76:77], s[28:29], v76, s68, v[44:45]
	global_load_dword v11, v[46:47], off
	global_load_dword v13, v[48:49], off
	global_load_dword v84, v[50:51], off
	global_load_dword v85, v[52:53], off
	global_load_dword v86, v[54:55], off
	global_load_dword v87, v[56:57], off
	global_load_dword v88, v[58:59], off
	global_load_dword v89, v[60:61], off
	global_load_dword v90, v[62:63], off
	global_load_dword v91, v[64:65], off
	global_load_dword v92, v[66:67], off
	global_load_dword v93, v[68:69], off
	global_load_dword v94, v[70:71], off
	global_load_dword v95, v[72:73], off
	global_load_dword v96, v[74:75], off
	global_load_dword v97, v[76:77], off
	s_add_i32 s5, s5, 16
	s_add_i32 s4, s4, 16
	s_lshl_b32 s11, s4, 1
	s_lshl_b32 s28, s5, 1
	v_or_b32_e32 v106, s11, v1
	v_or_b32_e32 v107, s28, v2
	s_add_i32 s29, s11, 4
	s_add_i32 s30, s28, 4
	s_add_i32 s36, s11, 8
	s_add_i32 s37, s28, 8
	s_add_i32 s38, s11, 12
	s_add_i32 s39, s28, 12
	s_add_i32 s40, s11, 16
	s_add_i32 s41, s28, 16
	s_add_i32 s42, s11, 20
	s_add_i32 s43, s28, 20
	s_add_i32 s44, s11, 24
	s_add_i32 s45, s28, 24
	s_add_i32 s11, s11, 28
	s_add_i32 s28, s28, 28
	v_add_u32_e32 v108, s0, v106
	v_add_u32_e32 v109, s8, v107
	v_or_b32_e32 v110, s29, v1
	v_or_b32_e32 v111, s30, v2
	v_or_b32_e32 v112, s36, v1
	v_or_b32_e32 v113, s37, v2
	v_or_b32_e32 v114, s38, v1
	v_or_b32_e32 v115, s39, v2
	v_or_b32_e32 v116, s40, v1
	v_or_b32_e32 v117, s41, v2
	v_or_b32_e32 v118, s42, v1
	v_or_b32_e32 v119, s43, v2
	v_or_b32_e32 v120, s44, v1
	v_or_b32_e32 v121, s45, v2
	v_or_b32_e32 v122, s11, v1
	v_or_b32_e32 v123, s28, v2
	v_mad_i64_i32 v[130:131], s[28:29], v109, s68, v[44:45]
	v_mad_i64_i32 v[132:133], s[28:29], v108, s68, v[44:45]
	v_add_u32_e32 v108, s0, v110
	v_add_u32_e32 v109, s8, v111
	v_add_u32_e32 v140, s0, v112
	v_add_u32_e32 v138, s8, v113
	v_add_u32_e32 v144, s0, v114
	v_add_u32_e32 v142, s8, v115
	v_add_u32_e32 v148, s0, v116
	v_add_u32_e32 v146, s8, v117
	v_add_u32_e32 v152, s0, v118
	v_add_u32_e32 v150, s8, v119
	v_add_u32_e32 v156, s0, v120
	v_add_u32_e32 v154, s8, v121
	v_add_u32_e32 v160, s0, v122
	v_add_u32_e32 v158, s8, v123
	v_mad_i64_i32 v[134:135], s[28:29], v109, s68, v[44:45]
	v_mad_i64_i32 v[136:137], s[28:29], v108, s68, v[44:45]
	v_mad_i64_i32 v[138:139], s[28:29], v138, s68, v[44:45]
	v_mad_i64_i32 v[140:141], s[28:29], v140, s68, v[44:45]
	v_mad_i64_i32 v[142:143], s[28:29], v142, s68, v[44:45]
	v_mad_i64_i32 v[144:145], s[28:29], v144, s68, v[44:45]
	v_mad_i64_i32 v[146:147], s[28:29], v146, s68, v[44:45]
	v_mad_i64_i32 v[148:149], s[28:29], v148, s68, v[44:45]
	v_mad_i64_i32 v[150:151], s[28:29], v150, s68, v[44:45]
	v_mad_i64_i32 v[152:153], s[28:29], v152, s68, v[44:45]
	v_mad_i64_i32 v[154:155], s[28:29], v154, s68, v[44:45]
	v_mad_i64_i32 v[156:157], s[28:29], v156, s68, v[44:45]
	v_mad_i64_i32 v[158:159], s[28:29], v158, s68, v[44:45]
	v_mad_i64_i32 v[160:161], s[28:29], v160, s68, v[44:45]
	global_load_dword v108, v[130:131], off
	global_load_dword v109, v[132:133], off
	global_load_dword v124, v[134:135], off
	global_load_dword v125, v[136:137], off
	global_load_dword v126, v[138:139], off
	global_load_dword v127, v[140:141], off
	global_load_dword v162, v[142:143], off
	global_load_dword v163, v[144:145], off
	global_load_dword v164, v[146:147], off
	global_load_dword v165, v[148:149], off
	global_load_dword v166, v[150:151], off
	global_load_dword v167, v[152:153], off
	global_load_dword v168, v[154:155], off
	global_load_dword v169, v[156:157], off
	global_load_dword v170, v[158:159], off
	global_load_dword v171, v[160:161], off
	v_mad_u64_u32 v[46:47], s[28:29], v9, s78, v[6:7]
	v_mad_u64_u32 v[48:49], s[28:29], v7, s78, v[6:7]
	v_mad_u64_u32 v[50:51], s[28:29], v17, s78, v[6:7]
	v_mad_u64_u32 v[52:53], s[28:29], v15, s78, v[6:7]
	v_mad_u64_u32 v[54:55], s[28:29], v35, s78, v[6:7]
	v_mad_u64_u32 v[56:57], s[28:29], v21, s78, v[6:7]
	v_mad_u64_u32 v[58:59], s[28:29], v39, s78, v[6:7]
	v_mad_u64_u32 v[60:61], s[28:29], v37, s78, v[6:7]
	v_mad_u64_u32 v[62:63], s[28:29], v43, s78, v[6:7]
	v_mad_u64_u32 v[64:65], s[28:29], v41, s78, v[6:7]
	v_mad_u64_u32 v[66:67], s[28:29], v79, s78, v[6:7]
	v_mad_u64_u32 v[68:69], s[28:29], v78, s78, v[6:7]
	v_mad_u64_u32 v[70:71], s[28:29], v81, s78, v[6:7]
	v_mad_u64_u32 v[72:73], s[28:29], v80, s78, v[6:7]
	v_mad_u64_u32 v[74:75], s[28:29], v83, s78, v[6:7]
	v_mad_u64_u32 v[76:77], s[28:29], v82, s78, v[6:7]
	s_waitcnt vmcnt(31)
	ds_write_b32 v46, v11
	s_waitcnt vmcnt(30)
	ds_write_b32 v48, v13
	s_waitcnt vmcnt(29)
	ds_write_b32 v50, v84
	s_waitcnt vmcnt(28)
	ds_write_b32 v52, v85
	s_waitcnt vmcnt(27)
	ds_write_b32 v54, v86
	s_waitcnt vmcnt(26)
	ds_write_b32 v56, v87
	s_waitcnt vmcnt(25)
	ds_write_b32 v58, v88
	s_waitcnt vmcnt(24)
	ds_write_b32 v60, v89
	s_waitcnt vmcnt(23)
	ds_write_b32 v62, v90
	s_waitcnt vmcnt(22)
	ds_write_b32 v64, v91
	s_waitcnt vmcnt(21)
	ds_write_b32 v66, v92
	s_waitcnt vmcnt(20)
	ds_write_b32 v68, v93
	s_waitcnt vmcnt(19)
	ds_write_b32 v70, v94
	s_waitcnt vmcnt(18)
	ds_write_b32 v72, v95
	s_waitcnt vmcnt(17)
	ds_write_b32 v74, v96
	s_waitcnt vmcnt(16)
	ds_write_b32 v76, v97
	v_mad_u64_u32 v[130:131], s[28:29], v107, s78, v[6:7]
	v_mad_u64_u32 v[132:133], s[28:29], v106, s78, v[6:7]
	v_mad_u64_u32 v[134:135], s[28:29], v111, s78, v[6:7]
	v_mad_u64_u32 v[136:137], s[28:29], v110, s78, v[6:7]
	v_mad_u64_u32 v[138:139], s[28:29], v113, s78, v[6:7]
	v_mad_u64_u32 v[140:141], s[28:29], v112, s78, v[6:7]
	v_mad_u64_u32 v[142:143], s[28:29], v115, s78, v[6:7]
	v_mad_u64_u32 v[144:145], s[28:29], v114, s78, v[6:7]
	v_mad_u64_u32 v[146:147], s[28:29], v117, s78, v[6:7]
	v_mad_u64_u32 v[148:149], s[28:29], v116, s78, v[6:7]
	v_mad_u64_u32 v[150:151], s[28:29], v119, s78, v[6:7]
	v_mad_u64_u32 v[152:153], s[28:29], v118, s78, v[6:7]
	v_mad_u64_u32 v[154:155], s[28:29], v121, s78, v[6:7]
	v_mad_u64_u32 v[156:157], s[28:29], v120, s78, v[6:7]
	v_mad_u64_u32 v[158:159], s[28:29], v123, s78, v[6:7]
	v_mad_u64_u32 v[160:161], s[28:29], v122, s78, v[6:7]
	s_waitcnt vmcnt(15)
	ds_write_b32 v130, v108
	s_waitcnt vmcnt(14)
	ds_write_b32 v132, v109
	s_waitcnt vmcnt(13)
	ds_write_b32 v134, v124
	s_waitcnt vmcnt(12)
	ds_write_b32 v136, v125
	s_waitcnt vmcnt(11)
	ds_write_b32 v138, v126
	s_waitcnt vmcnt(10)
	ds_write_b32 v140, v127
	s_waitcnt vmcnt(9)
	ds_write_b32 v142, v162
	s_waitcnt vmcnt(8)
	ds_write_b32 v144, v163
	s_waitcnt vmcnt(7)
	ds_write_b32 v146, v164
	s_waitcnt vmcnt(6)
	ds_write_b32 v148, v165
	s_waitcnt vmcnt(5)
	ds_write_b32 v150, v166
	s_waitcnt vmcnt(4)
	ds_write_b32 v152, v167
	s_waitcnt vmcnt(3)
	ds_write_b32 v154, v168
	s_waitcnt vmcnt(2)
	ds_write_b32 v156, v169
	s_waitcnt vmcnt(1)
	ds_write_b32 v158, v170
	s_waitcnt vmcnt(0)
	ds_write_b32 v160, v171
	s_add_i32 s5, s5, 16
	s_add_i32 s4, s4, 16
	s_add_i32 s9, s9, -16
	s_add_i32 s9, s9, -16
	s_cmp_lg_u32 s9, 0
	s_waitcnt lgkmcnt(0)
	ds_read2_b32 v[48:49], v3 offset1:8
	ds_read2_b32 v[52:53], v3 offset0:33 offset1:41
	ds_read2_b32 v[54:55], v3 offset0:66 offset1:74
	ds_read2_b32 v[56:57], v3 offset0:99 offset1:107
	ds_read2_b32 v[58:59], v3 offset0:132 offset1:140
	s_waitcnt lgkmcnt(4)
	v_bfe_u32 v7, v48, 16, 1
	v_add3_u32 v7, v48, v7, s33
	s_waitcnt lgkmcnt(3)
	v_bfe_u32 v9, v52, 16, 1
	v_lshrrev_b32_e32 v7, 16, v7
	v_add3_u32 v9, v52, v9, s33
	ds_read2_b32 v[60:61], v3 offset0:165 offset1:173
	v_and_or_b32 v44, v9, s69, v7
	s_waitcnt lgkmcnt(3)
	v_bfe_u32 v7, v54, 16, 1
	v_add3_u32 v7, v54, v7, s33
	s_waitcnt lgkmcnt(2)
	v_bfe_u32 v9, v56, 16, 1
	ds_read2_b32 v[62:63], v3 offset0:198 offset1:206
	v_lshrrev_b32_e32 v7, 16, v7
	v_add3_u32 v9, v56, v9, s33
	ds_read2_b32 v[64:65], v3 offset0:231 offset1:239
	v_and_or_b32 v45, v9, s69, v7
	s_waitcnt lgkmcnt(3)
	v_bfe_u32 v7, v58, 16, 1
	s_mul_i32 s4, s10, 0x300
	v_add3_u32 v7, v58, v7, s33
	s_waitcnt lgkmcnt(2)
	v_bfe_u32 v9, v60, 16, 1
	s_mul_hi_i32 s0, s10, 0x300
	s_add_u32 s10, s24, s4
	v_lshrrev_b32_e32 v7, 16, v7
	v_add3_u32 v9, v60, v9, s33
	s_addc_u32 s0, s25, s0
	s_ashr_i32 s9, s8, 31
	v_and_or_b32 v46, v9, s69, v7
	s_waitcnt lgkmcnt(1)
	v_bfe_u32 v7, v62, 16, 1
	s_lshl_b64 s[4:5], s[8:9], 1
	v_add3_u32 v7, v62, v7, s33
	s_waitcnt lgkmcnt(0)
	v_bfe_u32 v9, v64, 16, 1
	s_add_u32 s4, s10, s4
	v_lshrrev_b32_e32 v7, 16, v7
	v_add3_u32 v9, v64, v9, s33
	s_addc_u32 s5, s0, s5
	v_lshlrev_b32_e32 v128, 1, v8
	v_and_or_b32 v47, v9, s69, v7
	v_bfe_u32 v7, v49, 16, 1
	v_lshl_add_u64 v[50:51], s[4:5], 0, v[128:129]
	v_mov_b32_e32 v35, v129
	v_add3_u32 v7, v49, v7, s33
	v_bfe_u32 v9, v53, 16, 1
	v_lshl_add_u64 v[50:51], v[50:51], 0, v[34:35]
	v_lshrrev_b32_e32 v7, 16, v7
	v_add3_u32 v9, v53, v9, s33
	global_store_dwordx4 v[50:51], v[44:47], off
	s_movk_i32 s0, 0x1000
	v_add_co_u32_e32 v52, vcc, s0, v50
	v_and_or_b32 v44, v9, s69, v7
	v_bfe_u32 v7, v55, 16, 1
	v_add3_u32 v7, v55, v7, s33
	v_bfe_u32 v9, v57, 16, 1
	v_lshrrev_b32_e32 v7, 16, v7
	v_add3_u32 v9, v57, v9, s33
	v_and_or_b32 v45, v9, s69, v7
	v_bfe_u32 v7, v59, 16, 1
	v_add3_u32 v7, v59, v7, s33
	v_bfe_u32 v9, v61, 16, 1
	v_lshrrev_b32_e32 v7, 16, v7
	v_add3_u32 v9, v61, v9, s33
	v_and_or_b32 v46, v9, s69, v7
	v_bfe_u32 v7, v63, 16, 1
	v_add3_u32 v7, v63, v7, s33
	v_bfe_u32 v9, v65, 16, 1
	v_lshrrev_b32_e32 v7, 16, v7
	v_add3_u32 v9, v65, v9, s33
	v_and_or_b32 v47, v9, s69, v7
	ds_read2_b32 v[48:49], v3 offset0:16 offset1:24
	v_addc_co_u32_e32 v53, vcc, 0, v51, vcc
	global_store_dwordx4 v[52:53], v[44:47], off offset:2048
	ds_read2_b32 v[52:53], v3 offset0:49 offset1:57
	ds_read2_b32 v[54:55], v3 offset0:82 offset1:90
	ds_read2_b32 v[56:57], v3 offset0:115 offset1:123
	s_waitcnt lgkmcnt(3)
	v_bfe_u32 v7, v48, 16, 1
	v_add3_u32 v7, v48, v7, s33
	s_waitcnt lgkmcnt(2)
	v_bfe_u32 v9, v52, 16, 1
	ds_read2_b32 v[58:59], v3 offset0:148 offset1:156
	v_lshrrev_b32_e32 v7, 16, v7
	v_add3_u32 v9, v52, v9, s33
	ds_read2_b32 v[60:61], v3 offset0:181 offset1:189
	v_and_or_b32 v44, v9, s69, v7
	s_waitcnt lgkmcnt(3)
	v_bfe_u32 v7, v54, 16, 1
	v_add3_u32 v7, v54, v7, s33
	s_waitcnt lgkmcnt(2)
	v_bfe_u32 v9, v56, 16, 1
	ds_read2_b32 v[62:63], v3 offset0:214 offset1:222
	v_lshrrev_b32_e32 v7, 16, v7
	v_add3_u32 v9, v56, v9, s33
	ds_read2_b32 v[64:65], v3 offset0:247 offset1:255
	v_and_or_b32 v45, v9, s69, v7
	s_waitcnt lgkmcnt(3)
	v_bfe_u32 v7, v58, 16, 1
	v_add3_u32 v7, v58, v7, s33
	s_waitcnt lgkmcnt(2)
	v_bfe_u32 v9, v60, 16, 1
	v_lshrrev_b32_e32 v7, 16, v7
	v_add3_u32 v9, v60, v9, s33
	v_and_or_b32 v46, v9, s69, v7
	s_waitcnt lgkmcnt(1)
	v_bfe_u32 v7, v62, 16, 1
	v_add3_u32 v7, v62, v7, s33
	s_waitcnt lgkmcnt(0)
	v_bfe_u32 v9, v64, 16, 1
	v_lshrrev_b32_e32 v7, 16, v7
	v_add3_u32 v9, v64, v9, s33
	v_and_or_b32 v47, v9, s69, v7
	s_movk_i32 s0, 0x3000
	v_bfe_u32 v7, v49, 16, 1
	v_add_co_u32_e32 v66, vcc, s0, v50
	v_add3_u32 v7, v49, v7, s33
	v_bfe_u32 v9, v53, 16, 1
	v_addc_co_u32_e32 v67, vcc, 0, v51, vcc
	v_lshrrev_b32_e32 v7, 16, v7
	v_add3_u32 v9, v53, v9, s33
	global_store_dwordx4 v[66:67], v[44:47], off
	v_add_co_u32_e32 v48, vcc, 0x4000, v50
	s_nop 0
	v_and_or_b32 v44, v9, s69, v7
	v_bfe_u32 v7, v55, 16, 1
	v_add3_u32 v7, v55, v7, s33
	v_bfe_u32 v9, v57, 16, 1
	v_lshrrev_b32_e32 v7, 16, v7
	v_add3_u32 v9, v57, v9, s33
	v_and_or_b32 v45, v9, s69, v7
	v_bfe_u32 v7, v59, 16, 1
	v_add3_u32 v7, v59, v7, s33
	v_bfe_u32 v9, v61, 16, 1
	v_lshrrev_b32_e32 v7, 16, v7
	v_add3_u32 v9, v61, v9, s33
	v_and_or_b32 v46, v9, s69, v7
	v_bfe_u32 v7, v63, 16, 1
	v_add3_u32 v7, v63, v7, s33
	v_bfe_u32 v9, v65, 16, 1
	v_lshrrev_b32_e32 v7, 16, v7
	v_add3_u32 v9, v65, v9, s33
	v_and_or_b32 v47, v9, s69, v7
	v_addc_co_u32_e32 v49, vcc, 0, v51, vcc
	global_store_dwordx4 v[48:49], v[44:47], off offset:2048
	s_waitcnt lgkmcnt(0)
	s_mov_b32 s0, s1
	s_andn2_b64 vcc, exec, s[6:7]
	s_mov_b64 s[6:7], -1
	s_cbranch_vccnz .LBB0_832

.LBB0_826:
	s_lshl_b32 s28, s5, 1
	s_lshl_b32 s29, s9, 1
	v_or_b32_e32 v7, s28, v1
	v_or_b32_e32 v9, s29, v2
	s_add_i32 s30, s28, 4
	s_add_i32 s36, s29, 4
	s_add_i32 s37, s28, 8
	s_add_i32 s38, s29, 8
	s_add_i32 s39, s28, 12
	s_add_i32 s40, s29, 12
	s_add_i32 s41, s28, 16
	s_add_i32 s42, s29, 16
	s_add_i32 s43, s28, 20
	s_add_i32 s44, s29, 20
	s_add_i32 s45, s28, 24
	s_add_i32 s46, s29, 24
	s_add_i32 s28, s28, 28
	s_add_i32 s29, s29, 28
	v_add_u32_e32 v48, s8, v9
	v_or_b32_e32 v11, s30, v1
	v_or_b32_e32 v13, s36, v2
	v_or_b32_e32 v15, s37, v1
	v_or_b32_e32 v17, s38, v2
	v_or_b32_e32 v21, s39, v1
	v_or_b32_e32 v35, s40, v2
	v_or_b32_e32 v37, s41, v1
	v_or_b32_e32 v39, s42, v2
	v_or_b32_e32 v41, s43, v1
	v_or_b32_e32 v43, s44, v2
	v_or_b32_e32 v78, s45, v1
	v_or_b32_e32 v79, s46, v2
	v_or_b32_e32 v80, s28, v1
	v_or_b32_e32 v81, s29, v2
	v_add_u32_e32 v46, s4, v7
	v_ashrrev_i32_e32 v49, 31, v48
	v_add_u32_e32 v50, s4, v11
	v_add_u32_e32 v52, s8, v13
	v_add_u32_e32 v54, s4, v15
	v_add_u32_e32 v56, s8, v17
	v_add_u32_e32 v58, s4, v21
	v_add_u32_e32 v60, s8, v35
	v_add_u32_e32 v62, s4, v37
	v_add_u32_e32 v64, s8, v39
	v_add_u32_e32 v66, s4, v41
	v_add_u32_e32 v68, s8, v43
	v_add_u32_e32 v70, s4, v78
	v_add_u32_e32 v72, s8, v79
	v_add_u32_e32 v74, s4, v80
	v_add_u32_e32 v76, s8, v81
	v_ashrrev_i32_e32 v47, 31, v46
	v_lshlrev_b64 v[48:49], 13, v[48:49]
	v_ashrrev_i32_e32 v53, 31, v52
	v_ashrrev_i32_e32 v51, 31, v50
	v_ashrrev_i32_e32 v57, 31, v56
	v_ashrrev_i32_e32 v55, 31, v54
	v_ashrrev_i32_e32 v61, 31, v60
	v_ashrrev_i32_e32 v59, 31, v58
	v_ashrrev_i32_e32 v65, 31, v64
	v_ashrrev_i32_e32 v63, 31, v62
	v_ashrrev_i32_e32 v69, 31, v68
	v_ashrrev_i32_e32 v67, 31, v66
	v_ashrrev_i32_e32 v73, 31, v72
	v_ashrrev_i32_e32 v71, 31, v70
	v_ashrrev_i32_e32 v77, 31, v76
	v_ashrrev_i32_e32 v75, 31, v74
	v_lshlrev_b64 v[46:47], 13, v[46:47]
	v_lshl_add_u64 v[48:49], v[44:45], 0, v[48:49]
	v_lshlrev_b64 v[50:51], 13, v[50:51]
	v_lshlrev_b64 v[52:53], 13, v[52:53]
	v_lshlrev_b64 v[54:55], 13, v[54:55]
	v_lshlrev_b64 v[56:57], 13, v[56:57]
	v_lshlrev_b64 v[58:59], 13, v[58:59]
	v_lshlrev_b64 v[60:61], 13, v[60:61]
	v_lshlrev_b64 v[62:63], 13, v[62:63]
	v_lshlrev_b64 v[64:65], 13, v[64:65]
	v_lshlrev_b64 v[66:67], 13, v[66:67]
	v_lshlrev_b64 v[68:69], 13, v[68:69]
	v_lshlrev_b64 v[70:71], 13, v[70:71]
	v_lshlrev_b64 v[72:73], 13, v[72:73]
	v_lshlrev_b64 v[74:75], 13, v[74:75]
	v_lshlrev_b64 v[76:77], 13, v[76:77]
	v_lshl_add_u64 v[46:47], v[44:45], 0, v[46:47]
	v_lshl_add_u64 v[52:53], v[44:45], 0, v[52:53]
	v_lshl_add_u64 v[50:51], v[44:45], 0, v[50:51]
	v_lshl_add_u64 v[56:57], v[44:45], 0, v[56:57]
	v_lshl_add_u64 v[54:55], v[44:45], 0, v[54:55]
	v_lshl_add_u64 v[60:61], v[44:45], 0, v[60:61]
	v_lshl_add_u64 v[58:59], v[44:45], 0, v[58:59]
	v_lshl_add_u64 v[64:65], v[44:45], 0, v[64:65]
	v_lshl_add_u64 v[62:63], v[44:45], 0, v[62:63]
	v_lshl_add_u64 v[68:69], v[44:45], 0, v[68:69]
	v_lshl_add_u64 v[66:67], v[44:45], 0, v[66:67]
	v_lshl_add_u64 v[72:73], v[44:45], 0, v[72:73]
	v_lshl_add_u64 v[70:71], v[44:45], 0, v[70:71]
	v_lshl_add_u64 v[76:77], v[44:45], 0, v[76:77]
	v_lshl_add_u64 v[74:75], v[44:45], 0, v[74:75]
	global_load_dword v82, v[48:49], off
	global_load_dword v83, v[46:47], off
	global_load_dword v84, v[52:53], off
	global_load_dword v85, v[50:51], off
	global_load_dword v86, v[56:57], off
	global_load_dword v87, v[54:55], off
	global_load_dword v88, v[60:61], off
	global_load_dword v89, v[58:59], off
	global_load_dword v90, v[64:65], off
	global_load_dword v91, v[62:63], off
	global_load_dword v92, v[68:69], off
	global_load_dword v93, v[66:67], off
	global_load_dword v94, v[72:73], off
	global_load_dword v95, v[70:71], off
	global_load_dword v96, v[76:77], off
	global_load_dword v97, v[74:75], off
	s_add_i32 s9, s9, 16
	s_add_i32 s5, s5, 16
	s_lshl_b32 s28, s5, 1
	s_lshl_b32 s29, s9, 1
	v_or_b32_e32 v106, s28, v1
	v_or_b32_e32 v107, s29, v2
	s_add_i32 s30, s28, 4
	s_add_i32 s36, s29, 4
	s_add_i32 s37, s28, 8
	s_add_i32 s38, s29, 8
	s_add_i32 s39, s28, 12
	s_add_i32 s40, s29, 12
	s_add_i32 s41, s28, 16
	s_add_i32 s42, s29, 16
	s_add_i32 s43, s28, 20
	s_add_i32 s44, s29, 20
	s_add_i32 s45, s28, 24
	s_add_i32 s46, s29, 24
	s_add_i32 s28, s28, 28
	s_add_i32 s29, s29, 28
	v_add_u32_e32 v132, s8, v107
	v_or_b32_e32 v108, s30, v1
	v_or_b32_e32 v109, s36, v2
	v_or_b32_e32 v110, s37, v1
	v_or_b32_e32 v111, s38, v2
	v_or_b32_e32 v112, s39, v1
	v_or_b32_e32 v113, s40, v2
	v_or_b32_e32 v114, s41, v1
	v_or_b32_e32 v115, s42, v2
	v_or_b32_e32 v116, s43, v1
	v_or_b32_e32 v117, s44, v2
	v_or_b32_e32 v118, s45, v1
	v_or_b32_e32 v119, s46, v2
	v_or_b32_e32 v120, s28, v1
	v_or_b32_e32 v121, s29, v2
	v_add_u32_e32 v130, s4, v106
	v_ashrrev_i32_e32 v133, 31, v132
	v_add_u32_e32 v134, s4, v108
	v_add_u32_e32 v136, s8, v109
	v_add_u32_e32 v138, s4, v110
	v_add_u32_e32 v140, s8, v111
	v_add_u32_e32 v142, s4, v112
	v_add_u32_e32 v144, s8, v113
	v_add_u32_e32 v146, s4, v114
	v_add_u32_e32 v148, s8, v115
	v_add_u32_e32 v150, s4, v116
	v_add_u32_e32 v152, s8, v117
	v_add_u32_e32 v154, s4, v118
	v_add_u32_e32 v156, s8, v119
	v_add_u32_e32 v158, s4, v120
	v_add_u32_e32 v160, s8, v121
	v_ashrrev_i32_e32 v131, 31, v130
	v_lshlrev_b64 v[132:133], 13, v[132:133]
	v_ashrrev_i32_e32 v137, 31, v136
	v_ashrrev_i32_e32 v135, 31, v134
	v_ashrrev_i32_e32 v141, 31, v140
	v_ashrrev_i32_e32 v139, 31, v138
	v_ashrrev_i32_e32 v145, 31, v144
	v_ashrrev_i32_e32 v143, 31, v142
	v_ashrrev_i32_e32 v149, 31, v148
	v_ashrrev_i32_e32 v147, 31, v146
	v_ashrrev_i32_e32 v153, 31, v152
	v_ashrrev_i32_e32 v151, 31, v150
	v_ashrrev_i32_e32 v157, 31, v156
	v_ashrrev_i32_e32 v155, 31, v154
	v_ashrrev_i32_e32 v161, 31, v160
	v_ashrrev_i32_e32 v159, 31, v158
	v_lshlrev_b64 v[130:131], 13, v[130:131]
	v_lshl_add_u64 v[132:133], v[44:45], 0, v[132:133]
	v_lshlrev_b64 v[134:135], 13, v[134:135]
	v_lshlrev_b64 v[136:137], 13, v[136:137]
	v_lshlrev_b64 v[138:139], 13, v[138:139]
	v_lshlrev_b64 v[140:141], 13, v[140:141]
	v_lshlrev_b64 v[142:143], 13, v[142:143]
	v_lshlrev_b64 v[144:145], 13, v[144:145]
	v_lshlrev_b64 v[146:147], 13, v[146:147]
	v_lshlrev_b64 v[148:149], 13, v[148:149]
	v_lshlrev_b64 v[150:151], 13, v[150:151]
	v_lshlrev_b64 v[152:153], 13, v[152:153]
	v_lshlrev_b64 v[154:155], 13, v[154:155]
	v_lshlrev_b64 v[156:157], 13, v[156:157]
	v_lshlrev_b64 v[158:159], 13, v[158:159]
	v_lshlrev_b64 v[160:161], 13, v[160:161]
	v_lshl_add_u64 v[130:131], v[44:45], 0, v[130:131]
	v_lshl_add_u64 v[136:137], v[44:45], 0, v[136:137]
	v_lshl_add_u64 v[134:135], v[44:45], 0, v[134:135]
	v_lshl_add_u64 v[140:141], v[44:45], 0, v[140:141]
	v_lshl_add_u64 v[138:139], v[44:45], 0, v[138:139]
	v_lshl_add_u64 v[144:145], v[44:45], 0, v[144:145]
	v_lshl_add_u64 v[142:143], v[44:45], 0, v[142:143]
	v_lshl_add_u64 v[148:149], v[44:45], 0, v[148:149]
	v_lshl_add_u64 v[146:147], v[44:45], 0, v[146:147]
	v_lshl_add_u64 v[152:153], v[44:45], 0, v[152:153]
	v_lshl_add_u64 v[150:151], v[44:45], 0, v[150:151]
	v_lshl_add_u64 v[156:157], v[44:45], 0, v[156:157]
	v_lshl_add_u64 v[154:155], v[44:45], 0, v[154:155]
	v_lshl_add_u64 v[160:161], v[44:45], 0, v[160:161]
	v_lshl_add_u64 v[158:159], v[44:45], 0, v[158:159]
	global_load_dword v122, v[132:133], off
	global_load_dword v123, v[130:131], off
	global_load_dword v124, v[136:137], off
	global_load_dword v125, v[134:135], off
	global_load_dword v126, v[140:141], off
	global_load_dword v127, v[138:139], off
	global_load_dword v162, v[144:145], off
	global_load_dword v163, v[142:143], off
	global_load_dword v164, v[148:149], off
	global_load_dword v165, v[146:147], off
	global_load_dword v166, v[152:153], off
	global_load_dword v167, v[150:151], off
	global_load_dword v168, v[156:157], off
	global_load_dword v169, v[154:155], off
	global_load_dword v170, v[160:161], off
	global_load_dword v171, v[158:159], off
	v_mad_u64_u32 v[46:47], s[28:29], v9, s78, v[6:7]
	v_mad_u64_u32 v[48:49], s[28:29], v7, s78, v[6:7]
	v_mad_u64_u32 v[50:51], s[28:29], v13, s78, v[6:7]
	v_mad_u64_u32 v[52:53], s[28:29], v11, s78, v[6:7]
	v_mad_u64_u32 v[54:55], s[28:29], v17, s78, v[6:7]
	v_mad_u64_u32 v[56:57], s[28:29], v15, s78, v[6:7]
	v_mad_u64_u32 v[58:59], s[28:29], v35, s78, v[6:7]
	v_mad_u64_u32 v[60:61], s[28:29], v21, s78, v[6:7]
	v_mad_u64_u32 v[62:63], s[28:29], v39, s78, v[6:7]
	v_mad_u64_u32 v[64:65], s[28:29], v37, s78, v[6:7]
	v_mad_u64_u32 v[66:67], s[28:29], v43, s78, v[6:7]
	v_mad_u64_u32 v[68:69], s[28:29], v41, s78, v[6:7]
	v_mad_u64_u32 v[70:71], s[28:29], v79, s78, v[6:7]
	v_mad_u64_u32 v[72:73], s[28:29], v78, s78, v[6:7]
	v_mad_u64_u32 v[74:75], s[28:29], v81, s78, v[6:7]
	v_mad_u64_u32 v[76:77], s[28:29], v80, s78, v[6:7]
	s_waitcnt vmcnt(31)
	ds_write_b32 v46, v82
	s_waitcnt vmcnt(30)
	ds_write_b32 v48, v83
	s_waitcnt vmcnt(29)
	ds_write_b32 v50, v84
	s_waitcnt vmcnt(28)
	ds_write_b32 v52, v85
	s_waitcnt vmcnt(27)
	ds_write_b32 v54, v86
	s_waitcnt vmcnt(26)
	ds_write_b32 v56, v87
	s_waitcnt vmcnt(25)
	ds_write_b32 v58, v88
	s_waitcnt vmcnt(24)
	ds_write_b32 v60, v89
	s_waitcnt vmcnt(23)
	ds_write_b32 v62, v90
	s_waitcnt vmcnt(22)
	ds_write_b32 v64, v91
	s_waitcnt vmcnt(21)
	ds_write_b32 v66, v92
	s_waitcnt vmcnt(20)
	ds_write_b32 v68, v93
	s_waitcnt vmcnt(19)
	ds_write_b32 v70, v94
	s_waitcnt vmcnt(18)
	ds_write_b32 v72, v95
	s_waitcnt vmcnt(17)
	ds_write_b32 v74, v96
	s_waitcnt vmcnt(16)
	ds_write_b32 v76, v97
	v_mad_u64_u32 v[130:131], s[28:29], v107, s78, v[6:7]
	v_mad_u64_u32 v[132:133], s[28:29], v106, s78, v[6:7]
	v_mad_u64_u32 v[134:135], s[28:29], v109, s78, v[6:7]
	v_mad_u64_u32 v[136:137], s[28:29], v108, s78, v[6:7]
	v_mad_u64_u32 v[138:139], s[28:29], v111, s78, v[6:7]
	v_mad_u64_u32 v[140:141], s[28:29], v110, s78, v[6:7]
	v_mad_u64_u32 v[142:143], s[28:29], v113, s78, v[6:7]
	v_mad_u64_u32 v[144:145], s[28:29], v112, s78, v[6:7]
	v_mad_u64_u32 v[146:147], s[28:29], v115, s78, v[6:7]
	v_mad_u64_u32 v[148:149], s[28:29], v114, s78, v[6:7]
	v_mad_u64_u32 v[150:151], s[28:29], v117, s78, v[6:7]
	v_mad_u64_u32 v[152:153], s[28:29], v116, s78, v[6:7]
	v_mad_u64_u32 v[154:155], s[28:29], v119, s78, v[6:7]
	v_mad_u64_u32 v[156:157], s[28:29], v118, s78, v[6:7]
	v_mad_u64_u32 v[158:159], s[28:29], v121, s78, v[6:7]
	v_mad_u64_u32 v[160:161], s[28:29], v120, s78, v[6:7]
	s_waitcnt vmcnt(15)
	ds_write_b32 v130, v122
	s_waitcnt vmcnt(14)
	ds_write_b32 v132, v123
	s_waitcnt vmcnt(13)
	ds_write_b32 v134, v124
	s_waitcnt vmcnt(12)
	ds_write_b32 v136, v125
	s_waitcnt vmcnt(11)
	ds_write_b32 v138, v126
	s_waitcnt vmcnt(10)
	ds_write_b32 v140, v127
	s_waitcnt vmcnt(9)
	ds_write_b32 v142, v162
	s_waitcnt vmcnt(8)
	ds_write_b32 v144, v163
	s_waitcnt vmcnt(7)
	ds_write_b32 v146, v164
	s_waitcnt vmcnt(6)
	ds_write_b32 v148, v165
	s_waitcnt vmcnt(5)
	ds_write_b32 v150, v166
	s_waitcnt vmcnt(4)
	ds_write_b32 v152, v167
	s_waitcnt vmcnt(3)
	ds_write_b32 v154, v168
	s_waitcnt vmcnt(2)
	ds_write_b32 v156, v169
	s_waitcnt vmcnt(1)
	ds_write_b32 v158, v170
	s_waitcnt vmcnt(0)
	ds_write_b32 v160, v171
	s_add_i32 s9, s9, 16
	s_add_i32 s5, s5, 16
	s_add_i32 s11, s11, -16
	s_add_i32 s11, s11, -16
	s_cmp_lg_u32 s11, 0
	s_bfe_i32 s4, s1, 0x80000
	s_bfe_u32 s4, s4, 0x3000c
	s_waitcnt lgkmcnt(0)
	s_add_i32 s1, s1, s4
	s_bfe_u32 s4, s10, 0x80017
	ds_read2_b32 v[48:49], v3 offset1:8
	s_bfe_i32 s1, s1, 0x80000
	s_add_i32 s4, s10, s4
	ds_read2_b32 v[52:53], v3 offset0:33 offset1:41
	s_sext_i32_i16 s1, s1
	s_and_b32 s4, s4, 0xff00
	s_sub_i32 s4, s10, s4
	s_lshl_b32 s1, s1, 4
	ds_read2_b32 v[54:55], v3 offset0:66 offset1:74
	s_sext_i32_i16 s4, s4
	s_and_b32 s1, s1, 0xffffff80
	ds_read2_b32 v[56:57], v3 offset0:99 offset1:107
	s_add_i32 s1, s1, s4
	s_waitcnt lgkmcnt(3)
	v_bfe_u32 v7, v48, 16, 1
	s_add_i32 s5, s1, 0xffffff80
	v_add3_u32 v7, v48, v7, s33
	s_waitcnt lgkmcnt(2)
	v_bfe_u32 v9, v52, 16, 1
	ds_read2_b32 v[58:59], v3 offset0:132 offset1:140
	s_cmpk_lt_i32 s4, 0x80
	v_lshrrev_b32_e32 v7, 16, v7
	v_add3_u32 v9, v52, v9, s33
	ds_read2_b32 v[60:61], v3 offset0:165 offset1:173
	s_cselect_b32 s4, s1, s5
	s_mov_b32 s1, 0x23a0000
	v_and_or_b32 v44, v9, s69, v7
	s_waitcnt lgkmcnt(3)
	v_bfe_u32 v7, v54, 16, 1
	s_cselect_b32 s1, s1, 0x2420000
	s_ashr_i32 s5, s4, 31
	v_add3_u32 v7, v54, v7, s33
	s_waitcnt lgkmcnt(2)
	v_bfe_u32 v9, v56, 16, 1
	ds_read2_b32 v[62:63], v3 offset0:198 offset1:206
	s_lshl_b64 s[4:5], s[4:5], 9
	v_lshrrev_b32_e32 v7, 16, v7
	v_add3_u32 v9, v56, v9, s33
	ds_read2_b32 v[64:65], v3 offset0:231 offset1:239
	s_add_u32 s1, s13, s1
	v_and_or_b32 v45, v9, s69, v7
	s_waitcnt lgkmcnt(3)
	v_bfe_u32 v7, v58, 16, 1
	s_addc_u32 s9, s14, 0
	v_add3_u32 v7, v58, v7, s33
	s_waitcnt lgkmcnt(2)
	v_bfe_u32 v9, v60, 16, 1
	s_add_u32 s1, s1, s4
	v_lshrrev_b32_e32 v7, 16, v7
	v_add3_u32 v9, v60, v9, s33
	s_addc_u32 s10, s9, s5
	s_ashr_i32 s9, s8, 31
	v_and_or_b32 v46, v9, s69, v7
	s_waitcnt lgkmcnt(1)
	v_bfe_u32 v7, v62, 16, 1
	s_lshl_b64 s[4:5], s[8:9], 1
	v_add3_u32 v7, v62, v7, s33
	s_waitcnt lgkmcnt(0)
	v_bfe_u32 v9, v64, 16, 1
	s_add_u32 s4, s1, s4
	v_lshrrev_b32_e32 v7, 16, v7
	v_add3_u32 v9, v64, v9, s33
	s_addc_u32 s5, s10, s5
	v_lshlrev_b32_e32 v128, 1, v8
	v_and_or_b32 v47, v9, s69, v7
	v_bfe_u32 v7, v49, 16, 1
	v_lshl_add_u64 v[50:51], s[4:5], 0, v[128:129]
	v_mov_b32_e32 v37, v129
	v_add3_u32 v7, v49, v7, s33
	v_bfe_u32 v9, v53, 16, 1
	v_lshl_add_u64 v[66:67], v[50:51], 0, v[36:37]
	v_lshrrev_b32_e32 v7, 16, v7
	v_add3_u32 v9, v53, v9, s33
	global_store_dwordx4 v[66:67], v[44:47], off
	v_mov_b32_e32 v39, v129
	ds_read2_b32 v[48:49], v3 offset0:16 offset1:24
	v_and_or_b32 v44, v9, s69, v7
	v_bfe_u32 v7, v55, 16, 1
	v_add3_u32 v7, v55, v7, s33
	v_bfe_u32 v9, v57, 16, 1
	v_lshrrev_b32_e32 v7, 16, v7
	v_add3_u32 v9, v57, v9, s33
	v_and_or_b32 v45, v9, s69, v7
	v_bfe_u32 v7, v59, 16, 1
	v_add3_u32 v7, v59, v7, s33
	v_bfe_u32 v9, v61, 16, 1
	v_lshrrev_b32_e32 v7, 16, v7
	v_add3_u32 v9, v61, v9, s33
	v_and_or_b32 v46, v9, s69, v7
	v_bfe_u32 v7, v63, 16, 1
	v_add3_u32 v7, v63, v7, s33
	v_bfe_u32 v9, v65, 16, 1
	v_lshrrev_b32_e32 v7, 16, v7
	v_add3_u32 v9, v65, v9, s33
	v_and_or_b32 v47, v9, s69, v7
	v_lshl_add_u64 v[52:53], v[50:51], 0, v[38:39]
	global_store_dwordx4 v[52:53], v[44:47], off
	ds_read2_b32 v[52:53], v3 offset0:49 offset1:57
	ds_read2_b32 v[54:55], v3 offset0:82 offset1:90
	ds_read2_b32 v[56:57], v3 offset0:115 offset1:123
	s_waitcnt lgkmcnt(3)
	v_bfe_u32 v7, v48, 16, 1
	v_add3_u32 v7, v48, v7, s33
	s_waitcnt lgkmcnt(2)
	v_bfe_u32 v9, v52, 16, 1
	ds_read2_b32 v[58:59], v3 offset0:148 offset1:156
	v_lshrrev_b32_e32 v7, 16, v7
	v_add3_u32 v9, v52, v9, s33
	ds_read2_b32 v[60:61], v3 offset0:181 offset1:189
	v_and_or_b32 v44, v9, s69, v7
	s_waitcnt lgkmcnt(3)
	v_bfe_u32 v7, v54, 16, 1
	v_add3_u32 v7, v54, v7, s33
	s_waitcnt lgkmcnt(2)
	v_bfe_u32 v9, v56, 16, 1
	ds_read2_b32 v[62:63], v3 offset0:214 offset1:222
	v_lshrrev_b32_e32 v7, 16, v7
	v_add3_u32 v9, v56, v9, s33
	ds_read2_b32 v[64:65], v3 offset0:247 offset1:255
	v_and_or_b32 v45, v9, s69, v7
	s_waitcnt lgkmcnt(3)
	v_bfe_u32 v7, v58, 16, 1
	v_add3_u32 v7, v58, v7, s33
	s_waitcnt lgkmcnt(2)
	v_bfe_u32 v9, v60, 16, 1
	v_lshrrev_b32_e32 v7, 16, v7
	v_add3_u32 v9, v60, v9, s33
	v_and_or_b32 v46, v9, s69, v7
	s_waitcnt lgkmcnt(1)
	v_bfe_u32 v7, v62, 16, 1
	v_add3_u32 v7, v62, v7, s33
	s_waitcnt lgkmcnt(0)
	v_bfe_u32 v9, v64, 16, 1
	v_lshrrev_b32_e32 v7, 16, v7
	v_add3_u32 v9, v64, v9, s33
	v_and_or_b32 v47, v9, s69, v7
	v_bfe_u32 v7, v49, 16, 1
	v_mov_b32_e32 v41, v129
	v_add3_u32 v7, v49, v7, s33
	v_bfe_u32 v9, v53, 16, 1
	v_lshl_add_u64 v[66:67], v[50:51], 0, v[40:41]
	v_lshrrev_b32_e32 v7, 16, v7
	v_add3_u32 v9, v53, v9, s33
	global_store_dwordx4 v[66:67], v[44:47], off
	v_mov_b32_e32 v43, v129
	v_lshl_add_u64 v[48:49], v[50:51], 0, v[42:43]
	v_and_or_b32 v44, v9, s69, v7
	v_bfe_u32 v7, v55, 16, 1
	v_add3_u32 v7, v55, v7, s33
	v_bfe_u32 v9, v57, 16, 1
	v_lshrrev_b32_e32 v7, 16, v7
	v_add3_u32 v9, v57, v9, s33
	v_and_or_b32 v45, v9, s69, v7
	v_bfe_u32 v7, v59, 16, 1
	v_add3_u32 v7, v59, v7, s33
	v_bfe_u32 v9, v61, 16, 1
	v_lshrrev_b32_e32 v7, 16, v7
	v_add3_u32 v9, v61, v9, s33
	v_and_or_b32 v46, v9, s69, v7
	v_bfe_u32 v7, v63, 16, 1
	v_add3_u32 v7, v63, v7, s33
	v_bfe_u32 v9, v65, 16, 1
	v_lshrrev_b32_e32 v7, 16, v7
	v_add3_u32 v9, v65, v9, s33
	v_and_or_b32 v47, v9, s69, v7
	global_store_dwordx4 v[48:49], v[44:47], off
	s_waitcnt lgkmcnt(0)
	s_mov_b32 s1, s0
	s_andn2_b64 vcc, exec, s[6:7]
	s_mov_b64 s[6:7], -1
	s_cbranch_vccnz .LBB0_832

.LBB0_830:
	s_lshl_b32 s7, s0, 1
	s_lshl_b32 s10, s4, 1
	v_or_b32_e32 v7, s7, v1
	v_or_b32_e32 v9, s10, v2
	s_add_i32 s11, s7, 4
	s_add_i32 s28, s10, 4
	s_add_i32 s29, s7, 8
	s_add_i32 s30, s10, 8
	s_add_i32 s36, s7, 12
	s_add_i32 s37, s10, 12
	s_add_i32 s38, s7, 16
	s_add_i32 s39, s10, 16
	s_add_i32 s40, s7, 20
	s_add_i32 s41, s10, 20
	s_add_i32 s42, s7, 24
	s_add_i32 s43, s10, 24
	s_add_i32 s7, s7, 28
	s_add_i32 s10, s10, 28
	v_add_u32_e32 v48, s6, v9
	v_or_b32_e32 v11, s11, v1
	v_or_b32_e32 v13, s28, v2
	v_or_b32_e32 v15, s29, v1
	v_or_b32_e32 v17, s30, v2
	v_or_b32_e32 v21, s36, v1
	v_or_b32_e32 v35, s37, v2
	v_or_b32_e32 v37, s38, v1
	v_or_b32_e32 v39, s39, v2
	v_or_b32_e32 v41, s40, v1
	v_or_b32_e32 v43, s41, v2
	v_or_b32_e32 v78, s42, v1
	v_or_b32_e32 v79, s43, v2
	v_or_b32_e32 v80, s7, v1
	v_or_b32_e32 v81, s10, v2
	v_add_u32_e32 v46, s1, v7
	v_ashrrev_i32_e32 v49, 31, v48
	v_add_u32_e32 v50, s1, v11
	v_add_u32_e32 v52, s6, v13
	v_add_u32_e32 v54, s1, v15
	v_add_u32_e32 v56, s6, v17
	v_add_u32_e32 v58, s1, v21
	v_add_u32_e32 v60, s6, v35
	v_add_u32_e32 v62, s1, v37
	v_add_u32_e32 v64, s6, v39
	v_add_u32_e32 v66, s1, v41
	v_add_u32_e32 v68, s6, v43
	v_add_u32_e32 v70, s1, v78
	v_add_u32_e32 v72, s6, v79
	v_add_u32_e32 v74, s1, v80
	v_add_u32_e32 v76, s6, v81
	v_ashrrev_i32_e32 v47, 31, v46
	v_lshlrev_b64 v[48:49], 12, v[48:49]
	v_ashrrev_i32_e32 v53, 31, v52
	v_ashrrev_i32_e32 v51, 31, v50
	v_ashrrev_i32_e32 v57, 31, v56
	v_ashrrev_i32_e32 v55, 31, v54
	v_ashrrev_i32_e32 v61, 31, v60
	v_ashrrev_i32_e32 v59, 31, v58
	v_ashrrev_i32_e32 v65, 31, v64
	v_ashrrev_i32_e32 v63, 31, v62
	v_ashrrev_i32_e32 v69, 31, v68
	v_ashrrev_i32_e32 v67, 31, v66
	v_ashrrev_i32_e32 v73, 31, v72
	v_ashrrev_i32_e32 v71, 31, v70
	v_ashrrev_i32_e32 v77, 31, v76
	v_ashrrev_i32_e32 v75, 31, v74
	v_lshlrev_b64 v[46:47], 12, v[46:47]
	v_lshl_add_u64 v[48:49], v[44:45], 0, v[48:49]
	v_lshlrev_b64 v[50:51], 12, v[50:51]
	v_lshlrev_b64 v[52:53], 12, v[52:53]
	v_lshlrev_b64 v[54:55], 12, v[54:55]
	v_lshlrev_b64 v[56:57], 12, v[56:57]
	v_lshlrev_b64 v[58:59], 12, v[58:59]
	v_lshlrev_b64 v[60:61], 12, v[60:61]
	v_lshlrev_b64 v[62:63], 12, v[62:63]
	v_lshlrev_b64 v[64:65], 12, v[64:65]
	v_lshlrev_b64 v[66:67], 12, v[66:67]
	v_lshlrev_b64 v[68:69], 12, v[68:69]
	v_lshlrev_b64 v[70:71], 12, v[70:71]
	v_lshlrev_b64 v[72:73], 12, v[72:73]
	v_lshlrev_b64 v[74:75], 12, v[74:75]
	v_lshlrev_b64 v[76:77], 12, v[76:77]
	v_lshl_add_u64 v[46:47], v[44:45], 0, v[46:47]
	v_lshl_add_u64 v[52:53], v[44:45], 0, v[52:53]
	v_lshl_add_u64 v[50:51], v[44:45], 0, v[50:51]
	v_lshl_add_u64 v[56:57], v[44:45], 0, v[56:57]
	v_lshl_add_u64 v[54:55], v[44:45], 0, v[54:55]
	v_lshl_add_u64 v[60:61], v[44:45], 0, v[60:61]
	v_lshl_add_u64 v[58:59], v[44:45], 0, v[58:59]
	v_lshl_add_u64 v[64:65], v[44:45], 0, v[64:65]
	v_lshl_add_u64 v[62:63], v[44:45], 0, v[62:63]
	v_lshl_add_u64 v[68:69], v[44:45], 0, v[68:69]
	v_lshl_add_u64 v[66:67], v[44:45], 0, v[66:67]
	v_lshl_add_u64 v[72:73], v[44:45], 0, v[72:73]
	v_lshl_add_u64 v[70:71], v[44:45], 0, v[70:71]
	v_lshl_add_u64 v[76:77], v[44:45], 0, v[76:77]
	v_lshl_add_u64 v[74:75], v[44:45], 0, v[74:75]
	global_load_dword v82, v[48:49], off
	global_load_dword v83, v[46:47], off
	global_load_dword v84, v[52:53], off
	global_load_dword v85, v[50:51], off
	global_load_dword v86, v[56:57], off
	global_load_dword v87, v[54:55], off
	global_load_dword v88, v[60:61], off
	global_load_dword v89, v[58:59], off
	global_load_dword v90, v[64:65], off
	global_load_dword v91, v[62:63], off
	global_load_dword v92, v[68:69], off
	global_load_dword v93, v[66:67], off
	global_load_dword v94, v[72:73], off
	global_load_dword v95, v[70:71], off
	global_load_dword v96, v[76:77], off
	global_load_dword v97, v[74:75], off
	s_add_i32 s4, s4, 16
	s_add_i32 s0, s0, 16
	s_lshl_b32 s7, s0, 1
	s_lshl_b32 s10, s4, 1
	v_or_b32_e32 v106, s7, v1
	v_or_b32_e32 v107, s10, v2
	s_add_i32 s11, s7, 4
	s_add_i32 s28, s10, 4
	s_add_i32 s29, s7, 8
	s_add_i32 s30, s10, 8
	s_add_i32 s36, s7, 12
	s_add_i32 s37, s10, 12
	s_add_i32 s38, s7, 16
	s_add_i32 s39, s10, 16
	s_add_i32 s40, s7, 20
	s_add_i32 s41, s10, 20
	s_add_i32 s42, s7, 24
	s_add_i32 s43, s10, 24
	s_add_i32 s7, s7, 28
	s_add_i32 s10, s10, 28
	v_add_u32_e32 v132, s6, v107
	v_or_b32_e32 v108, s11, v1
	v_or_b32_e32 v109, s28, v2
	v_or_b32_e32 v110, s29, v1
	v_or_b32_e32 v111, s30, v2
	v_or_b32_e32 v112, s36, v1
	v_or_b32_e32 v113, s37, v2
	v_or_b32_e32 v114, s38, v1
	v_or_b32_e32 v115, s39, v2
	v_or_b32_e32 v116, s40, v1
	v_or_b32_e32 v117, s41, v2
	v_or_b32_e32 v118, s42, v1
	v_or_b32_e32 v119, s43, v2
	v_or_b32_e32 v120, s7, v1
	v_or_b32_e32 v121, s10, v2
	v_add_u32_e32 v130, s1, v106
	v_ashrrev_i32_e32 v133, 31, v132
	v_add_u32_e32 v134, s1, v108
	v_add_u32_e32 v136, s6, v109
	v_add_u32_e32 v138, s1, v110
	v_add_u32_e32 v140, s6, v111
	v_add_u32_e32 v142, s1, v112
	v_add_u32_e32 v144, s6, v113
	v_add_u32_e32 v146, s1, v114
	v_add_u32_e32 v148, s6, v115
	v_add_u32_e32 v150, s1, v116
	v_add_u32_e32 v152, s6, v117
	v_add_u32_e32 v154, s1, v118
	v_add_u32_e32 v156, s6, v119
	v_add_u32_e32 v158, s1, v120
	v_add_u32_e32 v160, s6, v121
	v_ashrrev_i32_e32 v131, 31, v130
	v_lshlrev_b64 v[132:133], 12, v[132:133]
	v_ashrrev_i32_e32 v137, 31, v136
	v_ashrrev_i32_e32 v135, 31, v134
	v_ashrrev_i32_e32 v141, 31, v140
	v_ashrrev_i32_e32 v139, 31, v138
	v_ashrrev_i32_e32 v145, 31, v144
	v_ashrrev_i32_e32 v143, 31, v142
	v_ashrrev_i32_e32 v149, 31, v148
	v_ashrrev_i32_e32 v147, 31, v146
	v_ashrrev_i32_e32 v153, 31, v152
	v_ashrrev_i32_e32 v151, 31, v150
	v_ashrrev_i32_e32 v157, 31, v156
	v_ashrrev_i32_e32 v155, 31, v154
	v_ashrrev_i32_e32 v161, 31, v160
	v_ashrrev_i32_e32 v159, 31, v158
	v_lshlrev_b64 v[130:131], 12, v[130:131]
	v_lshl_add_u64 v[132:133], v[44:45], 0, v[132:133]
	v_lshlrev_b64 v[134:135], 12, v[134:135]
	v_lshlrev_b64 v[136:137], 12, v[136:137]
	v_lshlrev_b64 v[138:139], 12, v[138:139]
	v_lshlrev_b64 v[140:141], 12, v[140:141]
	v_lshlrev_b64 v[142:143], 12, v[142:143]
	v_lshlrev_b64 v[144:145], 12, v[144:145]
	v_lshlrev_b64 v[146:147], 12, v[146:147]
	v_lshlrev_b64 v[148:149], 12, v[148:149]
	v_lshlrev_b64 v[150:151], 12, v[150:151]
	v_lshlrev_b64 v[152:153], 12, v[152:153]
	v_lshlrev_b64 v[154:155], 12, v[154:155]
	v_lshlrev_b64 v[156:157], 12, v[156:157]
	v_lshlrev_b64 v[158:159], 12, v[158:159]
	v_lshlrev_b64 v[160:161], 12, v[160:161]
	v_lshl_add_u64 v[130:131], v[44:45], 0, v[130:131]
	v_lshl_add_u64 v[136:137], v[44:45], 0, v[136:137]
	v_lshl_add_u64 v[134:135], v[44:45], 0, v[134:135]
	v_lshl_add_u64 v[140:141], v[44:45], 0, v[140:141]
	v_lshl_add_u64 v[138:139], v[44:45], 0, v[138:139]
	v_lshl_add_u64 v[144:145], v[44:45], 0, v[144:145]
	v_lshl_add_u64 v[142:143], v[44:45], 0, v[142:143]
	v_lshl_add_u64 v[148:149], v[44:45], 0, v[148:149]
	v_lshl_add_u64 v[146:147], v[44:45], 0, v[146:147]
	v_lshl_add_u64 v[152:153], v[44:45], 0, v[152:153]
	v_lshl_add_u64 v[150:151], v[44:45], 0, v[150:151]
	v_lshl_add_u64 v[156:157], v[44:45], 0, v[156:157]
	v_lshl_add_u64 v[154:155], v[44:45], 0, v[154:155]
	v_lshl_add_u64 v[160:161], v[44:45], 0, v[160:161]
	v_lshl_add_u64 v[158:159], v[44:45], 0, v[158:159]
	global_load_dword v122, v[132:133], off
	global_load_dword v123, v[130:131], off
	global_load_dword v124, v[136:137], off
	global_load_dword v125, v[134:135], off
	global_load_dword v126, v[140:141], off
	global_load_dword v127, v[138:139], off
	global_load_dword v162, v[144:145], off
	global_load_dword v163, v[142:143], off
	global_load_dword v164, v[148:149], off
	global_load_dword v165, v[146:147], off
	global_load_dword v166, v[152:153], off
	global_load_dword v167, v[150:151], off
	global_load_dword v168, v[156:157], off
	global_load_dword v169, v[154:155], off
	global_load_dword v170, v[160:161], off
	global_load_dword v171, v[158:159], off
	v_mad_u64_u32 v[46:47], s[10:11], v9, s78, v[6:7]
	v_mad_u64_u32 v[48:49], s[10:11], v7, s78, v[6:7]
	v_mad_u64_u32 v[50:51], s[10:11], v13, s78, v[6:7]
	v_mad_u64_u32 v[52:53], s[10:11], v11, s78, v[6:7]
	v_mad_u64_u32 v[54:55], s[10:11], v17, s78, v[6:7]
	v_mad_u64_u32 v[56:57], s[10:11], v15, s78, v[6:7]
	v_mad_u64_u32 v[58:59], s[10:11], v35, s78, v[6:7]
	v_mad_u64_u32 v[60:61], s[10:11], v21, s78, v[6:7]
	v_mad_u64_u32 v[62:63], s[10:11], v39, s78, v[6:7]
	v_mad_u64_u32 v[64:65], s[10:11], v37, s78, v[6:7]
	v_mad_u64_u32 v[66:67], s[10:11], v43, s78, v[6:7]
	v_mad_u64_u32 v[68:69], s[10:11], v41, s78, v[6:7]
	v_mad_u64_u32 v[70:71], s[10:11], v79, s78, v[6:7]
	v_mad_u64_u32 v[72:73], s[10:11], v78, s78, v[6:7]
	v_mad_u64_u32 v[74:75], s[10:11], v81, s78, v[6:7]
	v_mad_u64_u32 v[76:77], s[10:11], v80, s78, v[6:7]
	s_waitcnt vmcnt(31)
	ds_write_b32 v46, v82
	s_waitcnt vmcnt(30)
	ds_write_b32 v48, v83
	s_waitcnt vmcnt(29)
	ds_write_b32 v50, v84
	s_waitcnt vmcnt(28)
	ds_write_b32 v52, v85
	s_waitcnt vmcnt(27)
	ds_write_b32 v54, v86
	s_waitcnt vmcnt(26)
	ds_write_b32 v56, v87
	s_waitcnt vmcnt(25)
	ds_write_b32 v58, v88
	s_waitcnt vmcnt(24)
	ds_write_b32 v60, v89
	s_waitcnt vmcnt(23)
	ds_write_b32 v62, v90
	s_waitcnt vmcnt(22)
	ds_write_b32 v64, v91
	s_waitcnt vmcnt(21)
	ds_write_b32 v66, v92
	s_waitcnt vmcnt(20)
	ds_write_b32 v68, v93
	s_waitcnt vmcnt(19)
	ds_write_b32 v70, v94
	s_waitcnt vmcnt(18)
	ds_write_b32 v72, v95
	s_waitcnt vmcnt(17)
	ds_write_b32 v74, v96
	s_waitcnt vmcnt(16)
	ds_write_b32 v76, v97
	v_mad_u64_u32 v[130:131], s[10:11], v107, s78, v[6:7]
	v_mad_u64_u32 v[132:133], s[10:11], v106, s78, v[6:7]
	v_mad_u64_u32 v[134:135], s[10:11], v109, s78, v[6:7]
	v_mad_u64_u32 v[136:137], s[10:11], v108, s78, v[6:7]
	v_mad_u64_u32 v[138:139], s[10:11], v111, s78, v[6:7]
	v_mad_u64_u32 v[140:141], s[10:11], v110, s78, v[6:7]
	v_mad_u64_u32 v[142:143], s[10:11], v113, s78, v[6:7]
	v_mad_u64_u32 v[144:145], s[10:11], v112, s78, v[6:7]
	v_mad_u64_u32 v[146:147], s[10:11], v115, s78, v[6:7]
	v_mad_u64_u32 v[148:149], s[10:11], v114, s78, v[6:7]
	v_mad_u64_u32 v[150:151], s[10:11], v117, s78, v[6:7]
	v_mad_u64_u32 v[152:153], s[10:11], v116, s78, v[6:7]
	v_mad_u64_u32 v[154:155], s[10:11], v119, s78, v[6:7]
	v_mad_u64_u32 v[156:157], s[10:11], v118, s78, v[6:7]
	v_mad_u64_u32 v[158:159], s[10:11], v121, s78, v[6:7]
	v_mad_u64_u32 v[160:161], s[10:11], v120, s78, v[6:7]
	s_waitcnt vmcnt(15)
	ds_write_b32 v130, v122
	s_waitcnt vmcnt(14)
	ds_write_b32 v132, v123
	s_waitcnt vmcnt(13)
	ds_write_b32 v134, v124
	s_waitcnt vmcnt(12)
	ds_write_b32 v136, v125
	s_waitcnt vmcnt(11)
	ds_write_b32 v138, v126
	s_waitcnt vmcnt(10)
	ds_write_b32 v140, v127
	s_waitcnt vmcnt(9)
	ds_write_b32 v142, v162
	s_waitcnt vmcnt(8)
	ds_write_b32 v144, v163
	s_waitcnt vmcnt(7)
	ds_write_b32 v146, v164
	s_waitcnt vmcnt(6)
	ds_write_b32 v148, v165
	s_waitcnt vmcnt(5)
	ds_write_b32 v150, v166
	s_waitcnt vmcnt(4)
	ds_write_b32 v152, v167
	s_waitcnt vmcnt(3)
	ds_write_b32 v154, v168
	s_waitcnt vmcnt(2)
	ds_write_b32 v156, v169
	s_waitcnt vmcnt(1)
	ds_write_b32 v158, v170
	s_waitcnt vmcnt(0)
	ds_write_b32 v160, v171
	s_add_i32 s4, s4, 16
	s_add_i32 s0, s0, 16
	s_add_i32 s5, s5, -16
	s_add_i32 s5, s5, -16
	s_cmp_lg_u32 s5, 0
	s_waitcnt lgkmcnt(0)
	ds_read2_b32 v[48:49], v3 offset1:8
	ds_read2_b32 v[52:53], v3 offset0:33 offset1:41
	ds_read2_b32 v[54:55], v3 offset0:66 offset1:74
	ds_read2_b32 v[56:57], v3 offset0:99 offset1:107
	ds_read2_b32 v[58:59], v3 offset0:132 offset1:140
	s_waitcnt lgkmcnt(4)
	v_bfe_u32 v7, v48, 16, 1
	v_add3_u32 v7, v48, v7, s33
	s_waitcnt lgkmcnt(3)
	v_bfe_u32 v9, v52, 16, 1
	v_lshrrev_b32_e32 v7, 16, v7
	v_add3_u32 v9, v52, v9, s33
	ds_read2_b32 v[60:61], v3 offset0:165 offset1:173
	v_and_or_b32 v44, v9, s69, v7
	s_waitcnt lgkmcnt(3)
	v_bfe_u32 v7, v54, 16, 1
	v_add3_u32 v7, v54, v7, s33
	s_waitcnt lgkmcnt(2)
	v_bfe_u32 v9, v56, 16, 1
	ds_read2_b32 v[62:63], v3 offset0:198 offset1:206
	v_lshrrev_b32_e32 v7, 16, v7
	v_add3_u32 v9, v56, v9, s33
	ds_read2_b32 v[64:65], v3 offset0:231 offset1:239
	v_and_or_b32 v45, v9, s69, v7
	s_waitcnt lgkmcnt(3)
	v_bfe_u32 v7, v58, 16, 1
	s_lshl_b64 s[0:1], s[8:9], 11
	v_add3_u32 v7, v58, v7, s33
	s_waitcnt lgkmcnt(2)
	v_bfe_u32 v9, v60, 16, 1
	s_add_u32 s4, s26, s0
	v_lshrrev_b32_e32 v7, 16, v7
	v_add3_u32 v9, v60, v9, s33
	s_addc_u32 s5, s27, s1
	s_ashr_i32 s7, s6, 31
	v_and_or_b32 v46, v9, s69, v7
	s_waitcnt lgkmcnt(1)
	v_bfe_u32 v7, v62, 16, 1
	s_lshl_b64 s[0:1], s[6:7], 1
	v_add3_u32 v7, v62, v7, s33
	s_waitcnt lgkmcnt(0)
	v_bfe_u32 v9, v64, 16, 1
	s_add_u32 s0, s4, s0
	v_lshrrev_b32_e32 v7, 16, v7
	v_add3_u32 v9, v64, v9, s33
	s_addc_u32 s1, s5, s1
	v_lshlrev_b32_e32 v128, 1, v8
	v_and_or_b32 v47, v9, s69, v7
	v_bfe_u32 v7, v49, 16, 1
	v_lshl_add_u64 v[50:51], s[0:1], 0, v[128:129]
	v_lshlrev_b32_e32 v128, 1, v10
	v_add3_u32 v7, v49, v7, s33
	v_bfe_u32 v9, v53, 16, 1
	v_lshl_add_u64 v[66:67], v[50:51], 0, v[128:129]
	v_lshrrev_b32_e32 v7, 16, v7
	v_add3_u32 v9, v53, v9, s33
	global_store_dwordx4 v[66:67], v[44:47], off
	v_lshlrev_b32_e32 v128, 1, v12
	ds_read2_b32 v[48:49], v3 offset0:16 offset1:24
	v_and_or_b32 v44, v9, s69, v7
	v_bfe_u32 v7, v55, 16, 1
	v_add3_u32 v7, v55, v7, s33
	v_bfe_u32 v9, v57, 16, 1
	v_lshrrev_b32_e32 v7, 16, v7
	v_add3_u32 v9, v57, v9, s33
	v_and_or_b32 v45, v9, s69, v7
	v_bfe_u32 v7, v59, 16, 1
	v_add3_u32 v7, v59, v7, s33
	v_bfe_u32 v9, v61, 16, 1
	v_lshrrev_b32_e32 v7, 16, v7
	v_add3_u32 v9, v61, v9, s33
	v_and_or_b32 v46, v9, s69, v7
	v_bfe_u32 v7, v63, 16, 1
	v_add3_u32 v7, v63, v7, s33
	v_bfe_u32 v9, v65, 16, 1
	v_lshrrev_b32_e32 v7, 16, v7
	v_add3_u32 v9, v65, v9, s33
	v_and_or_b32 v47, v9, s69, v7
	v_lshl_add_u64 v[52:53], v[50:51], 0, v[128:129]
	global_store_dwordx4 v[52:53], v[44:47], off
	ds_read2_b32 v[52:53], v3 offset0:49 offset1:57
	ds_read2_b32 v[54:55], v3 offset0:82 offset1:90
	ds_read2_b32 v[56:57], v3 offset0:115 offset1:123
	s_waitcnt lgkmcnt(3)
	v_bfe_u32 v7, v48, 16, 1
	v_add3_u32 v7, v48, v7, s33
	s_waitcnt lgkmcnt(2)
	v_bfe_u32 v9, v52, 16, 1
	ds_read2_b32 v[58:59], v3 offset0:148 offset1:156
	v_lshrrev_b32_e32 v7, 16, v7
	v_add3_u32 v9, v52, v9, s33
	ds_read2_b32 v[60:61], v3 offset0:181 offset1:189
	v_and_or_b32 v44, v9, s69, v7
	s_waitcnt lgkmcnt(3)
	v_bfe_u32 v7, v54, 16, 1
	v_add3_u32 v7, v54, v7, s33
	s_waitcnt lgkmcnt(2)
	v_bfe_u32 v9, v56, 16, 1
	ds_read2_b32 v[62:63], v3 offset0:214 offset1:222
	v_lshrrev_b32_e32 v7, 16, v7
	v_add3_u32 v9, v56, v9, s33
	ds_read2_b32 v[64:65], v3 offset0:247 offset1:255
	v_and_or_b32 v45, v9, s69, v7
	s_waitcnt lgkmcnt(3)
	v_bfe_u32 v7, v58, 16, 1
	v_add3_u32 v7, v58, v7, s33
	s_waitcnt lgkmcnt(2)
	v_bfe_u32 v9, v60, 16, 1
	v_lshrrev_b32_e32 v7, 16, v7
	v_add3_u32 v9, v60, v9, s33
	v_and_or_b32 v46, v9, s69, v7
	s_waitcnt lgkmcnt(1)
	v_bfe_u32 v7, v62, 16, 1
	v_add3_u32 v7, v62, v7, s33
	s_waitcnt lgkmcnt(0)
	v_bfe_u32 v9, v64, 16, 1
	v_lshrrev_b32_e32 v7, 16, v7
	v_add3_u32 v9, v64, v9, s33
	v_and_or_b32 v47, v9, s69, v7
	v_bfe_u32 v7, v49, 16, 1
	v_lshlrev_b32_e32 v128, 1, v14
	v_add3_u32 v7, v49, v7, s33
	v_bfe_u32 v9, v53, 16, 1
	v_lshl_add_u64 v[66:67], v[50:51], 0, v[128:129]
	v_lshrrev_b32_e32 v7, 16, v7
	v_add3_u32 v9, v53, v9, s33
	global_store_dwordx4 v[66:67], v[44:47], off
	v_lshlrev_b32_e32 v128, 1, v16
	v_lshl_add_u64 v[48:49], v[50:51], 0, v[128:129]
	v_and_or_b32 v44, v9, s69, v7
	v_bfe_u32 v7, v55, 16, 1
	v_add3_u32 v7, v55, v7, s33
	v_bfe_u32 v9, v57, 16, 1
	v_lshrrev_b32_e32 v7, 16, v7
	v_add3_u32 v9, v57, v9, s33
	v_and_or_b32 v45, v9, s69, v7
	v_bfe_u32 v7, v59, 16, 1
	v_add3_u32 v7, v59, v7, s33
	v_bfe_u32 v9, v61, 16, 1
	v_lshrrev_b32_e32 v7, 16, v7
	v_add3_u32 v9, v61, v9, s33
	v_and_or_b32 v46, v9, s69, v7
	v_bfe_u32 v7, v63, 16, 1
	v_add3_u32 v7, v63, v7, s33
	v_bfe_u32 v9, v65, 16, 1
	v_lshrrev_b32_e32 v7, 16, v7
	v_add3_u32 v9, v65, v9, s33
	v_and_or_b32 v47, v9, s69, v7
	global_store_dwordx4 v[48:49], v[44:47], off
	s_waitcnt lgkmcnt(0)
	s_mov_b64 s[6:7], -1
